# GEMM loops: per-phase s_setprio flips removed, one static s_setprio 1 for the younger wave half (wr==1) per GEMM phase, reset after
# speedup vs baseline: 1.0076x; 1.0076x over previous
.LBB0_236:
	s_or_b64 exec, exec, s[0:1]
	v_lshrrev_b32_e32 v2, 1, v144
	v_and_b32_e32 v11, 24, v2
	v_lshrrev_b32_e32 v2, 5, v144
	v_and_b32_e32 v2, 4, v2
	v_bfe_u32 v3, v144, 2, 2
	v_lshlrev_b32_e32 v0, 4, v144
	v_and_b32_e32 v1, 32, v144
	v_bfe_u32 v10, v144, 2, 4
	v_or3_b32 v2, v2, v3, v11
	v_lshrrev_b32_e32 v3, 3, v144
	s_movk_i32 s0, 0x70
	v_bitop3_b32 v8, v0, v1, 48 bitop3:0x6c
	v_and_b32_e32 v9, 64, v144
	v_and_or_b32 v4, v3, s0, v10
	s_movk_i32 s0, 0x60
	v_add_u32_e32 v12, 0x2000, v0
	v_or_b32_e32 v1, v8, v9
	v_and_or_b32 v3, v3, s0, v2
	v_lshrrev_b32_e32 v0, 7, v12
	s_movk_i32 s0, 0xf0
	v_readfirstlane_b32 s2, v144
	v_lshl_or_b32 v130, v3, 12, v1
	v_and_or_b32 v3, v0, s0, v10
	s_movk_i32 s0, 0xe0
	v_and_or_b32 v0, v0, s0, v2
	s_lshr_b32 s6, s2, 6
	s_or_b32 s66, s12, 64
	s_lshr_b32 s0, s3, 3
	s_mov_b32 s1, 0
	s_lshr_b32 s8, s2, 8
	s_lshl_b32 s33, s6, 10
	s_lshl_b32 s7, s66, 20
	s_lshl_b64 s[10:11], s[0:1], 20
	s_add_u32 s36, s22, s10
	s_addc_u32 s37, s23, s11
	s_add_i32 s56, s33, 0
	s_add_i32 m0, s56, 0x10000
	s_barrier
	global_load_lds_dwordx4 v130, s[36:37]
	s_add_i32 m0, s56, 0x12000
	v_lshl_or_b32 v134, v0, 12, v1
	s_add_u32 s18, s34, s7
	v_lshl_or_b32 v128, v4, 12, v1
	global_load_lds_dwordx4 v134, s[36:37]
	s_addc_u32 s19, s35, 0
	s_mov_b32 m0, s56
	s_add_i32 s57, s56, 0x2000
	v_lshl_or_b32 v132, v3, 12, v1
	global_load_lds_dwordx4 v128, s[18:19]
	s_mov_b32 m0, s57
	s_add_u32 s10, s36, 0x80000
	global_load_lds_dwordx4 v132, s[18:19]
	s_addc_u32 s11, s37, 0
	s_add_i32 m0, s56, 0x14000
	v_mov_b32_e32 v131, 0
	global_load_lds_dwordx4 v130, s[10:11]
	s_add_i32 m0, s56, 0x16000
	v_mov_b32_e32 v135, v131
	global_load_lds_dwordx4 v134, s[10:11]
	s_add_u32 s10, s18, 0x80000
	s_addc_u32 s11, s19, 0
	s_add_i32 s58, s56, 0x4000
	s_mov_b32 m0, s58
	s_add_i32 s59, s56, 0x6000
	global_load_lds_dwordx4 v128, s[10:11]
	s_mov_b32 m0, s59
	v_mov_b32_e32 v129, v131
	global_load_lds_dwordx4 v132, s[10:11]
	v_mov_b32_e32 v133, v131
	v_lshl_add_u64 v[6:7], s[36:37], 0, v[130:131]
	v_lshl_add_u64 v[4:5], s[36:37], 0, v[134:135]
	v_lshl_add_u64 v[2:3], s[18:19], 0, v[128:129]
	s_cmp_lg_u32 s8, 1
	v_lshl_add_u64 v[0:1], s[18:19], 0, v[132:133]
	s_cbranch_scc1 .LBB0_238
	s_setprio 1
	s_barrier

.LBB0_242:
	s_ashr_i32 s11, s10, 31
	s_xor_b64 s[14:15], s[28:29], -1
	s_lshl_b64 s[12:13], s[10:11], 20
	s_add_u32 s12, s34, s12
	s_addc_u32 s13, s35, s13
	s_and_b64 s[16:17], s[28:29], exec
	s_cselect_b32 s11, s13, s19
	s_cselect_b32 s67, s12, s18
	s_ashr_i32 s9, s8, 31
	s_lshl_b64 s[16:17], s[8:9], 20
	s_add_u32 s16, s22, s16
	s_addc_u32 s17, s23, s17
	s_and_b64 s[28:29], s[28:29], exec
	s_cselect_b32 s9, s17, s37
	s_cselect_b32 s28, s16, s36
	s_add_u32 s18, s18, 0x80080
	s_addc_u32 s19, s19, 0
	s_add_u32 s29, s36, 0x100
	s_addc_u32 s72, s37, 0
	s_mov_b32 s73, -2
	ds_read_b128 v[150:153], v146
	ds_read_b128 v[154:157], v146 offset:1024
	ds_read_b128 v[158:161], v146 offset:2048
	ds_read_b128 v[162:165], v146 offset:3072
	s_add_u32 s36, s18, 0xfff80080
	s_addc_u32 s37, s19, -1
	s_cmp_eq_u32 s73, 28
	s_cselect_b32 s55, s11, s37
	s_cselect_b32 s54, s67, s36
	s_cselect_b32 s37, s9, s72
	s_cselect_b32 s36, s28, s29
	v_lshl_add_u64 v[198:199], s[18:19], 0, v[138:139]
	s_add_i32 m0, s56, 0xc000
	ds_read_b128 v[166:169], v147
	ds_read_b128 v[170:173], v147 offset:1024
	ds_read_b128 v[174:177], v147 offset:2048
	ds_read_b128 v[178:181], v147 offset:3072
	ds_read_b128 v[182:185], v147 offset:4096
	ds_read_b128 v[186:189], v147 offset:5120
	ds_read_b128 v[190:193], v147 offset:6144
	ds_read_b128 v[194:197], v147 offset:7168
	global_load_lds_dwordx4 v[198:199], off
	v_lshl_add_u64 v[198:199], s[18:19], 0, v[140:141]
	s_add_i32 m0, s56, 0xe000
	s_nop 0
	global_load_lds_dwordx4 v[198:199], off
	s_waitcnt lgkmcnt(8)
	s_barrier
	s_waitcnt lgkmcnt(0)
	s_waitcnt lgkmcnt(0)
	v_mfma_f32_16x16x32_bf16 v[124:127], v[150:153], v[166:169], 0
	v_mfma_f32_16x16x32_bf16 v[120:123], v[158:161], v[166:169], 0
	v_mfma_f32_16x16x32_bf16 v[116:119], v[150:153], v[174:177], 0
	v_mfma_f32_16x16x32_bf16 v[108:111], v[158:161], v[174:177], 0
	v_mfma_f32_16x16x32_bf16 v[100:103], v[150:153], v[182:185], 0
	v_mfma_f32_16x16x32_bf16 v[96:99], v[158:161], v[182:185], 0
	v_mfma_f32_16x16x32_bf16 v[84:87], v[150:153], v[190:193], 0
	v_mfma_f32_16x16x32_bf16 v[80:83], v[158:161], v[190:193], 0
	v_mfma_f32_16x16x32_bf16 v[124:127], v[154:157], v[170:173], v[124:127]
	v_mfma_f32_16x16x32_bf16 v[120:123], v[162:165], v[170:173], v[120:123]
	v_mfma_f32_16x16x32_bf16 v[116:119], v[154:157], v[178:181], v[116:119]
	v_mfma_f32_16x16x32_bf16 v[108:111], v[162:165], v[178:181], v[108:111]
	v_mfma_f32_16x16x32_bf16 v[100:103], v[154:157], v[186:189], v[100:103]
	v_mfma_f32_16x16x32_bf16 v[96:99], v[162:165], v[186:189], v[96:99]
	v_mfma_f32_16x16x32_bf16 v[84:87], v[154:157], v[194:197], v[84:87]
	v_mfma_f32_16x16x32_bf16 v[80:83], v[162:165], v[194:197], v[80:83]
	s_barrier
	s_add_i32 s74, s63, s33
	v_lshl_add_u64 v[214:215], s[36:37], 0, v[130:131]
	s_mov_b32 m0, s74
	ds_read_b128 v[198:201], v148
	ds_read_b128 v[202:205], v148 offset:1024
	ds_read_b128 v[206:209], v148 offset:2048
	ds_read_b128 v[210:213], v148 offset:3072
	global_load_lds_dwordx4 v[214:215], off
	v_lshl_add_u64 v[216:217], s[36:37], 0, v[134:135]
	s_add_i32 m0, s74, 0x2000
	s_nop 0
	global_load_lds_dwordx4 v[216:217], off
	s_barrier
	s_waitcnt lgkmcnt(0)
	s_waitcnt lgkmcnt(0)
	v_mfma_f32_16x16x32_bf16 v[112:115], v[198:201], v[166:169], 0
	v_mfma_f32_16x16x32_bf16 v[104:107], v[206:209], v[166:169], 0
	v_mfma_f32_16x16x32_bf16 v[92:95], v[198:201], v[174:177], 0
	v_mfma_f32_16x16x32_bf16 v[88:91], v[206:209], v[174:177], 0
	v_mfma_f32_16x16x32_bf16 v[76:79], v[198:201], v[182:185], 0
	v_mfma_f32_16x16x32_bf16 v[72:75], v[206:209], v[182:185], 0
	v_mfma_f32_16x16x32_bf16 v[68:71], v[198:201], v[190:193], 0
	v_mfma_f32_16x16x32_bf16 v[64:67], v[206:209], v[190:193], 0
	v_mfma_f32_16x16x32_bf16 v[112:115], v[202:205], v[170:173], v[112:115]
	v_mfma_f32_16x16x32_bf16 v[104:107], v[210:213], v[170:173], v[104:107]
	v_mfma_f32_16x16x32_bf16 v[92:95], v[202:205], v[178:181], v[92:95]
	v_mfma_f32_16x16x32_bf16 v[88:91], v[210:213], v[178:181], v[88:91]
	v_mfma_f32_16x16x32_bf16 v[76:79], v[202:205], v[186:189], v[76:79]
	v_mfma_f32_16x16x32_bf16 v[72:75], v[210:213], v[186:189], v[72:75]
	v_mfma_f32_16x16x32_bf16 v[68:71], v[202:205], v[194:197], v[68:71]
	v_mfma_f32_16x16x32_bf16 v[64:67], v[210:213], v[194:197], v[64:67]
	s_mov_b32 m0, s56
	v_lshl_add_u64 v[218:219], s[54:55], 0, v[128:129]
	s_barrier
	ds_read_b128 v[166:169], v147 offset:16384
	ds_read_b128 v[170:173], v147 offset:17408
	ds_read_b128 v[174:177], v147 offset:18432
	ds_read_b128 v[178:181], v147 offset:19456
	ds_read_b128 v[182:185], v147 offset:20480
	ds_read_b128 v[186:189], v147 offset:21504
	ds_read_b128 v[190:193], v147 offset:22528
	ds_read_b128 v[194:197], v147 offset:23552
	global_load_lds_dwordx4 v[218:219], off
	v_lshl_add_u64 v[220:221], s[54:55], 0, v[132:133]
	s_mov_b32 m0, s57
	s_nop 0
	global_load_lds_dwordx4 v[220:221], off
	s_barrier
	s_waitcnt lgkmcnt(0)
	s_waitcnt lgkmcnt(0)
	v_mfma_f32_16x16x32_bf16 v[60:63], v[150:153], v[166:169], 0
	v_mfma_f32_16x16x32_bf16 v[56:59], v[158:161], v[166:169], 0
	v_mfma_f32_16x16x32_bf16 v[52:55], v[150:153], v[174:177], 0
	v_mfma_f32_16x16x32_bf16 v[48:51], v[158:161], v[174:177], 0
	v_mfma_f32_16x16x32_bf16 v[36:39], v[150:153], v[182:185], 0
	v_mfma_f32_16x16x32_bf16 v[32:35], v[158:161], v[182:185], 0
	v_mfma_f32_16x16x32_bf16 v[20:23], v[150:153], v[190:193], 0
	v_mfma_f32_16x16x32_bf16 v[16:19], v[158:161], v[190:193], 0
	v_mfma_f32_16x16x32_bf16 v[60:63], v[154:157], v[170:173], v[60:63]
	v_mfma_f32_16x16x32_bf16 v[56:59], v[162:165], v[170:173], v[56:59]
	v_mfma_f32_16x16x32_bf16 v[52:55], v[154:157], v[178:181], v[52:55]
	v_mfma_f32_16x16x32_bf16 v[48:51], v[162:165], v[178:181], v[48:51]
	v_mfma_f32_16x16x32_bf16 v[36:39], v[154:157], v[186:189], v[36:39]
	v_mfma_f32_16x16x32_bf16 v[32:35], v[162:165], v[186:189], v[32:35]
	v_mfma_f32_16x16x32_bf16 v[20:23], v[154:157], v[194:197], v[20:23]
	v_mfma_f32_16x16x32_bf16 v[16:19], v[162:165], v[194:197], v[16:19]
	s_barrier
	s_add_u32 s74, s36, 0x80000
	s_addc_u32 s75, s37, 0
	s_add_i32 s76, s64, s33
	v_lshl_add_u64 v[150:151], s[74:75], 0, v[130:131]
	s_mov_b32 m0, s76
	s_nop 0
	global_load_lds_dwordx4 v[150:151], off
	v_lshl_add_u64 v[150:151], s[74:75], 0, v[134:135]
	s_add_i32 m0, s76, 0x2000
	s_nop 0
	global_load_lds_dwordx4 v[150:151], off
	s_waitcnt vmcnt(6)
	s_barrier
	v_mfma_f32_16x16x32_bf16 v[44:47], v[198:201], v[166:169], 0
	v_mfma_f32_16x16x32_bf16 v[40:43], v[206:209], v[166:169], 0
	v_mfma_f32_16x16x32_bf16 v[28:31], v[198:201], v[174:177], 0
	v_mfma_f32_16x16x32_bf16 v[24:27], v[206:209], v[174:177], 0
	v_mfma_f32_16x16x32_bf16 v[12:15], v[198:201], v[182:185], 0
	v_mfma_f32_16x16x32_bf16 v[8:11], v[206:209], v[182:185], 0
	v_mfma_f32_16x16x32_bf16 v[4:7], v[198:201], v[190:193], 0
	v_mfma_f32_16x16x32_bf16 v[0:3], v[206:209], v[190:193], 0
	v_mfma_f32_16x16x32_bf16 v[44:47], v[202:205], v[170:173], v[44:47]
	v_mfma_f32_16x16x32_bf16 v[40:43], v[210:213], v[170:173], v[40:43]
	v_mfma_f32_16x16x32_bf16 v[28:31], v[202:205], v[178:181], v[28:31]
	v_mfma_f32_16x16x32_bf16 v[24:27], v[210:213], v[178:181], v[24:27]
	v_mfma_f32_16x16x32_bf16 v[12:15], v[202:205], v[186:189], v[12:15]
	v_mfma_f32_16x16x32_bf16 v[8:11], v[210:213], v[186:189], v[8:11]
	v_mfma_f32_16x16x32_bf16 v[4:7], v[202:205], v[194:197], v[4:7]
	v_mfma_f32_16x16x32_bf16 v[0:3], v[210:213], v[194:197], v[0:3]
	s_add_i32 s74, 0, 0x18000
	v_add_u32_e32 v149, s74, v143
	s_barrier
	ds_read_b128 v[150:153], v149
	ds_read_b128 v[154:157], v149 offset:1024
	ds_read_b128 v[158:161], v149 offset:2048
	ds_read_b128 v[162:165], v149 offset:3072
	s_add_u32 s54, s54, 0x80000
	s_addc_u32 s55, s55, 0
	s_mov_b32 m0, s58
	v_lshl_add_u64 v[198:199], s[54:55], 0, v[128:129]
	ds_read_b128 v[166:169], v147 offset:32768
	ds_read_b128 v[170:173], v147 offset:33792
	ds_read_b128 v[174:177], v147 offset:34816
	ds_read_b128 v[178:181], v147 offset:35840
	ds_read_b128 v[182:185], v147 offset:36864
	ds_read_b128 v[186:189], v147 offset:37888
	ds_read_b128 v[190:193], v147 offset:38912
	ds_read_b128 v[194:197], v147 offset:39936
	global_load_lds_dwordx4 v[198:199], off
	v_lshl_add_u64 v[198:199], s[54:55], 0, v[132:133]
	s_mov_b32 m0, s59
	s_nop 0
	global_load_lds_dwordx4 v[198:199], off
	s_waitcnt lgkmcnt(8)
	s_barrier
	s_waitcnt lgkmcnt(0)
	s_waitcnt lgkmcnt(0)
	v_mfma_f32_16x16x32_bf16 v[124:127], v[150:153], v[166:169], v[124:127]
	v_mfma_f32_16x16x32_bf16 v[120:123], v[158:161], v[166:169], v[120:123]
	v_mfma_f32_16x16x32_bf16 v[116:119], v[150:153], v[174:177], v[116:119]
	v_mfma_f32_16x16x32_bf16 v[108:111], v[158:161], v[174:177], v[108:111]
	v_mfma_f32_16x16x32_bf16 v[100:103], v[150:153], v[182:185], v[100:103]
	v_mfma_f32_16x16x32_bf16 v[96:99], v[158:161], v[182:185], v[96:99]
	v_mfma_f32_16x16x32_bf16 v[84:87], v[150:153], v[190:193], v[84:87]
	v_mfma_f32_16x16x32_bf16 v[80:83], v[158:161], v[190:193], v[80:83]
	v_mfma_f32_16x16x32_bf16 v[124:127], v[154:157], v[170:173], v[124:127]
	v_mfma_f32_16x16x32_bf16 v[120:123], v[162:165], v[170:173], v[120:123]
	v_mfma_f32_16x16x32_bf16 v[116:119], v[154:157], v[178:181], v[116:119]
	v_mfma_f32_16x16x32_bf16 v[108:111], v[162:165], v[178:181], v[108:111]
	v_mfma_f32_16x16x32_bf16 v[100:103], v[154:157], v[186:189], v[100:103]
	v_mfma_f32_16x16x32_bf16 v[96:99], v[162:165], v[186:189], v[96:99]
	v_mfma_f32_16x16x32_bf16 v[84:87], v[154:157], v[194:197], v[84:87]
	v_mfma_f32_16x16x32_bf16 v[80:83], v[162:165], v[194:197], v[80:83]
	s_barrier
	s_add_i32 s54, 0, 0x1c000
	s_add_i32 s55, s74, s33
	v_add_u32_e32 v149, s54, v143
	v_lshl_add_u64 v[214:215], v[214:215], 0, s[6:7]
	s_mov_b32 m0, s55
	ds_read_b128 v[198:201], v149
	ds_read_b128 v[202:205], v149 offset:1024
	ds_read_b128 v[206:209], v149 offset:2048
	ds_read_b128 v[210:213], v149 offset:3072
	global_load_lds_dwordx4 v[214:215], off
	v_lshl_add_u64 v[214:215], v[216:217], 0, s[6:7]
	s_add_i32 m0, s55, 0x2000
	s_nop 0
	global_load_lds_dwordx4 v[214:215], off
	s_barrier
	s_waitcnt lgkmcnt(0)
	s_waitcnt lgkmcnt(0)
	v_mfma_f32_16x16x32_bf16 v[112:115], v[198:201], v[166:169], v[112:115]
	v_mfma_f32_16x16x32_bf16 v[104:107], v[206:209], v[166:169], v[104:107]
	v_mfma_f32_16x16x32_bf16 v[92:95], v[198:201], v[174:177], v[92:95]
	v_mfma_f32_16x16x32_bf16 v[88:91], v[206:209], v[174:177], v[88:91]
	v_mfma_f32_16x16x32_bf16 v[76:79], v[198:201], v[182:185], v[76:79]
	v_mfma_f32_16x16x32_bf16 v[72:75], v[206:209], v[182:185], v[72:75]
	v_mfma_f32_16x16x32_bf16 v[68:71], v[198:201], v[190:193], v[68:71]
	v_mfma_f32_16x16x32_bf16 v[64:67], v[206:209], v[190:193], v[64:67]
	v_mfma_f32_16x16x32_bf16 v[112:115], v[202:205], v[170:173], v[112:115]
	v_mfma_f32_16x16x32_bf16 v[104:107], v[210:213], v[170:173], v[104:107]
	v_mfma_f32_16x16x32_bf16 v[92:95], v[202:205], v[178:181], v[92:95]
	v_mfma_f32_16x16x32_bf16 v[88:91], v[210:213], v[178:181], v[88:91]
	v_mfma_f32_16x16x32_bf16 v[76:79], v[202:205], v[186:189], v[76:79]
	v_mfma_f32_16x16x32_bf16 v[72:75], v[210:213], v[186:189], v[72:75]
	v_mfma_f32_16x16x32_bf16 v[68:71], v[202:205], v[194:197], v[68:71]
	v_mfma_f32_16x16x32_bf16 v[64:67], v[210:213], v[194:197], v[64:67]
	s_mov_b32 m0, s60
	v_lshl_add_u64 v[214:215], v[218:219], 0, s[6:7]
	s_barrier
	ds_read_b128 v[166:169], v147 offset:49152
	ds_read_b128 v[170:173], v147 offset:50176
	ds_read_b128 v[174:177], v147 offset:51200
	ds_read_b128 v[178:181], v147 offset:52224
	ds_read_b128 v[182:185], v147 offset:53248
	ds_read_b128 v[186:189], v147 offset:54272
	ds_read_b128 v[190:193], v147 offset:55296
	ds_read_b128 v[194:197], v147 offset:56320
	global_load_lds_dwordx4 v[214:215], off
	v_lshl_add_u64 v[214:215], v[220:221], 0, s[6:7]
	s_mov_b32 m0, s61
	s_nop 0
	global_load_lds_dwordx4 v[214:215], off
	s_barrier
	s_waitcnt lgkmcnt(0)
	s_waitcnt lgkmcnt(0)
	v_mfma_f32_16x16x32_bf16 v[60:63], v[150:153], v[166:169], v[60:63]
	v_mfma_f32_16x16x32_bf16 v[56:59], v[158:161], v[166:169], v[56:59]
	v_mfma_f32_16x16x32_bf16 v[52:55], v[150:153], v[174:177], v[52:55]
	v_mfma_f32_16x16x32_bf16 v[48:51], v[158:161], v[174:177], v[48:51]
	v_mfma_f32_16x16x32_bf16 v[36:39], v[150:153], v[182:185], v[36:39]
	v_mfma_f32_16x16x32_bf16 v[32:35], v[158:161], v[182:185], v[32:35]
	v_mfma_f32_16x16x32_bf16 v[20:23], v[150:153], v[190:193], v[20:23]
	v_mfma_f32_16x16x32_bf16 v[16:19], v[158:161], v[190:193], v[16:19]
	v_mfma_f32_16x16x32_bf16 v[60:63], v[154:157], v[170:173], v[60:63]
	v_mfma_f32_16x16x32_bf16 v[56:59], v[162:165], v[170:173], v[56:59]
	v_mfma_f32_16x16x32_bf16 v[52:55], v[154:157], v[178:181], v[52:55]
	v_mfma_f32_16x16x32_bf16 v[48:51], v[162:165], v[178:181], v[48:51]
	v_mfma_f32_16x16x32_bf16 v[36:39], v[154:157], v[186:189], v[36:39]
	v_mfma_f32_16x16x32_bf16 v[32:35], v[162:165], v[186:189], v[32:35]
	v_mfma_f32_16x16x32_bf16 v[20:23], v[154:157], v[194:197], v[20:23]
	v_mfma_f32_16x16x32_bf16 v[16:19], v[162:165], v[194:197], v[16:19]
	s_barrier
	s_add_u32 s36, s36, 0x80080
	s_addc_u32 s37, s37, 0
	s_add_i32 s54, s54, s33
	v_lshl_add_u64 v[150:151], s[36:37], 0, v[130:131]
	s_mov_b32 m0, s54
	s_nop 0
	global_load_lds_dwordx4 v[150:151], off
	v_lshl_add_u64 v[150:151], s[36:37], 0, v[134:135]
	s_add_i32 m0, s54, 0x2000
	s_nop 0
	global_load_lds_dwordx4 v[150:151], off
	s_waitcnt vmcnt(6)
	s_barrier
	v_mfma_f32_16x16x32_bf16 v[44:47], v[198:201], v[166:169], v[44:47]
	v_mfma_f32_16x16x32_bf16 v[40:43], v[206:209], v[166:169], v[40:43]
	v_mfma_f32_16x16x32_bf16 v[28:31], v[198:201], v[174:177], v[28:31]
	v_mfma_f32_16x16x32_bf16 v[24:27], v[206:209], v[174:177], v[24:27]
	v_mfma_f32_16x16x32_bf16 v[12:15], v[198:201], v[182:185], v[12:15]
	v_mfma_f32_16x16x32_bf16 v[8:11], v[206:209], v[182:185], v[8:11]
	v_mfma_f32_16x16x32_bf16 v[4:7], v[198:201], v[190:193], v[4:7]
	v_mfma_f32_16x16x32_bf16 v[0:3], v[206:209], v[190:193], v[0:3]
	v_mfma_f32_16x16x32_bf16 v[44:47], v[202:205], v[170:173], v[44:47]
	v_mfma_f32_16x16x32_bf16 v[40:43], v[210:213], v[170:173], v[40:43]
	v_mfma_f32_16x16x32_bf16 v[28:31], v[202:205], v[178:181], v[28:31]
	v_mfma_f32_16x16x32_bf16 v[24:27], v[210:213], v[178:181], v[24:27]
	v_mfma_f32_16x16x32_bf16 v[12:15], v[202:205], v[186:189], v[12:15]
	v_mfma_f32_16x16x32_bf16 v[8:11], v[210:213], v[186:189], v[8:11]
	v_mfma_f32_16x16x32_bf16 v[4:7], v[202:205], v[194:197], v[4:7]
	v_mfma_f32_16x16x32_bf16 v[0:3], v[210:213], v[194:197], v[0:3]
	s_add_i32 s73, s73, 2
	s_add_u32 s18, s18, 0x100
	s_addc_u32 s19, s19, 0
	s_add_u32 s29, s29, 0x100
	s_addc_u32 s72, s72, 0
	s_cmp_gt_u32 s73, 29
	s_barrier
	s_cbranch_scc0 .LBB0_243
.LBB0_243:
	ds_read_b128 v[150:153], v146
	ds_read_b128 v[154:157], v146 offset:1024
	ds_read_b128 v[158:161], v146 offset:2048
	ds_read_b128 v[162:165], v146 offset:3072
	s_add_u32 s36, s18, 0xfff80080
	s_addc_u32 s37, s19, -1
	s_cmp_eq_u32 s73, 28
	s_cselect_b32 s55, s11, s37
	s_cselect_b32 s54, s67, s36
	s_cselect_b32 s37, s9, s72
	s_cselect_b32 s36, s28, s29
	v_lshl_add_u64 v[198:199], s[18:19], 0, v[138:139]
	s_add_i32 m0, s56, 0xc000
	ds_read_b128 v[166:169], v147
	ds_read_b128 v[170:173], v147 offset:1024
	ds_read_b128 v[174:177], v147 offset:2048
	ds_read_b128 v[178:181], v147 offset:3072
	ds_read_b128 v[182:185], v147 offset:4096
	ds_read_b128 v[186:189], v147 offset:5120
	ds_read_b128 v[190:193], v147 offset:6144
	ds_read_b128 v[194:197], v147 offset:7168
	global_load_lds_dwordx4 v[198:199], off
	v_lshl_add_u64 v[198:199], s[18:19], 0, v[140:141]
	s_add_i32 m0, s56, 0xe000
	s_nop 0
	global_load_lds_dwordx4 v[198:199], off
	s_waitcnt lgkmcnt(8)
	s_barrier
	s_waitcnt lgkmcnt(0)
	s_waitcnt lgkmcnt(0)
	v_mfma_f32_16x16x32_bf16 v[124:127], v[150:153], v[166:169], v[124:127]
	v_mfma_f32_16x16x32_bf16 v[120:123], v[158:161], v[166:169], v[120:123]
	v_mfma_f32_16x16x32_bf16 v[116:119], v[150:153], v[174:177], v[116:119]
	v_mfma_f32_16x16x32_bf16 v[108:111], v[158:161], v[174:177], v[108:111]
	v_mfma_f32_16x16x32_bf16 v[100:103], v[150:153], v[182:185], v[100:103]
	v_mfma_f32_16x16x32_bf16 v[96:99], v[158:161], v[182:185], v[96:99]
	v_mfma_f32_16x16x32_bf16 v[84:87], v[150:153], v[190:193], v[84:87]
	v_mfma_f32_16x16x32_bf16 v[80:83], v[158:161], v[190:193], v[80:83]
	v_mfma_f32_16x16x32_bf16 v[124:127], v[154:157], v[170:173], v[124:127]
	v_mfma_f32_16x16x32_bf16 v[120:123], v[162:165], v[170:173], v[120:123]
	v_mfma_f32_16x16x32_bf16 v[116:119], v[154:157], v[178:181], v[116:119]
	v_mfma_f32_16x16x32_bf16 v[108:111], v[162:165], v[178:181], v[108:111]
	v_mfma_f32_16x16x32_bf16 v[100:103], v[154:157], v[186:189], v[100:103]
	v_mfma_f32_16x16x32_bf16 v[96:99], v[162:165], v[186:189], v[96:99]
	v_mfma_f32_16x16x32_bf16 v[84:87], v[154:157], v[194:197], v[84:87]
	v_mfma_f32_16x16x32_bf16 v[80:83], v[162:165], v[194:197], v[80:83]
	s_barrier
	s_add_i32 s74, s63, s33
	v_lshl_add_u64 v[214:215], s[36:37], 0, v[130:131]
	s_mov_b32 m0, s74
	ds_read_b128 v[198:201], v148
	ds_read_b128 v[202:205], v148 offset:1024
	ds_read_b128 v[206:209], v148 offset:2048
	ds_read_b128 v[210:213], v148 offset:3072
	global_load_lds_dwordx4 v[214:215], off
	v_lshl_add_u64 v[216:217], s[36:37], 0, v[134:135]
	s_add_i32 m0, s74, 0x2000
	s_nop 0
	global_load_lds_dwordx4 v[216:217], off
	s_barrier
	s_waitcnt lgkmcnt(0)
	s_waitcnt lgkmcnt(0)
	v_mfma_f32_16x16x32_bf16 v[112:115], v[198:201], v[166:169], v[112:115]
	v_mfma_f32_16x16x32_bf16 v[104:107], v[206:209], v[166:169], v[104:107]
	v_mfma_f32_16x16x32_bf16 v[92:95], v[198:201], v[174:177], v[92:95]
	v_mfma_f32_16x16x32_bf16 v[88:91], v[206:209], v[174:177], v[88:91]
	v_mfma_f32_16x16x32_bf16 v[76:79], v[198:201], v[182:185], v[76:79]
	v_mfma_f32_16x16x32_bf16 v[72:75], v[206:209], v[182:185], v[72:75]
	v_mfma_f32_16x16x32_bf16 v[68:71], v[198:201], v[190:193], v[68:71]
	v_mfma_f32_16x16x32_bf16 v[64:67], v[206:209], v[190:193], v[64:67]
	v_mfma_f32_16x16x32_bf16 v[112:115], v[202:205], v[170:173], v[112:115]
	v_mfma_f32_16x16x32_bf16 v[104:107], v[210:213], v[170:173], v[104:107]
	v_mfma_f32_16x16x32_bf16 v[92:95], v[202:205], v[178:181], v[92:95]
	v_mfma_f32_16x16x32_bf16 v[88:91], v[210:213], v[178:181], v[88:91]
	v_mfma_f32_16x16x32_bf16 v[76:79], v[202:205], v[186:189], v[76:79]
	v_mfma_f32_16x16x32_bf16 v[72:75], v[210:213], v[186:189], v[72:75]
	v_mfma_f32_16x16x32_bf16 v[68:71], v[202:205], v[194:197], v[68:71]
	v_mfma_f32_16x16x32_bf16 v[64:67], v[210:213], v[194:197], v[64:67]
	s_mov_b32 m0, s56
	v_lshl_add_u64 v[218:219], s[54:55], 0, v[128:129]
	s_barrier
	ds_read_b128 v[166:169], v147 offset:16384
	ds_read_b128 v[170:173], v147 offset:17408
	ds_read_b128 v[174:177], v147 offset:18432
	ds_read_b128 v[178:181], v147 offset:19456
	ds_read_b128 v[182:185], v147 offset:20480
	ds_read_b128 v[186:189], v147 offset:21504
	ds_read_b128 v[190:193], v147 offset:22528
	ds_read_b128 v[194:197], v147 offset:23552
	global_load_lds_dwordx4 v[218:219], off
	v_lshl_add_u64 v[220:221], s[54:55], 0, v[132:133]
	s_mov_b32 m0, s57
	s_nop 0
	global_load_lds_dwordx4 v[220:221], off
	s_barrier
	s_waitcnt lgkmcnt(0)
	s_waitcnt lgkmcnt(0)
	v_mfma_f32_16x16x32_bf16 v[60:63], v[150:153], v[166:169], v[60:63]
	v_mfma_f32_16x16x32_bf16 v[56:59], v[158:161], v[166:169], v[56:59]
	v_mfma_f32_16x16x32_bf16 v[52:55], v[150:153], v[174:177], v[52:55]
	v_mfma_f32_16x16x32_bf16 v[48:51], v[158:161], v[174:177], v[48:51]
	v_mfma_f32_16x16x32_bf16 v[36:39], v[150:153], v[182:185], v[36:39]
	v_mfma_f32_16x16x32_bf16 v[32:35], v[158:161], v[182:185], v[32:35]
	v_mfma_f32_16x16x32_bf16 v[20:23], v[150:153], v[190:193], v[20:23]
	v_mfma_f32_16x16x32_bf16 v[16:19], v[158:161], v[190:193], v[16:19]
	v_mfma_f32_16x16x32_bf16 v[60:63], v[154:157], v[170:173], v[60:63]
	v_mfma_f32_16x16x32_bf16 v[56:59], v[162:165], v[170:173], v[56:59]
	v_mfma_f32_16x16x32_bf16 v[52:55], v[154:157], v[178:181], v[52:55]
	v_mfma_f32_16x16x32_bf16 v[48:51], v[162:165], v[178:181], v[48:51]
	v_mfma_f32_16x16x32_bf16 v[36:39], v[154:157], v[186:189], v[36:39]
	v_mfma_f32_16x16x32_bf16 v[32:35], v[162:165], v[186:189], v[32:35]
	v_mfma_f32_16x16x32_bf16 v[20:23], v[154:157], v[194:197], v[20:23]
	v_mfma_f32_16x16x32_bf16 v[16:19], v[162:165], v[194:197], v[16:19]
	s_barrier
	s_add_u32 s74, s36, 0x80000
	s_addc_u32 s75, s37, 0
	s_add_i32 s76, s64, s33
	v_lshl_add_u64 v[150:151], s[74:75], 0, v[130:131]
	s_mov_b32 m0, s76
	s_nop 0
	global_load_lds_dwordx4 v[150:151], off
	v_lshl_add_u64 v[150:151], s[74:75], 0, v[134:135]
	s_add_i32 m0, s76, 0x2000
	s_nop 0
	global_load_lds_dwordx4 v[150:151], off
	s_waitcnt vmcnt(6)
	s_barrier
	v_mfma_f32_16x16x32_bf16 v[44:47], v[198:201], v[166:169], v[44:47]
	v_mfma_f32_16x16x32_bf16 v[40:43], v[206:209], v[166:169], v[40:43]
	v_mfma_f32_16x16x32_bf16 v[28:31], v[198:201], v[174:177], v[28:31]
	v_mfma_f32_16x16x32_bf16 v[24:27], v[206:209], v[174:177], v[24:27]
	v_mfma_f32_16x16x32_bf16 v[12:15], v[198:201], v[182:185], v[12:15]
	v_mfma_f32_16x16x32_bf16 v[8:11], v[206:209], v[182:185], v[8:11]
	v_mfma_f32_16x16x32_bf16 v[4:7], v[198:201], v[190:193], v[4:7]
	v_mfma_f32_16x16x32_bf16 v[0:3], v[206:209], v[190:193], v[0:3]
	v_mfma_f32_16x16x32_bf16 v[44:47], v[202:205], v[170:173], v[44:47]
	v_mfma_f32_16x16x32_bf16 v[40:43], v[210:213], v[170:173], v[40:43]
	v_mfma_f32_16x16x32_bf16 v[28:31], v[202:205], v[178:181], v[28:31]
	v_mfma_f32_16x16x32_bf16 v[24:27], v[210:213], v[178:181], v[24:27]
	v_mfma_f32_16x16x32_bf16 v[12:15], v[202:205], v[186:189], v[12:15]
	v_mfma_f32_16x16x32_bf16 v[8:11], v[210:213], v[186:189], v[8:11]
	v_mfma_f32_16x16x32_bf16 v[4:7], v[202:205], v[194:197], v[4:7]
	v_mfma_f32_16x16x32_bf16 v[0:3], v[210:213], v[194:197], v[0:3]
	s_add_i32 s74, 0, 0x18000
	v_add_u32_e32 v149, s74, v143
	s_barrier
	ds_read_b128 v[150:153], v149
	ds_read_b128 v[154:157], v149 offset:1024
	ds_read_b128 v[158:161], v149 offset:2048
	ds_read_b128 v[162:165], v149 offset:3072
	s_add_u32 s54, s54, 0x80000
	s_addc_u32 s55, s55, 0
	s_mov_b32 m0, s58
	v_lshl_add_u64 v[198:199], s[54:55], 0, v[128:129]
	ds_read_b128 v[166:169], v147 offset:32768
	ds_read_b128 v[170:173], v147 offset:33792
	ds_read_b128 v[174:177], v147 offset:34816
	ds_read_b128 v[178:181], v147 offset:35840
	ds_read_b128 v[182:185], v147 offset:36864
	ds_read_b128 v[186:189], v147 offset:37888
	ds_read_b128 v[190:193], v147 offset:38912
	ds_read_b128 v[194:197], v147 offset:39936
	global_load_lds_dwordx4 v[198:199], off
	v_lshl_add_u64 v[198:199], s[54:55], 0, v[132:133]
	s_mov_b32 m0, s59
	s_nop 0
	global_load_lds_dwordx4 v[198:199], off
	s_waitcnt lgkmcnt(8)
	s_barrier
	s_waitcnt lgkmcnt(0)
	s_waitcnt lgkmcnt(0)
	v_mfma_f32_16x16x32_bf16 v[124:127], v[150:153], v[166:169], v[124:127]
	v_mfma_f32_16x16x32_bf16 v[120:123], v[158:161], v[166:169], v[120:123]
	v_mfma_f32_16x16x32_bf16 v[116:119], v[150:153], v[174:177], v[116:119]
	v_mfma_f32_16x16x32_bf16 v[108:111], v[158:161], v[174:177], v[108:111]
	v_mfma_f32_16x16x32_bf16 v[100:103], v[150:153], v[182:185], v[100:103]
	v_mfma_f32_16x16x32_bf16 v[96:99], v[158:161], v[182:185], v[96:99]
	v_mfma_f32_16x16x32_bf16 v[84:87], v[150:153], v[190:193], v[84:87]
	v_mfma_f32_16x16x32_bf16 v[80:83], v[158:161], v[190:193], v[80:83]
	v_mfma_f32_16x16x32_bf16 v[124:127], v[154:157], v[170:173], v[124:127]
	v_mfma_f32_16x16x32_bf16 v[120:123], v[162:165], v[170:173], v[120:123]
	v_mfma_f32_16x16x32_bf16 v[116:119], v[154:157], v[178:181], v[116:119]
	v_mfma_f32_16x16x32_bf16 v[108:111], v[162:165], v[178:181], v[108:111]
	v_mfma_f32_16x16x32_bf16 v[100:103], v[154:157], v[186:189], v[100:103]
	v_mfma_f32_16x16x32_bf16 v[96:99], v[162:165], v[186:189], v[96:99]
	v_mfma_f32_16x16x32_bf16 v[84:87], v[154:157], v[194:197], v[84:87]
	v_mfma_f32_16x16x32_bf16 v[80:83], v[162:165], v[194:197], v[80:83]
	s_barrier
	s_add_i32 s54, 0, 0x1c000
	s_add_i32 s55, s74, s33
	v_add_u32_e32 v149, s54, v143
	v_lshl_add_u64 v[214:215], v[214:215], 0, s[6:7]
	s_mov_b32 m0, s55
	ds_read_b128 v[198:201], v149
	ds_read_b128 v[202:205], v149 offset:1024
	ds_read_b128 v[206:209], v149 offset:2048
	ds_read_b128 v[210:213], v149 offset:3072
	global_load_lds_dwordx4 v[214:215], off
	v_lshl_add_u64 v[214:215], v[216:217], 0, s[6:7]
	s_add_i32 m0, s55, 0x2000
	s_nop 0
	global_load_lds_dwordx4 v[214:215], off
	s_barrier
	s_waitcnt lgkmcnt(0)
	s_waitcnt lgkmcnt(0)
	v_mfma_f32_16x16x32_bf16 v[112:115], v[198:201], v[166:169], v[112:115]
	v_mfma_f32_16x16x32_bf16 v[104:107], v[206:209], v[166:169], v[104:107]
	v_mfma_f32_16x16x32_bf16 v[92:95], v[198:201], v[174:177], v[92:95]
	v_mfma_f32_16x16x32_bf16 v[88:91], v[206:209], v[174:177], v[88:91]
	v_mfma_f32_16x16x32_bf16 v[76:79], v[198:201], v[182:185], v[76:79]
	v_mfma_f32_16x16x32_bf16 v[72:75], v[206:209], v[182:185], v[72:75]
	v_mfma_f32_16x16x32_bf16 v[68:71], v[198:201], v[190:193], v[68:71]
	v_mfma_f32_16x16x32_bf16 v[64:67], v[206:209], v[190:193], v[64:67]
	v_mfma_f32_16x16x32_bf16 v[112:115], v[202:205], v[170:173], v[112:115]
	v_mfma_f32_16x16x32_bf16 v[104:107], v[210:213], v[170:173], v[104:107]
	v_mfma_f32_16x16x32_bf16 v[92:95], v[202:205], v[178:181], v[92:95]
	v_mfma_f32_16x16x32_bf16 v[88:91], v[210:213], v[178:181], v[88:91]
	v_mfma_f32_16x16x32_bf16 v[76:79], v[202:205], v[186:189], v[76:79]
	v_mfma_f32_16x16x32_bf16 v[72:75], v[210:213], v[186:189], v[72:75]
	v_mfma_f32_16x16x32_bf16 v[68:71], v[202:205], v[194:197], v[68:71]
	v_mfma_f32_16x16x32_bf16 v[64:67], v[210:213], v[194:197], v[64:67]
	s_mov_b32 m0, s60
	v_lshl_add_u64 v[214:215], v[218:219], 0, s[6:7]
	s_barrier
	ds_read_b128 v[166:169], v147 offset:49152
	ds_read_b128 v[170:173], v147 offset:50176
	ds_read_b128 v[174:177], v147 offset:51200
	ds_read_b128 v[178:181], v147 offset:52224
	ds_read_b128 v[182:185], v147 offset:53248
	ds_read_b128 v[186:189], v147 offset:54272
	ds_read_b128 v[190:193], v147 offset:55296
	ds_read_b128 v[194:197], v147 offset:56320
	global_load_lds_dwordx4 v[214:215], off
	v_lshl_add_u64 v[214:215], v[220:221], 0, s[6:7]
	s_mov_b32 m0, s61
	s_nop 0
	global_load_lds_dwordx4 v[214:215], off
	s_barrier
	s_waitcnt lgkmcnt(0)
	s_waitcnt lgkmcnt(0)
	v_mfma_f32_16x16x32_bf16 v[60:63], v[150:153], v[166:169], v[60:63]
	v_mfma_f32_16x16x32_bf16 v[56:59], v[158:161], v[166:169], v[56:59]
	v_mfma_f32_16x16x32_bf16 v[52:55], v[150:153], v[174:177], v[52:55]
	v_mfma_f32_16x16x32_bf16 v[48:51], v[158:161], v[174:177], v[48:51]
	v_mfma_f32_16x16x32_bf16 v[36:39], v[150:153], v[182:185], v[36:39]
	v_mfma_f32_16x16x32_bf16 v[32:35], v[158:161], v[182:185], v[32:35]
	v_mfma_f32_16x16x32_bf16 v[20:23], v[150:153], v[190:193], v[20:23]
	v_mfma_f32_16x16x32_bf16 v[16:19], v[158:161], v[190:193], v[16:19]
	v_mfma_f32_16x16x32_bf16 v[60:63], v[154:157], v[170:173], v[60:63]
	v_mfma_f32_16x16x32_bf16 v[56:59], v[162:165], v[170:173], v[56:59]
	v_mfma_f32_16x16x32_bf16 v[52:55], v[154:157], v[178:181], v[52:55]
	v_mfma_f32_16x16x32_bf16 v[48:51], v[162:165], v[178:181], v[48:51]
	v_mfma_f32_16x16x32_bf16 v[36:39], v[154:157], v[186:189], v[36:39]
	v_mfma_f32_16x16x32_bf16 v[32:35], v[162:165], v[186:189], v[32:35]
	v_mfma_f32_16x16x32_bf16 v[20:23], v[154:157], v[194:197], v[20:23]
	v_mfma_f32_16x16x32_bf16 v[16:19], v[162:165], v[194:197], v[16:19]
	s_barrier
	s_add_u32 s36, s36, 0x80080
	s_addc_u32 s37, s37, 0
	s_add_i32 s54, s54, s33
	v_lshl_add_u64 v[150:151], s[36:37], 0, v[130:131]
	s_mov_b32 m0, s54
	s_nop 0
	global_load_lds_dwordx4 v[150:151], off
	v_lshl_add_u64 v[150:151], s[36:37], 0, v[134:135]
	s_add_i32 m0, s54, 0x2000
	s_nop 0
	global_load_lds_dwordx4 v[150:151], off
	s_waitcnt vmcnt(6)
	s_barrier
	v_mfma_f32_16x16x32_bf16 v[44:47], v[198:201], v[166:169], v[44:47]
	v_mfma_f32_16x16x32_bf16 v[40:43], v[206:209], v[166:169], v[40:43]
	v_mfma_f32_16x16x32_bf16 v[28:31], v[198:201], v[174:177], v[28:31]
	v_mfma_f32_16x16x32_bf16 v[24:27], v[206:209], v[174:177], v[24:27]
	v_mfma_f32_16x16x32_bf16 v[12:15], v[198:201], v[182:185], v[12:15]
	v_mfma_f32_16x16x32_bf16 v[8:11], v[206:209], v[182:185], v[8:11]
	v_mfma_f32_16x16x32_bf16 v[4:7], v[198:201], v[190:193], v[4:7]
	v_mfma_f32_16x16x32_bf16 v[0:3], v[206:209], v[190:193], v[0:3]
	v_mfma_f32_16x16x32_bf16 v[44:47], v[202:205], v[170:173], v[44:47]
	v_mfma_f32_16x16x32_bf16 v[40:43], v[210:213], v[170:173], v[40:43]
	v_mfma_f32_16x16x32_bf16 v[28:31], v[202:205], v[178:181], v[28:31]
	v_mfma_f32_16x16x32_bf16 v[24:27], v[210:213], v[178:181], v[24:27]
	v_mfma_f32_16x16x32_bf16 v[12:15], v[202:205], v[186:189], v[12:15]
	v_mfma_f32_16x16x32_bf16 v[8:11], v[210:213], v[186:189], v[8:11]
	v_mfma_f32_16x16x32_bf16 v[4:7], v[202:205], v[194:197], v[4:7]
	v_mfma_f32_16x16x32_bf16 v[0:3], v[210:213], v[194:197], v[0:3]
	s_add_i32 s73, s73, 2
	s_add_u32 s18, s18, 0x100
	s_addc_u32 s19, s19, 0
	s_add_u32 s29, s29, 0x100
	s_addc_u32 s72, s72, 0
	s_cmp_gt_u32 s73, 29
	s_barrier
	s_cbranch_scc0 .LBB0_243
	v_lshl_add_u32 v150, s66, 8, v142
	v_lshl_or_b32 v149, s0, 8, v145
	v_ashrrev_i32_e32 v151, 31, v150
	v_cvt_pk_bf16_f32 v124, v124, v125
	v_cvt_pk_bf16_f32 v125, v126, v127
	v_cvt_pk_bf16_f32 v127, v122, v123
	v_ashrrev_i32_e32 v122, 4, v149
	v_cvt_pk_bf16_f32 v126, v120, v121
	v_mad_i64_i32 v[120:121], s[18:19], v122, s65, v[150:151]
	v_lshlrev_b64 v[120:121], 5, v[120:121]
	v_lshl_add_u64 v[120:121], v[136:137], 0, v[120:121]
	global_store_dwordx4 v[120:121], v[124:127], off
	v_or_b32_e32 v120, 8, v122
	v_cvt_pk_bf16_f32 v112, v112, v113
	v_cvt_pk_bf16_f32 v113, v114, v115
	v_cvt_pk_bf16_f32 v114, v104, v105
	v_mad_i64_i32 v[104:105], s[18:19], v120, s65, v[150:151]
	v_lshlrev_b64 v[104:105], 5, v[104:105]
	v_cvt_pk_bf16_f32 v115, v106, v107
	v_lshl_add_u64 v[104:105], v[136:137], 0, v[104:105]
	global_store_dwordx4 v[104:105], v[112:115], off
	v_cvt_pk_bf16_f32 v92, v92, v93
	v_cvt_pk_bf16_f32 v93, v94, v95
	v_or_b32_e32 v112, 16, v150
	v_ashrrev_i32_e32 v113, 31, v112
	v_cvt_pk_bf16_f32 v94, v88, v89
	v_mad_i64_i32 v[88:89], s[18:19], v120, s65, v[112:113]
	v_lshlrev_b64 v[88:89], 5, v[88:89]
	v_cvt_pk_bf16_f32 v95, v90, v91
	v_lshl_add_u64 v[88:89], v[136:137], 0, v[88:89]
	global_store_dwordx4 v[88:89], v[92:95], off
	v_cvt_pk_bf16_f32 v76, v76, v77
	v_cvt_pk_bf16_f32 v77, v78, v79
	v_or_b32_e32 v92, 32, v150
	v_ashrrev_i32_e32 v93, 31, v92
	v_cvt_pk_bf16_f32 v78, v72, v73
	v_mad_i64_i32 v[72:73], s[18:19], v120, s65, v[92:93]
	v_lshlrev_b64 v[72:73], 5, v[72:73]
	v_cvt_pk_bf16_f32 v79, v74, v75
	v_lshl_add_u64 v[72:73], v[136:137], 0, v[72:73]
	global_store_dwordx4 v[72:73], v[76:79], off
	v_cvt_pk_bf16_f32 v68, v68, v69
	v_cvt_pk_bf16_f32 v69, v70, v71
	v_or_b32_e32 v76, 48, v150
	v_ashrrev_i32_e32 v77, 31, v76
	v_cvt_pk_bf16_f32 v70, v64, v65
	v_mad_i64_i32 v[64:65], s[18:19], v120, s65, v[76:77]
	v_lshlrev_b64 v[64:65], 5, v[64:65]
	v_cvt_pk_bf16_f32 v71, v66, v67
	v_lshl_add_u64 v[64:65], v[136:137], 0, v[64:65]
	global_store_dwordx4 v[64:65], v[68:71], off
	v_add_u32_e32 v64, 0x80, v150
	v_ashrrev_i32_e32 v65, 31, v64
	v_cvt_pk_bf16_f32 v44, v44, v45
	v_cvt_pk_bf16_f32 v45, v46, v47
	v_cvt_pk_bf16_f32 v46, v40, v41
	v_mad_i64_i32 v[40:41], s[18:19], v120, s65, v[64:65]
	v_lshlrev_b64 v[40:41], 5, v[40:41]
	v_cvt_pk_bf16_f32 v47, v42, v43
	v_lshl_add_u64 v[40:41], v[136:137], 0, v[40:41]
	global_store_dwordx4 v[40:41], v[44:47], off
	v_cvt_pk_bf16_f32 v106, v108, v109
	v_mad_i64_i32 v[108:109], s[18:19], v122, s65, v[112:113]
	v_add_u32_e32 v44, 0x90, v150
	v_ashrrev_i32_e32 v45, 31, v44
	v_cvt_pk_bf16_f32 v28, v28, v29
	v_cvt_pk_bf16_f32 v29, v30, v31
	v_cvt_pk_bf16_f32 v30, v24, v25
	v_mad_i64_i32 v[24:25], s[18:19], v120, s65, v[44:45]
	v_lshlrev_b64 v[108:109], 5, v[108:109]
	v_lshlrev_b64 v[24:25], 5, v[24:25]
	v_cvt_pk_bf16_f32 v104, v116, v117
	v_cvt_pk_bf16_f32 v105, v118, v119
	v_cvt_pk_bf16_f32 v107, v110, v111
	v_lshl_add_u64 v[108:109], v[136:137], 0, v[108:109]
	v_cvt_pk_bf16_f32 v31, v26, v27
	v_lshl_add_u64 v[24:25], v[136:137], 0, v[24:25]
	global_store_dwordx4 v[108:109], v[104:107], off
	global_store_dwordx4 v[24:25], v[28:31], off
	v_mad_i64_i32 v[94:95], s[18:19], v122, s65, v[92:93]
	s_nop 0
	v_add_u32_e32 v28, 0xa0, v150
	v_ashrrev_i32_e32 v29, 31, v28
	v_cvt_pk_bf16_f32 v12, v12, v13
	v_cvt_pk_bf16_f32 v13, v14, v15
	v_cvt_pk_bf16_f32 v14, v8, v9
	v_mad_i64_i32 v[8:9], s[18:19], v120, s65, v[28:29]
	v_lshlrev_b64 v[94:95], 5, v[94:95]
	v_lshlrev_b64 v[8:9], 5, v[8:9]
	v_cvt_pk_bf16_f32 v88, v100, v101
	v_cvt_pk_bf16_f32 v89, v102, v103
	v_cvt_pk_bf16_f32 v90, v96, v97
	v_cvt_pk_bf16_f32 v91, v98, v99
	v_lshl_add_u64 v[94:95], v[136:137], 0, v[94:95]
	v_cvt_pk_bf16_f32 v15, v10, v11
	v_lshl_add_u64 v[8:9], v[136:137], 0, v[8:9]
	global_store_dwordx4 v[94:95], v[88:91], off
	global_store_dwordx4 v[8:9], v[12:15], off
	v_mad_i64_i32 v[78:79], s[18:19], v122, s65, v[76:77]
	s_nop 0
	v_add_u32_e32 v12, 0xb0, v150
	v_ashrrev_i32_e32 v13, 31, v12
	v_cvt_pk_bf16_f32 v60, v60, v61
	v_cvt_pk_bf16_f32 v61, v62, v63
	v_cvt_pk_bf16_f32 v62, v56, v57
	v_mad_i64_i32 v[56:57], s[18:19], v122, s65, v[64:65]
	v_mad_i64_i32 v[46:47], s[18:19], v122, s65, v[44:45]
	v_mad_i64_i32 v[30:31], s[18:19], v122, s65, v[28:29]
	v_mad_i64_i32 v[14:15], s[18:19], v122, s65, v[12:13]
	v_cvt_pk_bf16_f32 v4, v4, v5
	v_cvt_pk_bf16_f32 v5, v6, v7
	v_cvt_pk_bf16_f32 v6, v0, v1
	v_mad_i64_i32 v[0:1], s[18:19], v120, s65, v[12:13]
	v_lshlrev_b64 v[78:79], 5, v[78:79]
	v_lshlrev_b64 v[56:57], 5, v[56:57]
	v_lshlrev_b64 v[46:47], 5, v[46:47]
	v_lshlrev_b64 v[30:31], 5, v[30:31]
	v_lshlrev_b64 v[14:15], 5, v[14:15]
	v_lshlrev_b64 v[0:1], 5, v[0:1]
	v_cvt_pk_bf16_f32 v72, v84, v85
	v_cvt_pk_bf16_f32 v73, v86, v87
	v_cvt_pk_bf16_f32 v74, v80, v81
	v_cvt_pk_bf16_f32 v75, v82, v83
	v_lshl_add_u64 v[78:79], v[136:137], 0, v[78:79]
	v_cvt_pk_bf16_f32 v63, v58, v59
	v_lshl_add_u64 v[56:57], v[136:137], 0, v[56:57]
	v_cvt_pk_bf16_f32 v40, v52, v53
	v_cvt_pk_bf16_f32 v41, v54, v55
	v_cvt_pk_bf16_f32 v42, v48, v49
	v_cvt_pk_bf16_f32 v43, v50, v51
	v_lshl_add_u64 v[46:47], v[136:137], 0, v[46:47]
	v_cvt_pk_bf16_f32 v24, v36, v37
	v_cvt_pk_bf16_f32 v25, v38, v39
	v_cvt_pk_bf16_f32 v26, v32, v33
	v_cvt_pk_bf16_f32 v27, v34, v35
	v_lshl_add_u64 v[30:31], v[136:137], 0, v[30:31]
	v_cvt_pk_bf16_f32 v8, v20, v21
	v_cvt_pk_bf16_f32 v9, v22, v23
	v_cvt_pk_bf16_f32 v10, v16, v17
	v_cvt_pk_bf16_f32 v11, v18, v19
	v_lshl_add_u64 v[14:15], v[136:137], 0, v[14:15]
	v_cvt_pk_bf16_f32 v7, v2, v3
	v_lshl_add_u64 v[0:1], v[136:137], 0, v[0:1]
	s_and_b64 vcc, exec, s[14:15]
	s_mov_b32 s0, s8
	s_mov_b32 s66, s10
	s_mov_b64 s[36:37], s[16:17]
	s_mov_b64 s[18:19], s[12:13]
	global_store_dwordx4 v[78:79], v[72:75], off
	global_store_dwordx4 v[56:57], v[60:63], off
	global_store_dwordx4 v[46:47], v[40:43], off
	global_store_dwordx4 v[30:31], v[24:27], off
	global_store_dwordx4 v[14:15], v[8:11], off
	global_store_dwordx4 v[0:1], v[4:7], off
	s_cbranch_vccz .LBB0_239
	s_waitcnt vmcnt(0)
	s_cmpk_gt_u32 s2, 0xff
	s_cbranch_scc1 .LBB0_247
	s_barrier
.LBB0_247:
	s_barrier
	s_setprio 0

.LBB0_315:
	s_andn2_b64 vcc, exec, s[8:9]
	s_cbranch_vccnz .LBB0_398
	s_waitcnt vmcnt(0)
	v_lshrrev_b32_e32 v2, 1, v144
	v_and_b32_e32 v11, 24, v2
	v_lshrrev_b32_e32 v2, 5, v144
	v_and_b32_e32 v2, 4, v2
	v_bfe_u32 v3, v144, 2, 2
	v_lshlrev_b32_e32 v0, 4, v144
	v_and_b32_e32 v1, 32, v144
	v_bfe_u32 v10, v144, 2, 4
	v_or3_b32 v2, v2, v3, v11
	v_lshrrev_b32_e32 v3, 3, v144
	s_movk_i32 s1, 0x70
	v_bitop3_b32 v8, v0, v1, 48 bitop3:0x6c
	v_and_b32_e32 v9, 64, v144
	v_and_or_b32 v4, v3, s1, v10
	s_movk_i32 s1, 0x60
	v_add_u32_e32 v12, 0x2000, v0
	v_or_b32_e32 v1, v8, v9
	v_and_or_b32 v3, v3, s1, v2
	v_lshrrev_b32_e32 v0, 7, v12
	s_movk_i32 s1, 0xf0
	s_add_u32 s58, s22, 0x5e00000
	v_lshl_or_b32 v130, v3, 12, v1
	v_and_or_b32 v3, v0, s1, v10
	s_movk_i32 s1, 0xe0
	s_addc_u32 s59, s23, 0
	v_and_or_b32 v0, v0, s1, v2
	s_lshr_b32 s10, s33, 6
	s_ashr_i32 s1, s0, 31
	s_ashr_i32 s35, s34, 31
	s_lshr_b32 s12, s33, 8
	s_lshl_b32 s60, s10, 10
	s_lshl_b64 s[8:9], s[0:1], 20
	s_lshl_b64 s[14:15], s[34:35], 20
	s_add_u32 s54, s22, s14
	s_addc_u32 s55, s23, s15
	s_add_i32 s61, s60, 0
	s_add_i32 m0, s61, 0x10000
	v_lshl_or_b32 v134, v0, 12, v1
	global_load_lds_dwordx4 v130, s[54:55]
	s_add_i32 m0, s61, 0x12000
	s_waitcnt lgkmcnt(0)
	s_add_u32 s36, s58, s8
	v_lshl_or_b32 v128, v4, 12, v1
	global_load_lds_dwordx4 v134, s[54:55]
	s_addc_u32 s37, s59, s9
	s_mov_b32 m0, s61
	s_add_i32 s62, s61, 0x2000
	v_lshl_or_b32 v132, v3, 12, v1
	global_load_lds_dwordx4 v128, s[36:37]
	s_mov_b32 m0, s62
	s_add_u32 s8, s54, 0x80000
	global_load_lds_dwordx4 v132, s[36:37]
	s_addc_u32 s9, s55, 0
	s_add_i32 m0, s61, 0x14000
	v_mov_b32_e32 v131, 0
	global_load_lds_dwordx4 v130, s[8:9]
	s_add_i32 m0, s61, 0x16000
	v_mov_b32_e32 v135, v131
	global_load_lds_dwordx4 v134, s[8:9]
	s_add_u32 s8, s36, 0x80000
	s_addc_u32 s9, s37, 0
	s_add_i32 s63, s61, 0x4000
	s_mov_b32 m0, s63
	s_add_i32 s64, s61, 0x6000
	global_load_lds_dwordx4 v128, s[8:9]
	s_mov_b32 m0, s64
	v_mov_b32_e32 v129, v131
	global_load_lds_dwordx4 v132, s[8:9]
	v_mov_b32_e32 v133, v131
	s_mov_b32 s65, 0
	v_lshl_add_u64 v[6:7], s[54:55], 0, v[130:131]
	v_lshl_add_u64 v[4:5], s[54:55], 0, v[134:135]
	v_lshl_add_u64 v[2:3], s[36:37], 0, v[128:129]
	s_cmp_lg_u32 s12, 1
	v_lshl_add_u64 v[0:1], s[36:37], 0, v[132:133]
	s_cbranch_scc1 .LBB0_318
	s_setprio 1
	s_barrier

.LBB0_329:
	s_ashr_i32 s15, s14, 31
	s_xor_b64 s[16:17], s[28:29], -1
	s_lshl_b64 s[18:19], s[14:15], 20
	s_add_u32 s18, s58, s18
	s_addc_u32 s19, s59, s19
	s_and_b64 s[30:31], s[28:29], exec
	s_cselect_b32 s1, s19, s37
	s_cselect_b32 s15, s18, s36
	s_ashr_i32 s13, s12, 31
	s_lshl_b64 s[30:31], s[12:13], 20
	s_add_u32 s30, s22, s30
	s_addc_u32 s31, s23, s31
	s_and_b64 s[28:29], s[28:29], exec
	s_cselect_b32 s13, s31, s55
	s_cselect_b32 s28, s30, s54
	s_add_u32 s36, s36, 0x80080
	s_addc_u32 s37, s37, 0
	s_add_u32 s29, s54, 0x100
	s_addc_u32 s35, s55, 0
	s_mov_b32 s78, -2
	ds_read_b128 v[146:149], v152
	ds_read_b128 v[156:159], v152 offset:1024
	ds_read_b128 v[160:163], v152 offset:2048
	ds_read_b128 v[164:167], v152 offset:3072
	s_add_u32 s54, s36, 0xfff80080
	s_addc_u32 s55, s37, -1
	s_cmp_eq_u32 s78, 28
	s_cselect_b32 s57, s1, s55
	s_cselect_b32 s56, s15, s54
	s_cselect_b32 s55, s13, s35
	s_cselect_b32 s54, s28, s29
	v_lshl_add_u64 v[200:201], s[36:37], 0, v[138:139]
	s_add_i32 m0, s61, 0xc000
	ds_read_b128 v[168:171], v153
	ds_read_b128 v[172:175], v153 offset:1024
	ds_read_b128 v[176:179], v153 offset:2048
	ds_read_b128 v[180:183], v153 offset:3072
	ds_read_b128 v[184:187], v153 offset:4096
	ds_read_b128 v[188:191], v153 offset:5120
	ds_read_b128 v[192:195], v153 offset:6144
	ds_read_b128 v[196:199], v153 offset:7168
	global_load_lds_dwordx4 v[200:201], off
	v_lshl_add_u64 v[200:201], s[36:37], 0, v[140:141]
	s_add_i32 m0, s61, 0xe000
	s_nop 0
	global_load_lds_dwordx4 v[200:201], off
	s_waitcnt lgkmcnt(8)
	s_barrier
	s_waitcnt lgkmcnt(0)
	s_waitcnt lgkmcnt(0)
	v_mfma_f32_16x16x32_bf16 v[124:127], v[146:149], v[168:171], 0
	v_mfma_f32_16x16x32_bf16 v[120:123], v[160:163], v[168:171], 0
	v_mfma_f32_16x16x32_bf16 v[108:111], v[146:149], v[176:179], 0
	v_mfma_f32_16x16x32_bf16 v[104:107], v[160:163], v[176:179], 0
	v_mfma_f32_16x16x32_bf16 v[92:95], v[146:149], v[184:187], 0
	v_mfma_f32_16x16x32_bf16 v[88:91], v[160:163], v[184:187], 0
	v_mfma_f32_16x16x32_bf16 v[76:79], v[146:149], v[192:195], 0
	v_mfma_f32_16x16x32_bf16 v[72:75], v[160:163], v[192:195], 0
	v_mfma_f32_16x16x32_bf16 v[124:127], v[156:159], v[172:175], v[124:127]
	v_mfma_f32_16x16x32_bf16 v[120:123], v[164:167], v[172:175], v[120:123]
	v_mfma_f32_16x16x32_bf16 v[108:111], v[156:159], v[180:183], v[108:111]
	v_mfma_f32_16x16x32_bf16 v[104:107], v[164:167], v[180:183], v[104:107]
	v_mfma_f32_16x16x32_bf16 v[92:95], v[156:159], v[188:191], v[92:95]
	v_mfma_f32_16x16x32_bf16 v[88:91], v[164:167], v[188:191], v[88:91]
	v_mfma_f32_16x16x32_bf16 v[76:79], v[156:159], v[196:199], v[76:79]
	v_mfma_f32_16x16x32_bf16 v[72:75], v[164:167], v[196:199], v[72:75]
	s_barrier
	s_add_i32 s79, s75, s60
	v_lshl_add_u64 v[216:217], s[54:55], 0, v[130:131]
	s_mov_b32 m0, s79
	ds_read_b128 v[200:203], v154
	ds_read_b128 v[204:207], v154 offset:1024
	ds_read_b128 v[208:211], v154 offset:2048
	ds_read_b128 v[212:215], v154 offset:3072
	global_load_lds_dwordx4 v[216:217], off
	v_lshl_add_u64 v[218:219], s[54:55], 0, v[134:135]
	s_add_i32 m0, s79, 0x2000
	s_nop 0
	global_load_lds_dwordx4 v[218:219], off
	s_barrier
	s_waitcnt lgkmcnt(0)
	s_waitcnt lgkmcnt(0)
	v_mfma_f32_16x16x32_bf16 v[116:119], v[200:203], v[168:171], 0
	v_mfma_f32_16x16x32_bf16 v[112:115], v[208:211], v[168:171], 0
	v_mfma_f32_16x16x32_bf16 v[100:103], v[200:203], v[176:179], 0
	v_mfma_f32_16x16x32_bf16 v[96:99], v[208:211], v[176:179], 0
	v_mfma_f32_16x16x32_bf16 v[84:87], v[200:203], v[184:187], 0
	v_mfma_f32_16x16x32_bf16 v[80:83], v[208:211], v[184:187], 0
	v_mfma_f32_16x16x32_bf16 v[68:71], v[200:203], v[192:195], 0
	v_mfma_f32_16x16x32_bf16 v[64:67], v[208:211], v[192:195], 0
	v_mfma_f32_16x16x32_bf16 v[116:119], v[204:207], v[172:175], v[116:119]
	v_mfma_f32_16x16x32_bf16 v[112:115], v[212:215], v[172:175], v[112:115]
	v_mfma_f32_16x16x32_bf16 v[100:103], v[204:207], v[180:183], v[100:103]
	v_mfma_f32_16x16x32_bf16 v[96:99], v[212:215], v[180:183], v[96:99]
	v_mfma_f32_16x16x32_bf16 v[84:87], v[204:207], v[188:191], v[84:87]
	v_mfma_f32_16x16x32_bf16 v[80:83], v[212:215], v[188:191], v[80:83]
	v_mfma_f32_16x16x32_bf16 v[68:71], v[204:207], v[196:199], v[68:71]
	v_mfma_f32_16x16x32_bf16 v[64:67], v[212:215], v[196:199], v[64:67]
	s_mov_b32 m0, s61
	v_lshl_add_u64 v[220:221], s[56:57], 0, v[128:129]
	s_barrier
	ds_read_b128 v[168:171], v153 offset:16384
	ds_read_b128 v[172:175], v153 offset:17408
	ds_read_b128 v[176:179], v153 offset:18432
	ds_read_b128 v[180:183], v153 offset:19456
	ds_read_b128 v[184:187], v153 offset:20480
	ds_read_b128 v[188:191], v153 offset:21504
	ds_read_b128 v[192:195], v153 offset:22528
	ds_read_b128 v[196:199], v153 offset:23552
	global_load_lds_dwordx4 v[220:221], off
	v_lshl_add_u64 v[222:223], s[56:57], 0, v[132:133]
	s_mov_b32 m0, s62
	s_nop 0
	global_load_lds_dwordx4 v[222:223], off
	s_barrier
	s_waitcnt lgkmcnt(0)
	s_waitcnt lgkmcnt(0)
	v_mfma_f32_16x16x32_bf16 v[60:63], v[146:149], v[168:171], 0
	v_mfma_f32_16x16x32_bf16 v[56:59], v[160:163], v[168:171], 0
	v_mfma_f32_16x16x32_bf16 v[44:47], v[146:149], v[176:179], 0
	v_mfma_f32_16x16x32_bf16 v[40:43], v[160:163], v[176:179], 0
	v_mfma_f32_16x16x32_bf16 v[28:31], v[146:149], v[184:187], 0
	v_mfma_f32_16x16x32_bf16 v[24:27], v[160:163], v[184:187], 0
	v_mfma_f32_16x16x32_bf16 v[12:15], v[146:149], v[192:195], 0
	v_mfma_f32_16x16x32_bf16 v[8:11], v[160:163], v[192:195], 0
	v_mfma_f32_16x16x32_bf16 v[60:63], v[156:159], v[172:175], v[60:63]
	v_mfma_f32_16x16x32_bf16 v[56:59], v[164:167], v[172:175], v[56:59]
	v_mfma_f32_16x16x32_bf16 v[44:47], v[156:159], v[180:183], v[44:47]
	v_mfma_f32_16x16x32_bf16 v[40:43], v[164:167], v[180:183], v[40:43]
	v_mfma_f32_16x16x32_bf16 v[28:31], v[156:159], v[188:191], v[28:31]
	v_mfma_f32_16x16x32_bf16 v[24:27], v[164:167], v[188:191], v[24:27]
	v_mfma_f32_16x16x32_bf16 v[12:15], v[156:159], v[196:199], v[12:15]
	v_mfma_f32_16x16x32_bf16 v[8:11], v[164:167], v[196:199], v[8:11]
	s_barrier
	s_add_u32 s80, s54, 0x80000
	s_addc_u32 s81, s55, 0
	s_add_i32 s79, s76, s60
	v_lshl_add_u64 v[146:147], s[80:81], 0, v[130:131]
	s_mov_b32 m0, s79
	s_nop 0
	global_load_lds_dwordx4 v[146:147], off
	v_lshl_add_u64 v[146:147], s[80:81], 0, v[134:135]
	s_add_i32 m0, s79, 0x2000
	s_nop 0
	global_load_lds_dwordx4 v[146:147], off
	s_waitcnt vmcnt(6)
	s_barrier
	v_mfma_f32_16x16x32_bf16 v[52:55], v[200:203], v[168:171], 0
	v_mfma_f32_16x16x32_bf16 v[48:51], v[208:211], v[168:171], 0
	v_mfma_f32_16x16x32_bf16 v[36:39], v[200:203], v[176:179], 0
	v_mfma_f32_16x16x32_bf16 v[32:35], v[208:211], v[176:179], 0
	v_mfma_f32_16x16x32_bf16 v[20:23], v[200:203], v[184:187], 0
	v_mfma_f32_16x16x32_bf16 v[16:19], v[208:211], v[184:187], 0
	v_mfma_f32_16x16x32_bf16 v[4:7], v[200:203], v[192:195], 0
	v_mfma_f32_16x16x32_bf16 v[0:3], v[208:211], v[192:195], 0
	v_mfma_f32_16x16x32_bf16 v[52:55], v[204:207], v[172:175], v[52:55]
	v_mfma_f32_16x16x32_bf16 v[48:51], v[212:215], v[172:175], v[48:51]
	v_mfma_f32_16x16x32_bf16 v[36:39], v[204:207], v[180:183], v[36:39]
	v_mfma_f32_16x16x32_bf16 v[32:35], v[212:215], v[180:183], v[32:35]
	v_mfma_f32_16x16x32_bf16 v[20:23], v[204:207], v[188:191], v[20:23]
	v_mfma_f32_16x16x32_bf16 v[16:19], v[212:215], v[188:191], v[16:19]
	v_mfma_f32_16x16x32_bf16 v[4:7], v[204:207], v[196:199], v[4:7]
	v_mfma_f32_16x16x32_bf16 v[0:3], v[212:215], v[196:199], v[0:3]
	s_add_i32 s79, 0, 0x18000
	v_add_u32_e32 v155, s79, v150
	s_barrier
	ds_read_b128 v[146:149], v155
	ds_read_b128 v[156:159], v155 offset:1024
	ds_read_b128 v[160:163], v155 offset:2048
	ds_read_b128 v[164:167], v155 offset:3072
	s_add_u32 s56, s56, 0x80000
	s_addc_u32 s57, s57, 0
	s_mov_b32 m0, s63
	v_lshl_add_u64 v[200:201], s[56:57], 0, v[128:129]
	ds_read_b128 v[168:171], v153 offset:32768
	ds_read_b128 v[172:175], v153 offset:33792
	ds_read_b128 v[176:179], v153 offset:34816
	ds_read_b128 v[180:183], v153 offset:35840
	ds_read_b128 v[184:187], v153 offset:36864
	ds_read_b128 v[188:191], v153 offset:37888
	ds_read_b128 v[192:195], v153 offset:38912
	ds_read_b128 v[196:199], v153 offset:39936
	global_load_lds_dwordx4 v[200:201], off
	v_lshl_add_u64 v[200:201], s[56:57], 0, v[132:133]
	s_mov_b32 m0, s64
	s_nop 0
	global_load_lds_dwordx4 v[200:201], off
	s_waitcnt lgkmcnt(8)
	s_barrier
	s_waitcnt lgkmcnt(0)
	s_waitcnt lgkmcnt(0)
	v_mfma_f32_16x16x32_bf16 v[124:127], v[146:149], v[168:171], v[124:127]
	v_mfma_f32_16x16x32_bf16 v[120:123], v[160:163], v[168:171], v[120:123]
	v_mfma_f32_16x16x32_bf16 v[108:111], v[146:149], v[176:179], v[108:111]
	v_mfma_f32_16x16x32_bf16 v[104:107], v[160:163], v[176:179], v[104:107]
	v_mfma_f32_16x16x32_bf16 v[92:95], v[146:149], v[184:187], v[92:95]
	v_mfma_f32_16x16x32_bf16 v[88:91], v[160:163], v[184:187], v[88:91]
	v_mfma_f32_16x16x32_bf16 v[76:79], v[146:149], v[192:195], v[76:79]
	v_mfma_f32_16x16x32_bf16 v[72:75], v[160:163], v[192:195], v[72:75]
	v_mfma_f32_16x16x32_bf16 v[124:127], v[156:159], v[172:175], v[124:127]
	v_mfma_f32_16x16x32_bf16 v[120:123], v[164:167], v[172:175], v[120:123]
	v_mfma_f32_16x16x32_bf16 v[108:111], v[156:159], v[180:183], v[108:111]
	v_mfma_f32_16x16x32_bf16 v[104:107], v[164:167], v[180:183], v[104:107]
	v_mfma_f32_16x16x32_bf16 v[92:95], v[156:159], v[188:191], v[92:95]
	v_mfma_f32_16x16x32_bf16 v[88:91], v[164:167], v[188:191], v[88:91]
	v_mfma_f32_16x16x32_bf16 v[76:79], v[156:159], v[196:199], v[76:79]
	v_mfma_f32_16x16x32_bf16 v[72:75], v[164:167], v[196:199], v[72:75]
	s_barrier
	s_add_i32 s56, 0, 0x1c000
	s_add_i32 s57, s79, s60
	v_add_u32_e32 v155, s56, v150
	v_lshl_add_u64 v[216:217], v[216:217], 0, s[10:11]
	s_mov_b32 m0, s57
	ds_read_b128 v[200:203], v155
	ds_read_b128 v[204:207], v155 offset:1024
	ds_read_b128 v[208:211], v155 offset:2048
	ds_read_b128 v[212:215], v155 offset:3072
	global_load_lds_dwordx4 v[216:217], off
	v_lshl_add_u64 v[216:217], v[218:219], 0, s[10:11]
	s_add_i32 m0, s57, 0x2000
	s_nop 0
	global_load_lds_dwordx4 v[216:217], off
	s_barrier
	s_waitcnt lgkmcnt(0)
	s_waitcnt lgkmcnt(0)
	v_mfma_f32_16x16x32_bf16 v[116:119], v[200:203], v[168:171], v[116:119]
	v_mfma_f32_16x16x32_bf16 v[112:115], v[208:211], v[168:171], v[112:115]
	v_mfma_f32_16x16x32_bf16 v[100:103], v[200:203], v[176:179], v[100:103]
	v_mfma_f32_16x16x32_bf16 v[96:99], v[208:211], v[176:179], v[96:99]
	v_mfma_f32_16x16x32_bf16 v[84:87], v[200:203], v[184:187], v[84:87]
	v_mfma_f32_16x16x32_bf16 v[80:83], v[208:211], v[184:187], v[80:83]
	v_mfma_f32_16x16x32_bf16 v[68:71], v[200:203], v[192:195], v[68:71]
	v_mfma_f32_16x16x32_bf16 v[64:67], v[208:211], v[192:195], v[64:67]
	v_mfma_f32_16x16x32_bf16 v[116:119], v[204:207], v[172:175], v[116:119]
	v_mfma_f32_16x16x32_bf16 v[112:115], v[212:215], v[172:175], v[112:115]
	v_mfma_f32_16x16x32_bf16 v[100:103], v[204:207], v[180:183], v[100:103]
	v_mfma_f32_16x16x32_bf16 v[96:99], v[212:215], v[180:183], v[96:99]
	v_mfma_f32_16x16x32_bf16 v[84:87], v[204:207], v[188:191], v[84:87]
	v_mfma_f32_16x16x32_bf16 v[80:83], v[212:215], v[188:191], v[80:83]
	v_mfma_f32_16x16x32_bf16 v[68:71], v[204:207], v[196:199], v[68:71]
	v_mfma_f32_16x16x32_bf16 v[64:67], v[212:215], v[196:199], v[64:67]
	s_mov_b32 m0, s66
	v_lshl_add_u64 v[216:217], v[220:221], 0, s[10:11]
	s_barrier
	ds_read_b128 v[168:171], v153 offset:49152
	ds_read_b128 v[172:175], v153 offset:50176
	ds_read_b128 v[176:179], v153 offset:51200
	ds_read_b128 v[180:183], v153 offset:52224
	ds_read_b128 v[184:187], v153 offset:53248
	ds_read_b128 v[188:191], v153 offset:54272
	ds_read_b128 v[192:195], v153 offset:55296
	ds_read_b128 v[196:199], v153 offset:56320
	global_load_lds_dwordx4 v[216:217], off
	v_lshl_add_u64 v[216:217], v[222:223], 0, s[10:11]
	s_mov_b32 m0, s67
	s_nop 0
	global_load_lds_dwordx4 v[216:217], off
	s_barrier
	s_waitcnt lgkmcnt(0)
	s_waitcnt lgkmcnt(0)
	v_mfma_f32_16x16x32_bf16 v[60:63], v[146:149], v[168:171], v[60:63]
	v_mfma_f32_16x16x32_bf16 v[56:59], v[160:163], v[168:171], v[56:59]
	v_mfma_f32_16x16x32_bf16 v[44:47], v[146:149], v[176:179], v[44:47]
	v_mfma_f32_16x16x32_bf16 v[40:43], v[160:163], v[176:179], v[40:43]
	v_mfma_f32_16x16x32_bf16 v[28:31], v[146:149], v[184:187], v[28:31]
	v_mfma_f32_16x16x32_bf16 v[24:27], v[160:163], v[184:187], v[24:27]
	v_mfma_f32_16x16x32_bf16 v[12:15], v[146:149], v[192:195], v[12:15]
	v_mfma_f32_16x16x32_bf16 v[8:11], v[160:163], v[192:195], v[8:11]
	v_mfma_f32_16x16x32_bf16 v[60:63], v[156:159], v[172:175], v[60:63]
	v_mfma_f32_16x16x32_bf16 v[56:59], v[164:167], v[172:175], v[56:59]
	v_mfma_f32_16x16x32_bf16 v[44:47], v[156:159], v[180:183], v[44:47]
	v_mfma_f32_16x16x32_bf16 v[40:43], v[164:167], v[180:183], v[40:43]
	v_mfma_f32_16x16x32_bf16 v[28:31], v[156:159], v[188:191], v[28:31]
	v_mfma_f32_16x16x32_bf16 v[24:27], v[164:167], v[188:191], v[24:27]
	v_mfma_f32_16x16x32_bf16 v[12:15], v[156:159], v[196:199], v[12:15]
	v_mfma_f32_16x16x32_bf16 v[8:11], v[164:167], v[196:199], v[8:11]
	s_barrier
	s_add_u32 s54, s54, 0x80080
	s_addc_u32 s55, s55, 0
	s_add_i32 s56, s56, s60
	v_lshl_add_u64 v[146:147], s[54:55], 0, v[130:131]
	s_mov_b32 m0, s56
	s_nop 0
	global_load_lds_dwordx4 v[146:147], off
	v_lshl_add_u64 v[146:147], s[54:55], 0, v[134:135]
	s_add_i32 m0, s56, 0x2000
	s_nop 0
	global_load_lds_dwordx4 v[146:147], off
	s_waitcnt vmcnt(6)
	s_barrier
	v_mfma_f32_16x16x32_bf16 v[52:55], v[200:203], v[168:171], v[52:55]
	v_mfma_f32_16x16x32_bf16 v[48:51], v[208:211], v[168:171], v[48:51]
	v_mfma_f32_16x16x32_bf16 v[36:39], v[200:203], v[176:179], v[36:39]
	v_mfma_f32_16x16x32_bf16 v[32:35], v[208:211], v[176:179], v[32:35]
	v_mfma_f32_16x16x32_bf16 v[20:23], v[200:203], v[184:187], v[20:23]
	v_mfma_f32_16x16x32_bf16 v[16:19], v[208:211], v[184:187], v[16:19]
	v_mfma_f32_16x16x32_bf16 v[4:7], v[200:203], v[192:195], v[4:7]
	v_mfma_f32_16x16x32_bf16 v[0:3], v[208:211], v[192:195], v[0:3]
	v_mfma_f32_16x16x32_bf16 v[52:55], v[204:207], v[172:175], v[52:55]
	v_mfma_f32_16x16x32_bf16 v[48:51], v[212:215], v[172:175], v[48:51]
	v_mfma_f32_16x16x32_bf16 v[36:39], v[204:207], v[180:183], v[36:39]
	v_mfma_f32_16x16x32_bf16 v[32:35], v[212:215], v[180:183], v[32:35]
	v_mfma_f32_16x16x32_bf16 v[20:23], v[204:207], v[188:191], v[20:23]
	v_mfma_f32_16x16x32_bf16 v[16:19], v[212:215], v[188:191], v[16:19]
	v_mfma_f32_16x16x32_bf16 v[4:7], v[204:207], v[196:199], v[4:7]
	v_mfma_f32_16x16x32_bf16 v[0:3], v[212:215], v[196:199], v[0:3]
	s_add_i32 s78, s78, 2
	s_add_u32 s36, s36, 0x100
	s_addc_u32 s37, s37, 0
	s_add_u32 s29, s29, 0x100
	s_addc_u32 s35, s35, 0
	s_cmp_gt_u32 s78, 29
	s_barrier
	s_cbranch_scc0 .LBB0_330
.LBB0_330:
	ds_read_b128 v[146:149], v152
	ds_read_b128 v[156:159], v152 offset:1024
	ds_read_b128 v[160:163], v152 offset:2048
	ds_read_b128 v[164:167], v152 offset:3072
	s_add_u32 s54, s36, 0xfff80080
	s_addc_u32 s55, s37, -1
	s_cmp_eq_u32 s78, 28
	s_cselect_b32 s57, s1, s55
	s_cselect_b32 s56, s15, s54
	s_cselect_b32 s55, s13, s35
	s_cselect_b32 s54, s28, s29
	v_lshl_add_u64 v[200:201], s[36:37], 0, v[138:139]
	s_add_i32 m0, s61, 0xc000
	ds_read_b128 v[168:171], v153
	ds_read_b128 v[172:175], v153 offset:1024
	ds_read_b128 v[176:179], v153 offset:2048
	ds_read_b128 v[180:183], v153 offset:3072
	ds_read_b128 v[184:187], v153 offset:4096
	ds_read_b128 v[188:191], v153 offset:5120
	ds_read_b128 v[192:195], v153 offset:6144
	ds_read_b128 v[196:199], v153 offset:7168
	global_load_lds_dwordx4 v[200:201], off
	v_lshl_add_u64 v[200:201], s[36:37], 0, v[140:141]
	s_add_i32 m0, s61, 0xe000
	s_nop 0
	global_load_lds_dwordx4 v[200:201], off
	s_waitcnt lgkmcnt(8)
	s_barrier
	s_waitcnt lgkmcnt(0)
	s_waitcnt lgkmcnt(0)
	v_mfma_f32_16x16x32_bf16 v[124:127], v[146:149], v[168:171], v[124:127]
	v_mfma_f32_16x16x32_bf16 v[120:123], v[160:163], v[168:171], v[120:123]
	v_mfma_f32_16x16x32_bf16 v[108:111], v[146:149], v[176:179], v[108:111]
	v_mfma_f32_16x16x32_bf16 v[104:107], v[160:163], v[176:179], v[104:107]
	v_mfma_f32_16x16x32_bf16 v[92:95], v[146:149], v[184:187], v[92:95]
	v_mfma_f32_16x16x32_bf16 v[88:91], v[160:163], v[184:187], v[88:91]
	v_mfma_f32_16x16x32_bf16 v[76:79], v[146:149], v[192:195], v[76:79]
	v_mfma_f32_16x16x32_bf16 v[72:75], v[160:163], v[192:195], v[72:75]
	v_mfma_f32_16x16x32_bf16 v[124:127], v[156:159], v[172:175], v[124:127]
	v_mfma_f32_16x16x32_bf16 v[120:123], v[164:167], v[172:175], v[120:123]
	v_mfma_f32_16x16x32_bf16 v[108:111], v[156:159], v[180:183], v[108:111]
	v_mfma_f32_16x16x32_bf16 v[104:107], v[164:167], v[180:183], v[104:107]
	v_mfma_f32_16x16x32_bf16 v[92:95], v[156:159], v[188:191], v[92:95]
	v_mfma_f32_16x16x32_bf16 v[88:91], v[164:167], v[188:191], v[88:91]
	v_mfma_f32_16x16x32_bf16 v[76:79], v[156:159], v[196:199], v[76:79]
	v_mfma_f32_16x16x32_bf16 v[72:75], v[164:167], v[196:199], v[72:75]
	s_barrier
	s_add_i32 s79, s75, s60
	v_lshl_add_u64 v[216:217], s[54:55], 0, v[130:131]
	s_mov_b32 m0, s79
	ds_read_b128 v[200:203], v154
	ds_read_b128 v[204:207], v154 offset:1024
	ds_read_b128 v[208:211], v154 offset:2048
	ds_read_b128 v[212:215], v154 offset:3072
	global_load_lds_dwordx4 v[216:217], off
	v_lshl_add_u64 v[218:219], s[54:55], 0, v[134:135]
	s_add_i32 m0, s79, 0x2000
	s_nop 0
	global_load_lds_dwordx4 v[218:219], off
	s_barrier
	s_waitcnt lgkmcnt(0)
	s_waitcnt lgkmcnt(0)
	v_mfma_f32_16x16x32_bf16 v[116:119], v[200:203], v[168:171], v[116:119]
	v_mfma_f32_16x16x32_bf16 v[112:115], v[208:211], v[168:171], v[112:115]
	v_mfma_f32_16x16x32_bf16 v[100:103], v[200:203], v[176:179], v[100:103]
	v_mfma_f32_16x16x32_bf16 v[96:99], v[208:211], v[176:179], v[96:99]
	v_mfma_f32_16x16x32_bf16 v[84:87], v[200:203], v[184:187], v[84:87]
	v_mfma_f32_16x16x32_bf16 v[80:83], v[208:211], v[184:187], v[80:83]
	v_mfma_f32_16x16x32_bf16 v[68:71], v[200:203], v[192:195], v[68:71]
	v_mfma_f32_16x16x32_bf16 v[64:67], v[208:211], v[192:195], v[64:67]
	v_mfma_f32_16x16x32_bf16 v[116:119], v[204:207], v[172:175], v[116:119]
	v_mfma_f32_16x16x32_bf16 v[112:115], v[212:215], v[172:175], v[112:115]
	v_mfma_f32_16x16x32_bf16 v[100:103], v[204:207], v[180:183], v[100:103]
	v_mfma_f32_16x16x32_bf16 v[96:99], v[212:215], v[180:183], v[96:99]
	v_mfma_f32_16x16x32_bf16 v[84:87], v[204:207], v[188:191], v[84:87]
	v_mfma_f32_16x16x32_bf16 v[80:83], v[212:215], v[188:191], v[80:83]
	v_mfma_f32_16x16x32_bf16 v[68:71], v[204:207], v[196:199], v[68:71]
	v_mfma_f32_16x16x32_bf16 v[64:67], v[212:215], v[196:199], v[64:67]
	s_mov_b32 m0, s61
	v_lshl_add_u64 v[220:221], s[56:57], 0, v[128:129]
	s_barrier
	ds_read_b128 v[168:171], v153 offset:16384
	ds_read_b128 v[172:175], v153 offset:17408
	ds_read_b128 v[176:179], v153 offset:18432
	ds_read_b128 v[180:183], v153 offset:19456
	ds_read_b128 v[184:187], v153 offset:20480
	ds_read_b128 v[188:191], v153 offset:21504
	ds_read_b128 v[192:195], v153 offset:22528
	ds_read_b128 v[196:199], v153 offset:23552
	global_load_lds_dwordx4 v[220:221], off
	v_lshl_add_u64 v[222:223], s[56:57], 0, v[132:133]
	s_mov_b32 m0, s62
	s_nop 0
	global_load_lds_dwordx4 v[222:223], off
	s_barrier
	s_waitcnt lgkmcnt(0)
	s_waitcnt lgkmcnt(0)
	v_mfma_f32_16x16x32_bf16 v[60:63], v[146:149], v[168:171], v[60:63]
	v_mfma_f32_16x16x32_bf16 v[56:59], v[160:163], v[168:171], v[56:59]
	v_mfma_f32_16x16x32_bf16 v[44:47], v[146:149], v[176:179], v[44:47]
	v_mfma_f32_16x16x32_bf16 v[40:43], v[160:163], v[176:179], v[40:43]
	v_mfma_f32_16x16x32_bf16 v[28:31], v[146:149], v[184:187], v[28:31]
	v_mfma_f32_16x16x32_bf16 v[24:27], v[160:163], v[184:187], v[24:27]
	v_mfma_f32_16x16x32_bf16 v[12:15], v[146:149], v[192:195], v[12:15]
	v_mfma_f32_16x16x32_bf16 v[8:11], v[160:163], v[192:195], v[8:11]
	v_mfma_f32_16x16x32_bf16 v[60:63], v[156:159], v[172:175], v[60:63]
	v_mfma_f32_16x16x32_bf16 v[56:59], v[164:167], v[172:175], v[56:59]
	v_mfma_f32_16x16x32_bf16 v[44:47], v[156:159], v[180:183], v[44:47]
	v_mfma_f32_16x16x32_bf16 v[40:43], v[164:167], v[180:183], v[40:43]
	v_mfma_f32_16x16x32_bf16 v[28:31], v[156:159], v[188:191], v[28:31]
	v_mfma_f32_16x16x32_bf16 v[24:27], v[164:167], v[188:191], v[24:27]
	v_mfma_f32_16x16x32_bf16 v[12:15], v[156:159], v[196:199], v[12:15]
	v_mfma_f32_16x16x32_bf16 v[8:11], v[164:167], v[196:199], v[8:11]
	s_barrier
	s_add_u32 s80, s54, 0x80000
	s_addc_u32 s81, s55, 0
	s_add_i32 s79, s76, s60
	v_lshl_add_u64 v[146:147], s[80:81], 0, v[130:131]
	s_mov_b32 m0, s79
	s_nop 0
	global_load_lds_dwordx4 v[146:147], off
	v_lshl_add_u64 v[146:147], s[80:81], 0, v[134:135]
	s_add_i32 m0, s79, 0x2000
	s_nop 0
	global_load_lds_dwordx4 v[146:147], off
	s_waitcnt vmcnt(6)
	s_barrier
	v_mfma_f32_16x16x32_bf16 v[52:55], v[200:203], v[168:171], v[52:55]
	v_mfma_f32_16x16x32_bf16 v[48:51], v[208:211], v[168:171], v[48:51]
	v_mfma_f32_16x16x32_bf16 v[36:39], v[200:203], v[176:179], v[36:39]
	v_mfma_f32_16x16x32_bf16 v[32:35], v[208:211], v[176:179], v[32:35]
	v_mfma_f32_16x16x32_bf16 v[20:23], v[200:203], v[184:187], v[20:23]
	v_mfma_f32_16x16x32_bf16 v[16:19], v[208:211], v[184:187], v[16:19]
	v_mfma_f32_16x16x32_bf16 v[4:7], v[200:203], v[192:195], v[4:7]
	v_mfma_f32_16x16x32_bf16 v[0:3], v[208:211], v[192:195], v[0:3]
	v_mfma_f32_16x16x32_bf16 v[52:55], v[204:207], v[172:175], v[52:55]
	v_mfma_f32_16x16x32_bf16 v[48:51], v[212:215], v[172:175], v[48:51]
	v_mfma_f32_16x16x32_bf16 v[36:39], v[204:207], v[180:183], v[36:39]
	v_mfma_f32_16x16x32_bf16 v[32:35], v[212:215], v[180:183], v[32:35]
	v_mfma_f32_16x16x32_bf16 v[20:23], v[204:207], v[188:191], v[20:23]
	v_mfma_f32_16x16x32_bf16 v[16:19], v[212:215], v[188:191], v[16:19]
	v_mfma_f32_16x16x32_bf16 v[4:7], v[204:207], v[196:199], v[4:7]
	v_mfma_f32_16x16x32_bf16 v[0:3], v[212:215], v[196:199], v[0:3]
	s_add_i32 s79, 0, 0x18000
	v_add_u32_e32 v155, s79, v150
	s_barrier
	ds_read_b128 v[146:149], v155
	ds_read_b128 v[156:159], v155 offset:1024
	ds_read_b128 v[160:163], v155 offset:2048
	ds_read_b128 v[164:167], v155 offset:3072
	s_add_u32 s56, s56, 0x80000
	s_addc_u32 s57, s57, 0
	s_mov_b32 m0, s63
	v_lshl_add_u64 v[200:201], s[56:57], 0, v[128:129]
	ds_read_b128 v[168:171], v153 offset:32768
	ds_read_b128 v[172:175], v153 offset:33792
	ds_read_b128 v[176:179], v153 offset:34816
	ds_read_b128 v[180:183], v153 offset:35840
	ds_read_b128 v[184:187], v153 offset:36864
	ds_read_b128 v[188:191], v153 offset:37888
	ds_read_b128 v[192:195], v153 offset:38912
	ds_read_b128 v[196:199], v153 offset:39936
	global_load_lds_dwordx4 v[200:201], off
	v_lshl_add_u64 v[200:201], s[56:57], 0, v[132:133]
	s_mov_b32 m0, s64
	s_nop 0
	global_load_lds_dwordx4 v[200:201], off
	s_waitcnt lgkmcnt(8)
	s_barrier
	s_waitcnt lgkmcnt(0)
	s_waitcnt lgkmcnt(0)
	v_mfma_f32_16x16x32_bf16 v[124:127], v[146:149], v[168:171], v[124:127]
	v_mfma_f32_16x16x32_bf16 v[120:123], v[160:163], v[168:171], v[120:123]
	v_mfma_f32_16x16x32_bf16 v[108:111], v[146:149], v[176:179], v[108:111]
	v_mfma_f32_16x16x32_bf16 v[104:107], v[160:163], v[176:179], v[104:107]
	v_mfma_f32_16x16x32_bf16 v[92:95], v[146:149], v[184:187], v[92:95]
	v_mfma_f32_16x16x32_bf16 v[88:91], v[160:163], v[184:187], v[88:91]
	v_mfma_f32_16x16x32_bf16 v[76:79], v[146:149], v[192:195], v[76:79]
	v_mfma_f32_16x16x32_bf16 v[72:75], v[160:163], v[192:195], v[72:75]
	v_mfma_f32_16x16x32_bf16 v[124:127], v[156:159], v[172:175], v[124:127]
	v_mfma_f32_16x16x32_bf16 v[120:123], v[164:167], v[172:175], v[120:123]
	v_mfma_f32_16x16x32_bf16 v[108:111], v[156:159], v[180:183], v[108:111]
	v_mfma_f32_16x16x32_bf16 v[104:107], v[164:167], v[180:183], v[104:107]
	v_mfma_f32_16x16x32_bf16 v[92:95], v[156:159], v[188:191], v[92:95]
	v_mfma_f32_16x16x32_bf16 v[88:91], v[164:167], v[188:191], v[88:91]
	v_mfma_f32_16x16x32_bf16 v[76:79], v[156:159], v[196:199], v[76:79]
	v_mfma_f32_16x16x32_bf16 v[72:75], v[164:167], v[196:199], v[72:75]
	s_barrier
	s_add_i32 s56, 0, 0x1c000
	s_add_i32 s57, s79, s60
	v_add_u32_e32 v155, s56, v150
	v_lshl_add_u64 v[216:217], v[216:217], 0, s[10:11]
	s_mov_b32 m0, s57
	ds_read_b128 v[200:203], v155
	ds_read_b128 v[204:207], v155 offset:1024
	ds_read_b128 v[208:211], v155 offset:2048
	ds_read_b128 v[212:215], v155 offset:3072
	global_load_lds_dwordx4 v[216:217], off
	v_lshl_add_u64 v[216:217], v[218:219], 0, s[10:11]
	s_add_i32 m0, s57, 0x2000
	s_nop 0
	global_load_lds_dwordx4 v[216:217], off
	s_barrier
	s_waitcnt lgkmcnt(0)
	s_waitcnt lgkmcnt(0)
	v_mfma_f32_16x16x32_bf16 v[116:119], v[200:203], v[168:171], v[116:119]
	v_mfma_f32_16x16x32_bf16 v[112:115], v[208:211], v[168:171], v[112:115]
	v_mfma_f32_16x16x32_bf16 v[100:103], v[200:203], v[176:179], v[100:103]
	v_mfma_f32_16x16x32_bf16 v[96:99], v[208:211], v[176:179], v[96:99]
	v_mfma_f32_16x16x32_bf16 v[84:87], v[200:203], v[184:187], v[84:87]
	v_mfma_f32_16x16x32_bf16 v[80:83], v[208:211], v[184:187], v[80:83]
	v_mfma_f32_16x16x32_bf16 v[68:71], v[200:203], v[192:195], v[68:71]
	v_mfma_f32_16x16x32_bf16 v[64:67], v[208:211], v[192:195], v[64:67]
	v_mfma_f32_16x16x32_bf16 v[116:119], v[204:207], v[172:175], v[116:119]
	v_mfma_f32_16x16x32_bf16 v[112:115], v[212:215], v[172:175], v[112:115]
	v_mfma_f32_16x16x32_bf16 v[100:103], v[204:207], v[180:183], v[100:103]
	v_mfma_f32_16x16x32_bf16 v[96:99], v[212:215], v[180:183], v[96:99]
	v_mfma_f32_16x16x32_bf16 v[84:87], v[204:207], v[188:191], v[84:87]
	v_mfma_f32_16x16x32_bf16 v[80:83], v[212:215], v[188:191], v[80:83]
	v_mfma_f32_16x16x32_bf16 v[68:71], v[204:207], v[196:199], v[68:71]
	v_mfma_f32_16x16x32_bf16 v[64:67], v[212:215], v[196:199], v[64:67]
	s_mov_b32 m0, s66
	v_lshl_add_u64 v[216:217], v[220:221], 0, s[10:11]
	s_barrier
	ds_read_b128 v[168:171], v153 offset:49152
	ds_read_b128 v[172:175], v153 offset:50176
	ds_read_b128 v[176:179], v153 offset:51200
	ds_read_b128 v[180:183], v153 offset:52224
	ds_read_b128 v[184:187], v153 offset:53248
	ds_read_b128 v[188:191], v153 offset:54272
	ds_read_b128 v[192:195], v153 offset:55296
	ds_read_b128 v[196:199], v153 offset:56320
	global_load_lds_dwordx4 v[216:217], off
	v_lshl_add_u64 v[216:217], v[222:223], 0, s[10:11]
	s_mov_b32 m0, s67
	s_nop 0
	global_load_lds_dwordx4 v[216:217], off
	s_barrier
	s_waitcnt lgkmcnt(0)
	s_waitcnt lgkmcnt(0)
	v_mfma_f32_16x16x32_bf16 v[60:63], v[146:149], v[168:171], v[60:63]
	v_mfma_f32_16x16x32_bf16 v[56:59], v[160:163], v[168:171], v[56:59]
	v_mfma_f32_16x16x32_bf16 v[44:47], v[146:149], v[176:179], v[44:47]
	v_mfma_f32_16x16x32_bf16 v[40:43], v[160:163], v[176:179], v[40:43]
	v_mfma_f32_16x16x32_bf16 v[28:31], v[146:149], v[184:187], v[28:31]
	v_mfma_f32_16x16x32_bf16 v[24:27], v[160:163], v[184:187], v[24:27]
	v_mfma_f32_16x16x32_bf16 v[12:15], v[146:149], v[192:195], v[12:15]
	v_mfma_f32_16x16x32_bf16 v[8:11], v[160:163], v[192:195], v[8:11]
	v_mfma_f32_16x16x32_bf16 v[60:63], v[156:159], v[172:175], v[60:63]
	v_mfma_f32_16x16x32_bf16 v[56:59], v[164:167], v[172:175], v[56:59]
	v_mfma_f32_16x16x32_bf16 v[44:47], v[156:159], v[180:183], v[44:47]
	v_mfma_f32_16x16x32_bf16 v[40:43], v[164:167], v[180:183], v[40:43]
	v_mfma_f32_16x16x32_bf16 v[28:31], v[156:159], v[188:191], v[28:31]
	v_mfma_f32_16x16x32_bf16 v[24:27], v[164:167], v[188:191], v[24:27]
	v_mfma_f32_16x16x32_bf16 v[12:15], v[156:159], v[196:199], v[12:15]
	v_mfma_f32_16x16x32_bf16 v[8:11], v[164:167], v[196:199], v[8:11]
	s_barrier
	s_add_u32 s54, s54, 0x80080
	s_addc_u32 s55, s55, 0
	s_add_i32 s56, s56, s60
	v_lshl_add_u64 v[146:147], s[54:55], 0, v[130:131]
	s_mov_b32 m0, s56
	s_nop 0
	global_load_lds_dwordx4 v[146:147], off
	v_lshl_add_u64 v[146:147], s[54:55], 0, v[134:135]
	s_add_i32 m0, s56, 0x2000
	s_nop 0
	global_load_lds_dwordx4 v[146:147], off
	s_waitcnt vmcnt(6)
	s_barrier
	v_mfma_f32_16x16x32_bf16 v[52:55], v[200:203], v[168:171], v[52:55]
	v_mfma_f32_16x16x32_bf16 v[48:51], v[208:211], v[168:171], v[48:51]
	v_mfma_f32_16x16x32_bf16 v[36:39], v[200:203], v[176:179], v[36:39]
	v_mfma_f32_16x16x32_bf16 v[32:35], v[208:211], v[176:179], v[32:35]
	v_mfma_f32_16x16x32_bf16 v[20:23], v[200:203], v[184:187], v[20:23]
	v_mfma_f32_16x16x32_bf16 v[16:19], v[208:211], v[184:187], v[16:19]
	v_mfma_f32_16x16x32_bf16 v[4:7], v[200:203], v[192:195], v[4:7]
	v_mfma_f32_16x16x32_bf16 v[0:3], v[208:211], v[192:195], v[0:3]
	v_mfma_f32_16x16x32_bf16 v[52:55], v[204:207], v[172:175], v[52:55]
	v_mfma_f32_16x16x32_bf16 v[48:51], v[212:215], v[172:175], v[48:51]
	v_mfma_f32_16x16x32_bf16 v[36:39], v[204:207], v[180:183], v[36:39]
	v_mfma_f32_16x16x32_bf16 v[32:35], v[212:215], v[180:183], v[32:35]
	v_mfma_f32_16x16x32_bf16 v[20:23], v[204:207], v[188:191], v[20:23]
	v_mfma_f32_16x16x32_bf16 v[16:19], v[212:215], v[188:191], v[16:19]
	v_mfma_f32_16x16x32_bf16 v[4:7], v[204:207], v[196:199], v[4:7]
	v_mfma_f32_16x16x32_bf16 v[0:3], v[212:215], v[196:199], v[0:3]
	s_add_i32 s78, s78, 2
	s_add_u32 s36, s36, 0x100
	s_addc_u32 s37, s37, 0
	s_add_u32 s29, s29, 0x100
	s_addc_u32 s35, s35, 0
	s_cmp_gt_u32 s78, 29
	s_barrier
	s_cbranch_scc0 .LBB0_330
	s_cmp_gt_i32 s34, 3
	v_lshl_add_u32 v146, s0, 8, v145
	v_lshl_or_b32 v148, s34, 8, v151
	s_cselect_b64 s[34:35], -1, 0
	v_ashrrev_i32_e32 v147, 31, v146
	s_mov_b64 s[0:1], -1
	s_and_b64 vcc, exec, s[34:35]
	v_ashrrev_i32_e32 v149, 31, v148
	s_cbranch_vccz .LBB0_333
	v_and_b32_e32 v160, 63, v144
	v_lshrrev_b32_e32 v161, 6, v144
	v_lshlrev_b32_e32 v162, 10, v161
	v_add_u32_e32 v162, 0x20000, v162
	v_lshrrev_b32_e32 v163, 4, v160
	v_and_b32_e32 v164, 15, v160
	v_lshlrev_b32_e32 v165, 8, v163
	v_lshl_add_u32 v165, v164, 1, v165
	v_add_u32_e32 v165, v162, v165
	v_lshl_add_u32 v166, v160, 4, v162
	v_sub_u32_e32 v167, v148, v151
	v_and_b32_e32 v168, 0x60, v151
	v_add_u32_e32 v167, v167, v168
	v_lshl_add_u32 v167, v163, 3, v167
	v_bfe_u32 v168, v160, 2, 2
	v_add_u32_e32 v167, v167, v168
	v_sub_u32_e32 v168, v146, v145
	v_and_b32_e32 v169, 0x40, v145
	v_add_u32_e32 v168, v168, v169
	v_and_b32_e32 v169, 3, v160
	v_lshl_add_u32 v168, v169, 3, v168
	v_mov_b32_e32 v170, v167
	v_mov_b32_e32 v171, 0
	v_lshlrev_b64 v[170:171], 15, v[170:171]
	v_lshl_add_u64 v[170:171], s[8:9], 0, v[170:171]
	v_lshlrev_b32_e32 v172, 1, v168
	v_mov_b32_e32 v173, 0
	v_lshl_add_u64 v[170:171], v[170:171], 0, v[172:173]
	s_mov_b32 s28, 0xfe000000
	s_mov_b32 s29, -1
	v_lshl_add_u64 v[170:171], v[170:171], 0, s[28:29]
	s_mov_b32 s29, 0
	v_cvt_pk_bf16_f32 v190, v124, v125
	v_cvt_pk_bf16_f32 v191, v126, v127
	v_lshrrev_b32_e32 v192, 16, v190
	v_lshrrev_b32_e32 v193, 16, v191
	ds_write_b16 v165, v190 offset:0
	ds_write_b16 v165, v192 offset:64
	ds_write_b16 v165, v191 offset:128
	ds_write_b16 v165, v193 offset:192
	v_cvt_pk_bf16_f32 v198, v108, v109
	v_cvt_pk_bf16_f32 v199, v110, v111
	v_lshrrev_b32_e32 v200, 16, v198
	v_lshrrev_b32_e32 v201, 16, v199
	ds_write_b16 v165, v198 offset:32
	ds_write_b16 v165, v200 offset:96
	ds_write_b16 v165, v199 offset:160
	ds_write_b16 v165, v201 offset:224
	ds_read_b128 v[180:183], v166
	s_waitcnt lgkmcnt(0)
	global_store_dwordx4 v[170:171], v[180:183], off
	v_cvt_pk_bf16_f32 v194, v92, v93
	v_cvt_pk_bf16_f32 v195, v94, v95
	v_lshrrev_b32_e32 v196, 16, v194
	v_lshrrev_b32_e32 v197, 16, v195
	ds_write_b16 v165, v194 offset:0
	ds_write_b16 v165, v196 offset:64
	ds_write_b16 v165, v195 offset:128
	ds_write_b16 v165, v197 offset:192
	v_cvt_pk_bf16_f32 v202, v76, v77
	v_cvt_pk_bf16_f32 v203, v78, v79
	v_lshrrev_b32_e32 v204, 16, v202
	v_lshrrev_b32_e32 v205, 16, v203
	ds_write_b16 v165, v202 offset:32
	ds_write_b16 v165, v204 offset:96
	ds_write_b16 v165, v203 offset:160
	ds_write_b16 v165, v205 offset:224
	ds_read_b128 v[184:187], v166
	s_waitcnt lgkmcnt(0)
	global_store_dwordx4 v[170:171], v[184:187], off offset:64
	v_cvt_pk_bf16_f32 v190, v60, v61
	v_cvt_pk_bf16_f32 v191, v62, v63
	v_lshrrev_b32_e32 v192, 16, v190
	v_lshrrev_b32_e32 v193, 16, v191
	ds_write_b16 v165, v190 offset:0
	ds_write_b16 v165, v192 offset:64
	ds_write_b16 v165, v191 offset:128
	ds_write_b16 v165, v193 offset:192
	v_cvt_pk_bf16_f32 v198, v44, v45
	v_cvt_pk_bf16_f32 v199, v46, v47
	v_lshrrev_b32_e32 v200, 16, v198
	v_lshrrev_b32_e32 v201, 16, v199
	ds_write_b16 v165, v198 offset:32
	ds_write_b16 v165, v200 offset:96
	ds_write_b16 v165, v199 offset:160
	ds_write_b16 v165, v201 offset:224
	ds_read_b128 v[180:183], v166
	s_waitcnt lgkmcnt(0)
	global_store_dwordx4 v[170:171], v[180:183], off offset:256
	v_cvt_pk_bf16_f32 v194, v28, v29
	v_cvt_pk_bf16_f32 v195, v30, v31
	v_lshrrev_b32_e32 v196, 16, v194
	v_lshrrev_b32_e32 v197, 16, v195
	ds_write_b16 v165, v194 offset:0
	ds_write_b16 v165, v196 offset:64
	ds_write_b16 v165, v195 offset:128
	ds_write_b16 v165, v197 offset:192
	v_cvt_pk_bf16_f32 v202, v12, v13
	v_cvt_pk_bf16_f32 v203, v14, v15
	v_lshrrev_b32_e32 v204, 16, v202
	v_lshrrev_b32_e32 v205, 16, v203
	ds_write_b16 v165, v202 offset:32
	ds_write_b16 v165, v204 offset:96
	ds_write_b16 v165, v203 offset:160
	ds_write_b16 v165, v205 offset:224
	ds_read_b128 v[184:187], v166
	s_waitcnt lgkmcnt(0)
	global_store_dwordx4 v[170:171], v[184:187], off offset:320
	s_mov_b32 s28, 0x20000
	v_lshl_add_u64 v[174:175], v[170:171], 0, s[28:29]
	v_cvt_pk_bf16_f32 v190, v120, v121
	v_cvt_pk_bf16_f32 v191, v122, v123
	v_lshrrev_b32_e32 v192, 16, v190
	v_lshrrev_b32_e32 v193, 16, v191
	ds_write_b16 v165, v190 offset:0
	ds_write_b16 v165, v192 offset:64
	ds_write_b16 v165, v191 offset:128
	ds_write_b16 v165, v193 offset:192
	v_cvt_pk_bf16_f32 v198, v104, v105
	v_cvt_pk_bf16_f32 v199, v106, v107
	v_lshrrev_b32_e32 v200, 16, v198
	v_lshrrev_b32_e32 v201, 16, v199
	ds_write_b16 v165, v198 offset:32
	ds_write_b16 v165, v200 offset:96
	ds_write_b16 v165, v199 offset:160
	ds_write_b16 v165, v201 offset:224
	ds_read_b128 v[180:183], v166
	s_waitcnt lgkmcnt(0)
	global_store_dwordx4 v[174:175], v[180:183], off
	v_cvt_pk_bf16_f32 v194, v88, v89
	v_cvt_pk_bf16_f32 v195, v90, v91
	v_lshrrev_b32_e32 v196, 16, v194
	v_lshrrev_b32_e32 v197, 16, v195
	ds_write_b16 v165, v194 offset:0
	ds_write_b16 v165, v196 offset:64
	ds_write_b16 v165, v195 offset:128
	ds_write_b16 v165, v197 offset:192
	v_cvt_pk_bf16_f32 v202, v72, v73
	v_cvt_pk_bf16_f32 v203, v74, v75
	v_lshrrev_b32_e32 v204, 16, v202
	v_lshrrev_b32_e32 v205, 16, v203
	ds_write_b16 v165, v202 offset:32
	ds_write_b16 v165, v204 offset:96
	ds_write_b16 v165, v203 offset:160
	ds_write_b16 v165, v205 offset:224
	ds_read_b128 v[184:187], v166
	s_waitcnt lgkmcnt(0)
	global_store_dwordx4 v[174:175], v[184:187], off offset:64
	v_cvt_pk_bf16_f32 v190, v56, v57
	v_cvt_pk_bf16_f32 v191, v58, v59
	v_lshrrev_b32_e32 v192, 16, v190
	v_lshrrev_b32_e32 v193, 16, v191
	ds_write_b16 v165, v190 offset:0
	ds_write_b16 v165, v192 offset:64
	ds_write_b16 v165, v191 offset:128
	ds_write_b16 v165, v193 offset:192
	v_cvt_pk_bf16_f32 v198, v40, v41
	v_cvt_pk_bf16_f32 v199, v42, v43
	v_lshrrev_b32_e32 v200, 16, v198
	v_lshrrev_b32_e32 v201, 16, v199
	ds_write_b16 v165, v198 offset:32
	ds_write_b16 v165, v200 offset:96
	ds_write_b16 v165, v199 offset:160
	ds_write_b16 v165, v201 offset:224
	ds_read_b128 v[180:183], v166
	s_waitcnt lgkmcnt(0)
	global_store_dwordx4 v[174:175], v[180:183], off offset:256
	v_cvt_pk_bf16_f32 v194, v24, v25
	v_cvt_pk_bf16_f32 v195, v26, v27
	v_lshrrev_b32_e32 v196, 16, v194
	v_lshrrev_b32_e32 v197, 16, v195
	ds_write_b16 v165, v194 offset:0
	ds_write_b16 v165, v196 offset:64
	ds_write_b16 v165, v195 offset:128
	ds_write_b16 v165, v197 offset:192
	v_cvt_pk_bf16_f32 v202, v8, v9
	v_cvt_pk_bf16_f32 v203, v10, v11
	v_lshrrev_b32_e32 v204, 16, v202
	v_lshrrev_b32_e32 v205, 16, v203
	ds_write_b16 v165, v202 offset:32
	ds_write_b16 v165, v204 offset:96
	ds_write_b16 v165, v203 offset:160
	ds_write_b16 v165, v205 offset:224
	ds_read_b128 v[184:187], v166
	s_waitcnt lgkmcnt(0)
	global_store_dwordx4 v[174:175], v[184:187], off offset:320
	s_mov_b32 s28, 0x400000
	v_lshl_add_u64 v[174:175], v[170:171], 0, s[28:29]
	v_cvt_pk_bf16_f32 v190, v116, v117
	v_cvt_pk_bf16_f32 v191, v118, v119
	v_lshrrev_b32_e32 v192, 16, v190
	v_lshrrev_b32_e32 v193, 16, v191
	ds_write_b16 v165, v190 offset:0
	ds_write_b16 v165, v192 offset:64
	ds_write_b16 v165, v191 offset:128
	ds_write_b16 v165, v193 offset:192
	v_cvt_pk_bf16_f32 v198, v100, v101
	v_cvt_pk_bf16_f32 v199, v102, v103
	v_lshrrev_b32_e32 v200, 16, v198
	v_lshrrev_b32_e32 v201, 16, v199
	ds_write_b16 v165, v198 offset:32
	ds_write_b16 v165, v200 offset:96
	ds_write_b16 v165, v199 offset:160
	ds_write_b16 v165, v201 offset:224
	ds_read_b128 v[180:183], v166
	s_waitcnt lgkmcnt(0)
	global_store_dwordx4 v[174:175], v[180:183], off
	v_cvt_pk_bf16_f32 v194, v84, v85
	v_cvt_pk_bf16_f32 v195, v86, v87
	v_lshrrev_b32_e32 v196, 16, v194
	v_lshrrev_b32_e32 v197, 16, v195
	ds_write_b16 v165, v194 offset:0
	ds_write_b16 v165, v196 offset:64
	ds_write_b16 v165, v195 offset:128
	ds_write_b16 v165, v197 offset:192
	v_cvt_pk_bf16_f32 v202, v68, v69
	v_cvt_pk_bf16_f32 v203, v70, v71
	v_lshrrev_b32_e32 v204, 16, v202
	v_lshrrev_b32_e32 v205, 16, v203
	ds_write_b16 v165, v202 offset:32
	ds_write_b16 v165, v204 offset:96
	ds_write_b16 v165, v203 offset:160
	ds_write_b16 v165, v205 offset:224
	ds_read_b128 v[184:187], v166
	s_waitcnt lgkmcnt(0)
	global_store_dwordx4 v[174:175], v[184:187], off offset:64
	v_cvt_pk_bf16_f32 v190, v52, v53
	v_cvt_pk_bf16_f32 v191, v54, v55
	v_lshrrev_b32_e32 v192, 16, v190
	v_lshrrev_b32_e32 v193, 16, v191
	ds_write_b16 v165, v190 offset:0
	ds_write_b16 v165, v192 offset:64
	ds_write_b16 v165, v191 offset:128
	ds_write_b16 v165, v193 offset:192
	v_cvt_pk_bf16_f32 v198, v36, v37
	v_cvt_pk_bf16_f32 v199, v38, v39
	v_lshrrev_b32_e32 v200, 16, v198
	v_lshrrev_b32_e32 v201, 16, v199
	ds_write_b16 v165, v198 offset:32
	ds_write_b16 v165, v200 offset:96
	ds_write_b16 v165, v199 offset:160
	ds_write_b16 v165, v201 offset:224
	ds_read_b128 v[180:183], v166
	s_waitcnt lgkmcnt(0)
	global_store_dwordx4 v[174:175], v[180:183], off offset:256
	v_cvt_pk_bf16_f32 v194, v20, v21
	v_cvt_pk_bf16_f32 v195, v22, v23
	v_lshrrev_b32_e32 v196, 16, v194
	v_lshrrev_b32_e32 v197, 16, v195
	ds_write_b16 v165, v194 offset:0
	ds_write_b16 v165, v196 offset:64
	ds_write_b16 v165, v195 offset:128
	ds_write_b16 v165, v197 offset:192
	v_cvt_pk_bf16_f32 v202, v4, v5
	v_cvt_pk_bf16_f32 v203, v6, v7
	v_lshrrev_b32_e32 v204, 16, v202
	v_lshrrev_b32_e32 v205, 16, v203
	ds_write_b16 v165, v202 offset:32
	ds_write_b16 v165, v204 offset:96
	ds_write_b16 v165, v203 offset:160
	ds_write_b16 v165, v205 offset:224
	ds_read_b128 v[184:187], v166
	s_waitcnt lgkmcnt(0)
	global_store_dwordx4 v[174:175], v[184:187], off offset:320
	s_mov_b32 s28, 0x420000
	v_lshl_add_u64 v[174:175], v[170:171], 0, s[28:29]
	v_cvt_pk_bf16_f32 v190, v112, v113
	v_cvt_pk_bf16_f32 v191, v114, v115
	v_lshrrev_b32_e32 v192, 16, v190
	v_lshrrev_b32_e32 v193, 16, v191
	ds_write_b16 v165, v190 offset:0
	ds_write_b16 v165, v192 offset:64
	ds_write_b16 v165, v191 offset:128
	ds_write_b16 v165, v193 offset:192
	v_cvt_pk_bf16_f32 v198, v96, v97
	v_cvt_pk_bf16_f32 v199, v98, v99
	v_lshrrev_b32_e32 v200, 16, v198
	v_lshrrev_b32_e32 v201, 16, v199
	ds_write_b16 v165, v198 offset:32
	ds_write_b16 v165, v200 offset:96
	ds_write_b16 v165, v199 offset:160
	ds_write_b16 v165, v201 offset:224
	ds_read_b128 v[180:183], v166
	s_waitcnt lgkmcnt(0)
	global_store_dwordx4 v[174:175], v[180:183], off
	v_cvt_pk_bf16_f32 v194, v80, v81
	v_cvt_pk_bf16_f32 v195, v82, v83
	v_lshrrev_b32_e32 v196, 16, v194
	v_lshrrev_b32_e32 v197, 16, v195
	ds_write_b16 v165, v194 offset:0
	ds_write_b16 v165, v196 offset:64
	ds_write_b16 v165, v195 offset:128
	ds_write_b16 v165, v197 offset:192
	v_cvt_pk_bf16_f32 v202, v64, v65
	v_cvt_pk_bf16_f32 v203, v66, v67
	v_lshrrev_b32_e32 v204, 16, v202
	v_lshrrev_b32_e32 v205, 16, v203
	ds_write_b16 v165, v202 offset:32
	ds_write_b16 v165, v204 offset:96
	ds_write_b16 v165, v203 offset:160
	ds_write_b16 v165, v205 offset:224
	ds_read_b128 v[184:187], v166
	s_waitcnt lgkmcnt(0)
	global_store_dwordx4 v[174:175], v[184:187], off offset:64
	v_cvt_pk_bf16_f32 v190, v48, v49
	v_cvt_pk_bf16_f32 v191, v50, v51
	v_lshrrev_b32_e32 v192, 16, v190
	v_lshrrev_b32_e32 v193, 16, v191
	ds_write_b16 v165, v190 offset:0
	ds_write_b16 v165, v192 offset:64
	ds_write_b16 v165, v191 offset:128
	ds_write_b16 v165, v193 offset:192
	v_cvt_pk_bf16_f32 v198, v32, v33
	v_cvt_pk_bf16_f32 v199, v34, v35
	v_lshrrev_b32_e32 v200, 16, v198
	v_lshrrev_b32_e32 v201, 16, v199
	ds_write_b16 v165, v198 offset:32
	ds_write_b16 v165, v200 offset:96
	ds_write_b16 v165, v199 offset:160
	ds_write_b16 v165, v201 offset:224
	ds_read_b128 v[180:183], v166
	s_waitcnt lgkmcnt(0)
	global_store_dwordx4 v[174:175], v[180:183], off offset:256
	v_cvt_pk_bf16_f32 v194, v16, v17
	v_cvt_pk_bf16_f32 v195, v18, v19
	v_lshrrev_b32_e32 v196, 16, v194
	v_lshrrev_b32_e32 v197, 16, v195
	ds_write_b16 v165, v194 offset:0
	ds_write_b16 v165, v196 offset:64
	ds_write_b16 v165, v195 offset:128
	ds_write_b16 v165, v197 offset:192
	v_cvt_pk_bf16_f32 v202, v0, v1
	v_cvt_pk_bf16_f32 v203, v2, v3
	v_lshrrev_b32_e32 v204, 16, v202
	v_lshrrev_b32_e32 v205, 16, v203
	ds_write_b16 v165, v202 offset:32
	ds_write_b16 v165, v204 offset:96
	ds_write_b16 v165, v203 offset:160
	ds_write_b16 v165, v205 offset:224
	ds_read_b128 v[184:187], v166
	s_waitcnt lgkmcnt(0)
	global_store_dwordx4 v[174:175], v[184:187], off offset:320
	s_branch .LBB0_319
	v_lshlrev_b64 v[156:157], 15, v[148:149]
	v_lshl_add_u64 v[156:157], s[8:9], 0, v[156:157]
	v_lshl_add_u64 v[156:157], v[146:147], 1, v[156:157]
	v_add_co_u32_e32 v158, vcc, 0xfe000000, v156
	v_cvt_pk_bf16_f32 v155, v124, s0
	s_nop 0
	v_addc_co_u32_e32 v159, vcc, -1, v157, vcc
	global_store_short v[158:159], v155, off
	v_add_co_u32_e32 v158, vcc, 0xfe020000, v156
	v_cvt_pk_bf16_f32 v155, v120, s0
	s_nop 0
	v_addc_co_u32_e32 v159, vcc, -1, v157, vcc
	global_store_short v[158:159], v155, off
	v_add_co_u32_e32 v158, vcc, 0xfe008000, v156
	v_cvt_pk_bf16_f32 v155, v125, s0
	s_nop 0
	v_addc_co_u32_e32 v159, vcc, -1, v157, vcc
	global_store_short v[158:159], v155, off
	v_add_co_u32_e32 v158, vcc, 0xfe028000, v156
	v_cvt_pk_bf16_f32 v155, v121, s0
	s_nop 0
	v_addc_co_u32_e32 v159, vcc, -1, v157, vcc
	global_store_short v[158:159], v155, off
	v_add_co_u32_e32 v158, vcc, 0xfe010000, v156
	v_cvt_pk_bf16_f32 v155, v126, s0
	s_nop 0
	v_addc_co_u32_e32 v159, vcc, -1, v157, vcc
	global_store_short v[158:159], v155, off
	v_add_co_u32_e32 v158, vcc, 0xfe030000, v156
	v_cvt_pk_bf16_f32 v155, v122, s0
	s_nop 0
	v_addc_co_u32_e32 v159, vcc, -1, v157, vcc
	global_store_short v[158:159], v155, off
	v_add_co_u32_e32 v158, vcc, 0xfe018000, v156
	v_cvt_pk_bf16_f32 v155, v127, s0
	s_nop 0
	v_addc_co_u32_e32 v159, vcc, -1, v157, vcc
	v_add_co_u32_e32 v156, vcc, 0xfe038000, v156
	global_store_short v[158:159], v155, off
	v_cvt_pk_bf16_f32 v155, v123, s0
	v_addc_co_u32_e32 v157, vcc, -1, v157, vcc
	global_store_short v[156:157], v155, off
	s_mov_b64 s[0:1], 0

.LBB0_920:
	s_waitcnt vmcnt(0)
	v_lshlrev_b32_e32 v2, 1, v145
	v_lshrrev_b32_e32 v3, 5, v144
	s_ashr_i32 s6, s8, 3
	v_and_b32_e32 v2, 24, v2
	v_and_b32_e32 v3, 4, v3
	v_and_b32_e32 v4, 3, v145
	s_waitcnt lgkmcnt(0)
	s_add_u32 s42, s22, 0x14a00000
	v_lshlrev_b32_e32 v0, 4, v144
	v_and_b32_e32 v1, 32, v144
	v_and_b32_e32 v10, 15, v145
	v_or3_b32 v2, v3, v4, v2
	v_lshrrev_b32_e32 v3, 3, v144
	s_movk_i32 s7, 0x70
	s_addc_u32 s43, s23, 0
	v_bitop3_b32 v8, v0, v1, 48 bitop3:0x6c
	v_and_b32_e32 v9, 64, v144
	v_and_or_b32 v4, v3, s7, v10
	s_movk_i32 s7, 0x60
	v_add_u32_e32 v11, 0x2000, v0
	s_add_u32 s44, s22, 0x1000000
	v_or_b32_e32 v1, v8, v9
	v_and_or_b32 v3, v3, s7, v2
	v_lshrrev_b32_e32 v0, 7, v11
	s_movk_i32 s7, 0xf0
	s_addc_u32 s45, s23, 0
	v_lshl_or_b32 v148, v3, 11, v1
	v_and_or_b32 v3, v0, s7, v10
	s_movk_i32 s7, 0xe0
	s_add_i32 s6, s9, s6
	v_and_or_b32 v0, v0, s7, v2
	s_ashr_i32 s7, s6, 31
	s_lshr_b32 s7, s7, 26
	s_add_i32 s7, s6, s7
	s_ashr_i32 s9, s7, 6
	s_andn2_b32 s7, s7, 63
	s_sub_i32 s6, s6, s7
	s_bfe_i32 s7, s6, 0x80000
	s_bfe_u32 s7, s7, 0x3000c
	s_add_i32 s7, s6, s7
	s_bfe_i32 s10, s7, 0x80000
	s_and_b32 s7, s7, 0xf8
	s_sub_i32 s6, s6, s7
	s_lshl_b32 s9, s9, 3
	s_sext_i32_i16 s10, s10
	s_sext_i32_i8 s6, s6
	s_lshr_b32 s11, s2, 8
	s_lshr_b32 s10, s10, 3
	s_add_i32 s34, s9, s6
	s_lshr_b32 s8, s2, 6
	s_ashr_i32 s35, s34, 31
	s_bfe_i64 s[12:13], s[10:11], 0x100000
	s_lshl_b32 s46, s8, 10
	s_lshl_b64 s[6:7], s[34:35], 19
	s_lshl_b64 s[12:13], s[12:13], 19
	s_add_u32 s38, s44, s12
	s_addc_u32 s39, s45, s13
	s_add_i32 s35, s46, 0
	s_add_i32 m0, s35, 0x10000
	v_lshl_or_b32 v152, v0, 11, v1
	global_load_lds_dwordx4 v148, s[38:39]
	s_add_i32 m0, s35, 0x12000
	s_add_u32 s36, s42, s6
	v_lshl_or_b32 v146, v4, 11, v1
	global_load_lds_dwordx4 v152, s[38:39]
	s_addc_u32 s37, s43, s7
	s_mov_b32 m0, s35
	s_add_i32 s47, s35, 0x2000
	v_lshl_or_b32 v150, v3, 11, v1
	global_load_lds_dwordx4 v146, s[36:37]
	s_mov_b32 m0, s47
	s_add_u32 s6, s38, 0x40000
	global_load_lds_dwordx4 v150, s[36:37]
	s_addc_u32 s7, s39, 0
	s_add_i32 m0, s35, 0x14000
	v_mov_b32_e32 v149, 0
	global_load_lds_dwordx4 v148, s[6:7]
	s_add_i32 m0, s35, 0x16000
	v_mov_b32_e32 v153, v149
	global_load_lds_dwordx4 v152, s[6:7]
	s_add_u32 s6, s36, 0x40000
	s_addc_u32 s7, s37, 0
	s_add_i32 s48, s35, 0x4000
	s_mov_b32 m0, s48
	s_add_i32 s49, s35, 0x6000
	global_load_lds_dwordx4 v146, s[6:7]
	s_mov_b32 m0, s49
	v_mov_b32_e32 v147, v149
	global_load_lds_dwordx4 v150, s[6:7]
	v_mov_b32_e32 v151, v149
	s_mov_b32 s50, 0
	v_lshl_add_u64 v[6:7], s[38:39], 0, v[148:149]
	v_lshl_add_u64 v[4:5], s[38:39], 0, v[152:153]
	v_lshl_add_u64 v[2:3], s[36:37], 0, v[146:147]
	s_cmp_lg_u32 s11, 1
	v_lshl_add_u64 v[0:1], s[36:37], 0, v[150:151]
	s_cbranch_scc1 .LBB0_922
	s_setprio 1
	s_barrier

.LBB0_931:
	s_ashr_i32 s15, s14, 31
	s_xor_b64 s[16:17], s[28:29], -1
	s_lshl_b64 s[18:19], s[14:15], 19
	s_add_u32 s18, s42, s18
	s_addc_u32 s19, s43, s19
	s_and_b64 s[30:31], s[28:29], exec
	s_cselect_b32 s15, s19, s37
	s_cselect_b32 s63, s18, s36
	s_ashr_i32 s13, s12, 31
	s_lshl_b64 s[30:31], s[12:13], 19
	s_add_u32 s30, s44, s30
	s_addc_u32 s31, s45, s31
	s_and_b64 s[28:29], s[28:29], exec
	s_cselect_b32 s13, s31, s39
	s_cselect_b32 s28, s30, s38
	s_add_u32 s36, s36, 0x40080
	s_addc_u32 s37, s37, 0
	s_add_u32 s29, s38, 0x100
	s_addc_u32 s64, s39, 0
	s_mov_b32 s65, -2
	ds_read_b128 v[128:131], v169
	ds_read_b128 v[132:135], v169 offset:1024
	ds_read_b128 v[136:139], v169 offset:2048
	ds_read_b128 v[140:143], v169 offset:3072
	s_add_u32 s38, s36, 0xfffc0080
	s_addc_u32 s39, s37, -1
	s_cmp_eq_u32 s65, 12
	s_cselect_b32 s41, s15, s39
	s_cselect_b32 s40, s63, s38
	s_cselect_b32 s39, s13, s64
	s_cselect_b32 s38, s28, s29
	v_lshl_add_u64 v[164:165], s[36:37], 0, v[154:155]
	s_add_i32 m0, s35, 0xc000
	ds_read_b128 v[160:163], v170
	ds_read_b128 v[172:175], v170 offset:1024
	ds_read_b128 v[176:179], v170 offset:2048
	ds_read_b128 v[180:183], v170 offset:3072
	ds_read_b128 v[184:187], v170 offset:4096
	ds_read_b128 v[188:191], v170 offset:5120
	ds_read_b128 v[192:195], v170 offset:6144
	ds_read_b128 v[196:199], v170 offset:7168
	global_load_lds_dwordx4 v[164:165], off
	v_lshl_add_u64 v[164:165], s[36:37], 0, v[156:157]
	s_add_i32 m0, s35, 0xe000
	s_nop 0
	global_load_lds_dwordx4 v[164:165], off
	s_waitcnt lgkmcnt(8)
	s_barrier
	s_waitcnt lgkmcnt(0)
	s_waitcnt lgkmcnt(0)
	v_mfma_f32_16x16x32_bf16 v[124:127], v[128:131], v[160:163], 0
	v_mfma_f32_16x16x32_bf16 v[120:123], v[136:139], v[160:163], 0
	v_mfma_f32_16x16x32_bf16 v[116:119], v[128:131], v[176:179], 0
	v_mfma_f32_16x16x32_bf16 v[100:103], v[136:139], v[176:179], 0
	v_mfma_f32_16x16x32_bf16 v[92:95], v[128:131], v[184:187], 0
	v_mfma_f32_16x16x32_bf16 v[84:87], v[136:139], v[184:187], 0
	v_mfma_f32_16x16x32_bf16 v[76:79], v[128:131], v[192:195], 0
	v_mfma_f32_16x16x32_bf16 v[68:71], v[136:139], v[192:195], 0
	v_mfma_f32_16x16x32_bf16 v[124:127], v[132:135], v[172:175], v[124:127]
	v_mfma_f32_16x16x32_bf16 v[120:123], v[140:143], v[172:175], v[120:123]
	v_mfma_f32_16x16x32_bf16 v[116:119], v[132:135], v[180:183], v[116:119]
	v_mfma_f32_16x16x32_bf16 v[100:103], v[140:143], v[180:183], v[100:103]
	v_mfma_f32_16x16x32_bf16 v[92:95], v[132:135], v[188:191], v[92:95]
	v_mfma_f32_16x16x32_bf16 v[84:87], v[140:143], v[188:191], v[84:87]
	v_mfma_f32_16x16x32_bf16 v[76:79], v[132:135], v[196:199], v[76:79]
	v_mfma_f32_16x16x32_bf16 v[68:71], v[140:143], v[196:199], v[68:71]
	s_barrier
	s_add_i32 s66, s57, s46
	v_lshl_add_u64 v[164:165], s[38:39], 0, v[148:149]
	s_mov_b32 m0, s66
	ds_read_b128 v[200:203], v171
	ds_read_b128 v[204:207], v171 offset:1024
	ds_read_b128 v[208:211], v171 offset:2048
	ds_read_b128 v[212:215], v171 offset:3072
	global_load_lds_dwordx4 v[164:165], off
	v_lshl_add_u64 v[216:217], s[38:39], 0, v[152:153]
	s_add_i32 m0, s66, 0x2000
	s_nop 0
	global_load_lds_dwordx4 v[216:217], off
	s_barrier
	s_waitcnt lgkmcnt(0)
	s_waitcnt lgkmcnt(0)
	v_mfma_f32_16x16x32_bf16 v[112:115], v[200:203], v[160:163], 0
	v_mfma_f32_16x16x32_bf16 v[108:111], v[208:211], v[160:163], 0
	v_mfma_f32_16x16x32_bf16 v[104:107], v[200:203], v[176:179], 0
	v_mfma_f32_16x16x32_bf16 v[96:99], v[208:211], v[176:179], 0
	v_mfma_f32_16x16x32_bf16 v[88:91], v[200:203], v[184:187], 0
	v_mfma_f32_16x16x32_bf16 v[80:83], v[208:211], v[184:187], 0
	v_mfma_f32_16x16x32_bf16 v[72:75], v[200:203], v[192:195], 0
	v_mfma_f32_16x16x32_bf16 v[64:67], v[208:211], v[192:195], 0
	v_mfma_f32_16x16x32_bf16 v[112:115], v[204:207], v[172:175], v[112:115]
	v_mfma_f32_16x16x32_bf16 v[108:111], v[212:215], v[172:175], v[108:111]
	v_mfma_f32_16x16x32_bf16 v[104:107], v[204:207], v[180:183], v[104:107]
	v_mfma_f32_16x16x32_bf16 v[96:99], v[212:215], v[180:183], v[96:99]
	v_mfma_f32_16x16x32_bf16 v[88:91], v[204:207], v[188:191], v[88:91]
	v_mfma_f32_16x16x32_bf16 v[80:83], v[212:215], v[188:191], v[80:83]
	v_mfma_f32_16x16x32_bf16 v[72:75], v[204:207], v[196:199], v[72:75]
	v_mfma_f32_16x16x32_bf16 v[64:67], v[212:215], v[196:199], v[64:67]
	s_mov_b32 m0, s35
	v_lshl_add_u64 v[218:219], s[40:41], 0, v[146:147]
	s_barrier
	ds_read_b128 v[160:163], v170 offset:16384
	ds_read_b128 v[172:175], v170 offset:17408
	ds_read_b128 v[176:179], v170 offset:18432
	ds_read_b128 v[180:183], v170 offset:19456
	ds_read_b128 v[184:187], v170 offset:20480
	ds_read_b128 v[188:191], v170 offset:21504
	ds_read_b128 v[192:195], v170 offset:22528
	ds_read_b128 v[196:199], v170 offset:23552
	global_load_lds_dwordx4 v[218:219], off
	v_lshl_add_u64 v[220:221], s[40:41], 0, v[150:151]
	s_mov_b32 m0, s47
	s_nop 0
	global_load_lds_dwordx4 v[220:221], off
	s_barrier
	s_waitcnt lgkmcnt(0)
	s_waitcnt lgkmcnt(0)
	v_mfma_f32_16x16x32_bf16 v[60:63], v[128:131], v[160:163], 0
	v_mfma_f32_16x16x32_bf16 v[52:55], v[136:139], v[160:163], 0
	v_mfma_f32_16x16x32_bf16 v[44:47], v[128:131], v[176:179], 0
	v_mfma_f32_16x16x32_bf16 v[36:39], v[136:139], v[176:179], 0
	v_mfma_f32_16x16x32_bf16 v[28:31], v[128:131], v[184:187], 0
	v_mfma_f32_16x16x32_bf16 v[20:23], v[136:139], v[184:187], 0
	v_mfma_f32_16x16x32_bf16 v[12:15], v[128:131], v[192:195], 0
	v_mfma_f32_16x16x32_bf16 v[4:7], v[136:139], v[192:195], 0
	v_mfma_f32_16x16x32_bf16 v[60:63], v[132:135], v[172:175], v[60:63]
	v_mfma_f32_16x16x32_bf16 v[52:55], v[140:143], v[172:175], v[52:55]
	v_mfma_f32_16x16x32_bf16 v[44:47], v[132:135], v[180:183], v[44:47]
	v_mfma_f32_16x16x32_bf16 v[36:39], v[140:143], v[180:183], v[36:39]
	v_mfma_f32_16x16x32_bf16 v[28:31], v[132:135], v[188:191], v[28:31]
	v_mfma_f32_16x16x32_bf16 v[20:23], v[140:143], v[188:191], v[20:23]
	v_mfma_f32_16x16x32_bf16 v[12:15], v[132:135], v[196:199], v[12:15]
	v_mfma_f32_16x16x32_bf16 v[4:7], v[140:143], v[196:199], v[4:7]
	s_barrier
	s_add_u32 s66, s38, 0x40000
	s_addc_u32 s67, s39, 0
	s_add_i32 s68, s58, s46
	v_lshl_add_u64 v[128:129], s[66:67], 0, v[148:149]
	s_mov_b32 m0, s68
	s_nop 0
	global_load_lds_dwordx4 v[128:129], off
	v_lshl_add_u64 v[128:129], s[66:67], 0, v[152:153]
	s_add_i32 m0, s68, 0x2000
	s_nop 0
	global_load_lds_dwordx4 v[128:129], off
	s_waitcnt vmcnt(6)
	s_barrier
	v_mfma_f32_16x16x32_bf16 v[56:59], v[200:203], v[160:163], 0
	v_mfma_f32_16x16x32_bf16 v[48:51], v[208:211], v[160:163], 0
	v_mfma_f32_16x16x32_bf16 v[40:43], v[200:203], v[176:179], 0
	v_mfma_f32_16x16x32_bf16 v[32:35], v[208:211], v[176:179], 0
	v_mfma_f32_16x16x32_bf16 v[24:27], v[200:203], v[184:187], 0
	v_mfma_f32_16x16x32_bf16 v[16:19], v[208:211], v[184:187], 0
	v_mfma_f32_16x16x32_bf16 v[8:11], v[200:203], v[192:195], 0
	v_mfma_f32_16x16x32_bf16 v[0:3], v[208:211], v[192:195], 0
	v_mfma_f32_16x16x32_bf16 v[56:59], v[204:207], v[172:175], v[56:59]
	v_mfma_f32_16x16x32_bf16 v[48:51], v[212:215], v[172:175], v[48:51]
	v_mfma_f32_16x16x32_bf16 v[40:43], v[204:207], v[180:183], v[40:43]
	v_mfma_f32_16x16x32_bf16 v[32:35], v[212:215], v[180:183], v[32:35]
	v_mfma_f32_16x16x32_bf16 v[24:27], v[204:207], v[188:191], v[24:27]
	v_mfma_f32_16x16x32_bf16 v[16:19], v[212:215], v[188:191], v[16:19]
	v_mfma_f32_16x16x32_bf16 v[8:11], v[204:207], v[196:199], v[8:11]
	v_mfma_f32_16x16x32_bf16 v[0:3], v[212:215], v[196:199], v[0:3]
	s_add_i32 s66, 0, 0x18000
	v_add_u32_e32 v140, s66, v167
	s_barrier
	ds_read_b128 v[128:131], v140
	ds_read_b128 v[132:135], v140 offset:1024
	ds_read_b128 v[136:139], v140 offset:2048
	ds_read_b128 v[140:143], v140 offset:3072
	s_add_u32 s40, s40, 0x40000
	s_addc_u32 s41, s41, 0
	s_mov_b32 m0, s48
	v_lshl_add_u64 v[200:201], s[40:41], 0, v[146:147]
	ds_read_b128 v[160:163], v170 offset:32768
	ds_read_b128 v[172:175], v170 offset:33792
	ds_read_b128 v[176:179], v170 offset:34816
	ds_read_b128 v[180:183], v170 offset:35840
	ds_read_b128 v[184:187], v170 offset:36864
	ds_read_b128 v[188:191], v170 offset:37888
	ds_read_b128 v[192:195], v170 offset:38912
	ds_read_b128 v[196:199], v170 offset:39936
	global_load_lds_dwordx4 v[200:201], off
	v_lshl_add_u64 v[200:201], s[40:41], 0, v[150:151]
	s_mov_b32 m0, s49
	s_nop 0
	global_load_lds_dwordx4 v[200:201], off
	s_waitcnt lgkmcnt(8)
	s_barrier
	s_waitcnt lgkmcnt(0)
	s_waitcnt lgkmcnt(0)
	v_mfma_f32_16x16x32_bf16 v[124:127], v[128:131], v[160:163], v[124:127]
	v_mfma_f32_16x16x32_bf16 v[120:123], v[136:139], v[160:163], v[120:123]
	v_mfma_f32_16x16x32_bf16 v[116:119], v[128:131], v[176:179], v[116:119]
	v_mfma_f32_16x16x32_bf16 v[100:103], v[136:139], v[176:179], v[100:103]
	v_mfma_f32_16x16x32_bf16 v[92:95], v[128:131], v[184:187], v[92:95]
	v_mfma_f32_16x16x32_bf16 v[84:87], v[136:139], v[184:187], v[84:87]
	v_mfma_f32_16x16x32_bf16 v[76:79], v[128:131], v[192:195], v[76:79]
	v_mfma_f32_16x16x32_bf16 v[68:71], v[136:139], v[192:195], v[68:71]
	v_mfma_f32_16x16x32_bf16 v[124:127], v[132:135], v[172:175], v[124:127]
	v_mfma_f32_16x16x32_bf16 v[120:123], v[140:143], v[172:175], v[120:123]
	v_mfma_f32_16x16x32_bf16 v[116:119], v[132:135], v[180:183], v[116:119]
	v_mfma_f32_16x16x32_bf16 v[100:103], v[140:143], v[180:183], v[100:103]
	v_mfma_f32_16x16x32_bf16 v[92:95], v[132:135], v[188:191], v[92:95]
	v_mfma_f32_16x16x32_bf16 v[84:87], v[140:143], v[188:191], v[84:87]
	v_mfma_f32_16x16x32_bf16 v[76:79], v[132:135], v[196:199], v[76:79]
	v_mfma_f32_16x16x32_bf16 v[68:71], v[140:143], v[196:199], v[68:71]
	s_barrier
	s_add_i32 s40, 0, 0x1c000
	s_add_i32 s41, s66, s46
	v_add_u32_e32 v212, s40, v167
	v_lshl_add_u64 v[164:165], v[164:165], 0, s[8:9]
	s_mov_b32 m0, s41
	ds_read_b128 v[200:203], v212
	ds_read_b128 v[204:207], v212 offset:1024
	ds_read_b128 v[208:211], v212 offset:2048
	ds_read_b128 v[212:215], v212 offset:3072
	global_load_lds_dwordx4 v[164:165], off
	v_lshl_add_u64 v[164:165], v[216:217], 0, s[8:9]
	s_add_i32 m0, s41, 0x2000
	s_nop 0
	global_load_lds_dwordx4 v[164:165], off
	s_barrier
	s_waitcnt lgkmcnt(0)
	s_waitcnt lgkmcnt(0)
	v_mfma_f32_16x16x32_bf16 v[112:115], v[200:203], v[160:163], v[112:115]
	v_mfma_f32_16x16x32_bf16 v[108:111], v[208:211], v[160:163], v[108:111]
	v_mfma_f32_16x16x32_bf16 v[104:107], v[200:203], v[176:179], v[104:107]
	v_mfma_f32_16x16x32_bf16 v[96:99], v[208:211], v[176:179], v[96:99]
	v_mfma_f32_16x16x32_bf16 v[88:91], v[200:203], v[184:187], v[88:91]
	v_mfma_f32_16x16x32_bf16 v[80:83], v[208:211], v[184:187], v[80:83]
	v_mfma_f32_16x16x32_bf16 v[72:75], v[200:203], v[192:195], v[72:75]
	v_mfma_f32_16x16x32_bf16 v[64:67], v[208:211], v[192:195], v[64:67]
	v_mfma_f32_16x16x32_bf16 v[112:115], v[204:207], v[172:175], v[112:115]
	v_mfma_f32_16x16x32_bf16 v[108:111], v[212:215], v[172:175], v[108:111]
	v_mfma_f32_16x16x32_bf16 v[104:107], v[204:207], v[180:183], v[104:107]
	v_mfma_f32_16x16x32_bf16 v[96:99], v[212:215], v[180:183], v[96:99]
	v_mfma_f32_16x16x32_bf16 v[88:91], v[204:207], v[188:191], v[88:91]
	v_mfma_f32_16x16x32_bf16 v[80:83], v[212:215], v[188:191], v[80:83]
	v_mfma_f32_16x16x32_bf16 v[72:75], v[204:207], v[196:199], v[72:75]
	v_mfma_f32_16x16x32_bf16 v[64:67], v[212:215], v[196:199], v[64:67]
	s_mov_b32 m0, s51
	v_lshl_add_u64 v[164:165], v[218:219], 0, s[8:9]
	s_barrier
	ds_read_b128 v[160:163], v170 offset:49152
	ds_read_b128 v[172:175], v170 offset:50176
	ds_read_b128 v[176:179], v170 offset:51200
	ds_read_b128 v[180:183], v170 offset:52224
	ds_read_b128 v[184:187], v170 offset:53248
	ds_read_b128 v[188:191], v170 offset:54272
	ds_read_b128 v[192:195], v170 offset:55296
	ds_read_b128 v[196:199], v170 offset:56320
	global_load_lds_dwordx4 v[164:165], off
	v_lshl_add_u64 v[164:165], v[220:221], 0, s[8:9]
	s_mov_b32 m0, s54
	s_nop 0
	global_load_lds_dwordx4 v[164:165], off
	s_barrier
	s_waitcnt lgkmcnt(0)
	s_waitcnt lgkmcnt(0)
	v_mfma_f32_16x16x32_bf16 v[60:63], v[128:131], v[160:163], v[60:63]
	v_mfma_f32_16x16x32_bf16 v[52:55], v[136:139], v[160:163], v[52:55]
	v_mfma_f32_16x16x32_bf16 v[44:47], v[128:131], v[176:179], v[44:47]
	v_mfma_f32_16x16x32_bf16 v[36:39], v[136:139], v[176:179], v[36:39]
	v_mfma_f32_16x16x32_bf16 v[28:31], v[128:131], v[184:187], v[28:31]
	v_mfma_f32_16x16x32_bf16 v[20:23], v[136:139], v[184:187], v[20:23]
	v_mfma_f32_16x16x32_bf16 v[12:15], v[128:131], v[192:195], v[12:15]
	v_mfma_f32_16x16x32_bf16 v[4:7], v[136:139], v[192:195], v[4:7]
	v_mfma_f32_16x16x32_bf16 v[60:63], v[132:135], v[172:175], v[60:63]
	v_mfma_f32_16x16x32_bf16 v[52:55], v[140:143], v[172:175], v[52:55]
	v_mfma_f32_16x16x32_bf16 v[44:47], v[132:135], v[180:183], v[44:47]
	v_mfma_f32_16x16x32_bf16 v[36:39], v[140:143], v[180:183], v[36:39]
	v_mfma_f32_16x16x32_bf16 v[28:31], v[132:135], v[188:191], v[28:31]
	v_mfma_f32_16x16x32_bf16 v[20:23], v[140:143], v[188:191], v[20:23]
	v_mfma_f32_16x16x32_bf16 v[12:15], v[132:135], v[196:199], v[12:15]
	v_mfma_f32_16x16x32_bf16 v[4:7], v[140:143], v[196:199], v[4:7]
	s_barrier
	s_add_u32 s38, s38, 0x40080
	s_addc_u32 s39, s39, 0
	s_add_i32 s40, s40, s46
	v_lshl_add_u64 v[128:129], s[38:39], 0, v[148:149]
	s_mov_b32 m0, s40
	s_nop 0
	global_load_lds_dwordx4 v[128:129], off
	v_lshl_add_u64 v[128:129], s[38:39], 0, v[152:153]
	s_add_i32 m0, s40, 0x2000
	s_nop 0
	global_load_lds_dwordx4 v[128:129], off
	s_waitcnt vmcnt(6)
	s_barrier
	v_mfma_f32_16x16x32_bf16 v[56:59], v[200:203], v[160:163], v[56:59]
	v_mfma_f32_16x16x32_bf16 v[48:51], v[208:211], v[160:163], v[48:51]
	v_mfma_f32_16x16x32_bf16 v[40:43], v[200:203], v[176:179], v[40:43]
	v_mfma_f32_16x16x32_bf16 v[32:35], v[208:211], v[176:179], v[32:35]
	v_mfma_f32_16x16x32_bf16 v[24:27], v[200:203], v[184:187], v[24:27]
	v_mfma_f32_16x16x32_bf16 v[16:19], v[208:211], v[184:187], v[16:19]
	v_mfma_f32_16x16x32_bf16 v[8:11], v[200:203], v[192:195], v[8:11]
	v_mfma_f32_16x16x32_bf16 v[0:3], v[208:211], v[192:195], v[0:3]
	v_mfma_f32_16x16x32_bf16 v[56:59], v[204:207], v[172:175], v[56:59]
	v_mfma_f32_16x16x32_bf16 v[48:51], v[212:215], v[172:175], v[48:51]
	v_mfma_f32_16x16x32_bf16 v[40:43], v[204:207], v[180:183], v[40:43]
	v_mfma_f32_16x16x32_bf16 v[32:35], v[212:215], v[180:183], v[32:35]
	v_mfma_f32_16x16x32_bf16 v[24:27], v[204:207], v[188:191], v[24:27]
	v_mfma_f32_16x16x32_bf16 v[16:19], v[212:215], v[188:191], v[16:19]
	v_mfma_f32_16x16x32_bf16 v[8:11], v[204:207], v[196:199], v[8:11]
	v_mfma_f32_16x16x32_bf16 v[0:3], v[212:215], v[196:199], v[0:3]
	s_add_i32 s65, s65, 2
	s_add_u32 s36, s36, 0x100
	s_addc_u32 s37, s37, 0
	s_add_u32 s29, s29, 0x100
	s_addc_u32 s64, s64, 0
	s_cmp_gt_u32 s65, 13
	s_barrier
	s_cbranch_scc0 .LBB0_932
.LBB0_932:
	ds_read_b128 v[128:131], v169
	ds_read_b128 v[132:135], v169 offset:1024
	ds_read_b128 v[136:139], v169 offset:2048
	ds_read_b128 v[140:143], v169 offset:3072
	s_add_u32 s38, s36, 0xfffc0080
	s_addc_u32 s39, s37, -1
	s_cmp_eq_u32 s65, 12
	s_cselect_b32 s41, s15, s39
	s_cselect_b32 s40, s63, s38
	s_cselect_b32 s39, s13, s64
	s_cselect_b32 s38, s28, s29
	v_lshl_add_u64 v[164:165], s[36:37], 0, v[154:155]
	s_add_i32 m0, s35, 0xc000
	ds_read_b128 v[160:163], v170
	ds_read_b128 v[172:175], v170 offset:1024
	ds_read_b128 v[176:179], v170 offset:2048
	ds_read_b128 v[180:183], v170 offset:3072
	ds_read_b128 v[184:187], v170 offset:4096
	ds_read_b128 v[188:191], v170 offset:5120
	ds_read_b128 v[192:195], v170 offset:6144
	ds_read_b128 v[196:199], v170 offset:7168
	global_load_lds_dwordx4 v[164:165], off
	v_lshl_add_u64 v[164:165], s[36:37], 0, v[156:157]
	s_add_i32 m0, s35, 0xe000
	s_nop 0
	global_load_lds_dwordx4 v[164:165], off
	s_waitcnt lgkmcnt(8)
	s_barrier
	s_waitcnt lgkmcnt(0)
	s_waitcnt lgkmcnt(0)
	v_mfma_f32_16x16x32_bf16 v[124:127], v[128:131], v[160:163], v[124:127]
	v_mfma_f32_16x16x32_bf16 v[120:123], v[136:139], v[160:163], v[120:123]
	v_mfma_f32_16x16x32_bf16 v[116:119], v[128:131], v[176:179], v[116:119]
	v_mfma_f32_16x16x32_bf16 v[100:103], v[136:139], v[176:179], v[100:103]
	v_mfma_f32_16x16x32_bf16 v[92:95], v[128:131], v[184:187], v[92:95]
	v_mfma_f32_16x16x32_bf16 v[84:87], v[136:139], v[184:187], v[84:87]
	v_mfma_f32_16x16x32_bf16 v[76:79], v[128:131], v[192:195], v[76:79]
	v_mfma_f32_16x16x32_bf16 v[68:71], v[136:139], v[192:195], v[68:71]
	v_mfma_f32_16x16x32_bf16 v[124:127], v[132:135], v[172:175], v[124:127]
	v_mfma_f32_16x16x32_bf16 v[120:123], v[140:143], v[172:175], v[120:123]
	v_mfma_f32_16x16x32_bf16 v[116:119], v[132:135], v[180:183], v[116:119]
	v_mfma_f32_16x16x32_bf16 v[100:103], v[140:143], v[180:183], v[100:103]
	v_mfma_f32_16x16x32_bf16 v[92:95], v[132:135], v[188:191], v[92:95]
	v_mfma_f32_16x16x32_bf16 v[84:87], v[140:143], v[188:191], v[84:87]
	v_mfma_f32_16x16x32_bf16 v[76:79], v[132:135], v[196:199], v[76:79]
	v_mfma_f32_16x16x32_bf16 v[68:71], v[140:143], v[196:199], v[68:71]
	s_barrier
	s_add_i32 s66, s57, s46
	v_lshl_add_u64 v[164:165], s[38:39], 0, v[148:149]
	s_mov_b32 m0, s66
	ds_read_b128 v[200:203], v171
	ds_read_b128 v[204:207], v171 offset:1024
	ds_read_b128 v[208:211], v171 offset:2048
	ds_read_b128 v[212:215], v171 offset:3072
	global_load_lds_dwordx4 v[164:165], off
	v_lshl_add_u64 v[216:217], s[38:39], 0, v[152:153]
	s_add_i32 m0, s66, 0x2000
	s_nop 0
	global_load_lds_dwordx4 v[216:217], off
	s_barrier
	s_waitcnt lgkmcnt(0)
	s_waitcnt lgkmcnt(0)
	v_mfma_f32_16x16x32_bf16 v[112:115], v[200:203], v[160:163], v[112:115]
	v_mfma_f32_16x16x32_bf16 v[108:111], v[208:211], v[160:163], v[108:111]
	v_mfma_f32_16x16x32_bf16 v[104:107], v[200:203], v[176:179], v[104:107]
	v_mfma_f32_16x16x32_bf16 v[96:99], v[208:211], v[176:179], v[96:99]
	v_mfma_f32_16x16x32_bf16 v[88:91], v[200:203], v[184:187], v[88:91]
	v_mfma_f32_16x16x32_bf16 v[80:83], v[208:211], v[184:187], v[80:83]
	v_mfma_f32_16x16x32_bf16 v[72:75], v[200:203], v[192:195], v[72:75]
	v_mfma_f32_16x16x32_bf16 v[64:67], v[208:211], v[192:195], v[64:67]
	v_mfma_f32_16x16x32_bf16 v[112:115], v[204:207], v[172:175], v[112:115]
	v_mfma_f32_16x16x32_bf16 v[108:111], v[212:215], v[172:175], v[108:111]
	v_mfma_f32_16x16x32_bf16 v[104:107], v[204:207], v[180:183], v[104:107]
	v_mfma_f32_16x16x32_bf16 v[96:99], v[212:215], v[180:183], v[96:99]
	v_mfma_f32_16x16x32_bf16 v[88:91], v[204:207], v[188:191], v[88:91]
	v_mfma_f32_16x16x32_bf16 v[80:83], v[212:215], v[188:191], v[80:83]
	v_mfma_f32_16x16x32_bf16 v[72:75], v[204:207], v[196:199], v[72:75]
	v_mfma_f32_16x16x32_bf16 v[64:67], v[212:215], v[196:199], v[64:67]
	s_mov_b32 m0, s35
	v_lshl_add_u64 v[218:219], s[40:41], 0, v[146:147]
	s_barrier
	ds_read_b128 v[160:163], v170 offset:16384
	ds_read_b128 v[172:175], v170 offset:17408
	ds_read_b128 v[176:179], v170 offset:18432
	ds_read_b128 v[180:183], v170 offset:19456
	ds_read_b128 v[184:187], v170 offset:20480
	ds_read_b128 v[188:191], v170 offset:21504
	ds_read_b128 v[192:195], v170 offset:22528
	ds_read_b128 v[196:199], v170 offset:23552
	global_load_lds_dwordx4 v[218:219], off
	v_lshl_add_u64 v[220:221], s[40:41], 0, v[150:151]
	s_mov_b32 m0, s47
	s_nop 0
	global_load_lds_dwordx4 v[220:221], off
	s_barrier
	s_waitcnt lgkmcnt(0)
	s_waitcnt lgkmcnt(0)
	v_mfma_f32_16x16x32_bf16 v[60:63], v[128:131], v[160:163], v[60:63]
	v_mfma_f32_16x16x32_bf16 v[52:55], v[136:139], v[160:163], v[52:55]
	v_mfma_f32_16x16x32_bf16 v[44:47], v[128:131], v[176:179], v[44:47]
	v_mfma_f32_16x16x32_bf16 v[36:39], v[136:139], v[176:179], v[36:39]
	v_mfma_f32_16x16x32_bf16 v[28:31], v[128:131], v[184:187], v[28:31]
	v_mfma_f32_16x16x32_bf16 v[20:23], v[136:139], v[184:187], v[20:23]
	v_mfma_f32_16x16x32_bf16 v[12:15], v[128:131], v[192:195], v[12:15]
	v_mfma_f32_16x16x32_bf16 v[4:7], v[136:139], v[192:195], v[4:7]
	v_mfma_f32_16x16x32_bf16 v[60:63], v[132:135], v[172:175], v[60:63]
	v_mfma_f32_16x16x32_bf16 v[52:55], v[140:143], v[172:175], v[52:55]
	v_mfma_f32_16x16x32_bf16 v[44:47], v[132:135], v[180:183], v[44:47]
	v_mfma_f32_16x16x32_bf16 v[36:39], v[140:143], v[180:183], v[36:39]
	v_mfma_f32_16x16x32_bf16 v[28:31], v[132:135], v[188:191], v[28:31]
	v_mfma_f32_16x16x32_bf16 v[20:23], v[140:143], v[188:191], v[20:23]
	v_mfma_f32_16x16x32_bf16 v[12:15], v[132:135], v[196:199], v[12:15]
	v_mfma_f32_16x16x32_bf16 v[4:7], v[140:143], v[196:199], v[4:7]
	s_barrier
	s_add_u32 s66, s38, 0x40000
	s_addc_u32 s67, s39, 0
	s_add_i32 s68, s58, s46
	v_lshl_add_u64 v[128:129], s[66:67], 0, v[148:149]
	s_mov_b32 m0, s68
	s_nop 0
	global_load_lds_dwordx4 v[128:129], off
	v_lshl_add_u64 v[128:129], s[66:67], 0, v[152:153]
	s_add_i32 m0, s68, 0x2000
	s_nop 0
	global_load_lds_dwordx4 v[128:129], off
	s_waitcnt vmcnt(6)
	s_barrier
	v_mfma_f32_16x16x32_bf16 v[56:59], v[200:203], v[160:163], v[56:59]
	v_mfma_f32_16x16x32_bf16 v[48:51], v[208:211], v[160:163], v[48:51]
	v_mfma_f32_16x16x32_bf16 v[40:43], v[200:203], v[176:179], v[40:43]
	v_mfma_f32_16x16x32_bf16 v[32:35], v[208:211], v[176:179], v[32:35]
	v_mfma_f32_16x16x32_bf16 v[24:27], v[200:203], v[184:187], v[24:27]
	v_mfma_f32_16x16x32_bf16 v[16:19], v[208:211], v[184:187], v[16:19]
	v_mfma_f32_16x16x32_bf16 v[8:11], v[200:203], v[192:195], v[8:11]
	v_mfma_f32_16x16x32_bf16 v[0:3], v[208:211], v[192:195], v[0:3]
	v_mfma_f32_16x16x32_bf16 v[56:59], v[204:207], v[172:175], v[56:59]
	v_mfma_f32_16x16x32_bf16 v[48:51], v[212:215], v[172:175], v[48:51]
	v_mfma_f32_16x16x32_bf16 v[40:43], v[204:207], v[180:183], v[40:43]
	v_mfma_f32_16x16x32_bf16 v[32:35], v[212:215], v[180:183], v[32:35]
	v_mfma_f32_16x16x32_bf16 v[24:27], v[204:207], v[188:191], v[24:27]
	v_mfma_f32_16x16x32_bf16 v[16:19], v[212:215], v[188:191], v[16:19]
	v_mfma_f32_16x16x32_bf16 v[8:11], v[204:207], v[196:199], v[8:11]
	v_mfma_f32_16x16x32_bf16 v[0:3], v[212:215], v[196:199], v[0:3]
	s_add_i32 s66, 0, 0x18000
	v_add_u32_e32 v140, s66, v167
	s_barrier
	ds_read_b128 v[128:131], v140
	ds_read_b128 v[132:135], v140 offset:1024
	ds_read_b128 v[136:139], v140 offset:2048
	ds_read_b128 v[140:143], v140 offset:3072
	s_add_u32 s40, s40, 0x40000
	s_addc_u32 s41, s41, 0
	s_mov_b32 m0, s48
	v_lshl_add_u64 v[200:201], s[40:41], 0, v[146:147]
	ds_read_b128 v[160:163], v170 offset:32768
	ds_read_b128 v[172:175], v170 offset:33792
	ds_read_b128 v[176:179], v170 offset:34816
	ds_read_b128 v[180:183], v170 offset:35840
	ds_read_b128 v[184:187], v170 offset:36864
	ds_read_b128 v[188:191], v170 offset:37888
	ds_read_b128 v[192:195], v170 offset:38912
	ds_read_b128 v[196:199], v170 offset:39936
	global_load_lds_dwordx4 v[200:201], off
	v_lshl_add_u64 v[200:201], s[40:41], 0, v[150:151]
	s_mov_b32 m0, s49
	s_nop 0
	global_load_lds_dwordx4 v[200:201], off
	s_waitcnt lgkmcnt(8)
	s_barrier
	s_waitcnt lgkmcnt(0)
	s_waitcnt lgkmcnt(0)
	v_mfma_f32_16x16x32_bf16 v[124:127], v[128:131], v[160:163], v[124:127]
	v_mfma_f32_16x16x32_bf16 v[120:123], v[136:139], v[160:163], v[120:123]
	v_mfma_f32_16x16x32_bf16 v[116:119], v[128:131], v[176:179], v[116:119]
	v_mfma_f32_16x16x32_bf16 v[100:103], v[136:139], v[176:179], v[100:103]
	v_mfma_f32_16x16x32_bf16 v[92:95], v[128:131], v[184:187], v[92:95]
	v_mfma_f32_16x16x32_bf16 v[84:87], v[136:139], v[184:187], v[84:87]
	v_mfma_f32_16x16x32_bf16 v[76:79], v[128:131], v[192:195], v[76:79]
	v_mfma_f32_16x16x32_bf16 v[68:71], v[136:139], v[192:195], v[68:71]
	v_mfma_f32_16x16x32_bf16 v[124:127], v[132:135], v[172:175], v[124:127]
	v_mfma_f32_16x16x32_bf16 v[120:123], v[140:143], v[172:175], v[120:123]
	v_mfma_f32_16x16x32_bf16 v[116:119], v[132:135], v[180:183], v[116:119]
	v_mfma_f32_16x16x32_bf16 v[100:103], v[140:143], v[180:183], v[100:103]
	v_mfma_f32_16x16x32_bf16 v[92:95], v[132:135], v[188:191], v[92:95]
	v_mfma_f32_16x16x32_bf16 v[84:87], v[140:143], v[188:191], v[84:87]
	v_mfma_f32_16x16x32_bf16 v[76:79], v[132:135], v[196:199], v[76:79]
	v_mfma_f32_16x16x32_bf16 v[68:71], v[140:143], v[196:199], v[68:71]
	s_barrier
	s_add_i32 s40, 0, 0x1c000
	s_add_i32 s41, s66, s46
	v_add_u32_e32 v212, s40, v167
	v_lshl_add_u64 v[164:165], v[164:165], 0, s[8:9]
	s_mov_b32 m0, s41
	ds_read_b128 v[200:203], v212
	ds_read_b128 v[204:207], v212 offset:1024
	ds_read_b128 v[208:211], v212 offset:2048
	ds_read_b128 v[212:215], v212 offset:3072
	global_load_lds_dwordx4 v[164:165], off
	v_lshl_add_u64 v[164:165], v[216:217], 0, s[8:9]
	s_add_i32 m0, s41, 0x2000
	s_nop 0
	global_load_lds_dwordx4 v[164:165], off
	s_barrier
	s_waitcnt lgkmcnt(0)
	s_waitcnt lgkmcnt(0)
	v_mfma_f32_16x16x32_bf16 v[112:115], v[200:203], v[160:163], v[112:115]
	v_mfma_f32_16x16x32_bf16 v[108:111], v[208:211], v[160:163], v[108:111]
	v_mfma_f32_16x16x32_bf16 v[104:107], v[200:203], v[176:179], v[104:107]
	v_mfma_f32_16x16x32_bf16 v[96:99], v[208:211], v[176:179], v[96:99]
	v_mfma_f32_16x16x32_bf16 v[88:91], v[200:203], v[184:187], v[88:91]
	v_mfma_f32_16x16x32_bf16 v[80:83], v[208:211], v[184:187], v[80:83]
	v_mfma_f32_16x16x32_bf16 v[72:75], v[200:203], v[192:195], v[72:75]
	v_mfma_f32_16x16x32_bf16 v[64:67], v[208:211], v[192:195], v[64:67]
	v_mfma_f32_16x16x32_bf16 v[112:115], v[204:207], v[172:175], v[112:115]
	v_mfma_f32_16x16x32_bf16 v[108:111], v[212:215], v[172:175], v[108:111]
	v_mfma_f32_16x16x32_bf16 v[104:107], v[204:207], v[180:183], v[104:107]
	v_mfma_f32_16x16x32_bf16 v[96:99], v[212:215], v[180:183], v[96:99]
	v_mfma_f32_16x16x32_bf16 v[88:91], v[204:207], v[188:191], v[88:91]
	v_mfma_f32_16x16x32_bf16 v[80:83], v[212:215], v[188:191], v[80:83]
	v_mfma_f32_16x16x32_bf16 v[72:75], v[204:207], v[196:199], v[72:75]
	v_mfma_f32_16x16x32_bf16 v[64:67], v[212:215], v[196:199], v[64:67]
	s_mov_b32 m0, s51
	v_lshl_add_u64 v[164:165], v[218:219], 0, s[8:9]
	s_barrier
	ds_read_b128 v[160:163], v170 offset:49152
	ds_read_b128 v[172:175], v170 offset:50176
	ds_read_b128 v[176:179], v170 offset:51200
	ds_read_b128 v[180:183], v170 offset:52224
	ds_read_b128 v[184:187], v170 offset:53248
	ds_read_b128 v[188:191], v170 offset:54272
	ds_read_b128 v[192:195], v170 offset:55296
	ds_read_b128 v[196:199], v170 offset:56320
	global_load_lds_dwordx4 v[164:165], off
	v_lshl_add_u64 v[164:165], v[220:221], 0, s[8:9]
	s_mov_b32 m0, s54
	s_nop 0
	global_load_lds_dwordx4 v[164:165], off
	s_barrier
	s_waitcnt lgkmcnt(0)
	s_waitcnt lgkmcnt(0)
	v_mfma_f32_16x16x32_bf16 v[60:63], v[128:131], v[160:163], v[60:63]
	v_mfma_f32_16x16x32_bf16 v[52:55], v[136:139], v[160:163], v[52:55]
	v_mfma_f32_16x16x32_bf16 v[44:47], v[128:131], v[176:179], v[44:47]
	v_mfma_f32_16x16x32_bf16 v[36:39], v[136:139], v[176:179], v[36:39]
	v_mfma_f32_16x16x32_bf16 v[28:31], v[128:131], v[184:187], v[28:31]
	v_mfma_f32_16x16x32_bf16 v[20:23], v[136:139], v[184:187], v[20:23]
	v_mfma_f32_16x16x32_bf16 v[12:15], v[128:131], v[192:195], v[12:15]
	v_mfma_f32_16x16x32_bf16 v[4:7], v[136:139], v[192:195], v[4:7]
	v_mfma_f32_16x16x32_bf16 v[60:63], v[132:135], v[172:175], v[60:63]
	v_mfma_f32_16x16x32_bf16 v[52:55], v[140:143], v[172:175], v[52:55]
	v_mfma_f32_16x16x32_bf16 v[44:47], v[132:135], v[180:183], v[44:47]
	v_mfma_f32_16x16x32_bf16 v[36:39], v[140:143], v[180:183], v[36:39]
	v_mfma_f32_16x16x32_bf16 v[28:31], v[132:135], v[188:191], v[28:31]
	v_mfma_f32_16x16x32_bf16 v[20:23], v[140:143], v[188:191], v[20:23]
	v_mfma_f32_16x16x32_bf16 v[12:15], v[132:135], v[196:199], v[12:15]
	v_mfma_f32_16x16x32_bf16 v[4:7], v[140:143], v[196:199], v[4:7]
	s_barrier
	s_add_u32 s38, s38, 0x40080
	s_addc_u32 s39, s39, 0
	s_add_i32 s40, s40, s46
	v_lshl_add_u64 v[128:129], s[38:39], 0, v[148:149]
	s_mov_b32 m0, s40
	s_nop 0
	global_load_lds_dwordx4 v[128:129], off
	v_lshl_add_u64 v[128:129], s[38:39], 0, v[152:153]
	s_add_i32 m0, s40, 0x2000
	s_nop 0
	global_load_lds_dwordx4 v[128:129], off
	s_waitcnt vmcnt(6)
	s_barrier
	v_mfma_f32_16x16x32_bf16 v[56:59], v[200:203], v[160:163], v[56:59]
	v_mfma_f32_16x16x32_bf16 v[48:51], v[208:211], v[160:163], v[48:51]
	v_mfma_f32_16x16x32_bf16 v[40:43], v[200:203], v[176:179], v[40:43]
	v_mfma_f32_16x16x32_bf16 v[32:35], v[208:211], v[176:179], v[32:35]
	v_mfma_f32_16x16x32_bf16 v[24:27], v[200:203], v[184:187], v[24:27]
	v_mfma_f32_16x16x32_bf16 v[16:19], v[208:211], v[184:187], v[16:19]
	v_mfma_f32_16x16x32_bf16 v[8:11], v[200:203], v[192:195], v[8:11]
	v_mfma_f32_16x16x32_bf16 v[0:3], v[208:211], v[192:195], v[0:3]
	v_mfma_f32_16x16x32_bf16 v[56:59], v[204:207], v[172:175], v[56:59]
	v_mfma_f32_16x16x32_bf16 v[48:51], v[212:215], v[172:175], v[48:51]
	v_mfma_f32_16x16x32_bf16 v[40:43], v[204:207], v[180:183], v[40:43]
	v_mfma_f32_16x16x32_bf16 v[32:35], v[212:215], v[180:183], v[32:35]
	v_mfma_f32_16x16x32_bf16 v[24:27], v[204:207], v[188:191], v[24:27]
	v_mfma_f32_16x16x32_bf16 v[16:19], v[212:215], v[188:191], v[16:19]
	v_mfma_f32_16x16x32_bf16 v[8:11], v[204:207], v[196:199], v[8:11]
	v_mfma_f32_16x16x32_bf16 v[0:3], v[212:215], v[196:199], v[0:3]
	s_add_i32 s65, s65, 2
	s_add_u32 s36, s36, 0x100
	s_addc_u32 s37, s37, 0
	s_add_u32 s29, s29, 0x100
	s_addc_u32 s64, s64, 0
	s_cmp_gt_u32 s65, 13
	s_barrier
	s_cbranch_scc0 .LBB0_932
	v_lshl_or_b32 v160, s62, 7, v168
	v_ashrrev_i32_e32 v161, 31, v160
	v_lshlrev_b64 v[128:129], 2, v[160:161]
	v_readlane_b32 s64, v248, 24
	v_lshl_add_u64 v[130:131], s[10:11], 0, v[128:129]
	v_readlane_b32 s70, v248, 30
	v_readlane_b32 s71, v248, 31
	global_load_dwordx4 v[136:139], v[130:131], off
	v_lshl_add_u32 v162, s34, 8, v166
	v_lshl_add_u64 v[128:129], s[70:71], 0, v[128:129]
	global_load_dwordx4 v[140:143], v[128:129], off
	global_load_dwordx4 v[132:135], v[130:131], off offset:16
	s_nop 0
	global_load_dwordx4 v[128:131], v[128:129], off offset:16
	v_ashrrev_i32_e32 v163, 31, v162
	v_lshlrev_b64 v[172:173], 12, v[162:163]
	v_lshlrev_b64 v[164:165], 1, v[160:161]
	v_lshl_add_u64 v[160:161], s[6:7], 0, v[172:173]
	v_lshl_add_u64 v[160:161], v[160:161], 0, v[164:165]
	s_mov_b32 s62, s12
	s_mov_b32 s34, s14
	s_mov_b64 s[38:39], s[30:31]
	s_mov_b64 s[36:37], s[18:19]
	v_readlane_b32 s65, v248, 25
	v_readlane_b32 s66, v248, 26
	v_readlane_b32 s67, v248, 27
	v_readlane_b32 s68, v248, 28
	v_readlane_b32 s69, v248, 29
	v_readlane_b32 s72, v248, 32
	v_readlane_b32 s73, v248, 33
	v_readlane_b32 s74, v248, 34
	v_readlane_b32 s75, v248, 35
	v_readlane_b32 s76, v248, 36
	v_readlane_b32 s77, v248, 37
	v_readlane_b32 s78, v248, 38
	v_readlane_b32 s79, v248, 39
	s_waitcnt vmcnt(0)
	v_add_f32_e32 v163, v112, v136
	v_add_f32_e32 v172, v113, v137
	v_add_f32_e32 v48, v48, v132
	v_add_f32_e32 v49, v49, v133
	v_pk_add_f32 v[112:113], v[126:127], v[142:143]
	v_add_f32_e32 v126, v114, v138
	v_add_f32_e32 v127, v115, v139
	v_add_f32_e32 v173, v108, v132
	v_add_f32_e32 v174, v109, v133
	v_pk_add_f32 v[108:109], v[122:123], v[130:131]
	v_pk_add_f32 v[114:115], v[120:121], v[128:129]
	v_add_f32_e32 v120, v110, v134
	v_add_f32_e32 v121, v111, v135
	v_add_f32_e32 v122, v104, v136
	v_add_f32_e32 v123, v105, v137
	v_pk_add_f32 v[110:111], v[116:117], v[140:141]
	v_add_f32_e32 v106, v106, v138
	v_add_f32_e32 v107, v107, v139
	v_mul_f32_e32 v116, 0xbfb8aa3b, v163
	v_mul_f32_e32 v117, 0xbfb8aa3b, v172
	v_mul_f32_e32 v48, 0xbfb8aa3b, v48
	v_mul_f32_e32 v49, 0xbfb8aa3b, v49
	v_add_f32_e32 v50, v50, v134
	v_add_f32_e32 v51, v51, v135
	v_pk_add_f32 v[104:105], v[118:119], v[142:143]
	v_mul_f32_e32 v118, 0xbfb8aa3b, v126
	v_mul_f32_e32 v119, 0xbfb8aa3b, v127
	v_mul_f32_e32 v126, 0xbfb8aa3b, v173
	v_mul_f32_e32 v127, 0xbfb8aa3b, v174
	v_mul_f32_e32 v120, 0xbfb8aa3b, v120
	v_mul_f32_e32 v121, 0xbfb8aa3b, v121
	v_mul_f32_e32 v122, 0xbfb8aa3b, v122
	v_mul_f32_e32 v123, 0xbfb8aa3b, v123
	v_mul_f32_e32 v106, 0xbfb8aa3b, v106
	v_mul_f32_e32 v107, 0xbfb8aa3b, v107
	v_exp_f32_e32 v116, v116
	v_exp_f32_e32 v117, v117
	v_exp_f32_e32 v48, v48
	v_exp_f32_e32 v49, v49
	v_mul_f32_e32 v50, 0xbfb8aa3b, v50
	v_mul_f32_e32 v51, 0xbfb8aa3b, v51
	v_add_f32_e32 v32, v32, v132
	v_add_f32_e32 v33, v33, v133
	v_exp_f32_e32 v118, v118
	v_exp_f32_e32 v119, v119
	v_exp_f32_e32 v126, v126
	v_exp_f32_e32 v127, v127
	v_exp_f32_e32 v120, v120
	v_exp_f32_e32 v121, v121
	v_exp_f32_e32 v122, v122
	v_exp_f32_e32 v123, v123
	v_exp_f32_e32 v106, v106
	v_exp_f32_e32 v107, v107
	v_exp_f32_e32 v50, v50
	v_exp_f32_e32 v51, v51
	v_mul_f32_e32 v32, 0xbfb8aa3b, v32
	v_mul_f32_e32 v33, 0xbfb8aa3b, v33
	v_add_f32_e32 v34, v34, v134
	v_add_f32_e32 v35, v35, v135
	v_add_f32_e32 v96, v96, v132
	v_add_f32_e32 v97, v97, v133
	v_exp_f32_e32 v32, v32
	v_exp_f32_e32 v33, v33
	v_mul_f32_e32 v34, 0xbfb8aa3b, v34
	v_mul_f32_e32 v35, 0xbfb8aa3b, v35
	v_add_f32_e32 v16, v16, v132
	v_add_f32_e32 v17, v17, v133
	v_mul_f32_e32 v96, 0xbfb8aa3b, v96
	v_mul_f32_e32 v97, 0xbfb8aa3b, v97
	v_add_f32_e32 v88, v88, v136
	v_add_f32_e32 v89, v89, v137
	v_add_f32_e32 v72, v72, v136
	v_add_f32_e32 v73, v73, v137
	v_exp_f32_e32 v34, v34
	v_exp_f32_e32 v35, v35
	v_mul_f32_e32 v16, 0xbfb8aa3b, v16
	v_mul_f32_e32 v17, 0xbfb8aa3b, v17
	v_add_f32_e32 v18, v18, v134
	v_add_f32_e32 v19, v19, v135
	v_exp_f32_e32 v163, v96
	v_exp_f32_e32 v172, v97
	v_add_f32_e32 v96, 1.0, v116
	v_add_f32_e32 v97, 1.0, v117
	v_mul_f32_e32 v88, 0xbfb8aa3b, v88
	v_mul_f32_e32 v89, 0xbfb8aa3b, v89
	v_add_f32_e32 v80, v80, v132
	v_add_f32_e32 v81, v81, v133
	v_mul_f32_e32 v72, 0xbfb8aa3b, v72
	v_mul_f32_e32 v73, 0xbfb8aa3b, v73
	v_add_f32_e32 v64, v64, v132
	v_add_f32_e32 v65, v65, v133
	v_add_f32_e32 v48, 1.0, v48
	v_add_f32_e32 v49, 1.0, v49
	v_exp_f32_e32 v16, v16
	v_exp_f32_e32 v17, v17
	v_mul_f32_e32 v18, 0xbfb8aa3b, v18
	v_mul_f32_e32 v19, 0xbfb8aa3b, v19
	v_add_f32_e32 v0, v0, v132
	v_add_f32_e32 v1, v1, v133
	v_add_f32_e32 v116, 1.0, v118
	v_add_f32_e32 v117, 1.0, v119
	v_add_f32_e32 v118, 1.0, v126
	v_add_f32_e32 v119, 1.0, v127
	v_add_f32_e32 v120, 1.0, v120
	v_add_f32_e32 v121, 1.0, v121
	v_add_f32_e32 v122, 1.0, v122
	v_add_f32_e32 v123, 1.0, v123
	v_add_f32_e32 v126, 1.0, v106
	v_add_f32_e32 v127, 1.0, v107
	v_rcp_f32_e32 v96, v96
	v_rcp_f32_e32 v97, v97
	v_add_f32_e32 v98, v98, v134
	v_add_f32_e32 v99, v99, v135
	v_exp_f32_e32 v88, v88
	v_exp_f32_e32 v89, v89
	v_mul_f32_e32 v80, 0xbfb8aa3b, v80
	v_mul_f32_e32 v81, 0xbfb8aa3b, v81
	v_add_f32_e32 v82, v82, v134
	v_add_f32_e32 v83, v83, v135
	v_exp_f32_e32 v72, v72
	v_exp_f32_e32 v73, v73
	v_mul_f32_e32 v64, 0xbfb8aa3b, v64
	v_mul_f32_e32 v65, 0xbfb8aa3b, v65
	v_add_f32_e32 v66, v66, v134
	v_add_f32_e32 v67, v67, v135
	v_rcp_f32_e32 v48, v48
	v_rcp_f32_e32 v49, v49
	v_add_f32_e32 v50, 1.0, v50
	v_add_f32_e32 v51, 1.0, v51
	v_exp_f32_e32 v18, v18
	v_exp_f32_e32 v19, v19
	v_mul_f32_e32 v0, 0xbfb8aa3b, v0
	v_mul_f32_e32 v1, 0xbfb8aa3b, v1
	v_add_f32_e32 v2, v2, v134
	v_add_f32_e32 v3, v3, v135
	v_rcp_f32_e32 v106, v116
	v_rcp_f32_e32 v107, v117
	v_rcp_f32_e32 v116, v118
	v_rcp_f32_e32 v117, v119
	v_rcp_f32_e32 v118, v120
	v_rcp_f32_e32 v119, v121
	v_rcp_f32_e32 v120, v122
	v_rcp_f32_e32 v121, v123
	v_rcp_f32_e32 v122, v126
	v_rcp_f32_e32 v123, v127
	v_mul_f32_e32 v98, 0xbfb8aa3b, v98
	v_mul_f32_e32 v99, 0xbfb8aa3b, v99
	v_add_f32_e32 v90, v90, v138
	v_add_f32_e32 v91, v91, v139
	v_exp_f32_e32 v80, v80
	v_exp_f32_e32 v81, v81
	v_mul_f32_e32 v82, 0xbfb8aa3b, v82
	v_mul_f32_e32 v83, 0xbfb8aa3b, v83
	v_add_f32_e32 v74, v74, v138
	v_add_f32_e32 v75, v75, v139
	v_exp_f32_e32 v64, v64
	v_exp_f32_e32 v65, v65
	v_mul_f32_e32 v66, 0xbfb8aa3b, v66
	v_mul_f32_e32 v67, 0xbfb8aa3b, v67
	v_add_f32_e32 v56, v56, v136
	v_add_f32_e32 v57, v57, v137
	v_add_f32_e32 v58, v58, v138
	v_add_f32_e32 v59, v59, v139
	v_rcp_f32_e32 v50, v50
	v_rcp_f32_e32 v51, v51
	v_add_f32_e32 v40, v40, v136
	v_add_f32_e32 v41, v41, v137
	v_add_f32_e32 v42, v42, v138
	v_add_f32_e32 v43, v43, v139
	v_add_f32_e32 v32, 1.0, v32
	v_add_f32_e32 v33, 1.0, v33
	v_add_f32_e32 v24, v24, v136
	v_add_f32_e32 v25, v25, v137
	v_add_f32_e32 v26, v26, v138
	v_add_f32_e32 v27, v27, v139
	v_add_f32_e32 v8, v8, v136
	v_add_f32_e32 v9, v9, v137
	v_add_f32_e32 v10, v10, v138
	v_add_f32_e32 v11, v11, v139
	v_exp_f32_e32 v0, v0
	v_exp_f32_e32 v1, v1
	v_mul_f32_e32 v2, 0xbfb8aa3b, v2
	v_mul_f32_e32 v3, 0xbfb8aa3b, v3
	v_exp_f32_e32 v98, v98
	v_exp_f32_e32 v99, v99
	v_mul_f32_e32 v90, 0xbfb8aa3b, v90
	v_mul_f32_e32 v91, 0xbfb8aa3b, v91
	v_exp_f32_e32 v82, v82
	v_exp_f32_e32 v83, v83
	v_mul_f32_e32 v74, 0xbfb8aa3b, v74
	v_mul_f32_e32 v75, 0xbfb8aa3b, v75
	v_exp_f32_e32 v66, v66
	v_exp_f32_e32 v67, v67
	v_mul_f32_e32 v56, 0xbfb8aa3b, v56
	v_mul_f32_e32 v57, 0xbfb8aa3b, v57
	v_mul_f32_e32 v58, 0xbfb8aa3b, v58
	v_mul_f32_e32 v59, 0xbfb8aa3b, v59
	v_mul_f32_e32 v40, 0xbfb8aa3b, v40
	v_mul_f32_e32 v41, 0xbfb8aa3b, v41
	v_mul_f32_e32 v42, 0xbfb8aa3b, v42
	v_mul_f32_e32 v43, 0xbfb8aa3b, v43
	v_rcp_f32_e32 v32, v32
	v_rcp_f32_e32 v33, v33
	v_add_f32_e32 v34, 1.0, v34
	v_add_f32_e32 v35, 1.0, v35
	v_mul_f32_e32 v24, 0xbfb8aa3b, v24
	v_mul_f32_e32 v25, 0xbfb8aa3b, v25
	v_mul_f32_e32 v26, 0xbfb8aa3b, v26
	v_mul_f32_e32 v27, 0xbfb8aa3b, v27
	v_mul_f32_e32 v8, 0xbfb8aa3b, v8
	v_mul_f32_e32 v9, 0xbfb8aa3b, v9
	v_mul_f32_e32 v10, 0xbfb8aa3b, v10
	v_mul_f32_e32 v11, 0xbfb8aa3b, v11
	v_exp_f32_e32 v2, v2
	v_exp_f32_e32 v3, v3
	v_pk_add_f32 v[124:125], v[124:125], v[140:141]
	v_exp_f32_e32 v90, v90
	v_exp_f32_e32 v91, v91
	v_exp_f32_e32 v74, v74
	v_exp_f32_e32 v75, v75
	v_exp_f32_e32 v56, v56
	v_exp_f32_e32 v57, v57
	v_exp_f32_e32 v58, v58
	v_exp_f32_e32 v59, v59
	v_pk_add_f32 v[52:53], v[52:53], v[128:129]
	v_exp_f32_e32 v40, v40
	v_exp_f32_e32 v41, v41
	v_exp_f32_e32 v42, v42
	v_exp_f32_e32 v43, v43
	v_rcp_f32_e32 v34, v34
	v_rcp_f32_e32 v35, v35
	v_exp_f32_e32 v24, v24
	v_exp_f32_e32 v25, v25
	v_exp_f32_e32 v26, v26
	v_exp_f32_e32 v27, v27
	v_add_f32_e32 v16, 1.0, v16
	v_add_f32_e32 v17, 1.0, v17
	v_exp_f32_e32 v8, v8
	v_exp_f32_e32 v9, v9
	v_exp_f32_e32 v10, v10
	v_exp_f32_e32 v11, v11
	v_pk_mul_f32 v[96:97], v[124:125], v[96:97]
	v_add_f32_e32 v88, 1.0, v88
	v_add_f32_e32 v89, 1.0, v89
	v_add_f32_e32 v72, 1.0, v72
	v_add_f32_e32 v73, 1.0, v73
	v_pk_add_f32 v[54:55], v[54:55], v[130:131]
	v_pk_mul_f32 v[52:53], v[52:53], v[48:49]
	v_rcp_f32_e32 v16, v16
	v_rcp_f32_e32 v17, v17
	v_add_f32_e32 v18, 1.0, v18
	v_add_f32_e32 v19, 1.0, v19
	v_pk_mul_f32 v[106:107], v[112:113], v[106:107]
	v_pk_mul_f32 v[112:113], v[114:115], v[116:117]
	v_pk_mul_f32 v[114:115], v[104:105], v[122:123]
	v_cvt_pk_bf16_f32 v104, v96, v97
	v_add_f32_e32 v96, 1.0, v163
	v_add_f32_e32 v97, 1.0, v172
	v_rcp_f32_e32 v88, v88
	v_rcp_f32_e32 v89, v89
	v_add_f32_e32 v80, 1.0, v80
	v_add_f32_e32 v81, 1.0, v81
	v_rcp_f32_e32 v72, v72
	v_rcp_f32_e32 v73, v73
	v_add_f32_e32 v64, 1.0, v64
	v_add_f32_e32 v65, 1.0, v65
	v_pk_mul_f32 v[54:55], v[54:55], v[50:51]
	v_cvt_pk_bf16_f32 v50, v52, v53
	v_add_co_u32_e32 v52, vcc, s59, v160
	v_pk_add_f32 v[36:37], v[36:37], v[128:129]
	v_rcp_f32_e32 v18, v18
	v_rcp_f32_e32 v19, v19
	v_add_f32_e32 v0, 1.0, v0
	v_add_f32_e32 v1, 1.0, v1
	v_rcp_f32_e32 v96, v96
	v_rcp_f32_e32 v97, v97
	v_add_f32_e32 v98, 1.0, v98
	v_add_f32_e32 v99, 1.0, v99
	v_rcp_f32_e32 v80, v80
	v_rcp_f32_e32 v81, v81
	v_add_f32_e32 v82, 1.0, v82
	v_add_f32_e32 v83, 1.0, v83
	v_rcp_f32_e32 v64, v64
	v_rcp_f32_e32 v65, v65
	v_add_f32_e32 v66, 1.0, v66
	v_add_f32_e32 v67, 1.0, v67
	v_addc_co_u32_e32 v53, vcc, 0, v161, vcc
	v_pk_add_f32 v[38:39], v[38:39], v[130:131]
	v_pk_mul_f32 v[36:37], v[36:37], v[32:33]
	v_rcp_f32_e32 v0, v0
	v_rcp_f32_e32 v1, v1
	v_add_f32_e32 v2, 1.0, v2
	v_add_f32_e32 v3, 1.0, v3
	v_pk_mul_f32 v[108:109], v[108:109], v[118:119]
	v_rcp_f32_e32 v98, v98
	v_rcp_f32_e32 v99, v99
	v_add_f32_e32 v90, 1.0, v90
	v_add_f32_e32 v91, 1.0, v91
	v_rcp_f32_e32 v82, v82
	v_rcp_f32_e32 v83, v83
	v_add_f32_e32 v74, 1.0, v74
	v_add_f32_e32 v75, 1.0, v75
	v_rcp_f32_e32 v66, v66
	v_rcp_f32_e32 v67, v67
	v_add_f32_e32 v56, 1.0, v56
	v_add_f32_e32 v57, 1.0, v57
	v_add_f32_e32 v58, 1.0, v58
	v_add_f32_e32 v59, 1.0, v59
	v_add_f32_e32 v40, 1.0, v40
	v_add_f32_e32 v41, 1.0, v41
	v_add_f32_e32 v42, 1.0, v42
	v_add_f32_e32 v43, 1.0, v43
	v_pk_mul_f32 v[38:39], v[38:39], v[34:35]
	v_cvt_pk_bf16_f32 v34, v36, v37
	v_add_co_u32_e32 v36, vcc, s60, v160
	v_add_f32_e32 v24, 1.0, v24
	v_add_f32_e32 v25, 1.0, v25
	v_add_f32_e32 v26, 1.0, v26
	v_add_f32_e32 v27, 1.0, v27
	v_pk_add_f32 v[20:21], v[20:21], v[128:129]
	v_add_f32_e32 v8, 1.0, v8
	v_add_f32_e32 v9, 1.0, v9
	v_add_f32_e32 v10, 1.0, v10
	v_add_f32_e32 v11, 1.0, v11
	v_rcp_f32_e32 v2, v2
	v_rcp_f32_e32 v3, v3
	v_cvt_pk_bf16_f32 v105, v106, v107
	v_cvt_pk_bf16_f32 v106, v112, v113
	v_cvt_pk_bf16_f32 v107, v108, v109
	v_pk_add_f32 v[92:93], v[92:93], v[140:141]
	v_rcp_f32_e32 v90, v90
	v_rcp_f32_e32 v91, v91
	v_pk_add_f32 v[76:77], v[76:77], v[140:141]
	v_rcp_f32_e32 v74, v74
	v_rcp_f32_e32 v75, v75
	v_rcp_f32_e32 v56, v56
	v_rcp_f32_e32 v57, v57
	v_rcp_f32_e32 v58, v58
	v_rcp_f32_e32 v59, v59
	v_rcp_f32_e32 v40, v40
	v_rcp_f32_e32 v41, v41
	v_rcp_f32_e32 v42, v42
	v_rcp_f32_e32 v43, v43
	v_addc_co_u32_e32 v37, vcc, 0, v161, vcc
	v_rcp_f32_e32 v24, v24
	v_rcp_f32_e32 v25, v25
	v_rcp_f32_e32 v26, v26
	v_rcp_f32_e32 v27, v27
	v_pk_add_f32 v[22:23], v[22:23], v[130:131]
	v_pk_mul_f32 v[20:21], v[20:21], v[16:17]
	v_rcp_f32_e32 v8, v8
	v_rcp_f32_e32 v9, v9
	v_rcp_f32_e32 v10, v10
	v_rcp_f32_e32 v11, v11
	global_store_dwordx4 v[160:161], v[104:107], off
	v_pk_add_f32 v[100:101], v[100:101], v[128:129]
	v_pk_mul_f32 v[88:89], v[92:93], v[88:89]
	v_or_b32_e32 v104, 16, v162
	v_pk_add_f32 v[84:85], v[84:85], v[128:129]
	v_or_b32_e32 v92, 32, v162
	v_pk_mul_f32 v[72:73], v[76:77], v[72:73]
	v_pk_add_f32 v[68:69], v[68:69], v[128:129]
	v_or_b32_e32 v76, 48, v162
	v_pk_mul_f32 v[22:23], v[22:23], v[18:19]
	v_cvt_pk_bf16_f32 v18, v20, v21
	v_add_co_u32_e32 v20, vcc, s61, v160
	v_pk_add_f32 v[4:5], v[4:5], v[128:129]
	v_pk_add_f32 v[102:103], v[102:103], v[130:131]
	v_pk_mul_f32 v[100:101], v[100:101], v[96:97]
	v_ashrrev_i32_e32 v105, 31, v104
	v_pk_add_f32 v[86:87], v[86:87], v[130:131]
	v_pk_mul_f32 v[84:85], v[84:85], v[80:81]
	v_ashrrev_i32_e32 v93, 31, v92
	v_pk_add_f32 v[70:71], v[70:71], v[130:131]
	v_pk_mul_f32 v[68:69], v[68:69], v[64:65]
	v_ashrrev_i32_e32 v77, 31, v76
	v_addc_co_u32_e32 v21, vcc, 0, v161, vcc
	v_pk_add_f32 v[6:7], v[6:7], v[130:131]
	v_pk_mul_f32 v[4:5], v[4:5], v[0:1]
	v_pk_mul_f32 v[102:103], v[102:103], v[98:99]
	v_cvt_pk_bf16_f32 v98, v100, v101
	v_lshlrev_b64 v[100:101], 12, v[104:105]
	v_pk_add_f32 v[94:95], v[94:95], v[142:143]
	v_pk_mul_f32 v[86:87], v[86:87], v[82:83]
	v_cvt_pk_bf16_f32 v82, v84, v85
	v_lshlrev_b64 v[84:85], 12, v[92:93]
	v_pk_add_f32 v[78:79], v[78:79], v[142:143]
	v_pk_mul_f32 v[70:71], v[70:71], v[66:67]
	v_cvt_pk_bf16_f32 v66, v68, v69
	v_lshlrev_b64 v[68:69], 12, v[76:77]
	v_pk_add_f32 v[62:63], v[62:63], v[142:143]
	v_pk_add_f32 v[60:61], v[60:61], v[140:141]
	v_pk_add_f32 v[46:47], v[46:47], v[142:143]
	v_pk_add_f32 v[44:45], v[44:45], v[140:141]
	v_pk_add_f32 v[30:31], v[30:31], v[142:143]
	v_pk_add_f32 v[28:29], v[28:29], v[140:141]
	v_pk_add_f32 v[14:15], v[14:15], v[142:143]
	v_pk_add_f32 v[12:13], v[12:13], v[140:141]
	v_pk_mul_f32 v[6:7], v[6:7], v[2:3]
	v_cvt_pk_bf16_f32 v2, v4, v5
	v_add_co_u32_e32 v4, vcc, 0xb0000, v160
	v_pk_mul_f32 v[110:111], v[110:111], v[120:121]
	v_lshl_add_u64 v[100:101], s[6:7], 0, v[100:101]
	v_pk_mul_f32 v[90:91], v[94:95], v[90:91]
	v_lshl_add_u64 v[84:85], s[6:7], 0, v[84:85]
	v_pk_mul_f32 v[74:75], v[78:79], v[74:75]
	v_lshl_add_u64 v[68:69], s[6:7], 0, v[68:69]
	v_pk_mul_f32 v[56:57], v[60:61], v[56:57]
	v_pk_mul_f32 v[58:59], v[62:63], v[58:59]
	v_pk_mul_f32 v[40:41], v[44:45], v[40:41]
	v_pk_mul_f32 v[42:43], v[46:47], v[42:43]
	v_pk_mul_f32 v[24:25], v[28:29], v[24:25]
	v_pk_mul_f32 v[26:27], v[30:31], v[26:27]
	v_pk_mul_f32 v[8:9], v[12:13], v[8:9]
	v_pk_mul_f32 v[10:11], v[14:15], v[10:11]
	v_addc_co_u32_e32 v5, vcc, 0, v161, vcc
	v_cvt_pk_bf16_f32 v96, v110, v111
	v_cvt_pk_bf16_f32 v97, v114, v115
	v_cvt_pk_bf16_f32 v99, v102, v103
	v_lshl_add_u64 v[100:101], v[100:101], 0, v[164:165]
	v_cvt_pk_bf16_f32 v80, v88, v89
	v_cvt_pk_bf16_f32 v81, v90, v91
	v_cvt_pk_bf16_f32 v83, v86, v87
	v_lshl_add_u64 v[84:85], v[84:85], 0, v[164:165]
	v_cvt_pk_bf16_f32 v64, v72, v73
	v_cvt_pk_bf16_f32 v65, v74, v75
	v_cvt_pk_bf16_f32 v67, v70, v71
	v_lshl_add_u64 v[68:69], v[68:69], 0, v[164:165]
	v_cvt_pk_bf16_f32 v48, v56, v57
	v_cvt_pk_bf16_f32 v49, v58, v59
	v_cvt_pk_bf16_f32 v51, v54, v55
	v_cvt_pk_bf16_f32 v32, v40, v41
	v_cvt_pk_bf16_f32 v33, v42, v43
	v_cvt_pk_bf16_f32 v35, v38, v39
	v_cvt_pk_bf16_f32 v16, v24, v25
	v_cvt_pk_bf16_f32 v17, v26, v27
	v_cvt_pk_bf16_f32 v19, v22, v23
	v_cvt_pk_bf16_f32 v0, v8, v9
	v_cvt_pk_bf16_f32 v1, v10, v11
	v_cvt_pk_bf16_f32 v3, v6, v7
	s_and_b64 vcc, exec, s[16:17]
	global_store_dwordx4 v[100:101], v[96:99], off
	global_store_dwordx4 v[84:85], v[80:83], off
	global_store_dwordx4 v[68:69], v[64:67], off
	global_store_dwordx4 v[52:53], v[48:51], off
	global_store_dwordx4 v[36:37], v[32:35], off
	global_store_dwordx4 v[20:21], v[16:19], off
	global_store_dwordx4 v[4:5], v[0:3], off
	s_cbranch_vccz .LBB0_923
	s_branch .LBB0_935

.LBB0_1062:
	s_ashr_i32 s6, s8, 3
	s_waitcnt lgkmcnt(0)
	s_add_u32 s48, s22, 0x5e00000
	s_addc_u32 s49, s23, 0
	s_waitcnt vmcnt(0)
	v_lshlrev_b32_e32 v0, 4, v144
	s_add_u32 s50, s22, 0x1400000
	v_and_b32_e32 v1, 32, v144
	v_bfe_u32 v10, v144, 2, 4
	v_lshrrev_b32_e32 v2, 3, v144
	s_movk_i32 s7, 0x70
	v_add_u32_e32 v11, 0x2000, v0
	s_addc_u32 s51, s23, 0
	v_bitop3_b32 v8, v0, v1, 48 bitop3:0x6c
	v_and_or_b32 v2, v2, s7, v10
	v_lshrrev_b32_e32 v0, 7, v11
	s_movk_i32 s7, 0xf0
	s_add_i32 s6, s9, s6
	v_and_or_b32 v0, v0, s7, v10
	s_ashr_i32 s7, s6, 31
	s_lshr_b32 s7, s7, 26
	s_add_i32 s7, s6, s7
	s_ashr_i32 s9, s7, 6
	s_andn2_b32 s7, s7, 63
	s_sub_i32 s6, s6, s7
	s_bfe_i32 s7, s6, 0x80000
	s_bfe_u32 s7, s7, 0x3000c
	s_add_i32 s7, s6, s7
	s_bfe_i32 s10, s7, 0x80000
	s_and_b32 s7, s7, 0xf8
	s_sub_i32 s6, s6, s7
	s_lshl_b32 s9, s9, 3
	s_sext_i32_i16 s10, s10
	s_sext_i32_i8 s6, s6
	s_lshr_b32 s11, s2, 8
	s_lshr_b32 s10, s10, 3
	s_add_i32 s40, s9, s6
	s_lshr_b32 s8, s2, 6
	s_ashr_i32 s41, s40, 31
	s_bfe_i64 s[12:13], s[10:11], 0x100000
	s_lshl_b32 s54, s8, 10
	s_lshl_b64 s[6:7], s[40:41], 20
	s_lshl_b64 s[12:13], s[12:13], 20
	v_and_b32_e32 v9, 64, v144
	s_add_u32 s44, s50, s12
	v_or_b32_e32 v1, v8, v9
	s_addc_u32 s45, s51, s13
	s_add_i32 s41, s54, 0
	v_lshl_or_b32 v146, v2, 12, v1
	s_add_i32 m0, s41, 0x10000
	v_lshl_or_b32 v148, v0, 12, v1
	global_load_lds_dwordx4 v146, s[44:45]
	s_add_i32 m0, s41, 0x12000
	s_add_u32 s42, s48, s6
	global_load_lds_dwordx4 v148, s[44:45]
	s_addc_u32 s43, s49, s7
	s_mov_b32 m0, s41
	s_add_i32 s55, s41, 0x2000
	global_load_lds_dwordx4 v146, s[42:43]
	s_mov_b32 m0, s55
	s_add_u32 s6, s44, 0x80000
	global_load_lds_dwordx4 v148, s[42:43]
	s_addc_u32 s7, s45, 0
	s_add_i32 m0, s41, 0x14000
	v_mov_b32_e32 v147, 0
	global_load_lds_dwordx4 v146, s[6:7]
	s_add_i32 m0, s41, 0x16000
	v_mov_b32_e32 v149, v147
	global_load_lds_dwordx4 v148, s[6:7]
	s_add_u32 s6, s42, 0x80000
	s_addc_u32 s7, s43, 0
	s_add_i32 s56, s41, 0x4000
	s_mov_b32 m0, s56
	s_add_i32 s57, s41, 0x6000
	global_load_lds_dwordx4 v146, s[6:7]
	s_mov_b32 m0, s57
	s_mov_b32 s58, 0
	global_load_lds_dwordx4 v148, s[6:7]
	v_lshl_add_u64 v[6:7], s[44:45], 0, v[146:147]
	v_lshl_add_u64 v[4:5], s[44:45], 0, v[148:149]
	v_lshl_add_u64 v[2:3], s[42:43], 0, v[146:147]
	s_cmp_lg_u32 s11, 1
	v_lshl_add_u64 v[0:1], s[42:43], 0, v[148:149]
	s_cbranch_scc1 .LBB0_1064
	s_setprio 1
	s_barrier

.LBB0_1073:
	s_ashr_i32 s31, s30, 31
	s_xor_b64 s[34:35], s[28:29], -1
	s_lshl_b64 s[36:37], s[30:31], 20
	s_add_u32 s36, s48, s36
	s_addc_u32 s37, s49, s37
	s_and_b64 s[38:39], s[28:29], exec
	s_cselect_b32 s31, s37, s43
	s_cselect_b32 s68, s36, s42
	s_ashr_i32 s19, s18, 31
	s_lshl_b64 s[38:39], s[18:19], 20
	s_add_u32 s38, s50, s38
	s_addc_u32 s39, s51, s39
	s_and_b64 s[28:29], s[28:29], exec
	s_cselect_b32 s19, s39, s45
	s_cselect_b32 s28, s38, s44
	s_add_u32 s42, s42, 0x80080
	s_addc_u32 s43, s43, 0
	s_add_u32 s29, s44, 0x100
	s_addc_u32 s69, s45, 0
	s_mov_b32 s70, -2
	ds_read_b128 v[128:131], v165
	ds_read_b128 v[132:135], v165 offset:1024
	ds_read_b128 v[136:139], v165 offset:2048
	ds_read_b128 v[140:143], v165 offset:3072
	s_add_u32 s44, s42, 0xfff80080
	s_addc_u32 s45, s43, -1
	s_cmp_eq_u32 s70, 28
	s_cselect_b32 s47, s31, s45
	s_cselect_b32 s46, s68, s44
	s_cselect_b32 s45, s19, s69
	s_cselect_b32 s44, s28, s29
	v_lshl_add_u64 v[160:161], s[42:43], 0, v[150:151]
	s_add_i32 m0, s41, 0xc000
	ds_read_b128 v[156:159], v166
	ds_read_b128 v[168:171], v166 offset:1024
	ds_read_b128 v[172:175], v166 offset:2048
	ds_read_b128 v[176:179], v166 offset:3072
	ds_read_b128 v[180:183], v166 offset:4096
	ds_read_b128 v[184:187], v166 offset:5120
	ds_read_b128 v[188:191], v166 offset:6144
	ds_read_b128 v[192:195], v166 offset:7168
	global_load_lds_dwordx4 v[160:161], off
	v_lshl_add_u64 v[160:161], s[42:43], 0, v[152:153]
	s_add_i32 m0, s41, 0xe000
	s_nop 0
	global_load_lds_dwordx4 v[160:161], off
	s_waitcnt lgkmcnt(8)
	s_barrier
	s_waitcnt lgkmcnt(0)
	s_waitcnt lgkmcnt(0)
	v_mfma_f32_16x16x32_bf16 v[124:127], v[128:131], v[156:159], 0
	v_mfma_f32_16x16x32_bf16 v[120:123], v[136:139], v[156:159], 0
	v_mfma_f32_16x16x32_bf16 v[112:115], v[128:131], v[172:175], 0
	v_mfma_f32_16x16x32_bf16 v[104:107], v[136:139], v[172:175], 0
	v_mfma_f32_16x16x32_bf16 v[96:99], v[128:131], v[180:183], 0
	v_mfma_f32_16x16x32_bf16 v[88:91], v[136:139], v[180:183], 0
	v_mfma_f32_16x16x32_bf16 v[80:83], v[128:131], v[188:191], 0
	v_mfma_f32_16x16x32_bf16 v[72:75], v[136:139], v[188:191], 0
	v_mfma_f32_16x16x32_bf16 v[124:127], v[132:135], v[168:171], v[124:127]
	v_mfma_f32_16x16x32_bf16 v[120:123], v[140:143], v[168:171], v[120:123]
	v_mfma_f32_16x16x32_bf16 v[112:115], v[132:135], v[176:179], v[112:115]
	v_mfma_f32_16x16x32_bf16 v[104:107], v[140:143], v[176:179], v[104:107]
	v_mfma_f32_16x16x32_bf16 v[96:99], v[132:135], v[184:187], v[96:99]
	v_mfma_f32_16x16x32_bf16 v[88:91], v[140:143], v[184:187], v[88:91]
	v_mfma_f32_16x16x32_bf16 v[80:83], v[132:135], v[192:195], v[80:83]
	v_mfma_f32_16x16x32_bf16 v[72:75], v[140:143], v[192:195], v[72:75]
	s_barrier
	s_add_i32 s71, s65, s54
	v_lshl_add_u64 v[160:161], s[44:45], 0, v[146:147]
	s_mov_b32 m0, s71
	ds_read_b128 v[196:199], v167
	ds_read_b128 v[200:203], v167 offset:1024
	ds_read_b128 v[204:207], v167 offset:2048
	ds_read_b128 v[208:211], v167 offset:3072
	global_load_lds_dwordx4 v[160:161], off
	v_lshl_add_u64 v[212:213], s[44:45], 0, v[148:149]
	s_add_i32 m0, s71, 0x2000
	s_nop 0
	global_load_lds_dwordx4 v[212:213], off
	s_barrier
	s_waitcnt lgkmcnt(0)
	s_waitcnt lgkmcnt(0)
	v_mfma_f32_16x16x32_bf16 v[116:119], v[196:199], v[156:159], 0
	v_mfma_f32_16x16x32_bf16 v[108:111], v[204:207], v[156:159], 0
	v_mfma_f32_16x16x32_bf16 v[100:103], v[196:199], v[172:175], 0
	v_mfma_f32_16x16x32_bf16 v[92:95], v[204:207], v[172:175], 0
	v_mfma_f32_16x16x32_bf16 v[84:87], v[196:199], v[180:183], 0
	v_mfma_f32_16x16x32_bf16 v[76:79], v[204:207], v[180:183], 0
	v_mfma_f32_16x16x32_bf16 v[68:71], v[196:199], v[188:191], 0
	v_mfma_f32_16x16x32_bf16 v[64:67], v[204:207], v[188:191], 0
	v_mfma_f32_16x16x32_bf16 v[116:119], v[200:203], v[168:171], v[116:119]
	v_mfma_f32_16x16x32_bf16 v[108:111], v[208:211], v[168:171], v[108:111]
	v_mfma_f32_16x16x32_bf16 v[100:103], v[200:203], v[176:179], v[100:103]
	v_mfma_f32_16x16x32_bf16 v[92:95], v[208:211], v[176:179], v[92:95]
	v_mfma_f32_16x16x32_bf16 v[84:87], v[200:203], v[184:187], v[84:87]
	v_mfma_f32_16x16x32_bf16 v[76:79], v[208:211], v[184:187], v[76:79]
	v_mfma_f32_16x16x32_bf16 v[68:71], v[200:203], v[192:195], v[68:71]
	v_mfma_f32_16x16x32_bf16 v[64:67], v[208:211], v[192:195], v[64:67]
	s_mov_b32 m0, s41
	v_lshl_add_u64 v[214:215], s[46:47], 0, v[146:147]
	s_barrier
	ds_read_b128 v[156:159], v166 offset:16384
	ds_read_b128 v[168:171], v166 offset:17408
	ds_read_b128 v[172:175], v166 offset:18432
	ds_read_b128 v[176:179], v166 offset:19456
	ds_read_b128 v[180:183], v166 offset:20480
	ds_read_b128 v[184:187], v166 offset:21504
	ds_read_b128 v[188:191], v166 offset:22528
	ds_read_b128 v[192:195], v166 offset:23552
	global_load_lds_dwordx4 v[214:215], off
	v_lshl_add_u64 v[216:217], s[46:47], 0, v[148:149]
	s_mov_b32 m0, s55
	s_nop 0
	global_load_lds_dwordx4 v[216:217], off
	s_barrier
	s_waitcnt lgkmcnt(0)
	s_waitcnt lgkmcnt(0)
	v_mfma_f32_16x16x32_bf16 v[60:63], v[128:131], v[156:159], 0
	v_mfma_f32_16x16x32_bf16 v[56:59], v[136:139], v[156:159], 0
	v_mfma_f32_16x16x32_bf16 v[48:51], v[128:131], v[172:175], 0
	v_mfma_f32_16x16x32_bf16 v[40:43], v[136:139], v[172:175], 0
	v_mfma_f32_16x16x32_bf16 v[32:35], v[128:131], v[180:183], 0
	v_mfma_f32_16x16x32_bf16 v[24:27], v[136:139], v[180:183], 0
	v_mfma_f32_16x16x32_bf16 v[16:19], v[128:131], v[188:191], 0
	v_mfma_f32_16x16x32_bf16 v[8:11], v[136:139], v[188:191], 0
	v_mfma_f32_16x16x32_bf16 v[60:63], v[132:135], v[168:171], v[60:63]
	v_mfma_f32_16x16x32_bf16 v[56:59], v[140:143], v[168:171], v[56:59]
	v_mfma_f32_16x16x32_bf16 v[48:51], v[132:135], v[176:179], v[48:51]
	v_mfma_f32_16x16x32_bf16 v[40:43], v[140:143], v[176:179], v[40:43]
	v_mfma_f32_16x16x32_bf16 v[32:35], v[132:135], v[184:187], v[32:35]
	v_mfma_f32_16x16x32_bf16 v[24:27], v[140:143], v[184:187], v[24:27]
	v_mfma_f32_16x16x32_bf16 v[16:19], v[132:135], v[192:195], v[16:19]
	v_mfma_f32_16x16x32_bf16 v[8:11], v[140:143], v[192:195], v[8:11]
	s_barrier
	s_add_u32 s72, s44, 0x80000
	s_addc_u32 s73, s45, 0
	s_add_i32 s71, s66, s54
	v_lshl_add_u64 v[128:129], s[72:73], 0, v[146:147]
	s_mov_b32 m0, s71
	s_nop 0
	global_load_lds_dwordx4 v[128:129], off
	v_lshl_add_u64 v[128:129], s[72:73], 0, v[148:149]
	s_add_i32 m0, s71, 0x2000
	s_nop 0
	global_load_lds_dwordx4 v[128:129], off
	s_waitcnt vmcnt(6)
	s_barrier
	v_mfma_f32_16x16x32_bf16 v[52:55], v[196:199], v[156:159], 0
	v_mfma_f32_16x16x32_bf16 v[44:47], v[204:207], v[156:159], 0
	v_mfma_f32_16x16x32_bf16 v[36:39], v[196:199], v[172:175], 0
	v_mfma_f32_16x16x32_bf16 v[28:31], v[204:207], v[172:175], 0
	v_mfma_f32_16x16x32_bf16 v[20:23], v[196:199], v[180:183], 0
	v_mfma_f32_16x16x32_bf16 v[12:15], v[204:207], v[180:183], 0
	v_mfma_f32_16x16x32_bf16 v[4:7], v[196:199], v[188:191], 0
	v_mfma_f32_16x16x32_bf16 v[0:3], v[204:207], v[188:191], 0
	v_mfma_f32_16x16x32_bf16 v[52:55], v[200:203], v[168:171], v[52:55]
	v_mfma_f32_16x16x32_bf16 v[44:47], v[208:211], v[168:171], v[44:47]
	v_mfma_f32_16x16x32_bf16 v[36:39], v[200:203], v[176:179], v[36:39]
	v_mfma_f32_16x16x32_bf16 v[28:31], v[208:211], v[176:179], v[28:31]
	v_mfma_f32_16x16x32_bf16 v[20:23], v[200:203], v[184:187], v[20:23]
	v_mfma_f32_16x16x32_bf16 v[12:15], v[208:211], v[184:187], v[12:15]
	v_mfma_f32_16x16x32_bf16 v[4:7], v[200:203], v[192:195], v[4:7]
	v_mfma_f32_16x16x32_bf16 v[0:3], v[208:211], v[192:195], v[0:3]
	s_add_i32 s71, 0, 0x18000
	v_add_u32_e32 v140, s71, v163
	s_barrier
	ds_read_b128 v[128:131], v140
	ds_read_b128 v[132:135], v140 offset:1024
	ds_read_b128 v[136:139], v140 offset:2048
	ds_read_b128 v[140:143], v140 offset:3072
	s_add_u32 s46, s46, 0x80000
	s_addc_u32 s47, s47, 0
	s_mov_b32 m0, s56
	v_lshl_add_u64 v[196:197], s[46:47], 0, v[146:147]
	ds_read_b128 v[156:159], v166 offset:32768
	ds_read_b128 v[168:171], v166 offset:33792
	ds_read_b128 v[172:175], v166 offset:34816
	ds_read_b128 v[176:179], v166 offset:35840
	ds_read_b128 v[180:183], v166 offset:36864
	ds_read_b128 v[184:187], v166 offset:37888
	ds_read_b128 v[188:191], v166 offset:38912
	ds_read_b128 v[192:195], v166 offset:39936
	global_load_lds_dwordx4 v[196:197], off
	v_lshl_add_u64 v[196:197], s[46:47], 0, v[148:149]
	s_mov_b32 m0, s57
	s_nop 0
	global_load_lds_dwordx4 v[196:197], off
	s_waitcnt lgkmcnt(8)
	s_barrier
	s_waitcnt lgkmcnt(0)
	s_waitcnt lgkmcnt(0)
	v_mfma_f32_16x16x32_bf16 v[124:127], v[128:131], v[156:159], v[124:127]
	v_mfma_f32_16x16x32_bf16 v[120:123], v[136:139], v[156:159], v[120:123]
	v_mfma_f32_16x16x32_bf16 v[112:115], v[128:131], v[172:175], v[112:115]
	v_mfma_f32_16x16x32_bf16 v[104:107], v[136:139], v[172:175], v[104:107]
	v_mfma_f32_16x16x32_bf16 v[96:99], v[128:131], v[180:183], v[96:99]
	v_mfma_f32_16x16x32_bf16 v[88:91], v[136:139], v[180:183], v[88:91]
	v_mfma_f32_16x16x32_bf16 v[80:83], v[128:131], v[188:191], v[80:83]
	v_mfma_f32_16x16x32_bf16 v[72:75], v[136:139], v[188:191], v[72:75]
	v_mfma_f32_16x16x32_bf16 v[124:127], v[132:135], v[168:171], v[124:127]
	v_mfma_f32_16x16x32_bf16 v[120:123], v[140:143], v[168:171], v[120:123]
	v_mfma_f32_16x16x32_bf16 v[112:115], v[132:135], v[176:179], v[112:115]
	v_mfma_f32_16x16x32_bf16 v[104:107], v[140:143], v[176:179], v[104:107]
	v_mfma_f32_16x16x32_bf16 v[96:99], v[132:135], v[184:187], v[96:99]
	v_mfma_f32_16x16x32_bf16 v[88:91], v[140:143], v[184:187], v[88:91]
	v_mfma_f32_16x16x32_bf16 v[80:83], v[132:135], v[192:195], v[80:83]
	v_mfma_f32_16x16x32_bf16 v[72:75], v[140:143], v[192:195], v[72:75]
	s_barrier
	s_add_i32 s46, 0, 0x1c000
	s_add_i32 s47, s71, s54
	v_add_u32_e32 v208, s46, v163
	v_lshl_add_u64 v[160:161], v[160:161], 0, s[8:9]
	s_mov_b32 m0, s47
	ds_read_b128 v[196:199], v208
	ds_read_b128 v[200:203], v208 offset:1024
	ds_read_b128 v[204:207], v208 offset:2048
	ds_read_b128 v[208:211], v208 offset:3072
	global_load_lds_dwordx4 v[160:161], off
	v_lshl_add_u64 v[160:161], v[212:213], 0, s[8:9]
	s_add_i32 m0, s47, 0x2000
	s_nop 0
	global_load_lds_dwordx4 v[160:161], off
	s_barrier
	s_waitcnt lgkmcnt(0)
	s_waitcnt lgkmcnt(0)
	v_mfma_f32_16x16x32_bf16 v[116:119], v[196:199], v[156:159], v[116:119]
	v_mfma_f32_16x16x32_bf16 v[108:111], v[204:207], v[156:159], v[108:111]
	v_mfma_f32_16x16x32_bf16 v[100:103], v[196:199], v[172:175], v[100:103]
	v_mfma_f32_16x16x32_bf16 v[92:95], v[204:207], v[172:175], v[92:95]
	v_mfma_f32_16x16x32_bf16 v[84:87], v[196:199], v[180:183], v[84:87]
	v_mfma_f32_16x16x32_bf16 v[76:79], v[204:207], v[180:183], v[76:79]
	v_mfma_f32_16x16x32_bf16 v[68:71], v[196:199], v[188:191], v[68:71]
	v_mfma_f32_16x16x32_bf16 v[64:67], v[204:207], v[188:191], v[64:67]
	v_mfma_f32_16x16x32_bf16 v[116:119], v[200:203], v[168:171], v[116:119]
	v_mfma_f32_16x16x32_bf16 v[108:111], v[208:211], v[168:171], v[108:111]
	v_mfma_f32_16x16x32_bf16 v[100:103], v[200:203], v[176:179], v[100:103]
	v_mfma_f32_16x16x32_bf16 v[92:95], v[208:211], v[176:179], v[92:95]
	v_mfma_f32_16x16x32_bf16 v[84:87], v[200:203], v[184:187], v[84:87]
	v_mfma_f32_16x16x32_bf16 v[76:79], v[208:211], v[184:187], v[76:79]
	v_mfma_f32_16x16x32_bf16 v[68:71], v[200:203], v[192:195], v[68:71]
	v_mfma_f32_16x16x32_bf16 v[64:67], v[208:211], v[192:195], v[64:67]
	s_mov_b32 m0, s61
	v_lshl_add_u64 v[160:161], v[214:215], 0, s[8:9]
	s_barrier
	ds_read_b128 v[156:159], v166 offset:49152
	ds_read_b128 v[168:171], v166 offset:50176
	ds_read_b128 v[172:175], v166 offset:51200
	ds_read_b128 v[176:179], v166 offset:52224
	ds_read_b128 v[180:183], v166 offset:53248
	ds_read_b128 v[184:187], v166 offset:54272
	ds_read_b128 v[188:191], v166 offset:55296
	ds_read_b128 v[192:195], v166 offset:56320
	global_load_lds_dwordx4 v[160:161], off
	v_lshl_add_u64 v[160:161], v[216:217], 0, s[8:9]
	s_mov_b32 m0, s62
	s_nop 0
	global_load_lds_dwordx4 v[160:161], off
	s_barrier
	s_waitcnt lgkmcnt(0)
	s_waitcnt lgkmcnt(0)
	v_mfma_f32_16x16x32_bf16 v[60:63], v[128:131], v[156:159], v[60:63]
	v_mfma_f32_16x16x32_bf16 v[56:59], v[136:139], v[156:159], v[56:59]
	v_mfma_f32_16x16x32_bf16 v[48:51], v[128:131], v[172:175], v[48:51]
	v_mfma_f32_16x16x32_bf16 v[40:43], v[136:139], v[172:175], v[40:43]
	v_mfma_f32_16x16x32_bf16 v[32:35], v[128:131], v[180:183], v[32:35]
	v_mfma_f32_16x16x32_bf16 v[24:27], v[136:139], v[180:183], v[24:27]
	v_mfma_f32_16x16x32_bf16 v[16:19], v[128:131], v[188:191], v[16:19]
	v_mfma_f32_16x16x32_bf16 v[8:11], v[136:139], v[188:191], v[8:11]
	v_mfma_f32_16x16x32_bf16 v[60:63], v[132:135], v[168:171], v[60:63]
	v_mfma_f32_16x16x32_bf16 v[56:59], v[140:143], v[168:171], v[56:59]
	v_mfma_f32_16x16x32_bf16 v[48:51], v[132:135], v[176:179], v[48:51]
	v_mfma_f32_16x16x32_bf16 v[40:43], v[140:143], v[176:179], v[40:43]
	v_mfma_f32_16x16x32_bf16 v[32:35], v[132:135], v[184:187], v[32:35]
	v_mfma_f32_16x16x32_bf16 v[24:27], v[140:143], v[184:187], v[24:27]
	v_mfma_f32_16x16x32_bf16 v[16:19], v[132:135], v[192:195], v[16:19]
	v_mfma_f32_16x16x32_bf16 v[8:11], v[140:143], v[192:195], v[8:11]
	s_barrier
	s_add_u32 s44, s44, 0x80080
	s_addc_u32 s45, s45, 0
	s_add_i32 s46, s46, s54
	v_lshl_add_u64 v[128:129], s[44:45], 0, v[146:147]
	s_mov_b32 m0, s46
	s_nop 0
	global_load_lds_dwordx4 v[128:129], off
	v_lshl_add_u64 v[128:129], s[44:45], 0, v[148:149]
	s_add_i32 m0, s46, 0x2000
	s_nop 0
	global_load_lds_dwordx4 v[128:129], off
	s_waitcnt vmcnt(6)
	s_barrier
	v_mfma_f32_16x16x32_bf16 v[52:55], v[196:199], v[156:159], v[52:55]
	v_mfma_f32_16x16x32_bf16 v[44:47], v[204:207], v[156:159], v[44:47]
	v_mfma_f32_16x16x32_bf16 v[36:39], v[196:199], v[172:175], v[36:39]
	v_mfma_f32_16x16x32_bf16 v[28:31], v[204:207], v[172:175], v[28:31]
	v_mfma_f32_16x16x32_bf16 v[20:23], v[196:199], v[180:183], v[20:23]
	v_mfma_f32_16x16x32_bf16 v[12:15], v[204:207], v[180:183], v[12:15]
	v_mfma_f32_16x16x32_bf16 v[4:7], v[196:199], v[188:191], v[4:7]
	v_mfma_f32_16x16x32_bf16 v[0:3], v[204:207], v[188:191], v[0:3]
	v_mfma_f32_16x16x32_bf16 v[52:55], v[200:203], v[168:171], v[52:55]
	v_mfma_f32_16x16x32_bf16 v[44:47], v[208:211], v[168:171], v[44:47]
	v_mfma_f32_16x16x32_bf16 v[36:39], v[200:203], v[176:179], v[36:39]
	v_mfma_f32_16x16x32_bf16 v[28:31], v[208:211], v[176:179], v[28:31]
	v_mfma_f32_16x16x32_bf16 v[20:23], v[200:203], v[184:187], v[20:23]
	v_mfma_f32_16x16x32_bf16 v[12:15], v[208:211], v[184:187], v[12:15]
	v_mfma_f32_16x16x32_bf16 v[4:7], v[200:203], v[192:195], v[4:7]
	v_mfma_f32_16x16x32_bf16 v[0:3], v[208:211], v[192:195], v[0:3]
	s_add_i32 s70, s70, 2
	s_add_u32 s42, s42, 0x100
	s_addc_u32 s43, s43, 0
	s_add_u32 s29, s29, 0x100
	s_addc_u32 s69, s69, 0
	s_cmp_gt_u32 s70, 29
	s_barrier
	s_cbranch_scc0 .LBB0_1074
.LBB0_1074:
	ds_read_b128 v[128:131], v165
	ds_read_b128 v[132:135], v165 offset:1024
	ds_read_b128 v[136:139], v165 offset:2048
	ds_read_b128 v[140:143], v165 offset:3072
	s_add_u32 s44, s42, 0xfff80080
	s_addc_u32 s45, s43, -1
	s_cmp_eq_u32 s70, 28
	s_cselect_b32 s47, s31, s45
	s_cselect_b32 s46, s68, s44
	s_cselect_b32 s45, s19, s69
	s_cselect_b32 s44, s28, s29
	v_lshl_add_u64 v[160:161], s[42:43], 0, v[150:151]
	s_add_i32 m0, s41, 0xc000
	ds_read_b128 v[156:159], v166
	ds_read_b128 v[168:171], v166 offset:1024
	ds_read_b128 v[172:175], v166 offset:2048
	ds_read_b128 v[176:179], v166 offset:3072
	ds_read_b128 v[180:183], v166 offset:4096
	ds_read_b128 v[184:187], v166 offset:5120
	ds_read_b128 v[188:191], v166 offset:6144
	ds_read_b128 v[192:195], v166 offset:7168
	global_load_lds_dwordx4 v[160:161], off
	v_lshl_add_u64 v[160:161], s[42:43], 0, v[152:153]
	s_add_i32 m0, s41, 0xe000
	s_nop 0
	global_load_lds_dwordx4 v[160:161], off
	s_waitcnt lgkmcnt(8)
	s_barrier
	s_waitcnt lgkmcnt(0)
	s_waitcnt lgkmcnt(0)
	v_mfma_f32_16x16x32_bf16 v[124:127], v[128:131], v[156:159], v[124:127]
	v_mfma_f32_16x16x32_bf16 v[120:123], v[136:139], v[156:159], v[120:123]
	v_mfma_f32_16x16x32_bf16 v[112:115], v[128:131], v[172:175], v[112:115]
	v_mfma_f32_16x16x32_bf16 v[104:107], v[136:139], v[172:175], v[104:107]
	v_mfma_f32_16x16x32_bf16 v[96:99], v[128:131], v[180:183], v[96:99]
	v_mfma_f32_16x16x32_bf16 v[88:91], v[136:139], v[180:183], v[88:91]
	v_mfma_f32_16x16x32_bf16 v[80:83], v[128:131], v[188:191], v[80:83]
	v_mfma_f32_16x16x32_bf16 v[72:75], v[136:139], v[188:191], v[72:75]
	v_mfma_f32_16x16x32_bf16 v[124:127], v[132:135], v[168:171], v[124:127]
	v_mfma_f32_16x16x32_bf16 v[120:123], v[140:143], v[168:171], v[120:123]
	v_mfma_f32_16x16x32_bf16 v[112:115], v[132:135], v[176:179], v[112:115]
	v_mfma_f32_16x16x32_bf16 v[104:107], v[140:143], v[176:179], v[104:107]
	v_mfma_f32_16x16x32_bf16 v[96:99], v[132:135], v[184:187], v[96:99]
	v_mfma_f32_16x16x32_bf16 v[88:91], v[140:143], v[184:187], v[88:91]
	v_mfma_f32_16x16x32_bf16 v[80:83], v[132:135], v[192:195], v[80:83]
	v_mfma_f32_16x16x32_bf16 v[72:75], v[140:143], v[192:195], v[72:75]
	s_barrier
	s_add_i32 s71, s65, s54
	v_lshl_add_u64 v[160:161], s[44:45], 0, v[146:147]
	s_mov_b32 m0, s71
	ds_read_b128 v[196:199], v167
	ds_read_b128 v[200:203], v167 offset:1024
	ds_read_b128 v[204:207], v167 offset:2048
	ds_read_b128 v[208:211], v167 offset:3072
	global_load_lds_dwordx4 v[160:161], off
	v_lshl_add_u64 v[212:213], s[44:45], 0, v[148:149]
	s_add_i32 m0, s71, 0x2000
	s_nop 0
	global_load_lds_dwordx4 v[212:213], off
	s_barrier
	s_waitcnt lgkmcnt(0)
	s_waitcnt lgkmcnt(0)
	v_mfma_f32_16x16x32_bf16 v[116:119], v[196:199], v[156:159], v[116:119]
	v_mfma_f32_16x16x32_bf16 v[108:111], v[204:207], v[156:159], v[108:111]
	v_mfma_f32_16x16x32_bf16 v[100:103], v[196:199], v[172:175], v[100:103]
	v_mfma_f32_16x16x32_bf16 v[92:95], v[204:207], v[172:175], v[92:95]
	v_mfma_f32_16x16x32_bf16 v[84:87], v[196:199], v[180:183], v[84:87]
	v_mfma_f32_16x16x32_bf16 v[76:79], v[204:207], v[180:183], v[76:79]
	v_mfma_f32_16x16x32_bf16 v[68:71], v[196:199], v[188:191], v[68:71]
	v_mfma_f32_16x16x32_bf16 v[64:67], v[204:207], v[188:191], v[64:67]
	v_mfma_f32_16x16x32_bf16 v[116:119], v[200:203], v[168:171], v[116:119]
	v_mfma_f32_16x16x32_bf16 v[108:111], v[208:211], v[168:171], v[108:111]
	v_mfma_f32_16x16x32_bf16 v[100:103], v[200:203], v[176:179], v[100:103]
	v_mfma_f32_16x16x32_bf16 v[92:95], v[208:211], v[176:179], v[92:95]
	v_mfma_f32_16x16x32_bf16 v[84:87], v[200:203], v[184:187], v[84:87]
	v_mfma_f32_16x16x32_bf16 v[76:79], v[208:211], v[184:187], v[76:79]
	v_mfma_f32_16x16x32_bf16 v[68:71], v[200:203], v[192:195], v[68:71]
	v_mfma_f32_16x16x32_bf16 v[64:67], v[208:211], v[192:195], v[64:67]
	s_mov_b32 m0, s41
	v_lshl_add_u64 v[214:215], s[46:47], 0, v[146:147]
	s_barrier
	ds_read_b128 v[156:159], v166 offset:16384
	ds_read_b128 v[168:171], v166 offset:17408
	ds_read_b128 v[172:175], v166 offset:18432
	ds_read_b128 v[176:179], v166 offset:19456
	ds_read_b128 v[180:183], v166 offset:20480
	ds_read_b128 v[184:187], v166 offset:21504
	ds_read_b128 v[188:191], v166 offset:22528
	ds_read_b128 v[192:195], v166 offset:23552
	global_load_lds_dwordx4 v[214:215], off
	v_lshl_add_u64 v[216:217], s[46:47], 0, v[148:149]
	s_mov_b32 m0, s55
	s_nop 0
	global_load_lds_dwordx4 v[216:217], off
	s_barrier
	s_waitcnt lgkmcnt(0)
	s_waitcnt lgkmcnt(0)
	v_mfma_f32_16x16x32_bf16 v[60:63], v[128:131], v[156:159], v[60:63]
	v_mfma_f32_16x16x32_bf16 v[56:59], v[136:139], v[156:159], v[56:59]
	v_mfma_f32_16x16x32_bf16 v[48:51], v[128:131], v[172:175], v[48:51]
	v_mfma_f32_16x16x32_bf16 v[40:43], v[136:139], v[172:175], v[40:43]
	v_mfma_f32_16x16x32_bf16 v[32:35], v[128:131], v[180:183], v[32:35]
	v_mfma_f32_16x16x32_bf16 v[24:27], v[136:139], v[180:183], v[24:27]
	v_mfma_f32_16x16x32_bf16 v[16:19], v[128:131], v[188:191], v[16:19]
	v_mfma_f32_16x16x32_bf16 v[8:11], v[136:139], v[188:191], v[8:11]
	v_mfma_f32_16x16x32_bf16 v[60:63], v[132:135], v[168:171], v[60:63]
	v_mfma_f32_16x16x32_bf16 v[56:59], v[140:143], v[168:171], v[56:59]
	v_mfma_f32_16x16x32_bf16 v[48:51], v[132:135], v[176:179], v[48:51]
	v_mfma_f32_16x16x32_bf16 v[40:43], v[140:143], v[176:179], v[40:43]
	v_mfma_f32_16x16x32_bf16 v[32:35], v[132:135], v[184:187], v[32:35]
	v_mfma_f32_16x16x32_bf16 v[24:27], v[140:143], v[184:187], v[24:27]
	v_mfma_f32_16x16x32_bf16 v[16:19], v[132:135], v[192:195], v[16:19]
	v_mfma_f32_16x16x32_bf16 v[8:11], v[140:143], v[192:195], v[8:11]
	s_barrier
	s_add_u32 s72, s44, 0x80000
	s_addc_u32 s73, s45, 0
	s_add_i32 s71, s66, s54
	v_lshl_add_u64 v[128:129], s[72:73], 0, v[146:147]
	s_mov_b32 m0, s71
	s_nop 0
	global_load_lds_dwordx4 v[128:129], off
	v_lshl_add_u64 v[128:129], s[72:73], 0, v[148:149]
	s_add_i32 m0, s71, 0x2000
	s_nop 0
	global_load_lds_dwordx4 v[128:129], off
	s_waitcnt vmcnt(6)
	s_barrier
	v_mfma_f32_16x16x32_bf16 v[52:55], v[196:199], v[156:159], v[52:55]
	v_mfma_f32_16x16x32_bf16 v[44:47], v[204:207], v[156:159], v[44:47]
	v_mfma_f32_16x16x32_bf16 v[36:39], v[196:199], v[172:175], v[36:39]
	v_mfma_f32_16x16x32_bf16 v[28:31], v[204:207], v[172:175], v[28:31]
	v_mfma_f32_16x16x32_bf16 v[20:23], v[196:199], v[180:183], v[20:23]
	v_mfma_f32_16x16x32_bf16 v[12:15], v[204:207], v[180:183], v[12:15]
	v_mfma_f32_16x16x32_bf16 v[4:7], v[196:199], v[188:191], v[4:7]
	v_mfma_f32_16x16x32_bf16 v[0:3], v[204:207], v[188:191], v[0:3]
	v_mfma_f32_16x16x32_bf16 v[52:55], v[200:203], v[168:171], v[52:55]
	v_mfma_f32_16x16x32_bf16 v[44:47], v[208:211], v[168:171], v[44:47]
	v_mfma_f32_16x16x32_bf16 v[36:39], v[200:203], v[176:179], v[36:39]
	v_mfma_f32_16x16x32_bf16 v[28:31], v[208:211], v[176:179], v[28:31]
	v_mfma_f32_16x16x32_bf16 v[20:23], v[200:203], v[184:187], v[20:23]
	v_mfma_f32_16x16x32_bf16 v[12:15], v[208:211], v[184:187], v[12:15]
	v_mfma_f32_16x16x32_bf16 v[4:7], v[200:203], v[192:195], v[4:7]
	v_mfma_f32_16x16x32_bf16 v[0:3], v[208:211], v[192:195], v[0:3]
	s_add_i32 s71, 0, 0x18000
	v_add_u32_e32 v140, s71, v163
	s_barrier
	ds_read_b128 v[128:131], v140
	ds_read_b128 v[132:135], v140 offset:1024
	ds_read_b128 v[136:139], v140 offset:2048
	ds_read_b128 v[140:143], v140 offset:3072
	s_add_u32 s46, s46, 0x80000
	s_addc_u32 s47, s47, 0
	s_mov_b32 m0, s56
	v_lshl_add_u64 v[196:197], s[46:47], 0, v[146:147]
	ds_read_b128 v[156:159], v166 offset:32768
	ds_read_b128 v[168:171], v166 offset:33792
	ds_read_b128 v[172:175], v166 offset:34816
	ds_read_b128 v[176:179], v166 offset:35840
	ds_read_b128 v[180:183], v166 offset:36864
	ds_read_b128 v[184:187], v166 offset:37888
	ds_read_b128 v[188:191], v166 offset:38912
	ds_read_b128 v[192:195], v166 offset:39936
	global_load_lds_dwordx4 v[196:197], off
	v_lshl_add_u64 v[196:197], s[46:47], 0, v[148:149]
	s_mov_b32 m0, s57
	s_nop 0
	global_load_lds_dwordx4 v[196:197], off
	s_waitcnt lgkmcnt(8)
	s_barrier
	s_waitcnt lgkmcnt(0)
	s_waitcnt lgkmcnt(0)
	v_mfma_f32_16x16x32_bf16 v[124:127], v[128:131], v[156:159], v[124:127]
	v_mfma_f32_16x16x32_bf16 v[120:123], v[136:139], v[156:159], v[120:123]
	v_mfma_f32_16x16x32_bf16 v[112:115], v[128:131], v[172:175], v[112:115]
	v_mfma_f32_16x16x32_bf16 v[104:107], v[136:139], v[172:175], v[104:107]
	v_mfma_f32_16x16x32_bf16 v[96:99], v[128:131], v[180:183], v[96:99]
	v_mfma_f32_16x16x32_bf16 v[88:91], v[136:139], v[180:183], v[88:91]
	v_mfma_f32_16x16x32_bf16 v[80:83], v[128:131], v[188:191], v[80:83]
	v_mfma_f32_16x16x32_bf16 v[72:75], v[136:139], v[188:191], v[72:75]
	v_mfma_f32_16x16x32_bf16 v[124:127], v[132:135], v[168:171], v[124:127]
	v_mfma_f32_16x16x32_bf16 v[120:123], v[140:143], v[168:171], v[120:123]
	v_mfma_f32_16x16x32_bf16 v[112:115], v[132:135], v[176:179], v[112:115]
	v_mfma_f32_16x16x32_bf16 v[104:107], v[140:143], v[176:179], v[104:107]
	v_mfma_f32_16x16x32_bf16 v[96:99], v[132:135], v[184:187], v[96:99]
	v_mfma_f32_16x16x32_bf16 v[88:91], v[140:143], v[184:187], v[88:91]
	v_mfma_f32_16x16x32_bf16 v[80:83], v[132:135], v[192:195], v[80:83]
	v_mfma_f32_16x16x32_bf16 v[72:75], v[140:143], v[192:195], v[72:75]
	s_barrier
	s_add_i32 s46, 0, 0x1c000
	s_add_i32 s47, s71, s54
	v_add_u32_e32 v208, s46, v163
	v_lshl_add_u64 v[160:161], v[160:161], 0, s[8:9]
	s_mov_b32 m0, s47
	ds_read_b128 v[196:199], v208
	ds_read_b128 v[200:203], v208 offset:1024
	ds_read_b128 v[204:207], v208 offset:2048
	ds_read_b128 v[208:211], v208 offset:3072
	global_load_lds_dwordx4 v[160:161], off
	v_lshl_add_u64 v[160:161], v[212:213], 0, s[8:9]
	s_add_i32 m0, s47, 0x2000
	s_nop 0
	global_load_lds_dwordx4 v[160:161], off
	s_barrier
	s_waitcnt lgkmcnt(0)
	s_waitcnt lgkmcnt(0)
	v_mfma_f32_16x16x32_bf16 v[116:119], v[196:199], v[156:159], v[116:119]
	v_mfma_f32_16x16x32_bf16 v[108:111], v[204:207], v[156:159], v[108:111]
	v_mfma_f32_16x16x32_bf16 v[100:103], v[196:199], v[172:175], v[100:103]
	v_mfma_f32_16x16x32_bf16 v[92:95], v[204:207], v[172:175], v[92:95]
	v_mfma_f32_16x16x32_bf16 v[84:87], v[196:199], v[180:183], v[84:87]
	v_mfma_f32_16x16x32_bf16 v[76:79], v[204:207], v[180:183], v[76:79]
	v_mfma_f32_16x16x32_bf16 v[68:71], v[196:199], v[188:191], v[68:71]
	v_mfma_f32_16x16x32_bf16 v[64:67], v[204:207], v[188:191], v[64:67]
	v_mfma_f32_16x16x32_bf16 v[116:119], v[200:203], v[168:171], v[116:119]
	v_mfma_f32_16x16x32_bf16 v[108:111], v[208:211], v[168:171], v[108:111]
	v_mfma_f32_16x16x32_bf16 v[100:103], v[200:203], v[176:179], v[100:103]
	v_mfma_f32_16x16x32_bf16 v[92:95], v[208:211], v[176:179], v[92:95]
	v_mfma_f32_16x16x32_bf16 v[84:87], v[200:203], v[184:187], v[84:87]
	v_mfma_f32_16x16x32_bf16 v[76:79], v[208:211], v[184:187], v[76:79]
	v_mfma_f32_16x16x32_bf16 v[68:71], v[200:203], v[192:195], v[68:71]
	v_mfma_f32_16x16x32_bf16 v[64:67], v[208:211], v[192:195], v[64:67]
	s_mov_b32 m0, s61
	v_lshl_add_u64 v[160:161], v[214:215], 0, s[8:9]
	s_barrier
	ds_read_b128 v[156:159], v166 offset:49152
	ds_read_b128 v[168:171], v166 offset:50176
	ds_read_b128 v[172:175], v166 offset:51200
	ds_read_b128 v[176:179], v166 offset:52224
	ds_read_b128 v[180:183], v166 offset:53248
	ds_read_b128 v[184:187], v166 offset:54272
	ds_read_b128 v[188:191], v166 offset:55296
	ds_read_b128 v[192:195], v166 offset:56320
	global_load_lds_dwordx4 v[160:161], off
	v_lshl_add_u64 v[160:161], v[216:217], 0, s[8:9]
	s_mov_b32 m0, s62
	s_nop 0
	global_load_lds_dwordx4 v[160:161], off
	s_barrier
	s_waitcnt lgkmcnt(0)
	s_waitcnt lgkmcnt(0)
	v_mfma_f32_16x16x32_bf16 v[60:63], v[128:131], v[156:159], v[60:63]
	v_mfma_f32_16x16x32_bf16 v[56:59], v[136:139], v[156:159], v[56:59]
	v_mfma_f32_16x16x32_bf16 v[48:51], v[128:131], v[172:175], v[48:51]
	v_mfma_f32_16x16x32_bf16 v[40:43], v[136:139], v[172:175], v[40:43]
	v_mfma_f32_16x16x32_bf16 v[32:35], v[128:131], v[180:183], v[32:35]
	v_mfma_f32_16x16x32_bf16 v[24:27], v[136:139], v[180:183], v[24:27]
	v_mfma_f32_16x16x32_bf16 v[16:19], v[128:131], v[188:191], v[16:19]
	v_mfma_f32_16x16x32_bf16 v[8:11], v[136:139], v[188:191], v[8:11]
	v_mfma_f32_16x16x32_bf16 v[60:63], v[132:135], v[168:171], v[60:63]
	v_mfma_f32_16x16x32_bf16 v[56:59], v[140:143], v[168:171], v[56:59]
	v_mfma_f32_16x16x32_bf16 v[48:51], v[132:135], v[176:179], v[48:51]
	v_mfma_f32_16x16x32_bf16 v[40:43], v[140:143], v[176:179], v[40:43]
	v_mfma_f32_16x16x32_bf16 v[32:35], v[132:135], v[184:187], v[32:35]
	v_mfma_f32_16x16x32_bf16 v[24:27], v[140:143], v[184:187], v[24:27]
	v_mfma_f32_16x16x32_bf16 v[16:19], v[132:135], v[192:195], v[16:19]
	v_mfma_f32_16x16x32_bf16 v[8:11], v[140:143], v[192:195], v[8:11]
	s_barrier
	s_add_u32 s44, s44, 0x80080
	s_addc_u32 s45, s45, 0
	s_add_i32 s46, s46, s54
	v_lshl_add_u64 v[128:129], s[44:45], 0, v[146:147]
	s_mov_b32 m0, s46
	s_nop 0
	global_load_lds_dwordx4 v[128:129], off
	v_lshl_add_u64 v[128:129], s[44:45], 0, v[148:149]
	s_add_i32 m0, s46, 0x2000
	s_nop 0
	global_load_lds_dwordx4 v[128:129], off
	s_waitcnt vmcnt(6)
	s_barrier
	v_mfma_f32_16x16x32_bf16 v[52:55], v[196:199], v[156:159], v[52:55]
	v_mfma_f32_16x16x32_bf16 v[44:47], v[204:207], v[156:159], v[44:47]
	v_mfma_f32_16x16x32_bf16 v[36:39], v[196:199], v[172:175], v[36:39]
	v_mfma_f32_16x16x32_bf16 v[28:31], v[204:207], v[172:175], v[28:31]
	v_mfma_f32_16x16x32_bf16 v[20:23], v[196:199], v[180:183], v[20:23]
	v_mfma_f32_16x16x32_bf16 v[12:15], v[204:207], v[180:183], v[12:15]
	v_mfma_f32_16x16x32_bf16 v[4:7], v[196:199], v[188:191], v[4:7]
	v_mfma_f32_16x16x32_bf16 v[0:3], v[204:207], v[188:191], v[0:3]
	v_mfma_f32_16x16x32_bf16 v[52:55], v[200:203], v[168:171], v[52:55]
	v_mfma_f32_16x16x32_bf16 v[44:47], v[208:211], v[168:171], v[44:47]
	v_mfma_f32_16x16x32_bf16 v[36:39], v[200:203], v[176:179], v[36:39]
	v_mfma_f32_16x16x32_bf16 v[28:31], v[208:211], v[176:179], v[28:31]
	v_mfma_f32_16x16x32_bf16 v[20:23], v[200:203], v[184:187], v[20:23]
	v_mfma_f32_16x16x32_bf16 v[12:15], v[208:211], v[184:187], v[12:15]
	v_mfma_f32_16x16x32_bf16 v[4:7], v[200:203], v[192:195], v[4:7]
	v_mfma_f32_16x16x32_bf16 v[0:3], v[208:211], v[192:195], v[0:3]
	s_add_i32 s70, s70, 2
	s_add_u32 s42, s42, 0x100
	s_addc_u32 s43, s43, 0
	s_add_u32 s29, s29, 0x100
	s_addc_u32 s69, s69, 0
	s_cmp_gt_u32 s70, 29
	s_barrier
	s_cbranch_scc0 .LBB0_1074
	s_ashr_i32 s19, s40, 3
	v_lshl_add_u32 v160, s40, 8, v162
	v_lshl_or_b32 v158, s67, 8, v164
	s_mul_hi_i32 s29, s19, 0xc000
	s_mul_i32 s19, s19, 0xc000
	v_ashrrev_i32_e32 v161, 31, v160
	s_add_u32 s28, s59, s19
	v_ashrrev_i32_e32 v159, 31, v158
	v_lshlrev_b64 v[130:131], 11, v[160:161]
	s_addc_u32 s29, s60, s29
	v_lshl_add_u64 v[156:157], v[130:131], 0, v[158:159]
	v_lshl_add_u64 v[128:129], v[158:159], 2, s[28:29]
	v_lshl_add_u64 v[172:173], v[156:157], 2, s[52:53]
	global_load_dwordx4 v[136:139], v[128:129], off
	v_lshlrev_b64 v[174:175], 1, v[156:157]
	v_lshl_add_u64 v[176:177], s[6:7], 0, v[174:175]
	global_load_dwordx4 v[140:143], v[128:129], off offset:64
	global_load_dwordx4 v[132:135], v[128:129], off offset:512
	s_nop 0
	global_load_dwordx4 v[128:131], v[128:129], off offset:576
	s_mov_b32 s67, s18
	s_mov_b32 s40, s30
	s_mov_b64 s[44:45], s[38:39]
	s_mov_b64 s[42:43], s[36:37]
	s_mov_b32 s29, 0
	global_load_dwordx4 v[180:183], v[172:173], off
	global_load_dwordx4 v[184:187], v[172:173], off offset:64
	global_load_dwordx4 v[188:191], v[172:173], off offset:512
	global_load_dwordx4 v[192:195], v[172:173], off offset:576
	s_mov_b32 s28, 0x20000
	v_lshl_add_u64 v[168:169], v[172:173], 0, s[28:29]
	global_load_dwordx4 v[196:199], v[168:169], off
	global_load_dwordx4 v[200:203], v[168:169], off offset:64
	global_load_dwordx4 v[204:207], v[168:169], off offset:512
	global_load_dwordx4 v[208:211], v[168:169], off offset:576
	s_mov_b32 s28, 0x40000
	v_lshl_add_u64 v[168:169], v[172:173], 0, s[28:29]
	global_load_dwordx4 v[212:215], v[168:169], off
	global_load_dwordx4 v[216:219], v[168:169], off offset:64
	global_load_dwordx4 v[220:223], v[168:169], off offset:512
	global_load_dwordx4 v[224:227], v[168:169], off offset:576
	s_mov_b32 s28, 0x60000
	v_lshl_add_u64 v[168:169], v[172:173], 0, s[28:29]
	global_load_dwordx4 v[228:231], v[168:169], off
	global_load_dwordx4 v[232:235], v[168:169], off offset:64
	global_load_dwordx4 v[236:239], v[168:169], off offset:512
	global_load_dwordx4 v[240:243], v[168:169], off offset:576
	s_mov_b32 s28, 0x100000
	v_lshl_add_u64 v[168:169], v[172:173], 0, s[28:29]
	s_waitcnt vmcnt(15)
	v_pk_fma_f32 v[124:125], v[124:125], v[136:137], v[180:181]
	v_pk_fma_f32 v[126:127], v[126:127], v[138:139], v[182:183]
	v_cvt_pk_bf16_f32 v124, v124, v125
	v_cvt_pk_bf16_f32 v125, v126, v127
	global_store_dwordx2 v[176:177], v[124:125], off
	global_load_dwordx4 v[180:183], v[168:169], off
	s_waitcnt vmcnt(16)
	v_pk_fma_f32 v[120:121], v[120:121], v[140:141], v[184:185]
	v_pk_fma_f32 v[122:123], v[122:123], v[142:143], v[186:187]
	v_cvt_pk_bf16_f32 v120, v120, v121
	v_cvt_pk_bf16_f32 v121, v122, v123
	global_store_dwordx2 v[176:177], v[120:121], off offset:32
	global_load_dwordx4 v[184:187], v[168:169], off offset:64
	s_waitcnt vmcnt(17)
	v_pk_fma_f32 v[116:117], v[116:117], v[132:133], v[188:189]
	v_pk_fma_f32 v[118:119], v[118:119], v[134:135], v[190:191]
	v_cvt_pk_bf16_f32 v116, v116, v117
	v_cvt_pk_bf16_f32 v117, v118, v119
	global_store_dwordx2 v[176:177], v[116:117], off offset:256
	global_load_dwordx4 v[188:191], v[168:169], off offset:512
	s_waitcnt vmcnt(18)
	v_pk_fma_f32 v[108:109], v[108:109], v[128:129], v[192:193]
	v_pk_fma_f32 v[110:111], v[110:111], v[130:131], v[194:195]
	v_cvt_pk_bf16_f32 v108, v108, v109
	v_cvt_pk_bf16_f32 v109, v110, v111
	global_store_dwordx2 v[176:177], v[108:109], off offset:288
	global_load_dwordx4 v[192:195], v[168:169], off offset:576
	s_mov_b32 s28, 0x10000
	v_lshl_add_u64 v[170:171], v[176:177], 0, s[28:29]
	s_mov_b32 s28, 0x120000
	v_lshl_add_u64 v[168:169], v[172:173], 0, s[28:29]
	s_waitcnt vmcnt(19)
	v_pk_fma_f32 v[112:113], v[112:113], v[136:137], v[196:197]
	v_pk_fma_f32 v[114:115], v[114:115], v[138:139], v[198:199]
	v_cvt_pk_bf16_f32 v112, v112, v113
	v_cvt_pk_bf16_f32 v113, v114, v115
	global_store_dwordx2 v[170:171], v[112:113], off
	global_load_dwordx4 v[196:199], v[168:169], off
	s_waitcnt vmcnt(20)
	v_pk_fma_f32 v[104:105], v[104:105], v[140:141], v[200:201]
	v_pk_fma_f32 v[106:107], v[106:107], v[142:143], v[202:203]
	v_cvt_pk_bf16_f32 v104, v104, v105
	v_cvt_pk_bf16_f32 v105, v106, v107
	global_store_dwordx2 v[170:171], v[104:105], off offset:32
	global_load_dwordx4 v[200:203], v[168:169], off offset:64
	s_waitcnt vmcnt(21)
	v_pk_fma_f32 v[100:101], v[100:101], v[132:133], v[204:205]
	v_pk_fma_f32 v[102:103], v[102:103], v[134:135], v[206:207]
	v_cvt_pk_bf16_f32 v100, v100, v101
	v_cvt_pk_bf16_f32 v101, v102, v103
	global_store_dwordx2 v[170:171], v[100:101], off offset:256
	global_load_dwordx4 v[204:207], v[168:169], off offset:512
	s_waitcnt vmcnt(22)
	v_pk_fma_f32 v[92:93], v[92:93], v[128:129], v[208:209]
	v_pk_fma_f32 v[94:95], v[94:95], v[130:131], v[210:211]
	v_cvt_pk_bf16_f32 v92, v92, v93
	v_cvt_pk_bf16_f32 v93, v94, v95
	global_store_dwordx2 v[170:171], v[92:93], off offset:288
	global_load_dwordx4 v[208:211], v[168:169], off offset:576
	s_mov_b32 s28, 0x20000
	v_lshl_add_u64 v[170:171], v[176:177], 0, s[28:29]
	s_mov_b32 s28, 0x140000
	v_lshl_add_u64 v[168:169], v[172:173], 0, s[28:29]
	s_waitcnt vmcnt(23)
	v_pk_fma_f32 v[96:97], v[96:97], v[136:137], v[212:213]
	v_pk_fma_f32 v[98:99], v[98:99], v[138:139], v[214:215]
	v_cvt_pk_bf16_f32 v96, v96, v97
	v_cvt_pk_bf16_f32 v97, v98, v99
	global_store_dwordx2 v[170:171], v[96:97], off
	global_load_dwordx4 v[212:215], v[168:169], off
	s_waitcnt vmcnt(24)
	v_pk_fma_f32 v[88:89], v[88:89], v[140:141], v[216:217]
	v_pk_fma_f32 v[90:91], v[90:91], v[142:143], v[218:219]
	v_cvt_pk_bf16_f32 v88, v88, v89
	v_cvt_pk_bf16_f32 v89, v90, v91
	global_store_dwordx2 v[170:171], v[88:89], off offset:32
	global_load_dwordx4 v[216:219], v[168:169], off offset:64
	s_waitcnt vmcnt(25)
	v_pk_fma_f32 v[84:85], v[84:85], v[132:133], v[220:221]
	v_pk_fma_f32 v[86:87], v[86:87], v[134:135], v[222:223]
	v_cvt_pk_bf16_f32 v84, v84, v85
	v_cvt_pk_bf16_f32 v85, v86, v87
	global_store_dwordx2 v[170:171], v[84:85], off offset:256
	global_load_dwordx4 v[220:223], v[168:169], off offset:512
	s_waitcnt vmcnt(26)
	v_pk_fma_f32 v[76:77], v[76:77], v[128:129], v[224:225]
	v_pk_fma_f32 v[78:79], v[78:79], v[130:131], v[226:227]
	v_cvt_pk_bf16_f32 v76, v76, v77
	v_cvt_pk_bf16_f32 v77, v78, v79
	global_store_dwordx2 v[170:171], v[76:77], off offset:288
	global_load_dwordx4 v[224:227], v[168:169], off offset:576
	s_mov_b32 s28, 0x30000
	v_lshl_add_u64 v[170:171], v[176:177], 0, s[28:29]
	s_mov_b32 s28, 0x160000
	v_lshl_add_u64 v[168:169], v[172:173], 0, s[28:29]
	s_waitcnt vmcnt(27)
	v_pk_fma_f32 v[80:81], v[80:81], v[136:137], v[228:229]
	v_pk_fma_f32 v[82:83], v[82:83], v[138:139], v[230:231]
	v_cvt_pk_bf16_f32 v80, v80, v81
	v_cvt_pk_bf16_f32 v81, v82, v83
	global_store_dwordx2 v[170:171], v[80:81], off
	global_load_dwordx4 v[228:231], v[168:169], off
	s_waitcnt vmcnt(28)
	v_pk_fma_f32 v[72:73], v[72:73], v[140:141], v[232:233]
	v_pk_fma_f32 v[74:75], v[74:75], v[142:143], v[234:235]
	v_cvt_pk_bf16_f32 v72, v72, v73
	v_cvt_pk_bf16_f32 v73, v74, v75
	global_store_dwordx2 v[170:171], v[72:73], off offset:32
	global_load_dwordx4 v[232:235], v[168:169], off offset:64
	s_waitcnt vmcnt(29)
	v_pk_fma_f32 v[68:69], v[68:69], v[132:133], v[236:237]
	v_pk_fma_f32 v[70:71], v[70:71], v[134:135], v[238:239]
	v_cvt_pk_bf16_f32 v68, v68, v69
	v_cvt_pk_bf16_f32 v69, v70, v71
	global_store_dwordx2 v[170:171], v[68:69], off offset:256
	global_load_dwordx4 v[236:239], v[168:169], off offset:512
	s_waitcnt vmcnt(30)
	v_pk_fma_f32 v[64:65], v[64:65], v[128:129], v[240:241]
	v_pk_fma_f32 v[66:67], v[66:67], v[130:131], v[242:243]
	v_cvt_pk_bf16_f32 v64, v64, v65
	v_cvt_pk_bf16_f32 v65, v66, v67
	global_store_dwordx2 v[170:171], v[64:65], off offset:288
	global_load_dwordx4 v[240:243], v[168:169], off offset:576
	s_mov_b32 s28, 0x80000
	v_lshl_add_u64 v[170:171], v[176:177], 0, s[28:29]
	s_waitcnt vmcnt(30)
	v_pk_fma_f32 v[60:61], v[60:61], v[136:137], v[180:181]
	v_pk_fma_f32 v[62:63], v[62:63], v[138:139], v[182:183]
	v_cvt_pk_bf16_f32 v60, v60, v61
	v_cvt_pk_bf16_f32 v61, v62, v63
	global_store_dwordx2 v[170:171], v[60:61], off
	s_waitcnt vmcnt(29)
	v_pk_fma_f32 v[56:57], v[56:57], v[140:141], v[184:185]
	v_pk_fma_f32 v[58:59], v[58:59], v[142:143], v[186:187]
	v_cvt_pk_bf16_f32 v56, v56, v57
	v_cvt_pk_bf16_f32 v57, v58, v59
	global_store_dwordx2 v[170:171], v[56:57], off offset:32
	s_waitcnt vmcnt(28)
	v_pk_fma_f32 v[52:53], v[52:53], v[132:133], v[188:189]
	v_pk_fma_f32 v[54:55], v[54:55], v[134:135], v[190:191]
	v_cvt_pk_bf16_f32 v52, v52, v53
	v_cvt_pk_bf16_f32 v53, v54, v55
	global_store_dwordx2 v[170:171], v[52:53], off offset:256
	s_waitcnt vmcnt(27)
	v_pk_fma_f32 v[44:45], v[44:45], v[128:129], v[192:193]
	v_pk_fma_f32 v[46:47], v[46:47], v[130:131], v[194:195]
	v_cvt_pk_bf16_f32 v44, v44, v45
	v_cvt_pk_bf16_f32 v45, v46, v47
	global_store_dwordx2 v[170:171], v[44:45], off offset:288
	s_mov_b32 s28, 0x90000
	v_lshl_add_u64 v[170:171], v[176:177], 0, s[28:29]
	s_waitcnt vmcnt(26)
	v_pk_fma_f32 v[48:49], v[48:49], v[136:137], v[196:197]
	v_pk_fma_f32 v[50:51], v[50:51], v[138:139], v[198:199]
	v_cvt_pk_bf16_f32 v48, v48, v49
	v_cvt_pk_bf16_f32 v49, v50, v51
	global_store_dwordx2 v[170:171], v[48:49], off
	s_waitcnt vmcnt(25)
	v_pk_fma_f32 v[40:41], v[40:41], v[140:141], v[200:201]
	v_pk_fma_f32 v[42:43], v[42:43], v[142:143], v[202:203]
	v_cvt_pk_bf16_f32 v40, v40, v41
	v_cvt_pk_bf16_f32 v41, v42, v43
	global_store_dwordx2 v[170:171], v[40:41], off offset:32
	s_waitcnt vmcnt(24)
	v_pk_fma_f32 v[36:37], v[36:37], v[132:133], v[204:205]
	v_pk_fma_f32 v[38:39], v[38:39], v[134:135], v[206:207]
	v_cvt_pk_bf16_f32 v36, v36, v37
	v_cvt_pk_bf16_f32 v37, v38, v39
	global_store_dwordx2 v[170:171], v[36:37], off offset:256
	s_waitcnt vmcnt(23)
	v_pk_fma_f32 v[28:29], v[28:29], v[128:129], v[208:209]
	v_pk_fma_f32 v[30:31], v[30:31], v[130:131], v[210:211]
	v_cvt_pk_bf16_f32 v28, v28, v29
	v_cvt_pk_bf16_f32 v29, v30, v31
	global_store_dwordx2 v[170:171], v[28:29], off offset:288
	s_mov_b32 s28, 0xa0000
	v_lshl_add_u64 v[170:171], v[176:177], 0, s[28:29]
	s_waitcnt vmcnt(22)
	v_pk_fma_f32 v[32:33], v[32:33], v[136:137], v[212:213]
	v_pk_fma_f32 v[34:35], v[34:35], v[138:139], v[214:215]
	v_cvt_pk_bf16_f32 v32, v32, v33
	v_cvt_pk_bf16_f32 v33, v34, v35
	global_store_dwordx2 v[170:171], v[32:33], off
	s_waitcnt vmcnt(21)
	v_pk_fma_f32 v[24:25], v[24:25], v[140:141], v[216:217]
	v_pk_fma_f32 v[26:27], v[26:27], v[142:143], v[218:219]
	v_cvt_pk_bf16_f32 v24, v24, v25
	v_cvt_pk_bf16_f32 v25, v26, v27
	global_store_dwordx2 v[170:171], v[24:25], off offset:32
	s_waitcnt vmcnt(20)
	v_pk_fma_f32 v[20:21], v[20:21], v[132:133], v[220:221]
	v_pk_fma_f32 v[22:23], v[22:23], v[134:135], v[222:223]
	v_cvt_pk_bf16_f32 v20, v20, v21
	v_cvt_pk_bf16_f32 v21, v22, v23
	global_store_dwordx2 v[170:171], v[20:21], off offset:256
	s_waitcnt vmcnt(19)
	v_pk_fma_f32 v[12:13], v[12:13], v[128:129], v[224:225]
	v_pk_fma_f32 v[14:15], v[14:15], v[130:131], v[226:227]
	v_cvt_pk_bf16_f32 v12, v12, v13
	v_cvt_pk_bf16_f32 v13, v14, v15
	global_store_dwordx2 v[170:171], v[12:13], off offset:288
	s_mov_b32 s28, 0xb0000
	v_lshl_add_u64 v[170:171], v[176:177], 0, s[28:29]
	s_waitcnt vmcnt(18)
	v_pk_fma_f32 v[16:17], v[16:17], v[136:137], v[228:229]
	v_pk_fma_f32 v[18:19], v[18:19], v[138:139], v[230:231]
	v_cvt_pk_bf16_f32 v16, v16, v17
	v_cvt_pk_bf16_f32 v17, v18, v19
	global_store_dwordx2 v[170:171], v[16:17], off
	s_waitcnt vmcnt(17)
	v_pk_fma_f32 v[8:9], v[8:9], v[140:141], v[232:233]
	v_pk_fma_f32 v[10:11], v[10:11], v[142:143], v[234:235]
	v_cvt_pk_bf16_f32 v8, v8, v9
	v_cvt_pk_bf16_f32 v9, v10, v11
	global_store_dwordx2 v[170:171], v[8:9], off offset:32
	s_waitcnt vmcnt(16)
	v_pk_fma_f32 v[4:5], v[4:5], v[132:133], v[236:237]
	v_pk_fma_f32 v[6:7], v[6:7], v[134:135], v[238:239]
	v_cvt_pk_bf16_f32 v4, v4, v5
	v_cvt_pk_bf16_f32 v5, v6, v7
	global_store_dwordx2 v[170:171], v[4:5], off offset:256
	s_waitcnt vmcnt(15)
	v_pk_fma_f32 v[0:1], v[0:1], v[128:129], v[240:241]
	v_pk_fma_f32 v[2:3], v[2:3], v[130:131], v[242:243]
	v_cvt_pk_bf16_f32 v0, v0, v1
	v_cvt_pk_bf16_f32 v1, v2, v3
	global_store_dwordx2 v[170:171], v[0:1], off offset:288
	s_and_b64 vcc, exec, s[34:35]
	s_cbranch_vccz .LBB0_1065
	s_branch .LBB0_1077

.LBB0_1193:
	s_cmp_lt_i32 s24, 9
	s_cselect_b64 s[0:1], -1, 0
	s_and_b64 s[0:1], s[0:1], s[6:7]
	s_andn2_b64 vcc, exec, s[0:1]
	s_cbranch_vccnz .LBB0_1209
	s_cmpk_gt_i32 s3, 0xaff
	v_readfirstlane_b32 s2, v144
	s_cbranch_scc1 .LBB0_1209
	s_waitcnt vmcnt(0)
	v_lshrrev_b32_e32 v0, 5, v144
	v_lshrrev_b32_e32 v2, 1, v144
	v_and_b32_e32 v0, 4, v0
	v_bfe_u32 v1, v144, 2, 2
	v_and_b32_e32 v11, 24, v2
	v_or3_b32 v0, v0, v1, v11
	v_lshlrev_b32_e32 v1, 4, v144
	v_add_u32_e32 v8, 0x2000, v1
	v_lshrrev_b32_e32 v2, 7, v8
	s_movk_i32 s6, 0xe0
	v_and_b32_e32 v4, 32, v144
	s_add_u32 s33, s22, 0x5e00000
	v_and_or_b32 v3, v2, s6, v0
	v_bitop3_b32 v9, v1, v4, 48 bitop3:0x6c
	v_and_b32_e32 v10, 64, v144
	v_bfe_u32 v12, v144, 2, 4
	s_movk_i32 s6, 0xf0
	s_waitcnt lgkmcnt(0)
	s_addc_u32 s40, s23, 0
	v_or_b32_e32 v1, v9, v10
	v_and_or_b32 v2, v2, s6, v12
	s_add_u32 s41, s22, 0x1c00000
	v_lshl_or_b32 v130, v2, 12, v1
	v_lshrrev_b32_e32 v2, 3, v144
	s_movk_i32 s6, 0x60
	s_addc_u32 s42, s23, 0
	v_and_or_b32 v0, v2, s6, v0
	s_movk_i32 s6, 0x70
	s_ashr_i32 s44, s3, 31
	v_lshl_or_b32 v132, v0, 12, v1
	v_and_or_b32 v0, v2, s6, v12
	s_lshr_b32 s6, s44, 29
	s_add_i32 s6, s3, s6
	s_lshr_b32 s8, s2, 6
	s_ashr_i32 s7, s6, 3
	s_and_b32 s6, s6, -8
	s_lshr_b32 s11, s2, 8
	s_lshl_b32 s43, s8, 10
	s_sub_i32 s6, s3, s6
	s_cmp_lt_i32 s6, 0
	s_movk_i32 s45, 0x161
	s_cselect_b32 s9, s45, 0x160
	s_mul_i32 s6, s6, s9
	s_add_i32 s6, s6, s7
	s_mul_hi_i32 s7, s6, 0x2e8ba2e9
	s_lshr_b32 s9, s7, 31
	s_ashr_i32 s7, s7, 6
	s_add_i32 s7, s7, s9
	s_lshl_b32 s9, s7, 3
	s_mulk_i32 s7, 0x160
	s_sub_i32 s6, s6, s7
	s_sext_i32_i16 s7, s6
	s_bfe_u32 s7, s7, 0x3001c
	s_add_i32 s7, s6, s7
	s_sext_i32_i16 s10, s7
	s_and_b32 s7, s7, 0xfff8
	s_sub_i32 s6, s6, s7
	s_sext_i32_i16 s6, s6
	s_lshr_b32 s10, s10, 3
	s_add_i32 s30, s9, s6
	s_ashr_i32 s31, s30, 31
	s_bfe_i64 s[12:13], s[10:11], 0x100000
	s_lshl_b64 s[6:7], s[30:31], 20
	s_lshl_b64 s[12:13], s[12:13], 20
	s_add_u32 s36, s41, s12
	s_addc_u32 s37, s42, s13
	s_add_i32 s31, s43, 0
	s_add_i32 m0, s31, 0x10000
	v_lshl_or_b32 v128, v3, 12, v1
	global_load_lds_dwordx4 v132, s[36:37]
	s_add_i32 m0, s31, 0x12000
	s_add_u32 s34, s33, s6
	v_lshl_or_b32 v134, v0, 12, v1
	global_load_lds_dwordx4 v128, s[36:37]
	s_addc_u32 s35, s40, s7
	s_mov_b32 m0, s31
	s_add_i32 s46, s31, 0x2000
	global_load_lds_dwordx4 v134, s[34:35]
	s_mov_b32 m0, s46
	s_add_u32 s6, s36, 0x80000
	global_load_lds_dwordx4 v130, s[34:35]
	s_addc_u32 s7, s37, 0
	s_add_i32 m0, s31, 0x14000
	v_mov_b32_e32 v133, 0
	global_load_lds_dwordx4 v132, s[6:7]
	s_add_i32 m0, s31, 0x16000
	v_mov_b32_e32 v129, v133
	global_load_lds_dwordx4 v128, s[6:7]
	s_add_u32 s6, s34, 0x80000
	s_addc_u32 s7, s35, 0
	s_add_i32 s47, s31, 0x4000
	s_mov_b32 m0, s47
	s_add_i32 s48, s31, 0x6000
	global_load_lds_dwordx4 v134, s[6:7]
	s_mov_b32 m0, s48
	v_mov_b32_e32 v135, v133
	global_load_lds_dwordx4 v130, s[6:7]
	v_mov_b32_e32 v131, v133
	s_mov_b32 s49, 0
	v_lshl_add_u64 v[6:7], s[36:37], 0, v[132:133]
	v_lshl_add_u64 v[4:5], s[36:37], 0, v[128:129]
	v_lshl_add_u64 v[2:3], s[34:35], 0, v[134:135]
	s_cmp_lg_u32 s11, 1
	v_lshl_add_u64 v[0:1], s[34:35], 0, v[130:131]
	s_cbranch_scc1 .LBB0_1197
	s_setprio 1
	s_barrier

.LBB0_1202:
	s_ashr_i32 s13, s12, 31
	s_xor_b64 s[16:17], s[28:29], -1
	s_lshl_b64 s[14:15], s[12:13], 20
	s_add_u32 s14, s33, s14
	s_addc_u32 s15, s40, s15
	s_and_b64 s[18:19], s[28:29], exec
	s_cselect_b32 s13, s15, s35
	s_cselect_b32 s58, s14, s34
	s_ashr_i32 s11, s10, 31
	s_lshl_b64 s[18:19], s[10:11], 20
	s_add_u32 s18, s41, s18
	s_addc_u32 s19, s42, s19
	s_and_b64 s[28:29], s[28:29], exec
	s_cselect_b32 s11, s19, s37
	s_cselect_b32 s28, s18, s36
	s_add_u32 s34, s34, 0x80080
	s_addc_u32 s35, s35, 0
	s_add_u32 s29, s36, 0x100
	s_addc_u32 s59, s37, 0
	s_mov_b32 s60, -2
	ds_read_b128 v[150:153], v147
	ds_read_b128 v[154:157], v147 offset:1024
	ds_read_b128 v[158:161], v147 offset:2048
	ds_read_b128 v[162:165], v147 offset:3072
	s_add_u32 s36, s34, 0xfff80080
	s_addc_u32 s37, s35, -1
	s_cmp_eq_u32 s60, 28
	s_cselect_b32 s39, s13, s37
	s_cselect_b32 s38, s58, s36
	s_cselect_b32 s37, s11, s59
	s_cselect_b32 s36, s28, s29
	v_lshl_add_u64 v[198:199], s[34:35], 0, v[136:137]
	s_add_i32 m0, s31, 0xc000
	ds_read_b128 v[166:169], v148
	ds_read_b128 v[170:173], v148 offset:1024
	ds_read_b128 v[174:177], v148 offset:2048
	ds_read_b128 v[178:181], v148 offset:3072
	ds_read_b128 v[182:185], v148 offset:4096
	ds_read_b128 v[186:189], v148 offset:5120
	ds_read_b128 v[190:193], v148 offset:6144
	ds_read_b128 v[194:197], v148 offset:7168
	global_load_lds_dwordx4 v[198:199], off
	v_lshl_add_u64 v[198:199], s[34:35], 0, v[138:139]
	s_add_i32 m0, s31, 0xe000
	s_nop 0
	global_load_lds_dwordx4 v[198:199], off
	s_waitcnt lgkmcnt(8)
	s_barrier
	s_waitcnt lgkmcnt(0)
	s_waitcnt lgkmcnt(0)
	v_mfma_f32_16x16x32_bf16 v[124:127], v[150:153], v[166:169], 0
	v_mfma_f32_16x16x32_bf16 v[120:123], v[158:161], v[166:169], 0
	v_mfma_f32_16x16x32_bf16 v[108:111], v[150:153], v[174:177], 0
	v_mfma_f32_16x16x32_bf16 v[104:107], v[158:161], v[174:177], 0
	v_mfma_f32_16x16x32_bf16 v[92:95], v[150:153], v[182:185], 0
	v_mfma_f32_16x16x32_bf16 v[88:91], v[158:161], v[182:185], 0
	v_mfma_f32_16x16x32_bf16 v[76:79], v[150:153], v[190:193], 0
	v_mfma_f32_16x16x32_bf16 v[72:75], v[158:161], v[190:193], 0
	v_mfma_f32_16x16x32_bf16 v[124:127], v[154:157], v[170:173], v[124:127]
	v_mfma_f32_16x16x32_bf16 v[120:123], v[162:165], v[170:173], v[120:123]
	v_mfma_f32_16x16x32_bf16 v[108:111], v[154:157], v[178:181], v[108:111]
	v_mfma_f32_16x16x32_bf16 v[104:107], v[162:165], v[178:181], v[104:107]
	v_mfma_f32_16x16x32_bf16 v[92:95], v[154:157], v[186:189], v[92:95]
	v_mfma_f32_16x16x32_bf16 v[88:91], v[162:165], v[186:189], v[88:91]
	v_mfma_f32_16x16x32_bf16 v[76:79], v[154:157], v[194:197], v[76:79]
	v_mfma_f32_16x16x32_bf16 v[72:75], v[162:165], v[194:197], v[72:75]
	s_barrier
	s_add_i32 s61, s54, s43
	v_lshl_add_u64 v[214:215], s[36:37], 0, v[132:133]
	s_mov_b32 m0, s61
	ds_read_b128 v[198:201], v149
	ds_read_b128 v[202:205], v149 offset:1024
	ds_read_b128 v[206:209], v149 offset:2048
	ds_read_b128 v[210:213], v149 offset:3072
	global_load_lds_dwordx4 v[214:215], off
	v_lshl_add_u64 v[216:217], s[36:37], 0, v[128:129]
	s_add_i32 m0, s61, 0x2000
	s_nop 0
	global_load_lds_dwordx4 v[216:217], off
	s_barrier
	s_waitcnt lgkmcnt(0)
	s_waitcnt lgkmcnt(0)
	v_mfma_f32_16x16x32_bf16 v[116:119], v[198:201], v[166:169], 0
	v_mfma_f32_16x16x32_bf16 v[112:115], v[206:209], v[166:169], 0
	v_mfma_f32_16x16x32_bf16 v[100:103], v[198:201], v[174:177], 0
	v_mfma_f32_16x16x32_bf16 v[96:99], v[206:209], v[174:177], 0
	v_mfma_f32_16x16x32_bf16 v[84:87], v[198:201], v[182:185], 0
	v_mfma_f32_16x16x32_bf16 v[80:83], v[206:209], v[182:185], 0
	v_mfma_f32_16x16x32_bf16 v[68:71], v[198:201], v[190:193], 0
	v_mfma_f32_16x16x32_bf16 v[64:67], v[206:209], v[190:193], 0
	v_mfma_f32_16x16x32_bf16 v[116:119], v[202:205], v[170:173], v[116:119]
	v_mfma_f32_16x16x32_bf16 v[112:115], v[210:213], v[170:173], v[112:115]
	v_mfma_f32_16x16x32_bf16 v[100:103], v[202:205], v[178:181], v[100:103]
	v_mfma_f32_16x16x32_bf16 v[96:99], v[210:213], v[178:181], v[96:99]
	v_mfma_f32_16x16x32_bf16 v[84:87], v[202:205], v[186:189], v[84:87]
	v_mfma_f32_16x16x32_bf16 v[80:83], v[210:213], v[186:189], v[80:83]
	v_mfma_f32_16x16x32_bf16 v[68:71], v[202:205], v[194:197], v[68:71]
	v_mfma_f32_16x16x32_bf16 v[64:67], v[210:213], v[194:197], v[64:67]
	s_mov_b32 m0, s31
	v_lshl_add_u64 v[218:219], s[38:39], 0, v[134:135]
	s_barrier
	ds_read_b128 v[166:169], v148 offset:16384
	ds_read_b128 v[170:173], v148 offset:17408
	ds_read_b128 v[174:177], v148 offset:18432
	ds_read_b128 v[178:181], v148 offset:19456
	ds_read_b128 v[182:185], v148 offset:20480
	ds_read_b128 v[186:189], v148 offset:21504
	ds_read_b128 v[190:193], v148 offset:22528
	ds_read_b128 v[194:197], v148 offset:23552
	global_load_lds_dwordx4 v[218:219], off
	v_lshl_add_u64 v[220:221], s[38:39], 0, v[130:131]
	s_mov_b32 m0, s46
	s_nop 0
	global_load_lds_dwordx4 v[220:221], off
	s_barrier
	s_waitcnt lgkmcnt(0)
	s_waitcnt lgkmcnt(0)
	v_mfma_f32_16x16x32_bf16 v[60:63], v[150:153], v[166:169], 0
	v_mfma_f32_16x16x32_bf16 v[56:59], v[158:161], v[166:169], 0
	v_mfma_f32_16x16x32_bf16 v[44:47], v[150:153], v[174:177], 0
	v_mfma_f32_16x16x32_bf16 v[40:43], v[158:161], v[174:177], 0
	v_mfma_f32_16x16x32_bf16 v[28:31], v[150:153], v[182:185], 0
	v_mfma_f32_16x16x32_bf16 v[24:27], v[158:161], v[182:185], 0
	v_mfma_f32_16x16x32_bf16 v[12:15], v[150:153], v[190:193], 0
	v_mfma_f32_16x16x32_bf16 v[8:11], v[158:161], v[190:193], 0
	v_mfma_f32_16x16x32_bf16 v[60:63], v[154:157], v[170:173], v[60:63]
	v_mfma_f32_16x16x32_bf16 v[56:59], v[162:165], v[170:173], v[56:59]
	v_mfma_f32_16x16x32_bf16 v[44:47], v[154:157], v[178:181], v[44:47]
	v_mfma_f32_16x16x32_bf16 v[40:43], v[162:165], v[178:181], v[40:43]
	v_mfma_f32_16x16x32_bf16 v[28:31], v[154:157], v[186:189], v[28:31]
	v_mfma_f32_16x16x32_bf16 v[24:27], v[162:165], v[186:189], v[24:27]
	v_mfma_f32_16x16x32_bf16 v[12:15], v[154:157], v[194:197], v[12:15]
	v_mfma_f32_16x16x32_bf16 v[8:11], v[162:165], v[194:197], v[8:11]
	s_barrier
	s_add_u32 s62, s36, 0x80000
	s_addc_u32 s63, s37, 0
	s_add_i32 s61, s55, s43
	v_lshl_add_u64 v[150:151], s[62:63], 0, v[132:133]
	s_mov_b32 m0, s61
	s_nop 0
	global_load_lds_dwordx4 v[150:151], off
	v_lshl_add_u64 v[150:151], s[62:63], 0, v[128:129]
	s_add_i32 m0, s61, 0x2000
	s_nop 0
	global_load_lds_dwordx4 v[150:151], off
	s_waitcnt vmcnt(6)
	s_barrier
	v_mfma_f32_16x16x32_bf16 v[52:55], v[198:201], v[166:169], 0
	v_mfma_f32_16x16x32_bf16 v[48:51], v[206:209], v[166:169], 0
	v_mfma_f32_16x16x32_bf16 v[36:39], v[198:201], v[174:177], 0
	v_mfma_f32_16x16x32_bf16 v[32:35], v[206:209], v[174:177], 0
	v_mfma_f32_16x16x32_bf16 v[20:23], v[198:201], v[182:185], 0
	v_mfma_f32_16x16x32_bf16 v[16:19], v[206:209], v[182:185], 0
	v_mfma_f32_16x16x32_bf16 v[4:7], v[198:201], v[190:193], 0
	v_mfma_f32_16x16x32_bf16 v[0:3], v[206:209], v[190:193], 0
	v_mfma_f32_16x16x32_bf16 v[52:55], v[202:205], v[170:173], v[52:55]
	v_mfma_f32_16x16x32_bf16 v[48:51], v[210:213], v[170:173], v[48:51]
	v_mfma_f32_16x16x32_bf16 v[36:39], v[202:205], v[178:181], v[36:39]
	v_mfma_f32_16x16x32_bf16 v[32:35], v[210:213], v[178:181], v[32:35]
	v_mfma_f32_16x16x32_bf16 v[20:23], v[202:205], v[186:189], v[20:23]
	v_mfma_f32_16x16x32_bf16 v[16:19], v[210:213], v[186:189], v[16:19]
	v_mfma_f32_16x16x32_bf16 v[4:7], v[202:205], v[194:197], v[4:7]
	v_mfma_f32_16x16x32_bf16 v[0:3], v[210:213], v[194:197], v[0:3]
	s_add_i32 s61, 0, 0x18000
	v_add_u32_e32 v162, s61, v143
	s_barrier
	ds_read_b128 v[150:153], v162
	ds_read_b128 v[154:157], v162 offset:1024
	ds_read_b128 v[158:161], v162 offset:2048
	ds_read_b128 v[162:165], v162 offset:3072
	s_add_u32 s38, s38, 0x80000
	s_addc_u32 s39, s39, 0
	s_mov_b32 m0, s47
	v_lshl_add_u64 v[198:199], s[38:39], 0, v[134:135]
	ds_read_b128 v[166:169], v148 offset:32768
	ds_read_b128 v[170:173], v148 offset:33792
	ds_read_b128 v[174:177], v148 offset:34816
	ds_read_b128 v[178:181], v148 offset:35840
	ds_read_b128 v[182:185], v148 offset:36864
	ds_read_b128 v[186:189], v148 offset:37888
	ds_read_b128 v[190:193], v148 offset:38912
	ds_read_b128 v[194:197], v148 offset:39936
	global_load_lds_dwordx4 v[198:199], off
	v_lshl_add_u64 v[198:199], s[38:39], 0, v[130:131]
	s_mov_b32 m0, s48
	s_nop 0
	global_load_lds_dwordx4 v[198:199], off
	s_waitcnt lgkmcnt(8)
	s_barrier
	s_waitcnt lgkmcnt(0)
	s_waitcnt lgkmcnt(0)
	v_mfma_f32_16x16x32_bf16 v[124:127], v[150:153], v[166:169], v[124:127]
	v_mfma_f32_16x16x32_bf16 v[120:123], v[158:161], v[166:169], v[120:123]
	v_mfma_f32_16x16x32_bf16 v[108:111], v[150:153], v[174:177], v[108:111]
	v_mfma_f32_16x16x32_bf16 v[104:107], v[158:161], v[174:177], v[104:107]
	v_mfma_f32_16x16x32_bf16 v[92:95], v[150:153], v[182:185], v[92:95]
	v_mfma_f32_16x16x32_bf16 v[88:91], v[158:161], v[182:185], v[88:91]
	v_mfma_f32_16x16x32_bf16 v[76:79], v[150:153], v[190:193], v[76:79]
	v_mfma_f32_16x16x32_bf16 v[72:75], v[158:161], v[190:193], v[72:75]
	v_mfma_f32_16x16x32_bf16 v[124:127], v[154:157], v[170:173], v[124:127]
	v_mfma_f32_16x16x32_bf16 v[120:123], v[162:165], v[170:173], v[120:123]
	v_mfma_f32_16x16x32_bf16 v[108:111], v[154:157], v[178:181], v[108:111]
	v_mfma_f32_16x16x32_bf16 v[104:107], v[162:165], v[178:181], v[104:107]
	v_mfma_f32_16x16x32_bf16 v[92:95], v[154:157], v[186:189], v[92:95]
	v_mfma_f32_16x16x32_bf16 v[88:91], v[162:165], v[186:189], v[88:91]
	v_mfma_f32_16x16x32_bf16 v[76:79], v[154:157], v[194:197], v[76:79]
	v_mfma_f32_16x16x32_bf16 v[72:75], v[162:165], v[194:197], v[72:75]
	s_barrier
	s_add_i32 s38, 0, 0x1c000
	s_add_i32 s39, s61, s43
	v_add_u32_e32 v210, s38, v143
	v_lshl_add_u64 v[214:215], v[214:215], 0, s[8:9]
	s_mov_b32 m0, s39
	ds_read_b128 v[198:201], v210
	ds_read_b128 v[202:205], v210 offset:1024
	ds_read_b128 v[206:209], v210 offset:2048
	ds_read_b128 v[210:213], v210 offset:3072
	global_load_lds_dwordx4 v[214:215], off
	v_lshl_add_u64 v[214:215], v[216:217], 0, s[8:9]
	s_add_i32 m0, s39, 0x2000
	s_nop 0
	global_load_lds_dwordx4 v[214:215], off
	s_barrier
	s_waitcnt lgkmcnt(0)
	s_waitcnt lgkmcnt(0)
	v_mfma_f32_16x16x32_bf16 v[116:119], v[198:201], v[166:169], v[116:119]
	v_mfma_f32_16x16x32_bf16 v[112:115], v[206:209], v[166:169], v[112:115]
	v_mfma_f32_16x16x32_bf16 v[100:103], v[198:201], v[174:177], v[100:103]
	v_mfma_f32_16x16x32_bf16 v[96:99], v[206:209], v[174:177], v[96:99]
	v_mfma_f32_16x16x32_bf16 v[84:87], v[198:201], v[182:185], v[84:87]
	v_mfma_f32_16x16x32_bf16 v[80:83], v[206:209], v[182:185], v[80:83]
	v_mfma_f32_16x16x32_bf16 v[68:71], v[198:201], v[190:193], v[68:71]
	v_mfma_f32_16x16x32_bf16 v[64:67], v[206:209], v[190:193], v[64:67]
	v_mfma_f32_16x16x32_bf16 v[116:119], v[202:205], v[170:173], v[116:119]
	v_mfma_f32_16x16x32_bf16 v[112:115], v[210:213], v[170:173], v[112:115]
	v_mfma_f32_16x16x32_bf16 v[100:103], v[202:205], v[178:181], v[100:103]
	v_mfma_f32_16x16x32_bf16 v[96:99], v[210:213], v[178:181], v[96:99]
	v_mfma_f32_16x16x32_bf16 v[84:87], v[202:205], v[186:189], v[84:87]
	v_mfma_f32_16x16x32_bf16 v[80:83], v[210:213], v[186:189], v[80:83]
	v_mfma_f32_16x16x32_bf16 v[68:71], v[202:205], v[194:197], v[68:71]
	v_mfma_f32_16x16x32_bf16 v[64:67], v[210:213], v[194:197], v[64:67]
	s_mov_b32 m0, s50
	v_lshl_add_u64 v[214:215], v[218:219], 0, s[8:9]
	s_barrier
	ds_read_b128 v[166:169], v148 offset:49152
	ds_read_b128 v[170:173], v148 offset:50176
	ds_read_b128 v[174:177], v148 offset:51200
	ds_read_b128 v[178:181], v148 offset:52224
	ds_read_b128 v[182:185], v148 offset:53248
	ds_read_b128 v[186:189], v148 offset:54272
	ds_read_b128 v[190:193], v148 offset:55296
	ds_read_b128 v[194:197], v148 offset:56320
	global_load_lds_dwordx4 v[214:215], off
	v_lshl_add_u64 v[214:215], v[220:221], 0, s[8:9]
	s_mov_b32 m0, s51
	s_nop 0
	global_load_lds_dwordx4 v[214:215], off
	s_barrier
	s_waitcnt lgkmcnt(0)
	s_waitcnt lgkmcnt(0)
	v_mfma_f32_16x16x32_bf16 v[60:63], v[150:153], v[166:169], v[60:63]
	v_mfma_f32_16x16x32_bf16 v[56:59], v[158:161], v[166:169], v[56:59]
	v_mfma_f32_16x16x32_bf16 v[44:47], v[150:153], v[174:177], v[44:47]
	v_mfma_f32_16x16x32_bf16 v[40:43], v[158:161], v[174:177], v[40:43]
	v_mfma_f32_16x16x32_bf16 v[28:31], v[150:153], v[182:185], v[28:31]
	v_mfma_f32_16x16x32_bf16 v[24:27], v[158:161], v[182:185], v[24:27]
	v_mfma_f32_16x16x32_bf16 v[12:15], v[150:153], v[190:193], v[12:15]
	v_mfma_f32_16x16x32_bf16 v[8:11], v[158:161], v[190:193], v[8:11]
	v_mfma_f32_16x16x32_bf16 v[60:63], v[154:157], v[170:173], v[60:63]
	v_mfma_f32_16x16x32_bf16 v[56:59], v[162:165], v[170:173], v[56:59]
	v_mfma_f32_16x16x32_bf16 v[44:47], v[154:157], v[178:181], v[44:47]
	v_mfma_f32_16x16x32_bf16 v[40:43], v[162:165], v[178:181], v[40:43]
	v_mfma_f32_16x16x32_bf16 v[28:31], v[154:157], v[186:189], v[28:31]
	v_mfma_f32_16x16x32_bf16 v[24:27], v[162:165], v[186:189], v[24:27]
	v_mfma_f32_16x16x32_bf16 v[12:15], v[154:157], v[194:197], v[12:15]
	v_mfma_f32_16x16x32_bf16 v[8:11], v[162:165], v[194:197], v[8:11]
	s_barrier
	s_add_u32 s36, s36, 0x80080
	s_addc_u32 s37, s37, 0
	s_add_i32 s38, s38, s43
	v_lshl_add_u64 v[150:151], s[36:37], 0, v[132:133]
	s_mov_b32 m0, s38
	s_nop 0
	global_load_lds_dwordx4 v[150:151], off
	v_lshl_add_u64 v[150:151], s[36:37], 0, v[128:129]
	s_add_i32 m0, s38, 0x2000
	s_nop 0
	global_load_lds_dwordx4 v[150:151], off
	s_waitcnt vmcnt(6)
	s_barrier
	v_mfma_f32_16x16x32_bf16 v[52:55], v[198:201], v[166:169], v[52:55]
	v_mfma_f32_16x16x32_bf16 v[48:51], v[206:209], v[166:169], v[48:51]
	v_mfma_f32_16x16x32_bf16 v[36:39], v[198:201], v[174:177], v[36:39]
	v_mfma_f32_16x16x32_bf16 v[32:35], v[206:209], v[174:177], v[32:35]
	v_mfma_f32_16x16x32_bf16 v[20:23], v[198:201], v[182:185], v[20:23]
	v_mfma_f32_16x16x32_bf16 v[16:19], v[206:209], v[182:185], v[16:19]
	v_mfma_f32_16x16x32_bf16 v[4:7], v[198:201], v[190:193], v[4:7]
	v_mfma_f32_16x16x32_bf16 v[0:3], v[206:209], v[190:193], v[0:3]
	v_mfma_f32_16x16x32_bf16 v[52:55], v[202:205], v[170:173], v[52:55]
	v_mfma_f32_16x16x32_bf16 v[48:51], v[210:213], v[170:173], v[48:51]
	v_mfma_f32_16x16x32_bf16 v[36:39], v[202:205], v[178:181], v[36:39]
	v_mfma_f32_16x16x32_bf16 v[32:35], v[210:213], v[178:181], v[32:35]
	v_mfma_f32_16x16x32_bf16 v[20:23], v[202:205], v[186:189], v[20:23]
	v_mfma_f32_16x16x32_bf16 v[16:19], v[210:213], v[186:189], v[16:19]
	v_mfma_f32_16x16x32_bf16 v[4:7], v[202:205], v[194:197], v[4:7]
	v_mfma_f32_16x16x32_bf16 v[0:3], v[210:213], v[194:197], v[0:3]
	s_add_i32 s60, s60, 2
	s_add_u32 s34, s34, 0x100
	s_addc_u32 s35, s35, 0
	s_add_u32 s29, s29, 0x100
	s_addc_u32 s59, s59, 0
	s_cmp_gt_u32 s60, 29
	s_barrier
	s_cbranch_scc0 .LBB0_1203
.LBB0_1203:
	ds_read_b128 v[150:153], v147
	ds_read_b128 v[154:157], v147 offset:1024
	ds_read_b128 v[158:161], v147 offset:2048
	ds_read_b128 v[162:165], v147 offset:3072
	s_add_u32 s36, s34, 0xfff80080
	s_addc_u32 s37, s35, -1
	s_cmp_eq_u32 s60, 28
	s_cselect_b32 s39, s13, s37
	s_cselect_b32 s38, s58, s36
	s_cselect_b32 s37, s11, s59
	s_cselect_b32 s36, s28, s29
	v_lshl_add_u64 v[198:199], s[34:35], 0, v[136:137]
	s_add_i32 m0, s31, 0xc000
	ds_read_b128 v[166:169], v148
	ds_read_b128 v[170:173], v148 offset:1024
	ds_read_b128 v[174:177], v148 offset:2048
	ds_read_b128 v[178:181], v148 offset:3072
	ds_read_b128 v[182:185], v148 offset:4096
	ds_read_b128 v[186:189], v148 offset:5120
	ds_read_b128 v[190:193], v148 offset:6144
	ds_read_b128 v[194:197], v148 offset:7168
	global_load_lds_dwordx4 v[198:199], off
	v_lshl_add_u64 v[198:199], s[34:35], 0, v[138:139]
	s_add_i32 m0, s31, 0xe000
	s_nop 0
	global_load_lds_dwordx4 v[198:199], off
	s_waitcnt lgkmcnt(8)
	s_barrier
	s_waitcnt lgkmcnt(0)
	s_waitcnt lgkmcnt(0)
	v_mfma_f32_16x16x32_bf16 v[124:127], v[150:153], v[166:169], v[124:127]
	v_mfma_f32_16x16x32_bf16 v[120:123], v[158:161], v[166:169], v[120:123]
	v_mfma_f32_16x16x32_bf16 v[108:111], v[150:153], v[174:177], v[108:111]
	v_mfma_f32_16x16x32_bf16 v[104:107], v[158:161], v[174:177], v[104:107]
	v_mfma_f32_16x16x32_bf16 v[92:95], v[150:153], v[182:185], v[92:95]
	v_mfma_f32_16x16x32_bf16 v[88:91], v[158:161], v[182:185], v[88:91]
	v_mfma_f32_16x16x32_bf16 v[76:79], v[150:153], v[190:193], v[76:79]
	v_mfma_f32_16x16x32_bf16 v[72:75], v[158:161], v[190:193], v[72:75]
	v_mfma_f32_16x16x32_bf16 v[124:127], v[154:157], v[170:173], v[124:127]
	v_mfma_f32_16x16x32_bf16 v[120:123], v[162:165], v[170:173], v[120:123]
	v_mfma_f32_16x16x32_bf16 v[108:111], v[154:157], v[178:181], v[108:111]
	v_mfma_f32_16x16x32_bf16 v[104:107], v[162:165], v[178:181], v[104:107]
	v_mfma_f32_16x16x32_bf16 v[92:95], v[154:157], v[186:189], v[92:95]
	v_mfma_f32_16x16x32_bf16 v[88:91], v[162:165], v[186:189], v[88:91]
	v_mfma_f32_16x16x32_bf16 v[76:79], v[154:157], v[194:197], v[76:79]
	v_mfma_f32_16x16x32_bf16 v[72:75], v[162:165], v[194:197], v[72:75]
	s_barrier
	s_add_i32 s61, s54, s43
	v_lshl_add_u64 v[214:215], s[36:37], 0, v[132:133]
	s_mov_b32 m0, s61
	ds_read_b128 v[198:201], v149
	ds_read_b128 v[202:205], v149 offset:1024
	ds_read_b128 v[206:209], v149 offset:2048
	ds_read_b128 v[210:213], v149 offset:3072
	global_load_lds_dwordx4 v[214:215], off
	v_lshl_add_u64 v[216:217], s[36:37], 0, v[128:129]
	s_add_i32 m0, s61, 0x2000
	s_nop 0
	global_load_lds_dwordx4 v[216:217], off
	s_barrier
	s_waitcnt lgkmcnt(0)
	s_waitcnt lgkmcnt(0)
	v_mfma_f32_16x16x32_bf16 v[116:119], v[198:201], v[166:169], v[116:119]
	v_mfma_f32_16x16x32_bf16 v[112:115], v[206:209], v[166:169], v[112:115]
	v_mfma_f32_16x16x32_bf16 v[100:103], v[198:201], v[174:177], v[100:103]
	v_mfma_f32_16x16x32_bf16 v[96:99], v[206:209], v[174:177], v[96:99]
	v_mfma_f32_16x16x32_bf16 v[84:87], v[198:201], v[182:185], v[84:87]
	v_mfma_f32_16x16x32_bf16 v[80:83], v[206:209], v[182:185], v[80:83]
	v_mfma_f32_16x16x32_bf16 v[68:71], v[198:201], v[190:193], v[68:71]
	v_mfma_f32_16x16x32_bf16 v[64:67], v[206:209], v[190:193], v[64:67]
	v_mfma_f32_16x16x32_bf16 v[116:119], v[202:205], v[170:173], v[116:119]
	v_mfma_f32_16x16x32_bf16 v[112:115], v[210:213], v[170:173], v[112:115]
	v_mfma_f32_16x16x32_bf16 v[100:103], v[202:205], v[178:181], v[100:103]
	v_mfma_f32_16x16x32_bf16 v[96:99], v[210:213], v[178:181], v[96:99]
	v_mfma_f32_16x16x32_bf16 v[84:87], v[202:205], v[186:189], v[84:87]
	v_mfma_f32_16x16x32_bf16 v[80:83], v[210:213], v[186:189], v[80:83]
	v_mfma_f32_16x16x32_bf16 v[68:71], v[202:205], v[194:197], v[68:71]
	v_mfma_f32_16x16x32_bf16 v[64:67], v[210:213], v[194:197], v[64:67]
	s_mov_b32 m0, s31
	v_lshl_add_u64 v[218:219], s[38:39], 0, v[134:135]
	s_barrier
	ds_read_b128 v[166:169], v148 offset:16384
	ds_read_b128 v[170:173], v148 offset:17408
	ds_read_b128 v[174:177], v148 offset:18432
	ds_read_b128 v[178:181], v148 offset:19456
	ds_read_b128 v[182:185], v148 offset:20480
	ds_read_b128 v[186:189], v148 offset:21504
	ds_read_b128 v[190:193], v148 offset:22528
	ds_read_b128 v[194:197], v148 offset:23552
	global_load_lds_dwordx4 v[218:219], off
	v_lshl_add_u64 v[220:221], s[38:39], 0, v[130:131]
	s_mov_b32 m0, s46
	s_nop 0
	global_load_lds_dwordx4 v[220:221], off
	s_barrier
	s_waitcnt lgkmcnt(0)
	s_waitcnt lgkmcnt(0)
	v_mfma_f32_16x16x32_bf16 v[60:63], v[150:153], v[166:169], v[60:63]
	v_mfma_f32_16x16x32_bf16 v[56:59], v[158:161], v[166:169], v[56:59]
	v_mfma_f32_16x16x32_bf16 v[44:47], v[150:153], v[174:177], v[44:47]
	v_mfma_f32_16x16x32_bf16 v[40:43], v[158:161], v[174:177], v[40:43]
	v_mfma_f32_16x16x32_bf16 v[28:31], v[150:153], v[182:185], v[28:31]
	v_mfma_f32_16x16x32_bf16 v[24:27], v[158:161], v[182:185], v[24:27]
	v_mfma_f32_16x16x32_bf16 v[12:15], v[150:153], v[190:193], v[12:15]
	v_mfma_f32_16x16x32_bf16 v[8:11], v[158:161], v[190:193], v[8:11]
	v_mfma_f32_16x16x32_bf16 v[60:63], v[154:157], v[170:173], v[60:63]
	v_mfma_f32_16x16x32_bf16 v[56:59], v[162:165], v[170:173], v[56:59]
	v_mfma_f32_16x16x32_bf16 v[44:47], v[154:157], v[178:181], v[44:47]
	v_mfma_f32_16x16x32_bf16 v[40:43], v[162:165], v[178:181], v[40:43]
	v_mfma_f32_16x16x32_bf16 v[28:31], v[154:157], v[186:189], v[28:31]
	v_mfma_f32_16x16x32_bf16 v[24:27], v[162:165], v[186:189], v[24:27]
	v_mfma_f32_16x16x32_bf16 v[12:15], v[154:157], v[194:197], v[12:15]
	v_mfma_f32_16x16x32_bf16 v[8:11], v[162:165], v[194:197], v[8:11]
	s_barrier
	s_add_u32 s62, s36, 0x80000
	s_addc_u32 s63, s37, 0
	s_add_i32 s61, s55, s43
	v_lshl_add_u64 v[150:151], s[62:63], 0, v[132:133]
	s_mov_b32 m0, s61
	s_nop 0
	global_load_lds_dwordx4 v[150:151], off
	v_lshl_add_u64 v[150:151], s[62:63], 0, v[128:129]
	s_add_i32 m0, s61, 0x2000
	s_nop 0
	global_load_lds_dwordx4 v[150:151], off
	s_waitcnt vmcnt(6)
	s_barrier
	v_mfma_f32_16x16x32_bf16 v[52:55], v[198:201], v[166:169], v[52:55]
	v_mfma_f32_16x16x32_bf16 v[48:51], v[206:209], v[166:169], v[48:51]
	v_mfma_f32_16x16x32_bf16 v[36:39], v[198:201], v[174:177], v[36:39]
	v_mfma_f32_16x16x32_bf16 v[32:35], v[206:209], v[174:177], v[32:35]
	v_mfma_f32_16x16x32_bf16 v[20:23], v[198:201], v[182:185], v[20:23]
	v_mfma_f32_16x16x32_bf16 v[16:19], v[206:209], v[182:185], v[16:19]
	v_mfma_f32_16x16x32_bf16 v[4:7], v[198:201], v[190:193], v[4:7]
	v_mfma_f32_16x16x32_bf16 v[0:3], v[206:209], v[190:193], v[0:3]
	v_mfma_f32_16x16x32_bf16 v[52:55], v[202:205], v[170:173], v[52:55]
	v_mfma_f32_16x16x32_bf16 v[48:51], v[210:213], v[170:173], v[48:51]
	v_mfma_f32_16x16x32_bf16 v[36:39], v[202:205], v[178:181], v[36:39]
	v_mfma_f32_16x16x32_bf16 v[32:35], v[210:213], v[178:181], v[32:35]
	v_mfma_f32_16x16x32_bf16 v[20:23], v[202:205], v[186:189], v[20:23]
	v_mfma_f32_16x16x32_bf16 v[16:19], v[210:213], v[186:189], v[16:19]
	v_mfma_f32_16x16x32_bf16 v[4:7], v[202:205], v[194:197], v[4:7]
	v_mfma_f32_16x16x32_bf16 v[0:3], v[210:213], v[194:197], v[0:3]
	s_add_i32 s61, 0, 0x18000
	v_add_u32_e32 v162, s61, v143
	s_barrier
	ds_read_b128 v[150:153], v162
	ds_read_b128 v[154:157], v162 offset:1024
	ds_read_b128 v[158:161], v162 offset:2048
	ds_read_b128 v[162:165], v162 offset:3072
	s_add_u32 s38, s38, 0x80000
	s_addc_u32 s39, s39, 0
	s_mov_b32 m0, s47
	v_lshl_add_u64 v[198:199], s[38:39], 0, v[134:135]
	ds_read_b128 v[166:169], v148 offset:32768
	ds_read_b128 v[170:173], v148 offset:33792
	ds_read_b128 v[174:177], v148 offset:34816
	ds_read_b128 v[178:181], v148 offset:35840
	ds_read_b128 v[182:185], v148 offset:36864
	ds_read_b128 v[186:189], v148 offset:37888
	ds_read_b128 v[190:193], v148 offset:38912
	ds_read_b128 v[194:197], v148 offset:39936
	global_load_lds_dwordx4 v[198:199], off
	v_lshl_add_u64 v[198:199], s[38:39], 0, v[130:131]
	s_mov_b32 m0, s48
	s_nop 0
	global_load_lds_dwordx4 v[198:199], off
	s_waitcnt lgkmcnt(8)
	s_barrier
	s_waitcnt lgkmcnt(0)
	s_waitcnt lgkmcnt(0)
	v_mfma_f32_16x16x32_bf16 v[124:127], v[150:153], v[166:169], v[124:127]
	v_mfma_f32_16x16x32_bf16 v[120:123], v[158:161], v[166:169], v[120:123]
	v_mfma_f32_16x16x32_bf16 v[108:111], v[150:153], v[174:177], v[108:111]
	v_mfma_f32_16x16x32_bf16 v[104:107], v[158:161], v[174:177], v[104:107]
	v_mfma_f32_16x16x32_bf16 v[92:95], v[150:153], v[182:185], v[92:95]
	v_mfma_f32_16x16x32_bf16 v[88:91], v[158:161], v[182:185], v[88:91]
	v_mfma_f32_16x16x32_bf16 v[76:79], v[150:153], v[190:193], v[76:79]
	v_mfma_f32_16x16x32_bf16 v[72:75], v[158:161], v[190:193], v[72:75]
	v_mfma_f32_16x16x32_bf16 v[124:127], v[154:157], v[170:173], v[124:127]
	v_mfma_f32_16x16x32_bf16 v[120:123], v[162:165], v[170:173], v[120:123]
	v_mfma_f32_16x16x32_bf16 v[108:111], v[154:157], v[178:181], v[108:111]
	v_mfma_f32_16x16x32_bf16 v[104:107], v[162:165], v[178:181], v[104:107]
	v_mfma_f32_16x16x32_bf16 v[92:95], v[154:157], v[186:189], v[92:95]
	v_mfma_f32_16x16x32_bf16 v[88:91], v[162:165], v[186:189], v[88:91]
	v_mfma_f32_16x16x32_bf16 v[76:79], v[154:157], v[194:197], v[76:79]
	v_mfma_f32_16x16x32_bf16 v[72:75], v[162:165], v[194:197], v[72:75]
	s_barrier
	s_add_i32 s38, 0, 0x1c000
	s_add_i32 s39, s61, s43
	v_add_u32_e32 v210, s38, v143
	v_lshl_add_u64 v[214:215], v[214:215], 0, s[8:9]
	s_mov_b32 m0, s39
	ds_read_b128 v[198:201], v210
	ds_read_b128 v[202:205], v210 offset:1024
	ds_read_b128 v[206:209], v210 offset:2048
	ds_read_b128 v[210:213], v210 offset:3072
	global_load_lds_dwordx4 v[214:215], off
	v_lshl_add_u64 v[214:215], v[216:217], 0, s[8:9]
	s_add_i32 m0, s39, 0x2000
	s_nop 0
	global_load_lds_dwordx4 v[214:215], off
	s_barrier
	s_waitcnt lgkmcnt(0)
	s_waitcnt lgkmcnt(0)
	v_mfma_f32_16x16x32_bf16 v[116:119], v[198:201], v[166:169], v[116:119]
	v_mfma_f32_16x16x32_bf16 v[112:115], v[206:209], v[166:169], v[112:115]
	v_mfma_f32_16x16x32_bf16 v[100:103], v[198:201], v[174:177], v[100:103]
	v_mfma_f32_16x16x32_bf16 v[96:99], v[206:209], v[174:177], v[96:99]
	v_mfma_f32_16x16x32_bf16 v[84:87], v[198:201], v[182:185], v[84:87]
	v_mfma_f32_16x16x32_bf16 v[80:83], v[206:209], v[182:185], v[80:83]
	v_mfma_f32_16x16x32_bf16 v[68:71], v[198:201], v[190:193], v[68:71]
	v_mfma_f32_16x16x32_bf16 v[64:67], v[206:209], v[190:193], v[64:67]
	v_mfma_f32_16x16x32_bf16 v[116:119], v[202:205], v[170:173], v[116:119]
	v_mfma_f32_16x16x32_bf16 v[112:115], v[210:213], v[170:173], v[112:115]
	v_mfma_f32_16x16x32_bf16 v[100:103], v[202:205], v[178:181], v[100:103]
	v_mfma_f32_16x16x32_bf16 v[96:99], v[210:213], v[178:181], v[96:99]
	v_mfma_f32_16x16x32_bf16 v[84:87], v[202:205], v[186:189], v[84:87]
	v_mfma_f32_16x16x32_bf16 v[80:83], v[210:213], v[186:189], v[80:83]
	v_mfma_f32_16x16x32_bf16 v[68:71], v[202:205], v[194:197], v[68:71]
	v_mfma_f32_16x16x32_bf16 v[64:67], v[210:213], v[194:197], v[64:67]
	s_mov_b32 m0, s50
	v_lshl_add_u64 v[214:215], v[218:219], 0, s[8:9]
	s_barrier
	ds_read_b128 v[166:169], v148 offset:49152
	ds_read_b128 v[170:173], v148 offset:50176
	ds_read_b128 v[174:177], v148 offset:51200
	ds_read_b128 v[178:181], v148 offset:52224
	ds_read_b128 v[182:185], v148 offset:53248
	ds_read_b128 v[186:189], v148 offset:54272
	ds_read_b128 v[190:193], v148 offset:55296
	ds_read_b128 v[194:197], v148 offset:56320
	global_load_lds_dwordx4 v[214:215], off
	v_lshl_add_u64 v[214:215], v[220:221], 0, s[8:9]
	s_mov_b32 m0, s51
	s_nop 0
	global_load_lds_dwordx4 v[214:215], off
	s_barrier
	s_waitcnt lgkmcnt(0)
	s_waitcnt lgkmcnt(0)
	v_mfma_f32_16x16x32_bf16 v[60:63], v[150:153], v[166:169], v[60:63]
	v_mfma_f32_16x16x32_bf16 v[56:59], v[158:161], v[166:169], v[56:59]
	v_mfma_f32_16x16x32_bf16 v[44:47], v[150:153], v[174:177], v[44:47]
	v_mfma_f32_16x16x32_bf16 v[40:43], v[158:161], v[174:177], v[40:43]
	v_mfma_f32_16x16x32_bf16 v[28:31], v[150:153], v[182:185], v[28:31]
	v_mfma_f32_16x16x32_bf16 v[24:27], v[158:161], v[182:185], v[24:27]
	v_mfma_f32_16x16x32_bf16 v[12:15], v[150:153], v[190:193], v[12:15]
	v_mfma_f32_16x16x32_bf16 v[8:11], v[158:161], v[190:193], v[8:11]
	v_mfma_f32_16x16x32_bf16 v[60:63], v[154:157], v[170:173], v[60:63]
	v_mfma_f32_16x16x32_bf16 v[56:59], v[162:165], v[170:173], v[56:59]
	v_mfma_f32_16x16x32_bf16 v[44:47], v[154:157], v[178:181], v[44:47]
	v_mfma_f32_16x16x32_bf16 v[40:43], v[162:165], v[178:181], v[40:43]
	v_mfma_f32_16x16x32_bf16 v[28:31], v[154:157], v[186:189], v[28:31]
	v_mfma_f32_16x16x32_bf16 v[24:27], v[162:165], v[186:189], v[24:27]
	v_mfma_f32_16x16x32_bf16 v[12:15], v[154:157], v[194:197], v[12:15]
	v_mfma_f32_16x16x32_bf16 v[8:11], v[162:165], v[194:197], v[8:11]
	s_barrier
	s_add_u32 s36, s36, 0x80080
	s_addc_u32 s37, s37, 0
	s_add_i32 s38, s38, s43
	v_lshl_add_u64 v[150:151], s[36:37], 0, v[132:133]
	s_mov_b32 m0, s38
	s_nop 0
	global_load_lds_dwordx4 v[150:151], off
	v_lshl_add_u64 v[150:151], s[36:37], 0, v[128:129]
	s_add_i32 m0, s38, 0x2000
	s_nop 0
	global_load_lds_dwordx4 v[150:151], off
	s_waitcnt vmcnt(6)
	s_barrier
	v_mfma_f32_16x16x32_bf16 v[52:55], v[198:201], v[166:169], v[52:55]
	v_mfma_f32_16x16x32_bf16 v[48:51], v[206:209], v[166:169], v[48:51]
	v_mfma_f32_16x16x32_bf16 v[36:39], v[198:201], v[174:177], v[36:39]
	v_mfma_f32_16x16x32_bf16 v[32:35], v[206:209], v[174:177], v[32:35]
	v_mfma_f32_16x16x32_bf16 v[20:23], v[198:201], v[182:185], v[20:23]
	v_mfma_f32_16x16x32_bf16 v[16:19], v[206:209], v[182:185], v[16:19]
	v_mfma_f32_16x16x32_bf16 v[4:7], v[198:201], v[190:193], v[4:7]
	v_mfma_f32_16x16x32_bf16 v[0:3], v[206:209], v[190:193], v[0:3]
	v_mfma_f32_16x16x32_bf16 v[52:55], v[202:205], v[170:173], v[52:55]
	v_mfma_f32_16x16x32_bf16 v[48:51], v[210:213], v[170:173], v[48:51]
	v_mfma_f32_16x16x32_bf16 v[36:39], v[202:205], v[178:181], v[36:39]
	v_mfma_f32_16x16x32_bf16 v[32:35], v[210:213], v[178:181], v[32:35]
	v_mfma_f32_16x16x32_bf16 v[20:23], v[202:205], v[186:189], v[20:23]
	v_mfma_f32_16x16x32_bf16 v[16:19], v[210:213], v[186:189], v[16:19]
	v_mfma_f32_16x16x32_bf16 v[4:7], v[202:205], v[194:197], v[4:7]
	v_mfma_f32_16x16x32_bf16 v[0:3], v[210:213], v[194:197], v[0:3]
	s_add_i32 s60, s60, 2
	s_add_u32 s34, s34, 0x100
	s_addc_u32 s35, s35, 0
	s_add_u32 s29, s29, 0x100
	s_addc_u32 s59, s59, 0
	s_cmp_gt_u32 s60, 29
	s_barrier
	s_cbranch_scc0 .LBB0_1203
	v_pk_add_f32 v[124:125], v[124:125], 0 op_sel_hi:[1,0]
	v_pk_add_f32 v[126:127], v[126:127], 0 op_sel_hi:[1,0]
	v_mul_f32_e32 v151, 0xbfb8aa3b, v124
	v_exp_f32_e32 v151, v151
	v_mul_f32_e32 v154, 0xbfb8aa3b, v125
	v_exp_f32_e32 v155, v154
	v_pk_add_f32 v[116:117], v[116:117], 0 op_sel_hi:[1,0]
	v_add_f32_e32 v151, 1.0, v151
	v_rcp_f32_e32 v154, v151
	v_add_f32_e32 v151, 1.0, v155
	v_mul_f32_e32 v155, 0xbfb8aa3b, v126
	v_exp_f32_e32 v156, v155
	v_mul_f32_e32 v155, 0xbfb8aa3b, v127
	v_exp_f32_e32 v157, v155
	v_rcp_f32_e32 v155, v151
	v_add_f32_e32 v151, 1.0, v156
	v_rcp_f32_e32 v156, v151
	v_add_f32_e32 v151, 1.0, v157
	v_rcp_f32_e32 v157, v151
	v_pk_mul_f32 v[124:125], v[124:125], v[154:155]
	v_pk_add_f32 v[120:121], v[120:121], 0 op_sel_hi:[1,0]
	v_pk_mul_f32 v[116:117], v[124:125], v[116:117]
	v_pk_mul_f32 v[124:125], v[126:127], v[156:157]
	v_mul_f32_e32 v126, 0xbfb8aa3b, v120
	v_exp_f32_e32 v126, v126
	v_pk_add_f32 v[118:119], v[118:119], 0 op_sel_hi:[1,0]
	v_pk_add_f32 v[122:123], v[122:123], 0 op_sel_hi:[1,0]
	v_pk_mul_f32 v[118:119], v[124:125], v[118:119]
	v_mul_f32_e32 v124, 0xbfb8aa3b, v121
	v_exp_f32_e32 v125, v124
	v_add_f32_e32 v124, 1.0, v126
	v_mul_f32_e32 v126, 0xbfb8aa3b, v122
	v_mul_f32_e32 v127, 0xbfb8aa3b, v123
	v_exp_f32_e32 v126, v126
	v_exp_f32_e32 v127, v127
	v_add_f32_e32 v125, 1.0, v125
	v_rcp_f32_e32 v124, v124
	v_rcp_f32_e32 v125, v125
	v_add_f32_e32 v126, 1.0, v126
	v_add_f32_e32 v127, 1.0, v127
	v_rcp_f32_e32 v126, v126
	v_rcp_f32_e32 v127, v127
	v_pk_add_f32 v[112:113], v[112:113], 0 op_sel_hi:[1,0]
	v_pk_mul_f32 v[120:121], v[120:121], v[124:125]
	v_lshl_or_b32 v152, s57, 7, v146
	v_pk_mul_f32 v[112:113], v[120:121], v[112:113]
	v_pk_add_f32 v[114:115], v[114:115], 0 op_sel_hi:[1,0]
	v_pk_mul_f32 v[120:121], v[122:123], v[126:127]
	v_lshl_add_u32 v150, s30, 8, v142
	v_ashrrev_i32_e32 v153, 31, v152
	v_pk_mul_f32 v[114:115], v[120:121], v[114:115]
	v_cvt_pk_bf16_f32 v116, v116, v117
	v_cvt_pk_bf16_f32 v117, v118, v119
	v_cvt_pk_bf16_f32 v118, v112, v113
	v_mov_b64_e32 v[112:113], s[6:7]
	v_cvt_pk_bf16_f32 v119, v114, v115
	v_mad_i64_i32 v[120:121], s[28:29], v150, s56, v[112:113]
	v_lshlrev_b64 v[114:115], 1, v[152:153]
	v_lshl_add_u64 v[120:121], v[120:121], 0, v[114:115]
	v_pk_add_f32 v[108:109], v[108:109], 0 op_sel_hi:[1,0]
	global_store_dwordx4 v[120:121], v[116:119], off sc0 sc1
	v_mul_f32_e32 v122, 0xbfb8aa3b, v108
	v_pk_add_f32 v[110:111], v[110:111], 0 op_sel_hi:[1,0]
	v_mul_f32_e32 v116, 0xbfb8aa3b, v109
	v_exp_f32_e32 v122, v122
	v_exp_f32_e32 v117, v116
	v_mul_f32_e32 v118, 0xbfb8aa3b, v110
	v_mul_f32_e32 v119, 0xbfb8aa3b, v111
	v_exp_f32_e32 v118, v118
	v_exp_f32_e32 v119, v119
	v_add_f32_e32 v116, 1.0, v122
	v_add_f32_e32 v117, 1.0, v117
	v_rcp_f32_e32 v116, v116
	v_rcp_f32_e32 v117, v117
	v_add_f32_e32 v118, 1.0, v118
	v_add_f32_e32 v119, 1.0, v119
	v_rcp_f32_e32 v118, v118
	v_rcp_f32_e32 v119, v119
	v_pk_add_f32 v[100:101], v[100:101], 0 op_sel_hi:[1,0]
	v_pk_mul_f32 v[108:109], v[108:109], v[116:117]
	v_pk_add_f32 v[104:105], v[104:105], 0 op_sel_hi:[1,0]
	v_pk_mul_f32 v[100:101], v[108:109], v[100:101]
	v_pk_mul_f32 v[108:109], v[110:111], v[118:119]
	v_mul_f32_e32 v110, 0xbfb8aa3b, v104
	v_exp_f32_e32 v110, v110
	v_pk_add_f32 v[102:103], v[102:103], 0 op_sel_hi:[1,0]
	v_pk_add_f32 v[106:107], v[106:107], 0 op_sel_hi:[1,0]
	v_pk_mul_f32 v[102:103], v[108:109], v[102:103]
	v_mul_f32_e32 v108, 0xbfb8aa3b, v105
	v_exp_f32_e32 v109, v108
	v_add_f32_e32 v108, 1.0, v110
	v_mul_f32_e32 v110, 0xbfb8aa3b, v106
	v_mul_f32_e32 v111, 0xbfb8aa3b, v107
	v_exp_f32_e32 v110, v110
	v_exp_f32_e32 v111, v111
	v_add_f32_e32 v109, 1.0, v109
	v_rcp_f32_e32 v108, v108
	v_rcp_f32_e32 v109, v109
	v_add_f32_e32 v110, 1.0, v110
	v_add_f32_e32 v111, 1.0, v111
	v_rcp_f32_e32 v110, v110
	v_rcp_f32_e32 v111, v111
	v_pk_add_f32 v[96:97], v[96:97], 0 op_sel_hi:[1,0]
	v_pk_mul_f32 v[104:105], v[104:105], v[108:109]
	v_or_b32_e32 v108, 16, v150
	v_pk_mul_f32 v[104:105], v[104:105], v[96:97]
	v_pk_add_f32 v[96:97], v[98:99], 0 op_sel_hi:[1,0]
	v_pk_mul_f32 v[98:99], v[106:107], v[110:111]
	v_pk_add_f32 v[92:93], v[92:93], 0 op_sel_hi:[1,0]
	v_pk_mul_f32 v[106:107], v[98:99], v[96:97]
	v_cvt_pk_bf16_f32 v96, v100, v101
	v_mad_i64_i32 v[100:101], s[28:29], v108, s56, v[112:113]
	v_cvt_pk_bf16_f32 v97, v102, v103
	v_cvt_pk_bf16_f32 v98, v104, v105
	v_cvt_pk_bf16_f32 v99, v106, v107
	v_lshl_add_u64 v[100:101], v[100:101], 0, v[114:115]
	v_mul_f32_e32 v102, 0xbfb8aa3b, v92
	global_store_dwordx4 v[100:101], v[96:99], off sc0 sc1
	v_pk_add_f32 v[94:95], v[94:95], 0 op_sel_hi:[1,0]
	v_exp_f32_e32 v102, v102
	v_mul_f32_e32 v96, 0xbfb8aa3b, v93
	v_exp_f32_e32 v97, v96
	v_mul_f32_e32 v98, 0xbfb8aa3b, v94
	v_mul_f32_e32 v99, 0xbfb8aa3b, v95
	v_exp_f32_e32 v98, v98
	v_exp_f32_e32 v99, v99
	v_add_f32_e32 v96, 1.0, v102
	v_add_f32_e32 v97, 1.0, v97
	v_rcp_f32_e32 v96, v96
	v_rcp_f32_e32 v97, v97
	v_add_f32_e32 v98, 1.0, v98
	v_add_f32_e32 v99, 1.0, v99
	v_rcp_f32_e32 v98, v98
	v_rcp_f32_e32 v99, v99
	v_pk_add_f32 v[84:85], v[84:85], 0 op_sel_hi:[1,0]
	v_pk_mul_f32 v[92:93], v[92:93], v[96:97]
	v_pk_add_f32 v[88:89], v[88:89], 0 op_sel_hi:[1,0]
	v_pk_mul_f32 v[84:85], v[92:93], v[84:85]
	v_pk_mul_f32 v[92:93], v[94:95], v[98:99]
	v_mul_f32_e32 v94, 0xbfb8aa3b, v88
	v_exp_f32_e32 v94, v94
	v_pk_add_f32 v[86:87], v[86:87], 0 op_sel_hi:[1,0]
	v_pk_add_f32 v[90:91], v[90:91], 0 op_sel_hi:[1,0]
	v_pk_mul_f32 v[86:87], v[92:93], v[86:87]
	v_mul_f32_e32 v92, 0xbfb8aa3b, v89
	v_exp_f32_e32 v93, v92
	v_add_f32_e32 v92, 1.0, v94
	v_mul_f32_e32 v94, 0xbfb8aa3b, v90
	v_mul_f32_e32 v95, 0xbfb8aa3b, v91
	v_exp_f32_e32 v94, v94
	v_exp_f32_e32 v95, v95
	v_add_f32_e32 v93, 1.0, v93
	v_rcp_f32_e32 v92, v92
	v_rcp_f32_e32 v93, v93
	v_add_f32_e32 v94, 1.0, v94
	v_add_f32_e32 v95, 1.0, v95
	v_rcp_f32_e32 v94, v94
	v_rcp_f32_e32 v95, v95
	v_pk_add_f32 v[80:81], v[80:81], 0 op_sel_hi:[1,0]
	v_pk_mul_f32 v[88:89], v[88:89], v[92:93]
	v_or_b32_e32 v92, 32, v150
	v_pk_mul_f32 v[88:89], v[88:89], v[80:81]
	v_pk_add_f32 v[80:81], v[82:83], 0 op_sel_hi:[1,0]
	v_pk_mul_f32 v[82:83], v[90:91], v[94:95]
	v_pk_add_f32 v[76:77], v[76:77], 0 op_sel_hi:[1,0]
	v_pk_mul_f32 v[90:91], v[82:83], v[80:81]
	v_cvt_pk_bf16_f32 v80, v84, v85
	v_mad_i64_i32 v[84:85], s[28:29], v92, s56, v[112:113]
	v_cvt_pk_bf16_f32 v81, v86, v87
	v_cvt_pk_bf16_f32 v82, v88, v89
	v_cvt_pk_bf16_f32 v83, v90, v91
	v_lshl_add_u64 v[84:85], v[84:85], 0, v[114:115]
	v_mul_f32_e32 v86, 0xbfb8aa3b, v76
	global_store_dwordx4 v[84:85], v[80:83], off sc0 sc1
	v_pk_add_f32 v[78:79], v[78:79], 0 op_sel_hi:[1,0]
	v_exp_f32_e32 v86, v86
	v_mul_f32_e32 v80, 0xbfb8aa3b, v77
	v_exp_f32_e32 v81, v80
	v_mul_f32_e32 v82, 0xbfb8aa3b, v78
	v_mul_f32_e32 v83, 0xbfb8aa3b, v79
	v_exp_f32_e32 v82, v82
	v_exp_f32_e32 v83, v83
	v_add_f32_e32 v80, 1.0, v86
	v_add_f32_e32 v81, 1.0, v81
	v_rcp_f32_e32 v80, v80
	v_rcp_f32_e32 v81, v81
	v_add_f32_e32 v82, 1.0, v82
	v_add_f32_e32 v83, 1.0, v83
	v_rcp_f32_e32 v82, v82
	v_rcp_f32_e32 v83, v83
	v_pk_add_f32 v[68:69], v[68:69], 0 op_sel_hi:[1,0]
	v_pk_mul_f32 v[76:77], v[76:77], v[80:81]
	v_pk_add_f32 v[72:73], v[72:73], 0 op_sel_hi:[1,0]
	v_pk_mul_f32 v[68:69], v[76:77], v[68:69]
	v_pk_mul_f32 v[76:77], v[78:79], v[82:83]
	v_mul_f32_e32 v78, 0xbfb8aa3b, v72
	v_exp_f32_e32 v78, v78
	v_pk_add_f32 v[70:71], v[70:71], 0 op_sel_hi:[1,0]
	v_pk_add_f32 v[74:75], v[74:75], 0 op_sel_hi:[1,0]
	v_pk_mul_f32 v[70:71], v[76:77], v[70:71]
	v_mul_f32_e32 v76, 0xbfb8aa3b, v73
	v_exp_f32_e32 v77, v76
	v_add_f32_e32 v76, 1.0, v78
	v_mul_f32_e32 v78, 0xbfb8aa3b, v74
	v_mul_f32_e32 v79, 0xbfb8aa3b, v75
	v_exp_f32_e32 v78, v78
	v_exp_f32_e32 v79, v79
	v_add_f32_e32 v77, 1.0, v77
	v_rcp_f32_e32 v76, v76
	v_rcp_f32_e32 v77, v77
	v_add_f32_e32 v78, 1.0, v78
	v_add_f32_e32 v79, 1.0, v79
	v_rcp_f32_e32 v78, v78
	v_rcp_f32_e32 v79, v79
	v_pk_add_f32 v[64:65], v[64:65], 0 op_sel_hi:[1,0]
	v_pk_mul_f32 v[72:73], v[72:73], v[76:77]
	v_or_b32_e32 v76, 48, v150
	v_pk_mul_f32 v[72:73], v[72:73], v[64:65]
	v_pk_add_f32 v[64:65], v[66:67], 0 op_sel_hi:[1,0]
	v_pk_mul_f32 v[66:67], v[74:75], v[78:79]
	v_pk_add_f32 v[60:61], v[60:61], 0 op_sel_hi:[1,0]
	v_pk_mul_f32 v[74:75], v[66:67], v[64:65]
	v_cvt_pk_bf16_f32 v64, v68, v69
	v_mad_i64_i32 v[68:69], s[28:29], v76, s56, v[112:113]
	v_cvt_pk_bf16_f32 v65, v70, v71
	v_cvt_pk_bf16_f32 v66, v72, v73
	v_cvt_pk_bf16_f32 v67, v74, v75
	v_lshl_add_u64 v[68:69], v[68:69], 0, v[114:115]
	global_store_dwordx4 v[68:69], v[64:67], off sc0 sc1
	v_pk_add_f32 v[62:63], v[62:63], 0 op_sel_hi:[1,0]
	v_pk_add_f32 v[52:53], v[52:53], 0 op_sel_hi:[1,0]
	v_mul_f32_e32 v64, 0xbfb8aa3b, v60
	v_mul_f32_e32 v65, 0xbfb8aa3b, v61
	v_exp_f32_e32 v64, v64
	v_exp_f32_e32 v65, v65
	v_mul_f32_e32 v66, 0xbfb8aa3b, v62
	v_mul_f32_e32 v67, 0xbfb8aa3b, v63
	v_exp_f32_e32 v66, v66
	v_exp_f32_e32 v67, v67
	v_add_f32_e32 v64, 1.0, v64
	v_add_f32_e32 v65, 1.0, v65
	v_rcp_f32_e32 v64, v64
	v_rcp_f32_e32 v65, v65
	v_add_f32_e32 v66, 1.0, v66
	v_add_f32_e32 v67, 1.0, v67
	v_rcp_f32_e32 v66, v66
	v_rcp_f32_e32 v67, v67
	v_pk_mul_f32 v[60:61], v[60:61], v[64:65]
	v_pk_add_f32 v[56:57], v[56:57], 0 op_sel_hi:[1,0]
	v_pk_mul_f32 v[52:53], v[60:61], v[52:53]
	v_pk_mul_f32 v[60:61], v[62:63], v[66:67]
	v_mul_f32_e32 v62, 0xbfb8aa3b, v56
	v_exp_f32_e32 v62, v62
	v_pk_add_f32 v[54:55], v[54:55], 0 op_sel_hi:[1,0]
	v_pk_add_f32 v[58:59], v[58:59], 0 op_sel_hi:[1,0]
	v_pk_mul_f32 v[54:55], v[60:61], v[54:55]
	v_mul_f32_e32 v60, 0xbfb8aa3b, v57
	v_exp_f32_e32 v61, v60
	v_add_f32_e32 v60, 1.0, v62
	v_mul_f32_e32 v62, 0xbfb8aa3b, v58
	v_mul_f32_e32 v63, 0xbfb8aa3b, v59
	v_exp_f32_e32 v62, v62
	v_exp_f32_e32 v63, v63
	v_add_f32_e32 v61, 1.0, v61
	v_rcp_f32_e32 v60, v60
	v_rcp_f32_e32 v61, v61
	v_add_f32_e32 v62, 1.0, v62
	v_add_f32_e32 v63, 1.0, v63
	v_rcp_f32_e32 v62, v62
	v_rcp_f32_e32 v63, v63
	v_pk_add_f32 v[48:49], v[48:49], 0 op_sel_hi:[1,0]
	v_pk_mul_f32 v[56:57], v[56:57], v[60:61]
	v_add_u32_e32 v68, 0x80, v150
	v_pk_mul_f32 v[56:57], v[56:57], v[48:49]
	v_pk_add_f32 v[48:49], v[50:51], 0 op_sel_hi:[1,0]
	v_pk_mul_f32 v[50:51], v[58:59], v[62:63]
	v_pk_add_f32 v[44:45], v[44:45], 0 op_sel_hi:[1,0]
	v_pk_mul_f32 v[58:59], v[50:51], v[48:49]
	v_cvt_pk_bf16_f32 v48, v52, v53
	v_mad_i64_i32 v[52:53], s[28:29], v68, s56, v[112:113]
	v_cvt_pk_bf16_f32 v49, v54, v55
	v_cvt_pk_bf16_f32 v50, v56, v57
	v_cvt_pk_bf16_f32 v51, v58, v59
	v_lshl_add_u64 v[52:53], v[52:53], 0, v[114:115]
	v_mul_f32_e32 v54, 0xbfb8aa3b, v44
	global_store_dwordx4 v[52:53], v[48:51], off sc0 sc1
	v_pk_add_f32 v[46:47], v[46:47], 0 op_sel_hi:[1,0]
	v_exp_f32_e32 v54, v54
	v_mul_f32_e32 v48, 0xbfb8aa3b, v45
	v_exp_f32_e32 v49, v48
	v_mul_f32_e32 v50, 0xbfb8aa3b, v46
	v_mul_f32_e32 v51, 0xbfb8aa3b, v47
	v_exp_f32_e32 v50, v50
	v_exp_f32_e32 v51, v51
	v_add_f32_e32 v48, 1.0, v54
	v_add_f32_e32 v49, 1.0, v49
	v_rcp_f32_e32 v48, v48
	v_rcp_f32_e32 v49, v49
	v_add_f32_e32 v50, 1.0, v50
	v_add_f32_e32 v51, 1.0, v51
	v_rcp_f32_e32 v50, v50
	v_rcp_f32_e32 v51, v51
	v_pk_add_f32 v[36:37], v[36:37], 0 op_sel_hi:[1,0]
	v_pk_mul_f32 v[44:45], v[44:45], v[48:49]
	v_pk_add_f32 v[40:41], v[40:41], 0 op_sel_hi:[1,0]
	v_pk_mul_f32 v[36:37], v[44:45], v[36:37]
	v_pk_mul_f32 v[44:45], v[46:47], v[50:51]
	v_mul_f32_e32 v46, 0xbfb8aa3b, v40
	v_exp_f32_e32 v46, v46
	v_pk_add_f32 v[38:39], v[38:39], 0 op_sel_hi:[1,0]
	v_pk_add_f32 v[42:43], v[42:43], 0 op_sel_hi:[1,0]
	v_pk_mul_f32 v[38:39], v[44:45], v[38:39]
	v_mul_f32_e32 v44, 0xbfb8aa3b, v41
	v_exp_f32_e32 v45, v44
	v_add_f32_e32 v44, 1.0, v46
	v_mul_f32_e32 v46, 0xbfb8aa3b, v42
	v_mul_f32_e32 v47, 0xbfb8aa3b, v43
	v_exp_f32_e32 v46, v46
	v_exp_f32_e32 v47, v47
	v_add_f32_e32 v45, 1.0, v45
	v_rcp_f32_e32 v44, v44
	v_rcp_f32_e32 v45, v45
	v_add_f32_e32 v46, 1.0, v46
	v_add_f32_e32 v47, 1.0, v47
	v_rcp_f32_e32 v46, v46
	v_rcp_f32_e32 v47, v47
	v_pk_add_f32 v[32:33], v[32:33], 0 op_sel_hi:[1,0]
	v_pk_mul_f32 v[40:41], v[40:41], v[44:45]
	v_add_u32_e32 v44, 0x90, v150
	v_pk_mul_f32 v[40:41], v[40:41], v[32:33]
	v_pk_add_f32 v[32:33], v[34:35], 0 op_sel_hi:[1,0]
	v_pk_mul_f32 v[34:35], v[42:43], v[46:47]
	v_pk_add_f32 v[28:29], v[28:29], 0 op_sel_hi:[1,0]
	v_pk_mul_f32 v[42:43], v[34:35], v[32:33]
	v_cvt_pk_bf16_f32 v32, v36, v37
	v_mad_i64_i32 v[36:37], s[28:29], v44, s56, v[112:113]
	v_cvt_pk_bf16_f32 v33, v38, v39
	v_cvt_pk_bf16_f32 v34, v40, v41
	v_cvt_pk_bf16_f32 v35, v42, v43
	v_lshl_add_u64 v[36:37], v[36:37], 0, v[114:115]
	v_mul_f32_e32 v38, 0xbfb8aa3b, v28
	global_store_dwordx4 v[36:37], v[32:35], off sc0 sc1
	v_pk_add_f32 v[30:31], v[30:31], 0 op_sel_hi:[1,0]
	v_exp_f32_e32 v38, v38
	v_mul_f32_e32 v32, 0xbfb8aa3b, v29
	v_exp_f32_e32 v33, v32
	v_mul_f32_e32 v34, 0xbfb8aa3b, v30
	v_mul_f32_e32 v35, 0xbfb8aa3b, v31
	v_exp_f32_e32 v34, v34
	v_exp_f32_e32 v35, v35
	v_add_f32_e32 v32, 1.0, v38
	v_add_f32_e32 v33, 1.0, v33
	v_rcp_f32_e32 v32, v32
	v_rcp_f32_e32 v33, v33
	v_add_f32_e32 v34, 1.0, v34
	v_add_f32_e32 v35, 1.0, v35
	v_rcp_f32_e32 v34, v34
	v_rcp_f32_e32 v35, v35
	v_pk_add_f32 v[20:21], v[20:21], 0 op_sel_hi:[1,0]
	v_pk_mul_f32 v[28:29], v[28:29], v[32:33]
	v_pk_add_f32 v[24:25], v[24:25], 0 op_sel_hi:[1,0]
	v_pk_mul_f32 v[20:21], v[28:29], v[20:21]
	v_pk_mul_f32 v[28:29], v[30:31], v[34:35]
	v_mul_f32_e32 v30, 0xbfb8aa3b, v24
	v_exp_f32_e32 v30, v30
	v_pk_add_f32 v[22:23], v[22:23], 0 op_sel_hi:[1,0]
	v_pk_add_f32 v[26:27], v[26:27], 0 op_sel_hi:[1,0]
	v_pk_mul_f32 v[22:23], v[28:29], v[22:23]
	v_mul_f32_e32 v28, 0xbfb8aa3b, v25
	v_exp_f32_e32 v29, v28
	v_add_f32_e32 v28, 1.0, v30
	v_mul_f32_e32 v30, 0xbfb8aa3b, v26
	v_mul_f32_e32 v31, 0xbfb8aa3b, v27
	v_exp_f32_e32 v30, v30
	v_exp_f32_e32 v31, v31
	v_add_f32_e32 v29, 1.0, v29
	v_rcp_f32_e32 v28, v28
	v_rcp_f32_e32 v29, v29
	v_add_f32_e32 v30, 1.0, v30
	v_add_f32_e32 v31, 1.0, v31
	v_rcp_f32_e32 v30, v30
	v_rcp_f32_e32 v31, v31
	v_pk_add_f32 v[16:17], v[16:17], 0 op_sel_hi:[1,0]
	v_pk_mul_f32 v[24:25], v[24:25], v[28:29]
	v_add_u32_e32 v28, 0xa0, v150
	v_pk_mul_f32 v[24:25], v[24:25], v[16:17]
	v_pk_add_f32 v[16:17], v[18:19], 0 op_sel_hi:[1,0]
	v_pk_mul_f32 v[18:19], v[26:27], v[30:31]
	v_pk_add_f32 v[12:13], v[12:13], 0 op_sel_hi:[1,0]
	v_pk_mul_f32 v[26:27], v[18:19], v[16:17]
	v_cvt_pk_bf16_f32 v16, v20, v21
	v_mad_i64_i32 v[20:21], s[28:29], v28, s56, v[112:113]
	v_cvt_pk_bf16_f32 v17, v22, v23
	v_cvt_pk_bf16_f32 v18, v24, v25
	v_cvt_pk_bf16_f32 v19, v26, v27
	v_lshl_add_u64 v[20:21], v[20:21], 0, v[114:115]
	v_mul_f32_e32 v22, 0xbfb8aa3b, v12
	global_store_dwordx4 v[20:21], v[16:19], off sc0 sc1
	v_pk_add_f32 v[14:15], v[14:15], 0 op_sel_hi:[1,0]
	v_exp_f32_e32 v22, v22
	v_mul_f32_e32 v16, 0xbfb8aa3b, v13
	v_exp_f32_e32 v17, v16
	v_mul_f32_e32 v18, 0xbfb8aa3b, v14
	v_mul_f32_e32 v19, 0xbfb8aa3b, v15
	v_exp_f32_e32 v18, v18
	v_exp_f32_e32 v19, v19
	v_add_f32_e32 v16, 1.0, v22
	v_add_f32_e32 v17, 1.0, v17
	v_rcp_f32_e32 v16, v16
	v_rcp_f32_e32 v17, v17
	v_add_f32_e32 v18, 1.0, v18
	v_add_f32_e32 v19, 1.0, v19
	v_rcp_f32_e32 v18, v18
	v_rcp_f32_e32 v19, v19
	v_pk_add_f32 v[4:5], v[4:5], 0 op_sel_hi:[1,0]
	v_pk_mul_f32 v[12:13], v[12:13], v[16:17]
	v_pk_add_f32 v[8:9], v[8:9], 0 op_sel_hi:[1,0]
	v_pk_mul_f32 v[4:5], v[12:13], v[4:5]
	v_pk_mul_f32 v[12:13], v[14:15], v[18:19]
	v_mul_f32_e32 v14, 0xbfb8aa3b, v8
	v_exp_f32_e32 v14, v14
	v_pk_add_f32 v[6:7], v[6:7], 0 op_sel_hi:[1,0]
	v_pk_add_f32 v[10:11], v[10:11], 0 op_sel_hi:[1,0]
	v_pk_mul_f32 v[6:7], v[12:13], v[6:7]
	v_mul_f32_e32 v12, 0xbfb8aa3b, v9
	v_exp_f32_e32 v13, v12
	v_add_f32_e32 v12, 1.0, v14
	v_mul_f32_e32 v14, 0xbfb8aa3b, v10
	v_mul_f32_e32 v15, 0xbfb8aa3b, v11
	v_exp_f32_e32 v14, v14
	v_exp_f32_e32 v15, v15
	v_add_f32_e32 v13, 1.0, v13
	v_rcp_f32_e32 v12, v12
	v_rcp_f32_e32 v13, v13
	v_add_f32_e32 v14, 1.0, v14
	v_add_f32_e32 v15, 1.0, v15
	v_rcp_f32_e32 v14, v14
	v_rcp_f32_e32 v15, v15
	v_pk_add_f32 v[0:1], v[0:1], 0 op_sel_hi:[1,0]
	v_pk_mul_f32 v[8:9], v[8:9], v[12:13]
	v_add_u32_e32 v12, 0xb0, v150
	v_pk_mul_f32 v[8:9], v[8:9], v[0:1]
	v_pk_add_f32 v[0:1], v[2:3], 0 op_sel_hi:[1,0]
	v_pk_mul_f32 v[2:3], v[10:11], v[14:15]
	s_and_b64 vcc, exec, s[16:17]
	v_pk_mul_f32 v[10:11], v[2:3], v[0:1]
	v_cvt_pk_bf16_f32 v0, v4, v5
	v_mad_i64_i32 v[4:5], s[28:29], v12, s56, v[112:113]
	v_cvt_pk_bf16_f32 v1, v6, v7
	v_cvt_pk_bf16_f32 v2, v8, v9
	v_cvt_pk_bf16_f32 v3, v10, v11
	v_lshl_add_u64 v[4:5], v[4:5], 0, v[114:115]
	s_mov_b32 s57, s10
	s_mov_b32 s30, s12
	s_mov_b64 s[36:37], s[18:19]
	s_mov_b64 s[34:35], s[14:15]
	global_store_dwordx4 v[4:5], v[0:3], off sc0 sc1
	s_cbranch_vccz .LBB0_1198
	s_branch .LBB0_1206

.LBB0_1269:
	s_waitcnt lgkmcnt(0)
	s_add_u32 s42, s22, 0xa600000
	s_addc_u32 s43, s23, 0
	s_add_u32 s44, s22, 0x4800000
	s_addc_u32 s45, s23, 0
	s_add_i32 s1, s8, s1
	s_waitcnt vmcnt(0)
	v_lshlrev_b32_e32 v0, 4, v144
	v_and_b32_e32 v1, 32, v144
	s_ashr_i32 s8, s1, 31
	v_bfe_u32 v2, v144, 2, 4
	v_bitop3_b32 v8, v0, v1, 48 bitop3:0x6c
	v_lshrrev_b32_e32 v3, 3, v144
	s_movk_i32 s9, 0x70
	v_add_u32_e32 v0, 0x2000, v0
	s_lshr_b32 s8, s8, 26
	v_and_or_b32 v3, v3, s9, v2
	v_lshrrev_b32_e32 v0, 7, v0
	s_movk_i32 s9, 0xf0
	s_add_i32 s8, s1, s8
	v_and_or_b32 v0, v0, s9, v2
	s_ashr_i32 s9, s8, 6
	s_and_b32 s8, s8, 0xffc0
	s_sub_i32 s8, s1, s8
	s_bfe_i32 s1, s8, 0x80000
	s_bfe_u32 s1, s1, 0x3000c
	s_add_i32 s11, s8, s1
	s_bfe_i32 s1, s11, 0x80000
	s_and_b32 s11, s11, 0xf8
	s_sext_i32_i16 s12, s1
	s_sub_i32 s8, s8, s11
	s_lshr_b32 s10, s2, 6
	s_lshl_b32 s9, s9, 3
	s_sext_i32_i8 s8, s8
	s_ashr_i32 s11, s12, 3
	s_lshr_b32 s0, s2, 8
	s_lshl_b32 s46, s10, 10
	s_lshr_b32 s1, s12, 3
	s_add_i32 s66, s9, s8
	s_mul_hi_i32 s12, s11, 0x2c0000
	s_mul_i32 s11, s11, 0x2c0000
	v_and_b32_e32 v9, 64, v144
	s_add_u32 s38, s44, s11
	v_or_b32_e32 v1, v8, v9
	v_mul_u32_u24_e32 v10, 0x2c00, v3
	s_addc_u32 s39, s45, s12
	s_add_i32 s47, s46, 0
	v_or_b32_e32 v146, v10, v1
	s_add_i32 m0, s47, 0x10000
	v_mul_u32_u24_e32 v11, 0x2c00, v0
	s_mul_i32 s9, s66, 0x2c0000
	global_load_lds_dwordx4 v146, s[38:39]
	s_add_i32 m0, s47, 0x12000
	v_or_b32_e32 v148, v11, v1
	s_mul_hi_i32 s8, s66, 0x2c0000
	s_add_u32 s36, s42, s9
	global_load_lds_dwordx4 v148, s[38:39]
	s_addc_u32 s37, s43, s8
	s_mov_b32 m0, s47
	s_add_i32 s48, s47, 0x2000
	global_load_lds_dwordx4 v146, s[36:37]
	s_mov_b32 m0, s48
	s_add_u32 s8, s38, 0x160000
	global_load_lds_dwordx4 v148, s[36:37]
	s_addc_u32 s9, s39, 0
	s_add_i32 m0, s47, 0x14000
	v_mov_b32_e32 v147, 0
	global_load_lds_dwordx4 v146, s[8:9]
	s_add_i32 m0, s47, 0x16000
	v_mov_b32_e32 v149, v147
	global_load_lds_dwordx4 v148, s[8:9]
	s_add_u32 s8, s36, 0x160000
	s_addc_u32 s9, s37, 0
	s_add_i32 s49, s47, 0x4000
	s_mov_b32 m0, s49
	s_add_i32 s50, s47, 0x6000
	global_load_lds_dwordx4 v146, s[8:9]
	s_mov_b32 m0, s50
	s_mov_b32 s51, 0
	global_load_lds_dwordx4 v148, s[8:9]
	v_lshl_add_u64 v[6:7], s[38:39], 0, v[146:147]
	v_lshl_add_u64 v[4:5], s[38:39], 0, v[148:149]
	v_lshl_add_u64 v[2:3], s[36:37], 0, v[146:147]
	s_cmp_lg_u32 s0, 1
	v_lshl_add_u64 v[0:1], s[36:37], 0, v[148:149]
	s_cbranch_scc1 .LBB0_1271
	s_setprio 1
	s_barrier

.LBB0_1284:
	s_add_u32 s36, s36, 0x160080
	s_addc_u32 s37, s37, 0
	s_add_u32 s28, s38, 0x100
	s_addc_u32 s29, s39, 0
	s_mov_b32 s68, -2
	ds_read_b128 v[128:131], v169
	ds_read_b128 v[132:135], v169 offset:1024
	ds_read_b128 v[136:139], v169 offset:2048
	ds_read_b128 v[140:143], v169 offset:3072
	s_add_u32 s38, s36, 0xffea0080
	s_addc_u32 s39, s37, -1
	s_cmpk_eq_i32 s68, 0x54
	s_cselect_b32 s41, s35, s39
	s_cselect_b32 s40, s34, s38
	s_cselect_b32 s39, s1, s29
	s_cselect_b32 s38, s0, s28
	v_lshl_add_u64 v[164:165], s[36:37], 0, v[150:151]
	s_add_i32 m0, s47, 0xc000
	ds_read_b128 v[156:159], v170
	ds_read_b128 v[160:163], v170 offset:1024
	ds_read_b128 v[172:175], v170 offset:2048
	ds_read_b128 v[176:179], v170 offset:3072
	ds_read_b128 v[180:183], v170 offset:4096
	ds_read_b128 v[184:187], v170 offset:5120
	ds_read_b128 v[188:191], v170 offset:6144
	ds_read_b128 v[192:195], v170 offset:7168
	global_load_lds_dwordx4 v[164:165], off
	v_lshl_add_u64 v[164:165], s[36:37], 0, v[152:153]
	s_add_i32 m0, s47, 0xe000
	s_nop 0
	global_load_lds_dwordx4 v[164:165], off
	s_waitcnt lgkmcnt(8)
	s_barrier
	s_waitcnt lgkmcnt(0)
	s_waitcnt lgkmcnt(0)
	v_mfma_f32_16x16x32_bf16 v[124:127], v[128:131], v[156:159], 0
	v_mfma_f32_16x16x32_bf16 v[120:123], v[136:139], v[156:159], 0
	v_mfma_f32_16x16x32_bf16 v[116:119], v[128:131], v[172:175], 0
	v_mfma_f32_16x16x32_bf16 v[104:107], v[136:139], v[172:175], 0
	v_mfma_f32_16x16x32_bf16 v[92:95], v[128:131], v[180:183], 0
	v_mfma_f32_16x16x32_bf16 v[88:91], v[136:139], v[180:183], 0
	v_mfma_f32_16x16x32_bf16 v[76:79], v[128:131], v[188:191], 0
	v_mfma_f32_16x16x32_bf16 v[72:75], v[136:139], v[188:191], 0
	v_mfma_f32_16x16x32_bf16 v[124:127], v[132:135], v[160:163], v[124:127]
	v_mfma_f32_16x16x32_bf16 v[120:123], v[140:143], v[160:163], v[120:123]
	v_mfma_f32_16x16x32_bf16 v[116:119], v[132:135], v[176:179], v[116:119]
	v_mfma_f32_16x16x32_bf16 v[104:107], v[140:143], v[176:179], v[104:107]
	v_mfma_f32_16x16x32_bf16 v[92:95], v[132:135], v[184:187], v[92:95]
	v_mfma_f32_16x16x32_bf16 v[88:91], v[140:143], v[184:187], v[88:91]
	v_mfma_f32_16x16x32_bf16 v[76:79], v[132:135], v[192:195], v[76:79]
	v_mfma_f32_16x16x32_bf16 v[72:75], v[140:143], v[192:195], v[72:75]
	s_barrier
	s_add_i32 s69, s58, s46
	v_lshl_add_u64 v[164:165], s[38:39], 0, v[146:147]
	s_mov_b32 m0, s69
	ds_read_b128 v[196:199], v171
	ds_read_b128 v[200:203], v171 offset:1024
	ds_read_b128 v[204:207], v171 offset:2048
	ds_read_b128 v[208:211], v171 offset:3072
	global_load_lds_dwordx4 v[164:165], off
	v_lshl_add_u64 v[212:213], s[38:39], 0, v[148:149]
	s_add_i32 m0, s69, 0x2000
	s_nop 0
	global_load_lds_dwordx4 v[212:213], off
	s_barrier
	s_waitcnt lgkmcnt(0)
	s_waitcnt lgkmcnt(0)
	v_mfma_f32_16x16x32_bf16 v[112:115], v[196:199], v[156:159], 0
	v_mfma_f32_16x16x32_bf16 v[108:111], v[204:207], v[156:159], 0
	v_mfma_f32_16x16x32_bf16 v[100:103], v[196:199], v[172:175], 0
	v_mfma_f32_16x16x32_bf16 v[96:99], v[204:207], v[172:175], 0
	v_mfma_f32_16x16x32_bf16 v[84:87], v[196:199], v[180:183], 0
	v_mfma_f32_16x16x32_bf16 v[80:83], v[204:207], v[180:183], 0
	v_mfma_f32_16x16x32_bf16 v[68:71], v[196:199], v[188:191], 0
	v_mfma_f32_16x16x32_bf16 v[64:67], v[204:207], v[188:191], 0
	v_mfma_f32_16x16x32_bf16 v[112:115], v[200:203], v[160:163], v[112:115]
	v_mfma_f32_16x16x32_bf16 v[108:111], v[208:211], v[160:163], v[108:111]
	v_mfma_f32_16x16x32_bf16 v[100:103], v[200:203], v[176:179], v[100:103]
	v_mfma_f32_16x16x32_bf16 v[96:99], v[208:211], v[176:179], v[96:99]
	v_mfma_f32_16x16x32_bf16 v[84:87], v[200:203], v[184:187], v[84:87]
	v_mfma_f32_16x16x32_bf16 v[80:83], v[208:211], v[184:187], v[80:83]
	v_mfma_f32_16x16x32_bf16 v[68:71], v[200:203], v[192:195], v[68:71]
	v_mfma_f32_16x16x32_bf16 v[64:67], v[208:211], v[192:195], v[64:67]
	s_mov_b32 m0, s47
	v_lshl_add_u64 v[214:215], s[40:41], 0, v[146:147]
	s_barrier
	ds_read_b128 v[156:159], v170 offset:16384
	ds_read_b128 v[160:163], v170 offset:17408
	ds_read_b128 v[172:175], v170 offset:18432
	ds_read_b128 v[176:179], v170 offset:19456
	ds_read_b128 v[180:183], v170 offset:20480
	ds_read_b128 v[184:187], v170 offset:21504
	ds_read_b128 v[188:191], v170 offset:22528
	ds_read_b128 v[192:195], v170 offset:23552
	global_load_lds_dwordx4 v[214:215], off
	v_lshl_add_u64 v[216:217], s[40:41], 0, v[148:149]
	s_mov_b32 m0, s48
	s_nop 0
	global_load_lds_dwordx4 v[216:217], off
	s_barrier
	s_waitcnt lgkmcnt(0)
	s_waitcnt lgkmcnt(0)
	v_mfma_f32_16x16x32_bf16 v[60:63], v[128:131], v[156:159], 0
	v_mfma_f32_16x16x32_bf16 v[56:59], v[136:139], v[156:159], 0
	v_mfma_f32_16x16x32_bf16 v[44:47], v[128:131], v[172:175], 0
	v_mfma_f32_16x16x32_bf16 v[40:43], v[136:139], v[172:175], 0
	v_mfma_f32_16x16x32_bf16 v[36:39], v[128:131], v[180:183], 0
	v_mfma_f32_16x16x32_bf16 v[28:31], v[136:139], v[180:183], 0
	v_mfma_f32_16x16x32_bf16 v[20:23], v[128:131], v[188:191], 0
	v_mfma_f32_16x16x32_bf16 v[12:15], v[136:139], v[188:191], 0
	v_mfma_f32_16x16x32_bf16 v[60:63], v[132:135], v[160:163], v[60:63]
	v_mfma_f32_16x16x32_bf16 v[56:59], v[140:143], v[160:163], v[56:59]
	v_mfma_f32_16x16x32_bf16 v[44:47], v[132:135], v[176:179], v[44:47]
	v_mfma_f32_16x16x32_bf16 v[40:43], v[140:143], v[176:179], v[40:43]
	v_mfma_f32_16x16x32_bf16 v[36:39], v[132:135], v[184:187], v[36:39]
	v_mfma_f32_16x16x32_bf16 v[28:31], v[140:143], v[184:187], v[28:31]
	v_mfma_f32_16x16x32_bf16 v[20:23], v[132:135], v[192:195], v[20:23]
	v_mfma_f32_16x16x32_bf16 v[12:15], v[140:143], v[192:195], v[12:15]
	s_barrier
	s_add_u32 s70, s38, 0x160000
	s_addc_u32 s71, s39, 0
	s_add_i32 s69, s59, s46
	v_lshl_add_u64 v[128:129], s[70:71], 0, v[146:147]
	s_mov_b32 m0, s69
	s_nop 0
	global_load_lds_dwordx4 v[128:129], off
	v_lshl_add_u64 v[128:129], s[70:71], 0, v[148:149]
	s_add_i32 m0, s69, 0x2000
	s_nop 0
	global_load_lds_dwordx4 v[128:129], off
	s_waitcnt vmcnt(6)
	s_barrier
	v_mfma_f32_16x16x32_bf16 v[52:55], v[196:199], v[156:159], 0
	v_mfma_f32_16x16x32_bf16 v[48:51], v[204:207], v[156:159], 0
	v_mfma_f32_16x16x32_bf16 v[32:35], v[196:199], v[172:175], 0
	v_mfma_f32_16x16x32_bf16 v[24:27], v[204:207], v[172:175], 0
	v_mfma_f32_16x16x32_bf16 v[16:19], v[196:199], v[180:183], 0
	v_mfma_f32_16x16x32_bf16 v[8:11], v[204:207], v[180:183], 0
	v_mfma_f32_16x16x32_bf16 v[4:7], v[196:199], v[188:191], 0
	v_mfma_f32_16x16x32_bf16 v[0:3], v[204:207], v[188:191], 0
	v_mfma_f32_16x16x32_bf16 v[52:55], v[200:203], v[160:163], v[52:55]
	v_mfma_f32_16x16x32_bf16 v[48:51], v[208:211], v[160:163], v[48:51]
	v_mfma_f32_16x16x32_bf16 v[32:35], v[200:203], v[176:179], v[32:35]
	v_mfma_f32_16x16x32_bf16 v[24:27], v[208:211], v[176:179], v[24:27]
	v_mfma_f32_16x16x32_bf16 v[16:19], v[200:203], v[184:187], v[16:19]
	v_mfma_f32_16x16x32_bf16 v[8:11], v[208:211], v[184:187], v[8:11]
	v_mfma_f32_16x16x32_bf16 v[4:7], v[200:203], v[192:195], v[4:7]
	v_mfma_f32_16x16x32_bf16 v[0:3], v[208:211], v[192:195], v[0:3]
	s_add_i32 s69, 0, 0x18000
	v_add_u32_e32 v140, s69, v167
	s_barrier
	ds_read_b128 v[128:131], v140
	ds_read_b128 v[132:135], v140 offset:1024
	ds_read_b128 v[136:139], v140 offset:2048
	ds_read_b128 v[140:143], v140 offset:3072
	s_add_u32 s40, s40, 0x160000
	s_addc_u32 s41, s41, 0
	s_mov_b32 m0, s49
	v_lshl_add_u64 v[196:197], s[40:41], 0, v[146:147]
	ds_read_b128 v[156:159], v170 offset:32768
	ds_read_b128 v[160:163], v170 offset:33792
	ds_read_b128 v[172:175], v170 offset:34816
	ds_read_b128 v[176:179], v170 offset:35840
	ds_read_b128 v[180:183], v170 offset:36864
	ds_read_b128 v[184:187], v170 offset:37888
	ds_read_b128 v[188:191], v170 offset:38912
	ds_read_b128 v[192:195], v170 offset:39936
	global_load_lds_dwordx4 v[196:197], off
	v_lshl_add_u64 v[196:197], s[40:41], 0, v[148:149]
	s_mov_b32 m0, s50
	s_nop 0
	global_load_lds_dwordx4 v[196:197], off
	s_waitcnt lgkmcnt(8)
	s_barrier
	s_waitcnt lgkmcnt(0)
	s_waitcnt lgkmcnt(0)
	v_mfma_f32_16x16x32_bf16 v[124:127], v[128:131], v[156:159], v[124:127]
	v_mfma_f32_16x16x32_bf16 v[120:123], v[136:139], v[156:159], v[120:123]
	v_mfma_f32_16x16x32_bf16 v[116:119], v[128:131], v[172:175], v[116:119]
	v_mfma_f32_16x16x32_bf16 v[104:107], v[136:139], v[172:175], v[104:107]
	v_mfma_f32_16x16x32_bf16 v[92:95], v[128:131], v[180:183], v[92:95]
	v_mfma_f32_16x16x32_bf16 v[88:91], v[136:139], v[180:183], v[88:91]
	v_mfma_f32_16x16x32_bf16 v[76:79], v[128:131], v[188:191], v[76:79]
	v_mfma_f32_16x16x32_bf16 v[72:75], v[136:139], v[188:191], v[72:75]
	v_mfma_f32_16x16x32_bf16 v[124:127], v[132:135], v[160:163], v[124:127]
	v_mfma_f32_16x16x32_bf16 v[120:123], v[140:143], v[160:163], v[120:123]
	v_mfma_f32_16x16x32_bf16 v[116:119], v[132:135], v[176:179], v[116:119]
	v_mfma_f32_16x16x32_bf16 v[104:107], v[140:143], v[176:179], v[104:107]
	v_mfma_f32_16x16x32_bf16 v[92:95], v[132:135], v[184:187], v[92:95]
	v_mfma_f32_16x16x32_bf16 v[88:91], v[140:143], v[184:187], v[88:91]
	v_mfma_f32_16x16x32_bf16 v[76:79], v[132:135], v[192:195], v[76:79]
	v_mfma_f32_16x16x32_bf16 v[72:75], v[140:143], v[192:195], v[72:75]
	s_barrier
	s_add_i32 s40, 0, 0x1c000
	s_add_i32 s41, s69, s46
	v_add_u32_e32 v208, s40, v167
	v_lshl_add_u64 v[164:165], v[164:165], 0, s[10:11]
	s_mov_b32 m0, s41
	ds_read_b128 v[196:199], v208
	ds_read_b128 v[200:203], v208 offset:1024
	ds_read_b128 v[204:207], v208 offset:2048
	ds_read_b128 v[208:211], v208 offset:3072
	global_load_lds_dwordx4 v[164:165], off
	v_lshl_add_u64 v[164:165], v[212:213], 0, s[10:11]
	s_add_i32 m0, s41, 0x2000
	s_nop 0
	global_load_lds_dwordx4 v[164:165], off
	s_barrier
	s_waitcnt lgkmcnt(0)
	s_waitcnt lgkmcnt(0)
	v_mfma_f32_16x16x32_bf16 v[112:115], v[196:199], v[156:159], v[112:115]
	v_mfma_f32_16x16x32_bf16 v[108:111], v[204:207], v[156:159], v[108:111]
	v_mfma_f32_16x16x32_bf16 v[100:103], v[196:199], v[172:175], v[100:103]
	v_mfma_f32_16x16x32_bf16 v[96:99], v[204:207], v[172:175], v[96:99]
	v_mfma_f32_16x16x32_bf16 v[84:87], v[196:199], v[180:183], v[84:87]
	v_mfma_f32_16x16x32_bf16 v[80:83], v[204:207], v[180:183], v[80:83]
	v_mfma_f32_16x16x32_bf16 v[68:71], v[196:199], v[188:191], v[68:71]
	v_mfma_f32_16x16x32_bf16 v[64:67], v[204:207], v[188:191], v[64:67]
	v_mfma_f32_16x16x32_bf16 v[112:115], v[200:203], v[160:163], v[112:115]
	v_mfma_f32_16x16x32_bf16 v[108:111], v[208:211], v[160:163], v[108:111]
	v_mfma_f32_16x16x32_bf16 v[100:103], v[200:203], v[176:179], v[100:103]
	v_mfma_f32_16x16x32_bf16 v[96:99], v[208:211], v[176:179], v[96:99]
	v_mfma_f32_16x16x32_bf16 v[84:87], v[200:203], v[184:187], v[84:87]
	v_mfma_f32_16x16x32_bf16 v[80:83], v[208:211], v[184:187], v[80:83]
	v_mfma_f32_16x16x32_bf16 v[68:71], v[200:203], v[192:195], v[68:71]
	v_mfma_f32_16x16x32_bf16 v[64:67], v[208:211], v[192:195], v[64:67]
	s_mov_b32 m0, s54
	v_lshl_add_u64 v[164:165], v[214:215], 0, s[10:11]
	s_barrier
	ds_read_b128 v[156:159], v170 offset:49152
	ds_read_b128 v[160:163], v170 offset:50176
	ds_read_b128 v[172:175], v170 offset:51200
	ds_read_b128 v[176:179], v170 offset:52224
	ds_read_b128 v[180:183], v170 offset:53248
	ds_read_b128 v[184:187], v170 offset:54272
	ds_read_b128 v[188:191], v170 offset:55296
	ds_read_b128 v[192:195], v170 offset:56320
	global_load_lds_dwordx4 v[164:165], off
	v_lshl_add_u64 v[164:165], v[216:217], 0, s[10:11]
	s_mov_b32 m0, s55
	s_nop 0
	global_load_lds_dwordx4 v[164:165], off
	s_barrier
	s_waitcnt lgkmcnt(0)
	s_waitcnt lgkmcnt(0)
	v_mfma_f32_16x16x32_bf16 v[60:63], v[128:131], v[156:159], v[60:63]
	v_mfma_f32_16x16x32_bf16 v[56:59], v[136:139], v[156:159], v[56:59]
	v_mfma_f32_16x16x32_bf16 v[44:47], v[128:131], v[172:175], v[44:47]
	v_mfma_f32_16x16x32_bf16 v[40:43], v[136:139], v[172:175], v[40:43]
	v_mfma_f32_16x16x32_bf16 v[36:39], v[128:131], v[180:183], v[36:39]
	v_mfma_f32_16x16x32_bf16 v[28:31], v[136:139], v[180:183], v[28:31]
	v_mfma_f32_16x16x32_bf16 v[20:23], v[128:131], v[188:191], v[20:23]
	v_mfma_f32_16x16x32_bf16 v[12:15], v[136:139], v[188:191], v[12:15]
	v_mfma_f32_16x16x32_bf16 v[60:63], v[132:135], v[160:163], v[60:63]
	v_mfma_f32_16x16x32_bf16 v[56:59], v[140:143], v[160:163], v[56:59]
	v_mfma_f32_16x16x32_bf16 v[44:47], v[132:135], v[176:179], v[44:47]
	v_mfma_f32_16x16x32_bf16 v[40:43], v[140:143], v[176:179], v[40:43]
	v_mfma_f32_16x16x32_bf16 v[36:39], v[132:135], v[184:187], v[36:39]
	v_mfma_f32_16x16x32_bf16 v[28:31], v[140:143], v[184:187], v[28:31]
	v_mfma_f32_16x16x32_bf16 v[20:23], v[132:135], v[192:195], v[20:23]
	v_mfma_f32_16x16x32_bf16 v[12:15], v[140:143], v[192:195], v[12:15]
	s_barrier
	s_add_u32 s38, s38, 0x160080
	s_addc_u32 s39, s39, 0
	s_add_i32 s40, s40, s46
	v_lshl_add_u64 v[128:129], s[38:39], 0, v[146:147]
	s_mov_b32 m0, s40
	s_nop 0
	global_load_lds_dwordx4 v[128:129], off
	v_lshl_add_u64 v[128:129], s[38:39], 0, v[148:149]
	s_add_i32 m0, s40, 0x2000
	s_nop 0
	global_load_lds_dwordx4 v[128:129], off
	s_waitcnt vmcnt(6)
	s_barrier
	v_mfma_f32_16x16x32_bf16 v[52:55], v[196:199], v[156:159], v[52:55]
	v_mfma_f32_16x16x32_bf16 v[48:51], v[204:207], v[156:159], v[48:51]
	v_mfma_f32_16x16x32_bf16 v[32:35], v[196:199], v[172:175], v[32:35]
	v_mfma_f32_16x16x32_bf16 v[24:27], v[204:207], v[172:175], v[24:27]
	v_mfma_f32_16x16x32_bf16 v[16:19], v[196:199], v[180:183], v[16:19]
	v_mfma_f32_16x16x32_bf16 v[8:11], v[204:207], v[180:183], v[8:11]
	v_mfma_f32_16x16x32_bf16 v[4:7], v[196:199], v[188:191], v[4:7]
	v_mfma_f32_16x16x32_bf16 v[0:3], v[204:207], v[188:191], v[0:3]
	v_mfma_f32_16x16x32_bf16 v[52:55], v[200:203], v[160:163], v[52:55]
	v_mfma_f32_16x16x32_bf16 v[48:51], v[208:211], v[160:163], v[48:51]
	v_mfma_f32_16x16x32_bf16 v[32:35], v[200:203], v[176:179], v[32:35]
	v_mfma_f32_16x16x32_bf16 v[24:27], v[208:211], v[176:179], v[24:27]
	v_mfma_f32_16x16x32_bf16 v[16:19], v[200:203], v[184:187], v[16:19]
	v_mfma_f32_16x16x32_bf16 v[8:11], v[208:211], v[184:187], v[8:11]
	v_mfma_f32_16x16x32_bf16 v[4:7], v[200:203], v[192:195], v[4:7]
	v_mfma_f32_16x16x32_bf16 v[0:3], v[208:211], v[192:195], v[0:3]
	s_add_i32 s68, s68, 2
	s_add_u32 s36, s36, 0x100
	s_addc_u32 s37, s37, 0
	s_add_u32 s28, s28, 0x100
	s_addc_u32 s29, s29, 0
	s_cmpk_gt_u32 s68, 0x55
	s_barrier
	s_cbranch_scc0 .LBB0_1285
.LBB0_1285:
	ds_read_b128 v[128:131], v169
	ds_read_b128 v[132:135], v169 offset:1024
	ds_read_b128 v[136:139], v169 offset:2048
	ds_read_b128 v[140:143], v169 offset:3072
	s_add_u32 s38, s36, 0xffea0080
	s_addc_u32 s39, s37, -1
	s_cmpk_eq_i32 s68, 0x54
	s_cselect_b32 s41, s35, s39
	s_cselect_b32 s40, s34, s38
	s_cselect_b32 s39, s1, s29
	s_cselect_b32 s38, s0, s28
	v_lshl_add_u64 v[164:165], s[36:37], 0, v[150:151]
	s_add_i32 m0, s47, 0xc000
	ds_read_b128 v[156:159], v170
	ds_read_b128 v[160:163], v170 offset:1024
	ds_read_b128 v[172:175], v170 offset:2048
	ds_read_b128 v[176:179], v170 offset:3072
	ds_read_b128 v[180:183], v170 offset:4096
	ds_read_b128 v[184:187], v170 offset:5120
	ds_read_b128 v[188:191], v170 offset:6144
	ds_read_b128 v[192:195], v170 offset:7168
	global_load_lds_dwordx4 v[164:165], off
	v_lshl_add_u64 v[164:165], s[36:37], 0, v[152:153]
	s_add_i32 m0, s47, 0xe000
	s_nop 0
	global_load_lds_dwordx4 v[164:165], off
	s_waitcnt lgkmcnt(8)
	s_barrier
	s_waitcnt lgkmcnt(0)
	s_waitcnt lgkmcnt(0)
	v_mfma_f32_16x16x32_bf16 v[124:127], v[128:131], v[156:159], v[124:127]
	v_mfma_f32_16x16x32_bf16 v[120:123], v[136:139], v[156:159], v[120:123]
	v_mfma_f32_16x16x32_bf16 v[116:119], v[128:131], v[172:175], v[116:119]
	v_mfma_f32_16x16x32_bf16 v[104:107], v[136:139], v[172:175], v[104:107]
	v_mfma_f32_16x16x32_bf16 v[92:95], v[128:131], v[180:183], v[92:95]
	v_mfma_f32_16x16x32_bf16 v[88:91], v[136:139], v[180:183], v[88:91]
	v_mfma_f32_16x16x32_bf16 v[76:79], v[128:131], v[188:191], v[76:79]
	v_mfma_f32_16x16x32_bf16 v[72:75], v[136:139], v[188:191], v[72:75]
	v_mfma_f32_16x16x32_bf16 v[124:127], v[132:135], v[160:163], v[124:127]
	v_mfma_f32_16x16x32_bf16 v[120:123], v[140:143], v[160:163], v[120:123]
	v_mfma_f32_16x16x32_bf16 v[116:119], v[132:135], v[176:179], v[116:119]
	v_mfma_f32_16x16x32_bf16 v[104:107], v[140:143], v[176:179], v[104:107]
	v_mfma_f32_16x16x32_bf16 v[92:95], v[132:135], v[184:187], v[92:95]
	v_mfma_f32_16x16x32_bf16 v[88:91], v[140:143], v[184:187], v[88:91]
	v_mfma_f32_16x16x32_bf16 v[76:79], v[132:135], v[192:195], v[76:79]
	v_mfma_f32_16x16x32_bf16 v[72:75], v[140:143], v[192:195], v[72:75]
	s_barrier
	s_add_i32 s69, s58, s46
	v_lshl_add_u64 v[164:165], s[38:39], 0, v[146:147]
	s_mov_b32 m0, s69
	ds_read_b128 v[196:199], v171
	ds_read_b128 v[200:203], v171 offset:1024
	ds_read_b128 v[204:207], v171 offset:2048
	ds_read_b128 v[208:211], v171 offset:3072
	global_load_lds_dwordx4 v[164:165], off
	v_lshl_add_u64 v[212:213], s[38:39], 0, v[148:149]
	s_add_i32 m0, s69, 0x2000
	s_nop 0
	global_load_lds_dwordx4 v[212:213], off
	s_barrier
	s_waitcnt lgkmcnt(0)
	s_waitcnt lgkmcnt(0)
	v_mfma_f32_16x16x32_bf16 v[112:115], v[196:199], v[156:159], v[112:115]
	v_mfma_f32_16x16x32_bf16 v[108:111], v[204:207], v[156:159], v[108:111]
	v_mfma_f32_16x16x32_bf16 v[100:103], v[196:199], v[172:175], v[100:103]
	v_mfma_f32_16x16x32_bf16 v[96:99], v[204:207], v[172:175], v[96:99]
	v_mfma_f32_16x16x32_bf16 v[84:87], v[196:199], v[180:183], v[84:87]
	v_mfma_f32_16x16x32_bf16 v[80:83], v[204:207], v[180:183], v[80:83]
	v_mfma_f32_16x16x32_bf16 v[68:71], v[196:199], v[188:191], v[68:71]
	v_mfma_f32_16x16x32_bf16 v[64:67], v[204:207], v[188:191], v[64:67]
	v_mfma_f32_16x16x32_bf16 v[112:115], v[200:203], v[160:163], v[112:115]
	v_mfma_f32_16x16x32_bf16 v[108:111], v[208:211], v[160:163], v[108:111]
	v_mfma_f32_16x16x32_bf16 v[100:103], v[200:203], v[176:179], v[100:103]
	v_mfma_f32_16x16x32_bf16 v[96:99], v[208:211], v[176:179], v[96:99]
	v_mfma_f32_16x16x32_bf16 v[84:87], v[200:203], v[184:187], v[84:87]
	v_mfma_f32_16x16x32_bf16 v[80:83], v[208:211], v[184:187], v[80:83]
	v_mfma_f32_16x16x32_bf16 v[68:71], v[200:203], v[192:195], v[68:71]
	v_mfma_f32_16x16x32_bf16 v[64:67], v[208:211], v[192:195], v[64:67]
	s_mov_b32 m0, s47
	v_lshl_add_u64 v[214:215], s[40:41], 0, v[146:147]
	s_barrier
	ds_read_b128 v[156:159], v170 offset:16384
	ds_read_b128 v[160:163], v170 offset:17408
	ds_read_b128 v[172:175], v170 offset:18432
	ds_read_b128 v[176:179], v170 offset:19456
	ds_read_b128 v[180:183], v170 offset:20480
	ds_read_b128 v[184:187], v170 offset:21504
	ds_read_b128 v[188:191], v170 offset:22528
	ds_read_b128 v[192:195], v170 offset:23552
	global_load_lds_dwordx4 v[214:215], off
	v_lshl_add_u64 v[216:217], s[40:41], 0, v[148:149]
	s_mov_b32 m0, s48
	s_nop 0
	global_load_lds_dwordx4 v[216:217], off
	s_barrier
	s_waitcnt lgkmcnt(0)
	s_waitcnt lgkmcnt(0)
	v_mfma_f32_16x16x32_bf16 v[60:63], v[128:131], v[156:159], v[60:63]
	v_mfma_f32_16x16x32_bf16 v[56:59], v[136:139], v[156:159], v[56:59]
	v_mfma_f32_16x16x32_bf16 v[44:47], v[128:131], v[172:175], v[44:47]
	v_mfma_f32_16x16x32_bf16 v[40:43], v[136:139], v[172:175], v[40:43]
	v_mfma_f32_16x16x32_bf16 v[36:39], v[128:131], v[180:183], v[36:39]
	v_mfma_f32_16x16x32_bf16 v[28:31], v[136:139], v[180:183], v[28:31]
	v_mfma_f32_16x16x32_bf16 v[20:23], v[128:131], v[188:191], v[20:23]
	v_mfma_f32_16x16x32_bf16 v[12:15], v[136:139], v[188:191], v[12:15]
	v_mfma_f32_16x16x32_bf16 v[60:63], v[132:135], v[160:163], v[60:63]
	v_mfma_f32_16x16x32_bf16 v[56:59], v[140:143], v[160:163], v[56:59]
	v_mfma_f32_16x16x32_bf16 v[44:47], v[132:135], v[176:179], v[44:47]
	v_mfma_f32_16x16x32_bf16 v[40:43], v[140:143], v[176:179], v[40:43]
	v_mfma_f32_16x16x32_bf16 v[36:39], v[132:135], v[184:187], v[36:39]
	v_mfma_f32_16x16x32_bf16 v[28:31], v[140:143], v[184:187], v[28:31]
	v_mfma_f32_16x16x32_bf16 v[20:23], v[132:135], v[192:195], v[20:23]
	v_mfma_f32_16x16x32_bf16 v[12:15], v[140:143], v[192:195], v[12:15]
	s_barrier
	s_add_u32 s70, s38, 0x160000
	s_addc_u32 s71, s39, 0
	s_add_i32 s69, s59, s46
	v_lshl_add_u64 v[128:129], s[70:71], 0, v[146:147]
	s_mov_b32 m0, s69
	s_nop 0
	global_load_lds_dwordx4 v[128:129], off
	v_lshl_add_u64 v[128:129], s[70:71], 0, v[148:149]
	s_add_i32 m0, s69, 0x2000
	s_nop 0
	global_load_lds_dwordx4 v[128:129], off
	s_waitcnt vmcnt(6)
	s_barrier
	v_mfma_f32_16x16x32_bf16 v[52:55], v[196:199], v[156:159], v[52:55]
	v_mfma_f32_16x16x32_bf16 v[48:51], v[204:207], v[156:159], v[48:51]
	v_mfma_f32_16x16x32_bf16 v[32:35], v[196:199], v[172:175], v[32:35]
	v_mfma_f32_16x16x32_bf16 v[24:27], v[204:207], v[172:175], v[24:27]
	v_mfma_f32_16x16x32_bf16 v[16:19], v[196:199], v[180:183], v[16:19]
	v_mfma_f32_16x16x32_bf16 v[8:11], v[204:207], v[180:183], v[8:11]
	v_mfma_f32_16x16x32_bf16 v[4:7], v[196:199], v[188:191], v[4:7]
	v_mfma_f32_16x16x32_bf16 v[0:3], v[204:207], v[188:191], v[0:3]
	v_mfma_f32_16x16x32_bf16 v[52:55], v[200:203], v[160:163], v[52:55]
	v_mfma_f32_16x16x32_bf16 v[48:51], v[208:211], v[160:163], v[48:51]
	v_mfma_f32_16x16x32_bf16 v[32:35], v[200:203], v[176:179], v[32:35]
	v_mfma_f32_16x16x32_bf16 v[24:27], v[208:211], v[176:179], v[24:27]
	v_mfma_f32_16x16x32_bf16 v[16:19], v[200:203], v[184:187], v[16:19]
	v_mfma_f32_16x16x32_bf16 v[8:11], v[208:211], v[184:187], v[8:11]
	v_mfma_f32_16x16x32_bf16 v[4:7], v[200:203], v[192:195], v[4:7]
	v_mfma_f32_16x16x32_bf16 v[0:3], v[208:211], v[192:195], v[0:3]
	s_add_i32 s69, 0, 0x18000
	v_add_u32_e32 v140, s69, v167
	s_barrier
	ds_read_b128 v[128:131], v140
	ds_read_b128 v[132:135], v140 offset:1024
	ds_read_b128 v[136:139], v140 offset:2048
	ds_read_b128 v[140:143], v140 offset:3072
	s_add_u32 s40, s40, 0x160000
	s_addc_u32 s41, s41, 0
	s_mov_b32 m0, s49
	v_lshl_add_u64 v[196:197], s[40:41], 0, v[146:147]
	ds_read_b128 v[156:159], v170 offset:32768
	ds_read_b128 v[160:163], v170 offset:33792
	ds_read_b128 v[172:175], v170 offset:34816
	ds_read_b128 v[176:179], v170 offset:35840
	ds_read_b128 v[180:183], v170 offset:36864
	ds_read_b128 v[184:187], v170 offset:37888
	ds_read_b128 v[188:191], v170 offset:38912
	ds_read_b128 v[192:195], v170 offset:39936
	global_load_lds_dwordx4 v[196:197], off
	v_lshl_add_u64 v[196:197], s[40:41], 0, v[148:149]
	s_mov_b32 m0, s50
	s_nop 0
	global_load_lds_dwordx4 v[196:197], off
	s_waitcnt lgkmcnt(8)
	s_barrier
	s_waitcnt lgkmcnt(0)
	s_waitcnt lgkmcnt(0)
	v_mfma_f32_16x16x32_bf16 v[124:127], v[128:131], v[156:159], v[124:127]
	v_mfma_f32_16x16x32_bf16 v[120:123], v[136:139], v[156:159], v[120:123]
	v_mfma_f32_16x16x32_bf16 v[116:119], v[128:131], v[172:175], v[116:119]
	v_mfma_f32_16x16x32_bf16 v[104:107], v[136:139], v[172:175], v[104:107]
	v_mfma_f32_16x16x32_bf16 v[92:95], v[128:131], v[180:183], v[92:95]
	v_mfma_f32_16x16x32_bf16 v[88:91], v[136:139], v[180:183], v[88:91]
	v_mfma_f32_16x16x32_bf16 v[76:79], v[128:131], v[188:191], v[76:79]
	v_mfma_f32_16x16x32_bf16 v[72:75], v[136:139], v[188:191], v[72:75]
	v_mfma_f32_16x16x32_bf16 v[124:127], v[132:135], v[160:163], v[124:127]
	v_mfma_f32_16x16x32_bf16 v[120:123], v[140:143], v[160:163], v[120:123]
	v_mfma_f32_16x16x32_bf16 v[116:119], v[132:135], v[176:179], v[116:119]
	v_mfma_f32_16x16x32_bf16 v[104:107], v[140:143], v[176:179], v[104:107]
	v_mfma_f32_16x16x32_bf16 v[92:95], v[132:135], v[184:187], v[92:95]
	v_mfma_f32_16x16x32_bf16 v[88:91], v[140:143], v[184:187], v[88:91]
	v_mfma_f32_16x16x32_bf16 v[76:79], v[132:135], v[192:195], v[76:79]
	v_mfma_f32_16x16x32_bf16 v[72:75], v[140:143], v[192:195], v[72:75]
	s_barrier
	s_add_i32 s40, 0, 0x1c000
	s_add_i32 s41, s69, s46
	v_add_u32_e32 v208, s40, v167
	v_lshl_add_u64 v[164:165], v[164:165], 0, s[10:11]
	s_mov_b32 m0, s41
	ds_read_b128 v[196:199], v208
	ds_read_b128 v[200:203], v208 offset:1024
	ds_read_b128 v[204:207], v208 offset:2048
	ds_read_b128 v[208:211], v208 offset:3072
	global_load_lds_dwordx4 v[164:165], off
	v_lshl_add_u64 v[164:165], v[212:213], 0, s[10:11]
	s_add_i32 m0, s41, 0x2000
	s_nop 0
	global_load_lds_dwordx4 v[164:165], off
	s_barrier
	s_waitcnt lgkmcnt(0)
	s_waitcnt lgkmcnt(0)
	v_mfma_f32_16x16x32_bf16 v[112:115], v[196:199], v[156:159], v[112:115]
	v_mfma_f32_16x16x32_bf16 v[108:111], v[204:207], v[156:159], v[108:111]
	v_mfma_f32_16x16x32_bf16 v[100:103], v[196:199], v[172:175], v[100:103]
	v_mfma_f32_16x16x32_bf16 v[96:99], v[204:207], v[172:175], v[96:99]
	v_mfma_f32_16x16x32_bf16 v[84:87], v[196:199], v[180:183], v[84:87]
	v_mfma_f32_16x16x32_bf16 v[80:83], v[204:207], v[180:183], v[80:83]
	v_mfma_f32_16x16x32_bf16 v[68:71], v[196:199], v[188:191], v[68:71]
	v_mfma_f32_16x16x32_bf16 v[64:67], v[204:207], v[188:191], v[64:67]
	v_mfma_f32_16x16x32_bf16 v[112:115], v[200:203], v[160:163], v[112:115]
	v_mfma_f32_16x16x32_bf16 v[108:111], v[208:211], v[160:163], v[108:111]
	v_mfma_f32_16x16x32_bf16 v[100:103], v[200:203], v[176:179], v[100:103]
	v_mfma_f32_16x16x32_bf16 v[96:99], v[208:211], v[176:179], v[96:99]
	v_mfma_f32_16x16x32_bf16 v[84:87], v[200:203], v[184:187], v[84:87]
	v_mfma_f32_16x16x32_bf16 v[80:83], v[208:211], v[184:187], v[80:83]
	v_mfma_f32_16x16x32_bf16 v[68:71], v[200:203], v[192:195], v[68:71]
	v_mfma_f32_16x16x32_bf16 v[64:67], v[208:211], v[192:195], v[64:67]
	s_mov_b32 m0, s54
	v_lshl_add_u64 v[164:165], v[214:215], 0, s[10:11]
	s_barrier
	ds_read_b128 v[156:159], v170 offset:49152
	ds_read_b128 v[160:163], v170 offset:50176
	ds_read_b128 v[172:175], v170 offset:51200
	ds_read_b128 v[176:179], v170 offset:52224
	ds_read_b128 v[180:183], v170 offset:53248
	ds_read_b128 v[184:187], v170 offset:54272
	ds_read_b128 v[188:191], v170 offset:55296
	ds_read_b128 v[192:195], v170 offset:56320
	global_load_lds_dwordx4 v[164:165], off
	v_lshl_add_u64 v[164:165], v[216:217], 0, s[10:11]
	s_mov_b32 m0, s55
	s_nop 0
	global_load_lds_dwordx4 v[164:165], off
	s_barrier
	s_waitcnt lgkmcnt(0)
	s_waitcnt lgkmcnt(0)
	v_mfma_f32_16x16x32_bf16 v[60:63], v[128:131], v[156:159], v[60:63]
	v_mfma_f32_16x16x32_bf16 v[56:59], v[136:139], v[156:159], v[56:59]
	v_mfma_f32_16x16x32_bf16 v[44:47], v[128:131], v[172:175], v[44:47]
	v_mfma_f32_16x16x32_bf16 v[40:43], v[136:139], v[172:175], v[40:43]
	v_mfma_f32_16x16x32_bf16 v[36:39], v[128:131], v[180:183], v[36:39]
	v_mfma_f32_16x16x32_bf16 v[28:31], v[136:139], v[180:183], v[28:31]
	v_mfma_f32_16x16x32_bf16 v[20:23], v[128:131], v[188:191], v[20:23]
	v_mfma_f32_16x16x32_bf16 v[12:15], v[136:139], v[188:191], v[12:15]
	v_mfma_f32_16x16x32_bf16 v[60:63], v[132:135], v[160:163], v[60:63]
	v_mfma_f32_16x16x32_bf16 v[56:59], v[140:143], v[160:163], v[56:59]
	v_mfma_f32_16x16x32_bf16 v[44:47], v[132:135], v[176:179], v[44:47]
	v_mfma_f32_16x16x32_bf16 v[40:43], v[140:143], v[176:179], v[40:43]
	v_mfma_f32_16x16x32_bf16 v[36:39], v[132:135], v[184:187], v[36:39]
	v_mfma_f32_16x16x32_bf16 v[28:31], v[140:143], v[184:187], v[28:31]
	v_mfma_f32_16x16x32_bf16 v[20:23], v[132:135], v[192:195], v[20:23]
	v_mfma_f32_16x16x32_bf16 v[12:15], v[140:143], v[192:195], v[12:15]
	s_barrier
	s_add_u32 s38, s38, 0x160080
	s_addc_u32 s39, s39, 0
	s_add_i32 s40, s40, s46
	v_lshl_add_u64 v[128:129], s[38:39], 0, v[146:147]
	s_mov_b32 m0, s40
	s_nop 0
	global_load_lds_dwordx4 v[128:129], off
	v_lshl_add_u64 v[128:129], s[38:39], 0, v[148:149]
	s_add_i32 m0, s40, 0x2000
	s_nop 0
	global_load_lds_dwordx4 v[128:129], off
	s_waitcnt vmcnt(6)
	s_barrier
	v_mfma_f32_16x16x32_bf16 v[52:55], v[196:199], v[156:159], v[52:55]
	v_mfma_f32_16x16x32_bf16 v[48:51], v[204:207], v[156:159], v[48:51]
	v_mfma_f32_16x16x32_bf16 v[32:35], v[196:199], v[172:175], v[32:35]
	v_mfma_f32_16x16x32_bf16 v[24:27], v[204:207], v[172:175], v[24:27]
	v_mfma_f32_16x16x32_bf16 v[16:19], v[196:199], v[180:183], v[16:19]
	v_mfma_f32_16x16x32_bf16 v[8:11], v[204:207], v[180:183], v[8:11]
	v_mfma_f32_16x16x32_bf16 v[4:7], v[196:199], v[188:191], v[4:7]
	v_mfma_f32_16x16x32_bf16 v[0:3], v[204:207], v[188:191], v[0:3]
	v_mfma_f32_16x16x32_bf16 v[52:55], v[200:203], v[160:163], v[52:55]
	v_mfma_f32_16x16x32_bf16 v[48:51], v[208:211], v[160:163], v[48:51]
	v_mfma_f32_16x16x32_bf16 v[32:35], v[200:203], v[176:179], v[32:35]
	v_mfma_f32_16x16x32_bf16 v[24:27], v[208:211], v[176:179], v[24:27]
	v_mfma_f32_16x16x32_bf16 v[16:19], v[200:203], v[184:187], v[16:19]
	v_mfma_f32_16x16x32_bf16 v[8:11], v[208:211], v[184:187], v[8:11]
	v_mfma_f32_16x16x32_bf16 v[4:7], v[200:203], v[192:195], v[4:7]
	v_mfma_f32_16x16x32_bf16 v[0:3], v[208:211], v[192:195], v[0:3]
	s_add_i32 s68, s68, 2
	s_add_u32 s36, s36, 0x100
	s_addc_u32 s37, s37, 0
	s_add_u32 s28, s28, 0x100
	s_addc_u32 s29, s29, 0
	s_cmpk_gt_u32 s68, 0x55
	s_barrier
	s_cbranch_scc0 .LBB0_1285
	v_lshl_add_u32 v164, s66, 8, v166
	v_lshl_or_b32 v128, s67, 8, v168
	v_ashrrev_i32_e32 v165, 31, v164
	s_ashr_i32 s28, s66, 3
	v_ashrrev_i32_e32 v129, 31, v128
	v_lshlrev_b64 v[130:131], 12, v[164:165]
	s_mul_hi_i32 s29, s28, 0xc000
	s_mul_i32 s28, s28, 0xc000
	v_lshl_add_u64 v[130:131], s[8:9], 0, v[130:131]
	v_lshlrev_b64 v[158:159], 1, v[128:129]
	s_add_u32 s28, s52, s28
	v_lshl_add_u64 v[156:157], v[130:131], 0, v[158:159]
	v_or_b32_e32 v130, 16, v164
	s_addc_u32 s29, s53, s29
	v_lshl_add_u64 v[128:129], v[128:129], 2, s[28:29]
	v_ashrrev_i32_e32 v131, 31, v130
	global_load_dwordx2 v[162:163], v[156:157], off
	global_load_dwordx2 v[172:173], v[156:157], off offset:32
	global_load_dwordx2 v[174:175], v[156:157], off offset:256
	global_load_dwordx4 v[132:135], v[128:129], off offset:512
	global_load_dwordx2 v[176:177], v[156:157], off offset:288
	global_load_dwordx4 v[140:143], v[128:129], off
	global_load_dwordx4 v[136:139], v[128:129], off offset:64
	v_lshlrev_b64 v[130:131], 12, v[130:131]
	v_lshl_add_u64 v[160:161], s[8:9], 0, v[130:131]
	global_load_dwordx4 v[128:131], v[128:129], off offset:576
	v_lshl_add_u64 v[160:161], v[160:161], 0, v[158:159]
	global_load_dwordx2 v[178:179], v[160:161], off
	global_load_dwordx2 v[180:181], v[160:161], off offset:32
	global_load_dwordx2 v[182:183], v[160:161], off offset:256
	global_load_dwordx2 v[186:187], v[160:161], off offset:288
	v_or_b32_e32 v184, 32, v164
	v_or_b32_e32 v164, 48, v164
	v_ashrrev_i32_e32 v185, 31, v184
	v_ashrrev_i32_e32 v165, 31, v164
	v_lshlrev_b64 v[184:185], 12, v[184:185]
	v_lshlrev_b64 v[164:165], 12, v[164:165]
	v_lshl_add_u64 v[184:185], s[8:9], 0, v[184:185]
	v_lshl_add_u64 v[164:165], s[8:9], 0, v[164:165]
	v_lshl_add_u64 v[184:185], v[184:185], 0, v[158:159]
	v_lshl_add_u64 v[158:159], v[164:165], 0, v[158:159]
	global_load_dwordx2 v[164:165], v[184:185], off
	global_load_dwordx2 v[188:189], v[184:185], off offset:32
	global_load_dwordx2 v[190:191], v[184:185], off offset:256
	global_load_dwordx2 v[192:193], v[184:185], off offset:288
	global_load_dwordx2 v[194:195], v[158:159], off
	s_mov_b32 s67, s64
	s_mov_b32 s66, s65
	s_mov_b64 s[38:39], s[0:1]
	s_mov_b64 s[36:37], s[34:35]
	s_waitcnt vmcnt(0)
	v_lshlrev_b32_e32 v196, 16, v162
	v_and_b32_e32 v197, 0xffff0000, v162
	v_lshlrev_b32_e32 v162, 16, v163
	v_and_b32_e32 v163, 0xffff0000, v163
	v_lshlrev_b32_e32 v198, 16, v172
	v_and_b32_e32 v199, 0xffff0000, v172
	v_lshlrev_b32_e32 v172, 16, v173
	v_and_b32_e32 v173, 0xffff0000, v173
	v_lshlrev_b32_e32 v200, 16, v174
	v_and_b32_e32 v201, 0xffff0000, v174
	v_lshlrev_b32_e32 v174, 16, v175
	v_and_b32_e32 v175, 0xffff0000, v175
	v_lshlrev_b32_e32 v202, 16, v176
	v_and_b32_e32 v203, 0xffff0000, v176
	v_lshlrev_b32_e32 v176, 16, v177
	v_and_b32_e32 v177, 0xffff0000, v177
	v_pk_fma_f32 v[126:127], v[126:127], v[142:143], v[162:163]
	v_pk_fma_f32 v[124:125], v[124:125], v[140:141], v[196:197]
	v_pk_fma_f32 v[122:123], v[122:123], v[138:139], v[172:173]
	v_pk_fma_f32 v[120:121], v[120:121], v[136:137], v[198:199]
	v_pk_fma_f32 v[114:115], v[114:115], v[134:135], v[174:175]
	v_pk_fma_f32 v[112:113], v[112:113], v[132:133], v[200:201]
	v_pk_fma_f32 v[110:111], v[110:111], v[130:131], v[176:177]
	v_pk_fma_f32 v[108:109], v[108:109], v[128:129], v[202:203]
	v_cvt_pk_bf16_f32 v124, v124, v125
	v_cvt_pk_bf16_f32 v125, v126, v127
	v_cvt_pk_bf16_f32 v120, v120, v121
	v_cvt_pk_bf16_f32 v121, v122, v123
	v_cvt_pk_bf16_f32 v112, v112, v113
	v_cvt_pk_bf16_f32 v113, v114, v115
	v_cvt_pk_bf16_f32 v108, v108, v109
	v_cvt_pk_bf16_f32 v109, v110, v111
	global_store_dwordx2 v[156:157], v[124:125], off
	global_store_dwordx2 v[156:157], v[120:121], off offset:32
	global_store_dwordx2 v[156:157], v[112:113], off offset:256
	global_store_dwordx2 v[156:157], v[108:109], off offset:288
	global_load_dwordx2 v[112:113], v[158:159], off offset:32
	v_lshlrev_b32_e32 v162, 16, v178
	v_and_b32_e32 v163, 0xffff0000, v178
	v_lshlrev_b32_e32 v172, 16, v179
	v_and_b32_e32 v173, 0xffff0000, v179
	v_pk_fma_f32 v[110:111], v[118:119], v[142:143], v[172:173]
	v_pk_fma_f32 v[114:115], v[116:117], v[140:141], v[162:163]
	v_cvt_pk_bf16_f32 v109, v110, v111
	v_cvt_pk_bf16_f32 v108, v114, v115
	global_store_dwordx2 v[160:161], v[108:109], off
	v_lshlrev_b32_e32 v108, 16, v180
	v_and_b32_e32 v109, 0xffff0000, v180
	v_lshlrev_b32_e32 v110, 16, v181
	v_and_b32_e32 v111, 0xffff0000, v181
	v_pk_fma_f32 v[106:107], v[106:107], v[138:139], v[110:111]
	v_pk_fma_f32 v[104:105], v[104:105], v[136:137], v[108:109]
	s_nop 0
	v_cvt_pk_bf16_f32 v104, v104, v105
	v_cvt_pk_bf16_f32 v105, v106, v107
	global_store_dwordx2 v[160:161], v[104:105], off offset:32
	v_lshlrev_b32_e32 v104, 16, v182
	v_and_b32_e32 v105, 0xffff0000, v182
	v_lshlrev_b32_e32 v106, 16, v183
	v_and_b32_e32 v107, 0xffff0000, v183
	v_pk_fma_f32 v[102:103], v[102:103], v[134:135], v[106:107]
	v_pk_fma_f32 v[100:101], v[100:101], v[132:133], v[104:105]
	v_lshlrev_b32_e32 v104, 16, v187
	v_cvt_pk_bf16_f32 v100, v100, v101
	v_cvt_pk_bf16_f32 v101, v102, v103
	global_load_dwordx2 v[102:103], v[158:159], off offset:256
	v_and_b32_e32 v105, 0xffff0000, v187
	global_store_dwordx2 v[160:161], v[100:101], off offset:256
	v_lshlrev_b32_e32 v100, 16, v186
	v_and_b32_e32 v101, 0xffff0000, v186
	v_pk_fma_f32 v[98:99], v[98:99], v[130:131], v[104:105]
	v_pk_fma_f32 v[96:97], v[96:97], v[128:129], v[100:101]
	v_lshlrev_b32_e32 v100, 16, v165
	v_cvt_pk_bf16_f32 v96, v96, v97
	v_cvt_pk_bf16_f32 v97, v98, v99
	global_store_dwordx2 v[160:161], v[96:97], off offset:288
	global_load_dwordx2 v[96:97], v[158:159], off offset:288
	v_and_b32_e32 v101, 0xffff0000, v165
	v_pk_fma_f32 v[94:95], v[94:95], v[142:143], v[100:101]
	v_add_co_u32_e32 v100, vcc, s60, v156
	v_lshlrev_b32_e32 v98, 16, v164
	v_and_b32_e32 v99, 0xffff0000, v164
	v_addc_co_u32_e32 v101, vcc, 0, v157, vcc
	global_load_dwordx2 v[104:105], v[100:101], off
	v_pk_fma_f32 v[92:93], v[92:93], v[140:141], v[98:99]
	s_nop 0
	v_cvt_pk_bf16_f32 v92, v92, v93
	v_cvt_pk_bf16_f32 v93, v94, v95
	global_store_dwordx2 v[184:185], v[92:93], off
	v_lshlrev_b32_e32 v92, 16, v188
	v_and_b32_e32 v93, 0xffff0000, v188
	v_lshlrev_b32_e32 v94, 16, v189
	v_and_b32_e32 v95, 0xffff0000, v189
	v_pk_fma_f32 v[90:91], v[90:91], v[138:139], v[94:95]
	v_pk_fma_f32 v[88:89], v[88:89], v[136:137], v[92:93]
	v_lshlrev_b32_e32 v92, 16, v190
	v_cvt_pk_bf16_f32 v88, v88, v89
	v_cvt_pk_bf16_f32 v89, v90, v91
	global_store_dwordx2 v[184:185], v[88:89], off offset:32
	v_lshl_add_u64 v[88:89], v[156:157], 0, s[12:13]
	global_load_dwordx2 v[90:91], v[88:89], off offset:32
	v_and_b32_e32 v93, 0xffff0000, v190
	v_lshlrev_b32_e32 v94, 16, v191
	v_and_b32_e32 v95, 0xffff0000, v191
	v_pk_fma_f32 v[86:87], v[86:87], v[134:135], v[94:95]
	v_pk_fma_f32 v[84:85], v[84:85], v[132:133], v[92:93]
	v_lshlrev_b32_e32 v92, 16, v193
	v_cvt_pk_bf16_f32 v84, v84, v85
	v_cvt_pk_bf16_f32 v85, v86, v87
	global_load_dwordx2 v[86:87], v[88:89], off offset:256
	v_and_b32_e32 v93, 0xffff0000, v193
	global_store_dwordx2 v[184:185], v[84:85], off offset:256
	v_lshlrev_b32_e32 v84, 16, v192
	v_and_b32_e32 v85, 0xffff0000, v192
	v_pk_fma_f32 v[82:83], v[82:83], v[130:131], v[92:93]
	v_pk_fma_f32 v[80:81], v[80:81], v[128:129], v[84:85]
	v_lshlrev_b32_e32 v84, 16, v195
	v_cvt_pk_bf16_f32 v80, v80, v81
	v_cvt_pk_bf16_f32 v81, v82, v83
	global_load_dwordx2 v[82:83], v[88:89], off offset:288
	v_and_b32_e32 v85, 0xffff0000, v195
	global_store_dwordx2 v[184:185], v[80:81], off offset:288
	v_lshlrev_b32_e32 v80, 16, v194
	v_and_b32_e32 v81, 0xffff0000, v194
	v_pk_fma_f32 v[78:79], v[78:79], v[142:143], v[84:85]
	v_pk_fma_f32 v[76:77], v[76:77], v[140:141], v[80:81]
	s_waitcnt vmcnt(0)
	v_lshlrev_b32_e32 v84, 16, v113
	v_cvt_pk_bf16_f32 v76, v76, v77
	v_cvt_pk_bf16_f32 v77, v78, v79
	v_add_co_u32_e32 v78, vcc, s61, v156
	global_store_dwordx2 v[158:159], v[76:77], off
	v_lshlrev_b32_e32 v76, 16, v112
	v_and_b32_e32 v77, 0xffff0000, v112
	v_addc_co_u32_e32 v79, vcc, 0, v157, vcc
	v_and_b32_e32 v85, 0xffff0000, v113
	global_load_dwordx2 v[80:81], v[78:79], off
	v_pk_fma_f32 v[74:75], v[74:75], v[138:139], v[84:85]
	v_pk_fma_f32 v[72:73], v[72:73], v[136:137], v[76:77]
	v_lshlrev_b32_e32 v84, 16, v103
	v_cvt_pk_bf16_f32 v72, v72, v73
	v_cvt_pk_bf16_f32 v73, v74, v75
	global_store_dwordx2 v[158:159], v[72:73], off offset:32
	v_lshl_add_u64 v[72:73], v[156:157], 0, s[14:15]
	global_load_dwordx2 v[76:77], v[72:73], off offset:32
	v_lshlrev_b32_e32 v74, 16, v102
	v_and_b32_e32 v75, 0xffff0000, v102
	v_and_b32_e32 v85, 0xffff0000, v103
	v_pk_fma_f32 v[70:71], v[70:71], v[134:135], v[84:85]
	v_pk_fma_f32 v[68:69], v[68:69], v[132:133], v[74:75]
	v_lshlrev_b32_e32 v74, 16, v97
	v_cvt_pk_bf16_f32 v68, v68, v69
	v_cvt_pk_bf16_f32 v69, v70, v71
	global_store_dwordx2 v[158:159], v[68:69], off offset:256
	v_lshlrev_b32_e32 v68, 16, v96
	v_and_b32_e32 v69, 0xffff0000, v96
	global_load_dwordx2 v[70:71], v[72:73], off offset:256
	v_and_b32_e32 v75, 0xffff0000, v97
	v_pk_fma_f32 v[66:67], v[66:67], v[130:131], v[74:75]
	v_pk_fma_f32 v[64:65], v[64:65], v[128:129], v[68:69]
	v_lshlrev_b32_e32 v68, 16, v105
	v_cvt_pk_bf16_f32 v64, v64, v65
	v_cvt_pk_bf16_f32 v65, v66, v67
	global_store_dwordx2 v[158:159], v[64:65], off offset:288
	v_lshlrev_b32_e32 v64, 16, v104
	v_and_b32_e32 v65, 0xffff0000, v104
	global_load_dwordx2 v[66:67], v[72:73], off offset:288
	v_pk_fma_f32 v[60:61], v[60:61], v[140:141], v[64:65]
	v_add_co_u32_e32 v64, vcc, s62, v156
	v_and_b32_e32 v69, 0xffff0000, v105
	s_nop 0
	v_addc_co_u32_e32 v65, vcc, 0, v157, vcc
	v_pk_fma_f32 v[62:63], v[62:63], v[142:143], v[68:69]
	global_load_dwordx2 v[68:69], v[64:65], off
	v_cvt_pk_bf16_f32 v60, v60, v61
	v_cvt_pk_bf16_f32 v61, v62, v63
	v_lshl_add_u64 v[74:75], v[156:157], 0, s[16:17]
	global_store_dwordx2 v[100:101], v[60:61], off
	v_lshlrev_b32_e32 v60, 16, v90
	v_and_b32_e32 v61, 0xffff0000, v90
	v_lshlrev_b32_e32 v62, 16, v91
	v_and_b32_e32 v63, 0xffff0000, v91
	global_load_dwordx2 v[84:85], v[74:75], off offset:32
	v_pk_fma_f32 v[58:59], v[58:59], v[138:139], v[62:63]
	v_pk_fma_f32 v[56:57], v[56:57], v[136:137], v[60:61]
	global_load_dwordx2 v[60:61], v[74:75], off offset:256
	v_cvt_pk_bf16_f32 v56, v56, v57
	v_cvt_pk_bf16_f32 v57, v58, v59
	global_store_dwordx2 v[88:89], v[56:57], off offset:32
	v_lshlrev_b32_e32 v56, 16, v86
	v_and_b32_e32 v57, 0xffff0000, v86
	v_lshlrev_b32_e32 v58, 16, v87
	v_and_b32_e32 v59, 0xffff0000, v87
	v_pk_fma_f32 v[54:55], v[54:55], v[134:135], v[58:59]
	v_pk_fma_f32 v[52:53], v[52:53], v[132:133], v[56:57]
	v_lshlrev_b32_e32 v56, 16, v83
	v_cvt_pk_bf16_f32 v52, v52, v53
	v_cvt_pk_bf16_f32 v53, v54, v55
	global_store_dwordx2 v[88:89], v[52:53], off offset:256
	v_lshlrev_b32_e32 v52, 16, v82
	v_and_b32_e32 v53, 0xffff0000, v82
	global_load_dwordx2 v[54:55], v[74:75], off offset:288
	v_pk_fma_f32 v[48:49], v[48:49], v[128:129], v[52:53]
	v_add_co_u32_e32 v52, vcc, s63, v156
	v_and_b32_e32 v57, 0xffff0000, v83
	s_nop 0
	v_addc_co_u32_e32 v53, vcc, 0, v157, vcc
	v_pk_fma_f32 v[50:51], v[50:51], v[130:131], v[56:57]
	global_load_dwordx2 v[56:57], v[52:53], off
	v_lshl_add_u64 v[58:59], v[156:157], 0, s[18:19]
	v_cvt_pk_bf16_f32 v48, v48, v49
	v_cvt_pk_bf16_f32 v49, v50, v51
	global_load_dwordx2 v[62:63], v[58:59], off offset:32
	s_waitcnt vmcnt(0)
	v_lshlrev_b32_e32 v50, 16, v81
	global_store_dwordx2 v[88:89], v[48:49], off offset:288
	v_lshlrev_b32_e32 v48, 16, v80
	v_and_b32_e32 v49, 0xffff0000, v80
	v_and_b32_e32 v51, 0xffff0000, v81
	v_pk_fma_f32 v[46:47], v[46:47], v[142:143], v[50:51]
	v_pk_fma_f32 v[44:45], v[44:45], v[140:141], v[48:49]
	global_load_dwordx2 v[48:49], v[58:59], off offset:256
	v_cvt_pk_bf16_f32 v44, v44, v45
	v_cvt_pk_bf16_f32 v45, v46, v47
	global_store_dwordx2 v[78:79], v[44:45], off
	v_lshlrev_b32_e32 v44, 16, v76
	v_and_b32_e32 v45, 0xffff0000, v76
	v_lshlrev_b32_e32 v46, 16, v77
	v_and_b32_e32 v47, 0xffff0000, v77
	v_pk_fma_f32 v[42:43], v[42:43], v[138:139], v[46:47]
	v_pk_fma_f32 v[40:41], v[40:41], v[136:137], v[44:45]
	s_and_b64 vcc, exec, s[30:31]
	v_cvt_pk_bf16_f32 v40, v40, v41
	v_cvt_pk_bf16_f32 v41, v42, v43
	global_load_dwordx2 v[42:43], v[58:59], off offset:288
	v_lshlrev_b32_e32 v44, 16, v71
	global_store_dwordx2 v[72:73], v[40:41], off offset:32
	v_lshlrev_b32_e32 v40, 16, v70
	v_and_b32_e32 v41, 0xffff0000, v70
	v_and_b32_e32 v45, 0xffff0000, v71
	v_pk_fma_f32 v[34:35], v[34:35], v[134:135], v[44:45]
	v_pk_fma_f32 v[32:33], v[32:33], v[132:133], v[40:41]
	s_nop 0
	v_cvt_pk_bf16_f32 v32, v32, v33
	v_cvt_pk_bf16_f32 v33, v34, v35
	global_store_dwordx2 v[72:73], v[32:33], off offset:256
	v_lshlrev_b32_e32 v32, 16, v66
	v_and_b32_e32 v33, 0xffff0000, v66
	v_lshlrev_b32_e32 v34, 16, v67
	v_and_b32_e32 v35, 0xffff0000, v67
	v_pk_fma_f32 v[26:27], v[26:27], v[130:131], v[34:35]
	v_pk_fma_f32 v[24:25], v[24:25], v[128:129], v[32:33]
	s_nop 0
	v_cvt_pk_bf16_f32 v24, v24, v25
	v_cvt_pk_bf16_f32 v25, v26, v27
	global_store_dwordx2 v[72:73], v[24:25], off offset:288
	v_lshlrev_b32_e32 v24, 16, v68
	v_and_b32_e32 v25, 0xffff0000, v68
	v_lshlrev_b32_e32 v26, 16, v69
	v_and_b32_e32 v27, 0xffff0000, v69
	v_pk_fma_f32 v[26:27], v[38:39], v[142:143], v[26:27]
	v_pk_fma_f32 v[24:25], v[36:37], v[140:141], v[24:25]
	s_nop 0
	v_cvt_pk_bf16_f32 v24, v24, v25
	v_cvt_pk_bf16_f32 v25, v26, v27
	global_store_dwordx2 v[64:65], v[24:25], off
	v_lshlrev_b32_e32 v24, 16, v84
	v_and_b32_e32 v25, 0xffff0000, v84
	v_lshlrev_b32_e32 v26, 16, v85
	v_and_b32_e32 v27, 0xffff0000, v85
	v_pk_fma_f32 v[26:27], v[30:31], v[138:139], v[26:27]
	v_pk_fma_f32 v[24:25], v[28:29], v[136:137], v[24:25]
	s_nop 0
	v_cvt_pk_bf16_f32 v24, v24, v25
	v_cvt_pk_bf16_f32 v25, v26, v27
	global_store_dwordx2 v[74:75], v[24:25], off offset:32
	v_lshlrev_b32_e32 v24, 16, v60
	v_and_b32_e32 v25, 0xffff0000, v60
	v_lshlrev_b32_e32 v26, 16, v61
	v_and_b32_e32 v27, 0xffff0000, v61
	v_pk_fma_f32 v[18:19], v[18:19], v[134:135], v[26:27]
	v_pk_fma_f32 v[16:17], v[16:17], v[132:133], v[24:25]
	s_nop 0
	v_cvt_pk_bf16_f32 v16, v16, v17
	v_cvt_pk_bf16_f32 v17, v18, v19
	global_store_dwordx2 v[74:75], v[16:17], off offset:256
	v_lshlrev_b32_e32 v16, 16, v54
	v_and_b32_e32 v17, 0xffff0000, v54
	v_lshlrev_b32_e32 v18, 16, v55
	v_and_b32_e32 v19, 0xffff0000, v55
	v_pk_fma_f32 v[10:11], v[10:11], v[130:131], v[18:19]
	v_pk_fma_f32 v[8:9], v[8:9], v[128:129], v[16:17]
	s_nop 0
	v_cvt_pk_bf16_f32 v8, v8, v9
	v_cvt_pk_bf16_f32 v9, v10, v11
	global_store_dwordx2 v[74:75], v[8:9], off offset:288
	v_lshlrev_b32_e32 v8, 16, v56
	v_and_b32_e32 v9, 0xffff0000, v56
	v_lshlrev_b32_e32 v10, 16, v57
	v_and_b32_e32 v11, 0xffff0000, v57
	v_pk_fma_f32 v[10:11], v[22:23], v[142:143], v[10:11]
	v_pk_fma_f32 v[8:9], v[20:21], v[140:141], v[8:9]
	s_nop 0
	v_cvt_pk_bf16_f32 v8, v8, v9
	v_cvt_pk_bf16_f32 v9, v10, v11
	global_store_dwordx2 v[52:53], v[8:9], off
	v_lshlrev_b32_e32 v8, 16, v62
	v_and_b32_e32 v9, 0xffff0000, v62
	v_lshlrev_b32_e32 v10, 16, v63
	v_and_b32_e32 v11, 0xffff0000, v63
	v_pk_fma_f32 v[10:11], v[14:15], v[138:139], v[10:11]
	v_pk_fma_f32 v[8:9], v[12:13], v[136:137], v[8:9]
	s_nop 0
	v_cvt_pk_bf16_f32 v8, v8, v9
	v_cvt_pk_bf16_f32 v9, v10, v11
	global_store_dwordx2 v[58:59], v[8:9], off offset:32
	s_waitcnt vmcnt(0)
	v_lshlrev_b32_e32 v8, 16, v48
	v_and_b32_e32 v9, 0xffff0000, v48
	v_lshlrev_b32_e32 v10, 16, v49
	v_and_b32_e32 v11, 0xffff0000, v49
	v_pk_fma_f32 v[6:7], v[6:7], v[134:135], v[10:11]
	v_pk_fma_f32 v[4:5], v[4:5], v[132:133], v[8:9]
	s_nop 0
	v_cvt_pk_bf16_f32 v4, v4, v5
	v_cvt_pk_bf16_f32 v5, v6, v7
	global_store_dwordx2 v[58:59], v[4:5], off offset:256
	v_lshlrev_b32_e32 v4, 16, v42
	v_and_b32_e32 v5, 0xffff0000, v42
	v_lshlrev_b32_e32 v6, 16, v43
	v_and_b32_e32 v7, 0xffff0000, v43
	v_pk_fma_f32 v[2:3], v[2:3], v[130:131], v[6:7]
	v_pk_fma_f32 v[0:1], v[0:1], v[128:129], v[4:5]
	s_nop 0
	v_cvt_pk_bf16_f32 v0, v0, v1
	v_cvt_pk_bf16_f32 v1, v2, v3
	global_store_dwordx2 v[58:59], v[0:1], off offset:288
	s_cbranch_vccz .LBB0_1272
	s_branch .LBB0_1288
